# v40 + s_setprio 1 raised just before the barrier that opens each MFMA segment (the wave leaves the barrier already prioritised)
# speedup vs baseline: 1.0005x; 1.0005x over previous
; #define PG8_STAGE(bufoff, gbase, voff) do { _Pragma("unroll") for (int _i = 0; _i < 2; ++_i) \
;         __builtin_amdgcn_global_load_lds((const unsigned*)((const char*)(gbase) + (voff)[_i]), (LAS unsigned*)(lds + (bufoff) + ldsw + _i * 8192), 16, 0, 0); } while (0)
; #define PG8_LDA(dst, b, h) do { _Pragma("unroll") for (int m = 0; m < 4; ++m) _Pragma("unroll") for (int k = 0; k < 2; ++k) dst[m][k] = *(const LAS bf16x8*)(lds + PG8_SA(b, h) + aoff + m * 2048 + k * 1024); } while (0)
; #define PG8_LDB(dst, b, h) do { _Pragma("unroll") for (int n = 0; n < 2; ++n) _Pragma("unroll") for (int k = 0; k < 2; ++k) dst[n][k] = *(const LAS bf16x8*)(lds + PG8_SB(b, h) + boff + n * 2048 + k * 1024); } while (0)
; #define PG8_MMA(ai, bj, At, Bt) do { __builtin_amdgcn_s_setprio(1); _Pragma("unroll") for (int m = 0; m < 4; ++m) _Pragma("unroll") for (int n = 0; n < 2; ++n) _Pragma("unroll") for (int k = 0; k < 2; ++k) \
;         acc[ai][bj][m][n] = __builtin_amdgcn_mfma_f32_16x16x32_bf16(Bt[n][k], At[m][k], acc[ai][bj][m][n], 0, 0, 0); __builtin_amdgcn_s_setprio(0); } while (0)
; #define PG8_WAIT_V(n) asm volatile("s_waitcnt vmcnt(" #n ")" ::: "memory")
; #define PG8_WAIT_L(n) asm volatile("s_waitcnt lgkmcnt(" #n ")" ::: "memory")
; #define PG8_BAR __builtin_amdgcn_s_barrier()
; #define PG8_SCHED __builtin_amdgcn_sched_barrier(0)
; template <class Epi>
; __device__ __forceinline__ void gemm_phase(LAS unsigned char* lds, const Gemm g, const StaticOrder& S, const Epi& E) {
;     ...
;             const bool last = (t == nt - 2);
;             const char* a1 = cA + (size_t)(t + 1) * kstep;
;             const char* a2 = last ? nA : cA + (size_t)(t + 2) * kstep; const char* b2 = last ? nB : cB + (size_t)(t + 2) * kstep;
;             const char* a3 = a2 + kstep; const char* b3 = b2 + kstep;
;             PG8_LDB(B0, 0, 0); PG8_LDB(B1, 0, 1); PG8_SCHED; PG8_LDA(At, 0, 0); PG8_STAGE(PG8_SA(1, 1), a1 + hstepA, voffA);
;             PG8_WAIT_V(8); PG8_WAIT_L(0); PG8_BAR; PG8_MMA(0, 0, At, B0); PG8_MMA(0, 1, At, B1); PG8_BAR; PG8_SCHED;
;             PG8_LDA(At, 0, 1); PG8_STAGE(PG8_SB(0, 0), b2, voffB); PG8_STAGE(PG8_SB(0, 1), b2 + hstepB, voffB); PG8_STAGE(PG8_SA(0, 0), a2, voffA);
;             PG8_WAIT_V(8); PG8_WAIT_L(0); PG8_BAR; PG8_MMA(1, 0, At, B0); PG8_MMA(1, 1, At, B1); PG8_BAR; PG8_SCHED;
.LBB0_414:
	s_add_u32 s14, s26, 0xfff80080
	s_addc_u32 s15, s27, -1
	s_add_i32 s33, 0, 0x10000
	s_cmp_eq_u32 s21, 28
	s_cselect_b32 s29, s0, s15
	s_cselect_b32 s28, s1, s14
	s_cselect_b32 s15, s3, s19
	s_cselect_b32 s14, s7, s9
	s_add_i32 s52, 0, 0x14000
	v_add_u32_e32 v150, s33, v1
	v_add_u32_e32 v159, s52, v1
	ds_read_b128 v[138:141], v150
	ds_read_b128 v[142:145], v150 offset:1024
	ds_read_b128 v[146:149], v150 offset:2048
	ds_read_b128 v[150:153], v150 offset:3072
	ds_read_b128 v[154:157], v159
	ds_read_b128 v[160:163], v159 offset:1024
	ds_read_b128 v[164:167], v159 offset:2048
	ds_read_b128 v[168:171], v159 offset:3072
	v_lshl_add_u64 v[184:185], s[26:27], 0, v[134:135]
	s_add_i32 m0, s35, 0xc000
	ds_read_b128 v[172:175], v158
	ds_read_b128 v[176:179], v158 offset:1024
	ds_read_b128 v[188:191], v158 offset:2048
	ds_read_b128 v[192:195], v158 offset:3072
	ds_read_b128 v[196:199], v158 offset:4096
	ds_read_b128 v[200:203], v158 offset:5120
	ds_read_b128 v[204:207], v158 offset:6144
	ds_read_b128 v[208:211], v158 offset:7168
	global_load_lds_dwordx4 v[184:185], off
	v_lshl_add_u64 v[184:185], s[26:27], 0, v[136:137]
	s_add_i32 m0, s35, 0xe000
	s_nop 0
	global_load_lds_dwordx4 v[184:185], off
	s_waitcnt vmcnt(8)
	s_waitcnt lgkmcnt(0)
	s_setprio 1
	s_barrier
	s_waitcnt lgkmcnt(0)
	v_mfma_f32_16x16x32_bf16 v[126:129], v[138:141], v[172:175], v[126:129]
	v_mfma_f32_16x16x32_bf16 v[122:125], v[146:149], v[172:175], v[122:125]
	v_mfma_f32_16x16x32_bf16 v[110:113], v[138:141], v[188:191], v[110:113]
	v_mfma_f32_16x16x32_bf16 v[106:109], v[146:149], v[188:191], v[106:109]
	v_mfma_f32_16x16x32_bf16 v[94:97], v[138:141], v[196:199], v[94:97]
	v_mfma_f32_16x16x32_bf16 v[90:93], v[146:149], v[196:199], v[90:93]
	v_mfma_f32_16x16x32_bf16 v[78:81], v[138:141], v[204:207], v[78:81]
	v_mfma_f32_16x16x32_bf16 v[74:77], v[146:149], v[204:207], v[74:77]
	v_mfma_f32_16x16x32_bf16 v[126:129], v[142:145], v[176:179], v[126:129]
	v_mfma_f32_16x16x32_bf16 v[122:125], v[150:153], v[176:179], v[122:125]
	v_mfma_f32_16x16x32_bf16 v[110:113], v[142:145], v[192:195], v[110:113]
	v_mfma_f32_16x16x32_bf16 v[106:109], v[150:153], v[192:195], v[106:109]
	v_mfma_f32_16x16x32_bf16 v[94:97], v[142:145], v[200:203], v[94:97]
	v_mfma_f32_16x16x32_bf16 v[90:93], v[150:153], v[200:203], v[90:93]
	v_mfma_f32_16x16x32_bf16 v[78:81], v[142:145], v[208:211], v[78:81]
	v_mfma_f32_16x16x32_bf16 v[74:77], v[150:153], v[208:211], v[74:77]
	v_mfma_f32_16x16x32_bf16 v[118:121], v[154:157], v[172:175], v[118:121]
	v_mfma_f32_16x16x32_bf16 v[114:117], v[164:167], v[172:175], v[114:117]
	v_mfma_f32_16x16x32_bf16 v[102:105], v[154:157], v[188:191], v[102:105]
	v_mfma_f32_16x16x32_bf16 v[98:101], v[164:167], v[188:191], v[98:101]
	v_mfma_f32_16x16x32_bf16 v[86:89], v[154:157], v[196:199], v[86:89]
	v_mfma_f32_16x16x32_bf16 v[82:85], v[164:167], v[196:199], v[82:85]
	v_mfma_f32_16x16x32_bf16 v[70:73], v[154:157], v[204:207], v[70:73]
	v_mfma_f32_16x16x32_bf16 v[66:69], v[164:167], v[204:207], v[66:69]
	v_mfma_f32_16x16x32_bf16 v[118:121], v[160:163], v[176:179], v[118:121]
	v_mfma_f32_16x16x32_bf16 v[114:117], v[168:171], v[176:179], v[114:117]
	v_mfma_f32_16x16x32_bf16 v[102:105], v[160:163], v[192:195], v[102:105]
	v_mfma_f32_16x16x32_bf16 v[98:101], v[168:171], v[192:195], v[98:101]
	v_mfma_f32_16x16x32_bf16 v[86:89], v[160:163], v[200:203], v[86:89]
	v_mfma_f32_16x16x32_bf16 v[82:85], v[168:171], v[200:203], v[82:85]
	v_mfma_f32_16x16x32_bf16 v[70:73], v[160:163], v[208:211], v[70:73]
	v_mfma_f32_16x16x32_bf16 v[66:69], v[168:171], v[208:211], v[66:69]
	s_setprio 0
	s_barrier
	s_add_i32 s33, s33, s34
	v_lshl_add_u64 v[184:185], s[14:15], 0, v[130:131]
	s_mov_b32 m0, s33
	ds_read_b128 v[172:175], v158 offset:16384
	ds_read_b128 v[176:179], v158 offset:17408
	ds_read_b128 v[188:191], v158 offset:18432
	ds_read_b128 v[192:195], v158 offset:19456
	ds_read_b128 v[196:199], v158 offset:20480
	ds_read_b128 v[200:203], v158 offset:21504
	ds_read_b128 v[204:207], v158 offset:22528
	ds_read_b128 v[208:211], v158 offset:23552
	global_load_lds_dwordx4 v[184:185], off
	s_add_i32 m0, s33, 0x2000
	s_add_u32 s40, s14, 0x80000
	v_lshl_add_u64 v[212:213], s[14:15], 0, v[132:133]
	s_addc_u32 s41, s15, 0
	s_add_i32 s33, s52, s34
	global_load_lds_dwordx4 v[212:213], off
	v_lshl_add_u64 v[214:215], s[40:41], 0, v[130:131]
	s_mov_b32 m0, s33
	v_lshl_add_u64 v[216:217], s[28:29], 0, v[132:133]
	global_load_lds_dwordx4 v[214:215], off
	v_lshl_add_u64 v[214:215], s[40:41], 0, v[132:133]
	s_add_i32 m0, s33, 0x2000
	s_nop 0
	global_load_lds_dwordx4 v[214:215], off
	v_lshl_add_u64 v[214:215], s[28:29], 0, v[130:131]
	s_mov_b32 m0, s35
	s_nop 0
	global_load_lds_dwordx4 v[214:215], off
	s_mov_b32 m0, s42
	s_nop 0
	global_load_lds_dwordx4 v[216:217], off
	s_waitcnt vmcnt(8)
	s_waitcnt lgkmcnt(0)
	s_setprio 1
	s_barrier
; #define PG8_STAGE(bufoff, gbase, voff) do { _Pragma("unroll") for (int _i = 0; _i < 2; ++_i) \
;         __builtin_amdgcn_global_load_lds((const unsigned*)((const char*)(gbase) + (voff)[_i]), (LAS unsigned*)(lds + (bufoff) + ldsw + _i * 8192), 16, 0, 0); } while (0)
; #define PG8_LDA(dst, b, h) do { _Pragma("unroll") for (int m = 0; m < 4; ++m) _Pragma("unroll") for (int k = 0; k < 2; ++k) dst[m][k] = *(const LAS bf16x8*)(lds + PG8_SA(b, h) + aoff + m * 2048 + k * 1024); } while (0)
; #define PG8_LDB(dst, b, h) do { _Pragma("unroll") for (int n = 0; n < 2; ++n) _Pragma("unroll") for (int k = 0; k < 2; ++k) dst[n][k] = *(const LAS bf16x8*)(lds + PG8_SB(b, h) + boff + n * 2048 + k * 1024); } while (0)
; #define PG8_MMA(ai, bj, At, Bt) do { __builtin_amdgcn_s_setprio(1); _Pragma("unroll") for (int m = 0; m < 4; ++m) _Pragma("unroll") for (int n = 0; n < 2; ++n) _Pragma("unroll") for (int k = 0; k < 2; ++k) \
;         acc[ai][bj][m][n] = __builtin_amdgcn_mfma_f32_16x16x32_bf16(Bt[n][k], At[m][k], acc[ai][bj][m][n], 0, 0, 0); __builtin_amdgcn_s_setprio(0); } while (0)
; #define PG8_WAIT_V(n) asm volatile("s_waitcnt vmcnt(" #n ")" ::: "memory")
; #define PG8_WAIT_L(n) asm volatile("s_waitcnt lgkmcnt(" #n ")" ::: "memory")
; #define PG8_BAR __builtin_amdgcn_s_barrier()
; #define PG8_SCHED __builtin_amdgcn_sched_barrier(0)
; template <class Epi>
; __device__ __forceinline__ void gemm_phase(LAS unsigned char* lds, const Gemm g, const StaticOrder& S, const Epi& E) {
;     ...
;             PG8_WAIT_V(8); PG8_WAIT_L(0); PG8_BAR; PG8_MMA(1, 0, At, B0); PG8_MMA(1, 1, At, B1); PG8_BAR; PG8_SCHED;
;             PG8_LDB(B0, 1, 0); PG8_LDB(B1, 1, 1); PG8_SCHED; PG8_LDA(At, 1, 0); PG8_STAGE(PG8_SA(0, 1), a2 + hstepA, voffA);
;             PG8_WAIT_V(8); PG8_WAIT_L(0); PG8_BAR; PG8_MMA(0, 0, At, B0); PG8_MMA(0, 1, At, B1); PG8_BAR; PG8_SCHED;
	s_waitcnt lgkmcnt(0)
	v_mfma_f32_16x16x32_bf16 v[62:65], v[138:141], v[172:175], v[62:65]
	v_mfma_f32_16x16x32_bf16 v[58:61], v[146:149], v[172:175], v[58:61]
	v_mfma_f32_16x16x32_bf16 v[46:49], v[138:141], v[188:191], v[46:49]
	v_mfma_f32_16x16x32_bf16 v[42:45], v[146:149], v[188:191], v[42:45]
	v_mfma_f32_16x16x32_bf16 v[30:33], v[138:141], v[196:199], v[30:33]
	v_mfma_f32_16x16x32_bf16 v[26:29], v[146:149], v[196:199], v[26:29]
	v_mfma_f32_16x16x32_bf16 v[14:17], v[138:141], v[204:207], v[14:17]
	v_mfma_f32_16x16x32_bf16 v[10:13], v[146:149], v[204:207], v[10:13]
	v_mfma_f32_16x16x32_bf16 v[62:65], v[142:145], v[176:179], v[62:65]
	v_mfma_f32_16x16x32_bf16 v[58:61], v[150:153], v[176:179], v[58:61]
	v_mfma_f32_16x16x32_bf16 v[46:49], v[142:145], v[192:195], v[46:49]
	v_mfma_f32_16x16x32_bf16 v[42:45], v[150:153], v[192:195], v[42:45]
	v_mfma_f32_16x16x32_bf16 v[30:33], v[142:145], v[200:203], v[30:33]
	v_mfma_f32_16x16x32_bf16 v[26:29], v[150:153], v[200:203], v[26:29]
	v_mfma_f32_16x16x32_bf16 v[14:17], v[142:145], v[208:211], v[14:17]
	v_mfma_f32_16x16x32_bf16 v[10:13], v[150:153], v[208:211], v[10:13]
	v_mfma_f32_16x16x32_bf16 v[54:57], v[154:157], v[172:175], v[54:57]
	v_mfma_f32_16x16x32_bf16 v[50:53], v[164:167], v[172:175], v[50:53]
	v_mfma_f32_16x16x32_bf16 v[38:41], v[154:157], v[188:191], v[38:41]
	v_mfma_f32_16x16x32_bf16 v[34:37], v[164:167], v[188:191], v[34:37]
	v_mfma_f32_16x16x32_bf16 v[22:25], v[154:157], v[196:199], v[22:25]
	v_mfma_f32_16x16x32_bf16 v[18:21], v[164:167], v[196:199], v[18:21]
	v_mfma_f32_16x16x32_bf16 v[6:9], v[154:157], v[204:207], v[6:9]
	v_mfma_f32_16x16x32_bf16 v[2:5], v[164:167], v[204:207], v[2:5]
	v_mfma_f32_16x16x32_bf16 v[54:57], v[160:163], v[176:179], v[54:57]
	v_mfma_f32_16x16x32_bf16 v[50:53], v[168:171], v[176:179], v[50:53]
	v_mfma_f32_16x16x32_bf16 v[38:41], v[160:163], v[192:195], v[38:41]
	v_mfma_f32_16x16x32_bf16 v[34:37], v[168:171], v[192:195], v[34:37]
	v_mfma_f32_16x16x32_bf16 v[22:25], v[160:163], v[200:203], v[22:25]
	v_mfma_f32_16x16x32_bf16 v[18:21], v[168:171], v[200:203], v[18:21]
	v_mfma_f32_16x16x32_bf16 v[6:9], v[160:163], v[208:211], v[6:9]
	v_mfma_f32_16x16x32_bf16 v[2:5], v[168:171], v[208:211], v[2:5]
	s_setprio 0
	s_barrier
	s_add_i32 s33, 0, 0x18000
	s_add_i32 s40, 0, 0x1c000
	v_add_u32_e32 v150, s33, v1
	v_add_u32_e32 v159, s40, v1
	ds_read_b128 v[138:141], v150
	ds_read_b128 v[142:145], v150 offset:1024
	ds_read_b128 v[146:149], v150 offset:2048
	ds_read_b128 v[150:153], v150 offset:3072
	ds_read_b128 v[154:157], v159
	ds_read_b128 v[160:163], v159 offset:1024
	ds_read_b128 v[164:167], v159 offset:2048
	ds_read_b128 v[168:171], v159 offset:3072
	s_add_u32 s28, s28, 0x80000
	s_addc_u32 s29, s29, 0
	s_mov_b32 m0, s45
	v_lshl_add_u64 v[218:219], s[28:29], 0, v[130:131]
	ds_read_b128 v[172:175], v158 offset:32768
	ds_read_b128 v[176:179], v158 offset:33792
	ds_read_b128 v[188:191], v158 offset:34816
	ds_read_b128 v[192:195], v158 offset:35840
	ds_read_b128 v[196:199], v158 offset:36864
	ds_read_b128 v[200:203], v158 offset:37888
	ds_read_b128 v[204:207], v158 offset:38912
	ds_read_b128 v[208:211], v158 offset:39936
	global_load_lds_dwordx4 v[218:219], off
	v_lshl_add_u64 v[218:219], s[28:29], 0, v[132:133]
	s_mov_b32 m0, s68
	s_nop 0
	global_load_lds_dwordx4 v[218:219], off
	s_waitcnt vmcnt(8)
	s_waitcnt lgkmcnt(0)
	s_setprio 1
	s_barrier
	s_waitcnt lgkmcnt(0)
	v_mfma_f32_16x16x32_bf16 v[126:129], v[138:141], v[172:175], v[126:129]
	v_mfma_f32_16x16x32_bf16 v[122:125], v[146:149], v[172:175], v[122:125]
	v_mfma_f32_16x16x32_bf16 v[110:113], v[138:141], v[188:191], v[110:113]
	v_mfma_f32_16x16x32_bf16 v[106:109], v[146:149], v[188:191], v[106:109]
	v_mfma_f32_16x16x32_bf16 v[94:97], v[138:141], v[196:199], v[94:97]
	v_mfma_f32_16x16x32_bf16 v[90:93], v[146:149], v[196:199], v[90:93]
	v_mfma_f32_16x16x32_bf16 v[78:81], v[138:141], v[204:207], v[78:81]
	v_mfma_f32_16x16x32_bf16 v[74:77], v[146:149], v[204:207], v[74:77]
	v_mfma_f32_16x16x32_bf16 v[126:129], v[142:145], v[176:179], v[126:129]
	v_mfma_f32_16x16x32_bf16 v[122:125], v[150:153], v[176:179], v[122:125]
	v_mfma_f32_16x16x32_bf16 v[110:113], v[142:145], v[192:195], v[110:113]
	v_mfma_f32_16x16x32_bf16 v[106:109], v[150:153], v[192:195], v[106:109]
	v_mfma_f32_16x16x32_bf16 v[94:97], v[142:145], v[200:203], v[94:97]
	v_mfma_f32_16x16x32_bf16 v[90:93], v[150:153], v[200:203], v[90:93]
	v_mfma_f32_16x16x32_bf16 v[78:81], v[142:145], v[208:211], v[78:81]
	v_mfma_f32_16x16x32_bf16 v[74:77], v[150:153], v[208:211], v[74:77]
	v_mfma_f32_16x16x32_bf16 v[118:121], v[154:157], v[172:175], v[118:121]
	v_mfma_f32_16x16x32_bf16 v[114:117], v[164:167], v[172:175], v[114:117]
	v_mfma_f32_16x16x32_bf16 v[102:105], v[154:157], v[188:191], v[102:105]
	v_mfma_f32_16x16x32_bf16 v[98:101], v[164:167], v[188:191], v[98:101]
	v_mfma_f32_16x16x32_bf16 v[86:89], v[154:157], v[196:199], v[86:89]
	v_mfma_f32_16x16x32_bf16 v[82:85], v[164:167], v[196:199], v[82:85]
	v_mfma_f32_16x16x32_bf16 v[70:73], v[154:157], v[204:207], v[70:73]
	v_mfma_f32_16x16x32_bf16 v[66:69], v[164:167], v[204:207], v[66:69]
	v_mfma_f32_16x16x32_bf16 v[118:121], v[160:163], v[176:179], v[118:121]
	v_mfma_f32_16x16x32_bf16 v[114:117], v[168:171], v[176:179], v[114:117]
	v_mfma_f32_16x16x32_bf16 v[102:105], v[160:163], v[192:195], v[102:105]
	v_mfma_f32_16x16x32_bf16 v[98:101], v[168:171], v[192:195], v[98:101]
	v_mfma_f32_16x16x32_bf16 v[86:89], v[160:163], v[200:203], v[86:89]
	v_mfma_f32_16x16x32_bf16 v[82:85], v[168:171], v[200:203], v[82:85]
	v_mfma_f32_16x16x32_bf16 v[70:73], v[160:163], v[208:211], v[70:73]
	v_mfma_f32_16x16x32_bf16 v[66:69], v[168:171], v[208:211], v[66:69]
	s_setprio 0
	s_barrier
; #define PG8_STAGE(bufoff, gbase, voff) do { _Pragma("unroll") for (int _i = 0; _i < 2; ++_i) \
;         __builtin_amdgcn_global_load_lds((const unsigned*)((const char*)(gbase) + (voff)[_i]), (LAS unsigned*)(lds + (bufoff) + ldsw + _i * 8192), 16, 0, 0); } while (0)
; #define PG8_LDA(dst, b, h) do { _Pragma("unroll") for (int m = 0; m < 4; ++m) _Pragma("unroll") for (int k = 0; k < 2; ++k) dst[m][k] = *(const LAS bf16x8*)(lds + PG8_SA(b, h) + aoff + m * 2048 + k * 1024); } while (0)
; #define PG8_MMA(ai, bj, At, Bt) do { __builtin_amdgcn_s_setprio(1); _Pragma("unroll") for (int m = 0; m < 4; ++m) _Pragma("unroll") for (int n = 0; n < 2; ++n) _Pragma("unroll") for (int k = 0; k < 2; ++k) \
;         acc[ai][bj][m][n] = __builtin_amdgcn_mfma_f32_16x16x32_bf16(Bt[n][k], At[m][k], acc[ai][bj][m][n], 0, 0, 0); __builtin_amdgcn_s_setprio(0); } while (0)
; #define PG8_WAIT_V(n) asm volatile("s_waitcnt vmcnt(" #n ")" ::: "memory")
; #define PG8_WAIT_L(n) asm volatile("s_waitcnt lgkmcnt(" #n ")" ::: "memory")
; #define PG8_BAR __builtin_amdgcn_s_barrier()
; #define PG8_SCHED __builtin_amdgcn_sched_barrier(0)
; template <class Epi>
; __device__ __forceinline__ void gemm_phase(LAS unsigned char* lds, const Gemm g, const StaticOrder& S, const Epi& E) {
;     ...
;             PG8_LDA(At, 1, 1); PG8_STAGE(PG8_SB(1, 0), b3, voffB); PG8_STAGE(PG8_SB(1, 1), b3 + hstepB, voffB); PG8_STAGE(PG8_SA(1, 0), a3, voffA);
;             PG8_WAIT_V(8); PG8_WAIT_L(0); PG8_BAR; PG8_MMA(1, 0, At, B0); PG8_MMA(1, 1, At, B1); PG8_BAR; PG8_SCHED;
;         }
;         if (wr == 0) PG8_BAR;
	s_add_i32 s28, s33, s34
	v_lshl_add_u64 v[184:185], v[184:185], 0, s[84:85]
	s_mov_b32 m0, s28
	ds_read_b128 v[172:175], v158 offset:49152
	ds_read_b128 v[176:179], v158 offset:50176
	ds_read_b128 v[188:191], v158 offset:51200
	ds_read_b128 v[192:195], v158 offset:52224
	ds_read_b128 v[196:199], v158 offset:53248
	ds_read_b128 v[200:203], v158 offset:54272
	ds_read_b128 v[204:207], v158 offset:55296
	ds_read_b128 v[208:211], v158 offset:56320
	global_load_lds_dwordx4 v[184:185], off
	s_add_i32 m0, s28, 0x2000
	s_add_u32 s14, s14, 0x80080
	v_lshl_add_u64 v[184:185], v[212:213], 0, s[84:85]
	s_addc_u32 s15, s15, 0
	s_add_i32 s28, s40, s34
	global_load_lds_dwordx4 v[184:185], off
	v_lshl_add_u64 v[184:185], s[14:15], 0, v[130:131]
	s_mov_b32 m0, s28
	s_nop 0
	global_load_lds_dwordx4 v[184:185], off
	v_lshl_add_u64 v[184:185], s[14:15], 0, v[132:133]
	s_add_i32 m0, s28, 0x2000
	s_nop 0
	global_load_lds_dwordx4 v[184:185], off
	v_lshl_add_u64 v[184:185], v[214:215], 0, s[84:85]
	s_mov_b32 m0, s87
	s_nop 0
	global_load_lds_dwordx4 v[184:185], off
	v_lshl_add_u64 v[184:185], v[216:217], 0, s[84:85]
	s_mov_b32 m0, s91
	s_nop 0
	global_load_lds_dwordx4 v[184:185], off
	s_waitcnt vmcnt(8)
	s_waitcnt lgkmcnt(0)
	s_setprio 1
	s_barrier
	s_waitcnt lgkmcnt(0)
	v_mfma_f32_16x16x32_bf16 v[62:65], v[138:141], v[172:175], v[62:65]
	v_mfma_f32_16x16x32_bf16 v[58:61], v[146:149], v[172:175], v[58:61]
	v_mfma_f32_16x16x32_bf16 v[46:49], v[138:141], v[188:191], v[46:49]
	v_mfma_f32_16x16x32_bf16 v[42:45], v[146:149], v[188:191], v[42:45]
	v_mfma_f32_16x16x32_bf16 v[30:33], v[138:141], v[196:199], v[30:33]
	v_mfma_f32_16x16x32_bf16 v[26:29], v[146:149], v[196:199], v[26:29]
	v_mfma_f32_16x16x32_bf16 v[14:17], v[138:141], v[204:207], v[14:17]
	v_mfma_f32_16x16x32_bf16 v[10:13], v[146:149], v[204:207], v[10:13]
	v_mfma_f32_16x16x32_bf16 v[62:65], v[142:145], v[176:179], v[62:65]
	v_mfma_f32_16x16x32_bf16 v[58:61], v[150:153], v[176:179], v[58:61]
	v_mfma_f32_16x16x32_bf16 v[46:49], v[142:145], v[192:195], v[46:49]
	v_mfma_f32_16x16x32_bf16 v[42:45], v[150:153], v[192:195], v[42:45]
	v_mfma_f32_16x16x32_bf16 v[30:33], v[142:145], v[200:203], v[30:33]
	v_mfma_f32_16x16x32_bf16 v[26:29], v[150:153], v[200:203], v[26:29]
	v_mfma_f32_16x16x32_bf16 v[14:17], v[142:145], v[208:211], v[14:17]
	v_mfma_f32_16x16x32_bf16 v[10:13], v[150:153], v[208:211], v[10:13]
	v_mfma_f32_16x16x32_bf16 v[54:57], v[154:157], v[172:175], v[54:57]
	v_mfma_f32_16x16x32_bf16 v[50:53], v[164:167], v[172:175], v[50:53]
	v_mfma_f32_16x16x32_bf16 v[38:41], v[154:157], v[188:191], v[38:41]
	v_mfma_f32_16x16x32_bf16 v[34:37], v[164:167], v[188:191], v[34:37]
	v_mfma_f32_16x16x32_bf16 v[22:25], v[154:157], v[196:199], v[22:25]
	v_mfma_f32_16x16x32_bf16 v[18:21], v[164:167], v[196:199], v[18:21]
	v_mfma_f32_16x16x32_bf16 v[6:9], v[154:157], v[204:207], v[6:9]
	v_mfma_f32_16x16x32_bf16 v[2:5], v[164:167], v[204:207], v[2:5]
	v_mfma_f32_16x16x32_bf16 v[54:57], v[160:163], v[176:179], v[54:57]
	v_mfma_f32_16x16x32_bf16 v[50:53], v[168:171], v[176:179], v[50:53]
	v_mfma_f32_16x16x32_bf16 v[38:41], v[160:163], v[192:195], v[38:41]
	v_mfma_f32_16x16x32_bf16 v[34:37], v[168:171], v[192:195], v[34:37]
	v_mfma_f32_16x16x32_bf16 v[22:25], v[160:163], v[200:203], v[22:25]
	v_mfma_f32_16x16x32_bf16 v[18:21], v[168:171], v[200:203], v[18:21]
	v_mfma_f32_16x16x32_bf16 v[6:9], v[160:163], v[208:211], v[6:9]
	v_mfma_f32_16x16x32_bf16 v[2:5], v[168:171], v[208:211], v[2:5]
	s_setprio 0
	s_barrier
	s_add_i32 s21, s21, 2
	s_add_u32 s26, s26, 0x100
	s_addc_u32 s27, s27, 0
	s_add_u32 s9, s9, 0x100
	s_addc_u32 s19, s19, 0
	s_cmp_gt_u32 s21, 29
	s_cbranch_scc0 .LBB0_414
	s_and_b64 vcc, exec, s[16:17]
	s_cbranch_vccz .LBB0_417
	s_barrier

; #define PG8_STAGE(bufoff, gbase, voff) do { _Pragma("unroll") for (int _i = 0; _i < 2; ++_i) \
;         __builtin_amdgcn_global_load_lds((const unsigned*)((const char*)(gbase) + (voff)[_i]), (LAS unsigned*)(lds + (bufoff) + ldsw + _i * 8192), 16, 0, 0); } while (0)
; #define PG8_LDA(dst, b, h) do { _Pragma("unroll") for (int m = 0; m < 4; ++m) _Pragma("unroll") for (int k = 0; k < 2; ++k) dst[m][k] = *(const LAS bf16x8*)(lds + PG8_SA(b, h) + aoff + m * 2048 + k * 1024); } while (0)
; #define PG8_LDB(dst, b, h) do { _Pragma("unroll") for (int n = 0; n < 2; ++n) _Pragma("unroll") for (int k = 0; k < 2; ++k) dst[n][k] = *(const LAS bf16x8*)(lds + PG8_SB(b, h) + boff + n * 2048 + k * 1024); } while (0)
; #define PG8_MMA(ai, bj, At, Bt) do { __builtin_amdgcn_s_setprio(1); _Pragma("unroll") for (int m = 0; m < 4; ++m) _Pragma("unroll") for (int n = 0; n < 2; ++n) _Pragma("unroll") for (int k = 0; k < 2; ++k) \
;         acc[ai][bj][m][n] = __builtin_amdgcn_mfma_f32_16x16x32_bf16(Bt[n][k], At[m][k], acc[ai][bj][m][n], 0, 0, 0); __builtin_amdgcn_s_setprio(0); } while (0)
; #define PG8_WAIT_V(n) asm volatile("s_waitcnt vmcnt(" #n ")" ::: "memory")
; #define PG8_BAR __builtin_amdgcn_s_barrier()
; template <class Epi>
; __device__ __forceinline__ void gemm_phase(LAS unsigned char* lds, const Gemm g, const StaticOrder& S, const Epi& E) {
;     ...
;         const bool has_next = S.next(ui + 1, nxt);
;         const char* nA = has_next ? PG8_UA(nxt) : cA; const char* nB = has_next ? PG8_UB(nxt) : cB;
;         for (int t = 0; t < nt; t += 2) {
;             const bool last = (t == nt - 2);
;             const char* a1 = cA + (size_t)(t + 1) * kstep;
;             const char* a2 = last ? nA : cA + (size_t)(t + 2) * kstep; const char* b2 = last ? nB : cB + (size_t)(t + 2) * kstep;
;             const char* a3 = a2 + kstep; const char* b3 = b2 + kstep;
;             PG8_LDB(B0, 0, 0); PG8_LDB(B1, 0, 1); PG8_SCHED; PG8_LDA(At, 0, 0); PG8_STAGE(PG8_SA(1, 1), a1 + hstepA, voffA);
;             PG8_WAIT_V(8); PG8_WAIT_L(0); PG8_BAR; PG8_MMA(0, 0, At, B0); PG8_MMA(0, 1, At, B1); PG8_BAR; PG8_SCHED;
;             PG8_LDA(At, 0, 1); PG8_STAGE(PG8_SB(0, 0), b2, voffB); PG8_STAGE(PG8_SB(0, 1), b2 + hstepB, voffB); PG8_STAGE(PG8_SA(0, 0), a2, voffA);
;             PG8_WAIT_V(8); PG8_WAIT_L(0); PG8_BAR; PG8_MMA(1, 0, At, B0); PG8_MMA(1, 1, At, B1); PG8_BAR; PG8_SCHED;
.LBB0_682:
	s_ashr_i32 s21, s20, 31
	s_lshl_b64 s[26:27], s[20:21], 17
	v_readlane_b32 s40, v254, 33
	v_readlane_b32 s41, v254, 34
	s_add_u32 s26, s40, s26
	s_addc_u32 s27, s41, s27
	s_and_b64 s[6:7], s[6:7], exec
	s_cselect_b32 s7, s27, s35
	s_cselect_b32 s6, s26, s34
	s_add_i32 s33, 0, 0x10000
	s_add_i32 s21, 0, 0x14000
	v_add_u32_e32 v147, s33, v1
	v_add_u32_e32 v181, s21, v1
	ds_read_b128 v[2:5], v147
	ds_read_b128 v[6:9], v147 offset:1024
	ds_read_b128 v[10:13], v147 offset:2048
	ds_read_b128 v[14:17], v147 offset:3072
	ds_read_b128 v[18:21], v181
	ds_read_b128 v[22:25], v181 offset:1024
	ds_read_b128 v[26:29], v181 offset:2048
	ds_read_b128 v[30:33], v181 offset:3072
	s_add_u32 s52, s30, 0x80080
	s_addc_u32 s53, s31, 0
	s_add_i32 s41, s14, 0xc000
	v_lshl_add_u64 v[66:67], s[52:53], 0, v[130:131]
	s_mov_b32 m0, s41
	s_add_i32 s1, s14, 0xe000
	ds_read_b128 v[34:37], v146
	ds_read_b128 v[38:41], v146 offset:1024
	ds_read_b128 v[42:45], v146 offset:2048
	ds_read_b128 v[46:49], v146 offset:3072
	ds_read_b128 v[50:53], v146 offset:4096
	ds_read_b128 v[54:57], v146 offset:5120
	ds_read_b128 v[58:61], v146 offset:6144
	ds_read_b128 v[62:65], v146 offset:7168
	global_load_lds_dwordx4 v[66:67], off
	v_lshl_add_u64 v[66:67], s[52:53], 0, v[134:135]
	s_mov_b32 m0, s1
	s_nop 0
	global_load_lds_dwordx4 v[66:67], off
	s_waitcnt vmcnt(8)
	s_waitcnt lgkmcnt(0)
	s_setprio 1
	s_barrier
	s_waitcnt lgkmcnt(0)
	v_mfma_f32_16x16x32_bf16 v[66:69], v[2:5], v[34:37], 0
	v_mfma_f32_16x16x32_bf16 v[70:73], v[10:13], v[34:37], 0
	v_mfma_f32_16x16x32_bf16 v[74:77], v[2:5], v[42:45], 0
	v_mfma_f32_16x16x32_bf16 v[78:81], v[10:13], v[42:45], 0
	v_mfma_f32_16x16x32_bf16 v[82:85], v[2:5], v[50:53], 0
	v_mfma_f32_16x16x32_bf16 v[86:89], v[10:13], v[50:53], 0
	v_mfma_f32_16x16x32_bf16 v[90:93], v[2:5], v[58:61], 0
	v_mfma_f32_16x16x32_bf16 v[94:97], v[10:13], v[58:61], 0
	v_mfma_f32_16x16x32_bf16 v[66:69], v[6:9], v[38:41], v[66:69]
	v_mfma_f32_16x16x32_bf16 v[70:73], v[14:17], v[38:41], v[70:73]
	v_mfma_f32_16x16x32_bf16 v[74:77], v[6:9], v[46:49], v[74:77]
	v_mfma_f32_16x16x32_bf16 v[78:81], v[14:17], v[46:49], v[78:81]
	v_mfma_f32_16x16x32_bf16 v[82:85], v[6:9], v[54:57], v[82:85]
	v_mfma_f32_16x16x32_bf16 v[86:89], v[14:17], v[54:57], v[86:89]
	v_mfma_f32_16x16x32_bf16 v[90:93], v[6:9], v[62:65], v[90:93]
	v_mfma_f32_16x16x32_bf16 v[94:97], v[14:17], v[62:65], v[94:97]
	v_mfma_f32_16x16x32_bf16 v[98:101], v[18:21], v[34:37], 0
	v_mfma_f32_16x16x32_bf16 v[34:37], v[26:29], v[34:37], 0
	v_mfma_f32_16x16x32_bf16 v[98:101], v[22:25], v[38:41], v[98:101]
	v_mfma_f32_16x16x32_bf16 v[34:37], v[30:33], v[38:41], v[34:37]
	v_mfma_f32_16x16x32_bf16 v[38:41], v[18:21], v[42:45], 0
	v_mfma_f32_16x16x32_bf16 v[42:45], v[26:29], v[42:45], 0
	v_mfma_f32_16x16x32_bf16 v[38:41], v[22:25], v[46:49], v[38:41]
	v_mfma_f32_16x16x32_bf16 v[42:45], v[30:33], v[46:49], v[42:45]
	v_mfma_f32_16x16x32_bf16 v[46:49], v[18:21], v[50:53], 0
	v_mfma_f32_16x16x32_bf16 v[50:53], v[26:29], v[50:53], 0
	v_mfma_f32_16x16x32_bf16 v[46:49], v[22:25], v[54:57], v[46:49]
	v_mfma_f32_16x16x32_bf16 v[50:53], v[30:33], v[54:57], v[50:53]
	v_mfma_f32_16x16x32_bf16 v[54:57], v[18:21], v[58:61], 0
	v_mfma_f32_16x16x32_bf16 v[58:61], v[26:29], v[58:61], 0
	v_mfma_f32_16x16x32_bf16 v[54:57], v[22:25], v[62:65], v[54:57]
	v_mfma_f32_16x16x32_bf16 v[58:61], v[30:33], v[62:65], v[58:61]
	s_setprio 0
	s_barrier
	s_add_i32 s33, s33, s11
	v_lshl_add_u64 v[184:185], s[34:35], 0, v[132:133]
	s_mov_b64 s[62:63], 0x100
	s_add_i32 s3, s33, 0x2000
	v_lshl_add_u64 v[138:139], v[184:185], 0, s[62:63]
	s_mov_b32 m0, s33
	v_lshl_add_u64 v[212:213], s[34:35], 0, v[136:137]
	s_add_u32 s52, s34, 0x10100
	ds_read_b128 v[62:65], v146 offset:16384
	ds_read_b128 v[102:105], v146 offset:17408
	ds_read_b128 v[106:109], v146 offset:18432
	ds_read_b128 v[110:113], v146 offset:19456
	ds_read_b128 v[114:117], v146 offset:20480
	ds_read_b128 v[118:121], v146 offset:21504
	ds_read_b128 v[122:125], v146 offset:22528
	ds_read_b128 v[126:129], v146 offset:23552
	global_load_lds_dwordx4 v[138:139], off
	v_lshl_add_u64 v[138:139], v[212:213], 0, s[62:63]
	s_mov_b32 m0, s3
	s_addc_u32 s53, s35, 0
	s_add_i32 s21, s21, s11
	global_load_lds_dwordx4 v[138:139], off
	v_lshl_add_u64 v[138:139], s[52:53], 0, v[132:133]
	s_mov_b32 m0, s21
	s_add_i32 s23, s21, 0x2000
	global_load_lds_dwordx4 v[138:139], off
	v_lshl_add_u64 v[138:139], s[52:53], 0, v[136:137]
	s_mov_b32 m0, s23
	v_lshl_add_u64 v[214:215], s[30:31], 0, v[130:131]
	global_load_lds_dwordx4 v[138:139], off
	v_lshl_add_u64 v[138:139], v[214:215], 0, s[62:63]
	s_mov_b32 m0, s14
	v_lshl_add_u64 v[216:217], s[30:31], 0, v[134:135]
	global_load_lds_dwordx4 v[138:139], off
	v_lshl_add_u64 v[138:139], v[216:217], 0, s[62:63]
	s_mov_b32 m0, s15
	s_nop 0
	global_load_lds_dwordx4 v[138:139], off
	s_waitcnt vmcnt(8)
	s_waitcnt lgkmcnt(0)
	s_setprio 1
	s_barrier
; #define PG8_STAGE(bufoff, gbase, voff) do { _Pragma("unroll") for (int _i = 0; _i < 2; ++_i) \
;         __builtin_amdgcn_global_load_lds((const unsigned*)((const char*)(gbase) + (voff)[_i]), (LAS unsigned*)(lds + (bufoff) + ldsw + _i * 8192), 16, 0, 0); } while (0)
; #define PG8_LDA(dst, b, h) do { _Pragma("unroll") for (int m = 0; m < 4; ++m) _Pragma("unroll") for (int k = 0; k < 2; ++k) dst[m][k] = *(const LAS bf16x8*)(lds + PG8_SA(b, h) + aoff + m * 2048 + k * 1024); } while (0)
; #define PG8_LDB(dst, b, h) do { _Pragma("unroll") for (int n = 0; n < 2; ++n) _Pragma("unroll") for (int k = 0; k < 2; ++k) dst[n][k] = *(const LAS bf16x8*)(lds + PG8_SB(b, h) + boff + n * 2048 + k * 1024); } while (0)
; #define PG8_MMA(ai, bj, At, Bt) do { __builtin_amdgcn_s_setprio(1); _Pragma("unroll") for (int m = 0; m < 4; ++m) _Pragma("unroll") for (int n = 0; n < 2; ++n) _Pragma("unroll") for (int k = 0; k < 2; ++k) \
;         acc[ai][bj][m][n] = __builtin_amdgcn_mfma_f32_16x16x32_bf16(Bt[n][k], At[m][k], acc[ai][bj][m][n], 0, 0, 0); __builtin_amdgcn_s_setprio(0); } while (0)
; #define PG8_WAIT_V(n) asm volatile("s_waitcnt vmcnt(" #n ")" ::: "memory")
; #define PG8_WAIT_L(n) asm volatile("s_waitcnt lgkmcnt(" #n ")" ::: "memory")
; #define PG8_BAR __builtin_amdgcn_s_barrier()
; #define PG8_SCHED __builtin_amdgcn_sched_barrier(0)
; template <class Epi>
; __device__ __forceinline__ void gemm_phase(LAS unsigned char* lds, const Gemm g, const StaticOrder& S, const Epi& E) {
;     ...
;             PG8_WAIT_V(8); PG8_WAIT_L(0); PG8_BAR; PG8_MMA(1, 0, At, B0); PG8_MMA(1, 1, At, B1); PG8_BAR; PG8_SCHED;
;             PG8_LDB(B0, 1, 0); PG8_LDB(B1, 1, 1); PG8_SCHED; PG8_LDA(At, 1, 0); PG8_STAGE(PG8_SA(0, 1), a2 + hstepA, voffA);
;             PG8_WAIT_V(8); PG8_WAIT_L(0); PG8_BAR; PG8_MMA(0, 0, At, B0); PG8_MMA(0, 1, At, B1); PG8_BAR; PG8_SCHED;
	s_waitcnt lgkmcnt(0)
	v_mfma_f32_16x16x32_bf16 v[138:141], v[2:5], v[62:65], 0
	v_mfma_f32_16x16x32_bf16 v[148:151], v[2:5], v[106:109], 0
	v_mfma_f32_16x16x32_bf16 v[156:159], v[2:5], v[114:117], 0
	v_mfma_f32_16x16x32_bf16 v[2:5], v[2:5], v[122:125], 0
	v_mfma_f32_16x16x32_bf16 v[138:141], v[6:9], v[102:105], v[138:141]
	v_mfma_f32_16x16x32_bf16 v[148:151], v[6:9], v[110:113], v[148:151]
	v_mfma_f32_16x16x32_bf16 v[156:159], v[6:9], v[118:121], v[156:159]
	v_mfma_f32_16x16x32_bf16 v[2:5], v[6:9], v[126:129], v[2:5]
	v_mfma_f32_16x16x32_bf16 v[6:9], v[10:13], v[122:125], 0
	v_mfma_f32_16x16x32_bf16 v[142:145], v[10:13], v[62:65], 0
	v_mfma_f32_16x16x32_bf16 v[152:155], v[10:13], v[106:109], 0
	v_mfma_f32_16x16x32_bf16 v[160:163], v[10:13], v[114:117], 0
	v_mfma_f32_16x16x32_bf16 v[6:9], v[14:17], v[126:129], v[6:9]
	v_mfma_f32_16x16x32_bf16 v[142:145], v[14:17], v[102:105], v[142:145]
	v_mfma_f32_16x16x32_bf16 v[152:155], v[14:17], v[110:113], v[152:155]
	v_mfma_f32_16x16x32_bf16 v[160:163], v[14:17], v[118:121], v[160:163]
	v_mfma_f32_16x16x32_bf16 v[10:13], v[18:21], v[62:65], 0
	v_mfma_f32_16x16x32_bf16 v[14:17], v[26:29], v[62:65], 0
	v_mfma_f32_16x16x32_bf16 v[10:13], v[22:25], v[102:105], v[10:13]
	v_mfma_f32_16x16x32_bf16 v[14:17], v[30:33], v[102:105], v[14:17]
	v_mfma_f32_16x16x32_bf16 v[62:65], v[18:21], v[106:109], 0
	v_mfma_f32_16x16x32_bf16 v[102:105], v[26:29], v[106:109], 0
	v_mfma_f32_16x16x32_bf16 v[106:109], v[18:21], v[114:117], 0
	v_mfma_f32_16x16x32_bf16 v[18:21], v[18:21], v[122:125], 0
	v_mfma_f32_16x16x32_bf16 v[62:65], v[22:25], v[110:113], v[62:65]
	v_mfma_f32_16x16x32_bf16 v[102:105], v[30:33], v[110:113], v[102:105]
	v_mfma_f32_16x16x32_bf16 v[106:109], v[22:25], v[118:121], v[106:109]
	v_mfma_f32_16x16x32_bf16 v[110:113], v[26:29], v[114:117], 0
	v_mfma_f32_16x16x32_bf16 v[18:21], v[22:25], v[126:129], v[18:21]
	v_mfma_f32_16x16x32_bf16 v[22:25], v[26:29], v[122:125], 0
	v_mfma_f32_16x16x32_bf16 v[110:113], v[30:33], v[118:121], v[110:113]
	v_mfma_f32_16x16x32_bf16 v[22:25], v[30:33], v[126:129], v[22:25]
	s_setprio 0
	s_barrier
	s_add_i32 s40, 0, 0x18000
	s_add_i32 s64, 0, 0x1c000
	v_add_u32_e32 v183, s40, v1
	v_add_u32_e32 v186, s64, v1
	ds_read_b128 v[26:29], v183
	ds_read_b128 v[30:33], v183 offset:1024
	ds_read_b128 v[114:117], v183 offset:2048
	ds_read_b128 v[118:121], v183 offset:3072
	ds_read_b128 v[122:125], v186
	ds_read_b128 v[126:129], v186 offset:1024
	ds_read_b128 v[164:167], v186 offset:2048
	ds_read_b128 v[168:171], v186 offset:3072
	s_add_u32 s52, s30, 0x80100
	s_addc_u32 s53, s31, 0
	s_mov_b32 m0, s29
	v_lshl_add_u64 v[218:219], s[52:53], 0, v[130:131]
	ds_read_b128 v[172:175], v146 offset:32768
	ds_read_b128 v[176:179], v146 offset:33792
	ds_read_b128 v[188:191], v146 offset:34816
	ds_read_b128 v[192:195], v146 offset:35840
	ds_read_b128 v[196:199], v146 offset:36864
	ds_read_b128 v[200:203], v146 offset:37888
	ds_read_b128 v[204:207], v146 offset:38912
	ds_read_b128 v[208:211], v146 offset:39936
	global_load_lds_dwordx4 v[218:219], off
	v_lshl_add_u64 v[218:219], s[52:53], 0, v[134:135]
	s_mov_b32 m0, s42
	s_nop 0
	global_load_lds_dwordx4 v[218:219], off
	s_waitcnt vmcnt(8)
	s_waitcnt lgkmcnt(0)
	s_setprio 1
	s_barrier
	s_waitcnt lgkmcnt(0)
	v_mfma_f32_16x16x32_bf16 v[66:69], v[26:29], v[172:175], v[66:69]
	v_mfma_f32_16x16x32_bf16 v[70:73], v[114:117], v[172:175], v[70:73]
	v_mfma_f32_16x16x32_bf16 v[74:77], v[26:29], v[188:191], v[74:77]
	v_mfma_f32_16x16x32_bf16 v[78:81], v[114:117], v[188:191], v[78:81]
	v_mfma_f32_16x16x32_bf16 v[82:85], v[26:29], v[196:199], v[82:85]
	v_mfma_f32_16x16x32_bf16 v[86:89], v[114:117], v[196:199], v[86:89]
	v_mfma_f32_16x16x32_bf16 v[90:93], v[26:29], v[204:207], v[90:93]
	v_mfma_f32_16x16x32_bf16 v[94:97], v[114:117], v[204:207], v[94:97]
	v_mfma_f32_16x16x32_bf16 v[66:69], v[30:33], v[176:179], v[66:69]
	v_mfma_f32_16x16x32_bf16 v[70:73], v[118:121], v[176:179], v[70:73]
	v_mfma_f32_16x16x32_bf16 v[74:77], v[30:33], v[192:195], v[74:77]
	v_mfma_f32_16x16x32_bf16 v[78:81], v[118:121], v[192:195], v[78:81]
	v_mfma_f32_16x16x32_bf16 v[82:85], v[30:33], v[200:203], v[82:85]
	v_mfma_f32_16x16x32_bf16 v[86:89], v[118:121], v[200:203], v[86:89]
	v_mfma_f32_16x16x32_bf16 v[90:93], v[30:33], v[208:211], v[90:93]
	v_mfma_f32_16x16x32_bf16 v[94:97], v[118:121], v[208:211], v[94:97]
	v_mfma_f32_16x16x32_bf16 v[98:101], v[122:125], v[172:175], v[98:101]
	v_mfma_f32_16x16x32_bf16 v[34:37], v[164:167], v[172:175], v[34:37]
	v_mfma_f32_16x16x32_bf16 v[38:41], v[122:125], v[188:191], v[38:41]
	v_mfma_f32_16x16x32_bf16 v[42:45], v[164:167], v[188:191], v[42:45]
	v_mfma_f32_16x16x32_bf16 v[46:49], v[122:125], v[196:199], v[46:49]
	v_mfma_f32_16x16x32_bf16 v[50:53], v[164:167], v[196:199], v[50:53]
	v_mfma_f32_16x16x32_bf16 v[54:57], v[122:125], v[204:207], v[54:57]
	v_mfma_f32_16x16x32_bf16 v[58:61], v[164:167], v[204:207], v[58:61]
	v_mfma_f32_16x16x32_bf16 v[98:101], v[126:129], v[176:179], v[98:101]
	v_mfma_f32_16x16x32_bf16 v[34:37], v[168:171], v[176:179], v[34:37]
	v_mfma_f32_16x16x32_bf16 v[38:41], v[126:129], v[192:195], v[38:41]
	v_mfma_f32_16x16x32_bf16 v[42:45], v[168:171], v[192:195], v[42:45]
	v_mfma_f32_16x16x32_bf16 v[46:49], v[126:129], v[200:203], v[46:49]
	v_mfma_f32_16x16x32_bf16 v[50:53], v[168:171], v[200:203], v[50:53]
	v_mfma_f32_16x16x32_bf16 v[54:57], v[126:129], v[208:211], v[54:57]
	v_mfma_f32_16x16x32_bf16 v[58:61], v[168:171], v[208:211], v[58:61]
	s_setprio 0
	s_barrier
; #define PG8_STAGE(bufoff, gbase, voff) do { _Pragma("unroll") for (int _i = 0; _i < 2; ++_i) \
;         __builtin_amdgcn_global_load_lds((const unsigned*)((const char*)(gbase) + (voff)[_i]), (LAS unsigned*)(lds + (bufoff) + ldsw + _i * 8192), 16, 0, 0); } while (0)
; #define PG8_LDA(dst, b, h) do { _Pragma("unroll") for (int m = 0; m < 4; ++m) _Pragma("unroll") for (int k = 0; k < 2; ++k) dst[m][k] = *(const LAS bf16x8*)(lds + PG8_SA(b, h) + aoff + m * 2048 + k * 1024); } while (0)
; #define PG8_LDB(dst, b, h) do { _Pragma("unroll") for (int n = 0; n < 2; ++n) _Pragma("unroll") for (int k = 0; k < 2; ++k) dst[n][k] = *(const LAS bf16x8*)(lds + PG8_SB(b, h) + boff + n * 2048 + k * 1024); } while (0)
; #define PG8_MMA(ai, bj, At, Bt) do { __builtin_amdgcn_s_setprio(1); _Pragma("unroll") for (int m = 0; m < 4; ++m) _Pragma("unroll") for (int n = 0; n < 2; ++n) _Pragma("unroll") for (int k = 0; k < 2; ++k) \
;         acc[ai][bj][m][n] = __builtin_amdgcn_mfma_f32_16x16x32_bf16(Bt[n][k], At[m][k], acc[ai][bj][m][n], 0, 0, 0); __builtin_amdgcn_s_setprio(0); } while (0)
; #define PG8_WAIT_V(n) asm volatile("s_waitcnt vmcnt(" #n ")" ::: "memory")
; #define PG8_WAIT_L(n) asm volatile("s_waitcnt lgkmcnt(" #n ")" ::: "memory")
; #define PG8_BAR __builtin_amdgcn_s_barrier()
; #define PG8_SCHED __builtin_amdgcn_sched_barrier(0)
; template <class Epi>
; __device__ __forceinline__ void gemm_phase(LAS unsigned char* lds, const Gemm g, const StaticOrder& S, const Epi& E) {
;     ...
;             PG8_LDB(B0, 0, 0); PG8_LDB(B1, 0, 1); PG8_SCHED; PG8_LDA(At, 0, 0); PG8_STAGE(PG8_SA(1, 1), a1 + hstepA, voffA);
;             PG8_WAIT_V(8); PG8_WAIT_L(0); PG8_BAR; PG8_MMA(0, 0, At, B0); PG8_MMA(0, 1, At, B1); PG8_BAR; PG8_SCHED;
;     ...
;             PG8_LDA(At, 1, 1); PG8_STAGE(PG8_SB(1, 0), b3, voffB); PG8_STAGE(PG8_SB(1, 1), b3 + hstepB, voffB); PG8_STAGE(PG8_SA(1, 0), a3, voffA);
;             PG8_WAIT_V(8); PG8_WAIT_L(0); PG8_BAR; PG8_MMA(1, 0, At, B0); PG8_MMA(1, 1, At, B1); PG8_BAR; PG8_SCHED;
	s_add_i32 s52, s40, s11
	s_mov_b64 vcc, 0x180
	s_add_i32 s40, s52, 0x2000
	v_lshl_add_u64 v[184:185], v[184:185], 0, vcc
	s_mov_b32 m0, s52
	s_add_u32 s62, s34, 0x10180
	ds_read_b128 v[172:175], v146 offset:49152
	ds_read_b128 v[176:179], v146 offset:50176
	ds_read_b128 v[188:191], v146 offset:51200
	ds_read_b128 v[192:195], v146 offset:52224
	ds_read_b128 v[196:199], v146 offset:53248
	ds_read_b128 v[200:203], v146 offset:54272
	ds_read_b128 v[204:207], v146 offset:55296
	ds_read_b128 v[208:211], v146 offset:56320
	global_load_lds_dwordx4 v[184:185], off
	v_lshl_add_u64 v[184:185], v[212:213], 0, vcc
	s_mov_b32 m0, s40
	s_addc_u32 s63, s35, 0
	s_add_i32 s34, s64, s11
	global_load_lds_dwordx4 v[184:185], off
	v_lshl_add_u64 v[184:185], s[62:63], 0, v[132:133]
	s_mov_b32 m0, s34
	s_add_i32 s35, s34, 0x2000
	global_load_lds_dwordx4 v[184:185], off
	v_lshl_add_u64 v[184:185], s[62:63], 0, v[136:137]
	s_mov_b32 m0, s35
	s_nop 0
	global_load_lds_dwordx4 v[184:185], off
	v_lshl_add_u64 v[184:185], v[214:215], 0, vcc
	s_mov_b32 m0, s68
	s_nop 0
	global_load_lds_dwordx4 v[184:185], off
	v_lshl_add_u64 v[184:185], v[216:217], 0, vcc
	s_mov_b32 m0, s69
	s_nop 0
	global_load_lds_dwordx4 v[184:185], off
	s_waitcnt vmcnt(8)
	s_waitcnt lgkmcnt(0)
	s_setprio 1
	s_barrier
	s_waitcnt lgkmcnt(0)
	v_mfma_f32_16x16x32_bf16 v[2:5], v[26:29], v[204:207], v[2:5]
	v_mfma_f32_16x16x32_bf16 v[6:9], v[114:117], v[204:207], v[6:9]
	v_mfma_f32_16x16x32_bf16 v[138:141], v[26:29], v[172:175], v[138:141]
	v_mfma_f32_16x16x32_bf16 v[142:145], v[114:117], v[172:175], v[142:145]
	v_mfma_f32_16x16x32_bf16 v[148:151], v[26:29], v[188:191], v[148:151]
	v_mfma_f32_16x16x32_bf16 v[152:155], v[114:117], v[188:191], v[152:155]
	v_mfma_f32_16x16x32_bf16 v[156:159], v[26:29], v[196:199], v[156:159]
	v_mfma_f32_16x16x32_bf16 v[160:163], v[114:117], v[196:199], v[160:163]
	v_mfma_f32_16x16x32_bf16 v[2:5], v[30:33], v[208:211], v[2:5]
	v_mfma_f32_16x16x32_bf16 v[6:9], v[118:121], v[208:211], v[6:9]
	v_mfma_f32_16x16x32_bf16 v[138:141], v[30:33], v[176:179], v[138:141]
	v_mfma_f32_16x16x32_bf16 v[142:145], v[118:121], v[176:179], v[142:145]
	v_mfma_f32_16x16x32_bf16 v[148:151], v[30:33], v[192:195], v[148:151]
	v_mfma_f32_16x16x32_bf16 v[152:155], v[118:121], v[192:195], v[152:155]
	v_mfma_f32_16x16x32_bf16 v[156:159], v[30:33], v[200:203], v[156:159]
	v_mfma_f32_16x16x32_bf16 v[160:163], v[118:121], v[200:203], v[160:163]
	v_mfma_f32_16x16x32_bf16 v[10:13], v[122:125], v[172:175], v[10:13]
	v_mfma_f32_16x16x32_bf16 v[14:17], v[164:167], v[172:175], v[14:17]
	v_mfma_f32_16x16x32_bf16 v[26:29], v[122:125], v[188:191], v[62:65]
	v_mfma_f32_16x16x32_bf16 v[30:33], v[164:167], v[188:191], v[102:105]
	v_mfma_f32_16x16x32_bf16 v[62:65], v[122:125], v[196:199], v[106:109]
	v_mfma_f32_16x16x32_bf16 v[102:105], v[164:167], v[196:199], v[110:113]
	v_mfma_f32_16x16x32_bf16 v[18:21], v[122:125], v[204:207], v[18:21]
	v_mfma_f32_16x16x32_bf16 v[22:25], v[164:167], v[204:207], v[22:25]
	v_mfma_f32_16x16x32_bf16 v[10:13], v[126:129], v[176:179], v[10:13]
	v_mfma_f32_16x16x32_bf16 v[14:17], v[168:171], v[176:179], v[14:17]
	v_mfma_f32_16x16x32_bf16 v[26:29], v[126:129], v[192:195], v[26:29]
	v_mfma_f32_16x16x32_bf16 v[30:33], v[168:171], v[192:195], v[30:33]
	v_mfma_f32_16x16x32_bf16 v[62:65], v[126:129], v[200:203], v[62:65]
	v_mfma_f32_16x16x32_bf16 v[102:105], v[168:171], v[200:203], v[102:105]
	v_mfma_f32_16x16x32_bf16 v[18:21], v[126:129], v[208:211], v[18:21]
	v_mfma_f32_16x16x32_bf16 v[22:25], v[168:171], v[208:211], v[22:25]
	s_setprio 0
	s_barrier
	ds_read_b128 v[106:109], v147
	ds_read_b128 v[110:113], v147 offset:1024
	ds_read_b128 v[114:117], v147 offset:2048
	ds_read_b128 v[118:121], v147 offset:3072
	ds_read_b128 v[122:125], v181
	ds_read_b128 v[126:129], v181 offset:1024
	ds_read_b128 v[164:167], v181 offset:2048
	ds_read_b128 v[168:171], v181 offset:3072
	s_add_u32 s30, s30, 0x80180
	s_addc_u32 s31, s31, 0
	s_mov_b32 m0, s41
	v_lshl_add_u64 v[184:185], s[30:31], 0, v[130:131]
	ds_read_b128 v[172:175], v146
	ds_read_b128 v[176:179], v146 offset:1024
	ds_read_b128 v[188:191], v146 offset:2048
	ds_read_b128 v[192:195], v146 offset:3072
	ds_read_b128 v[196:199], v146 offset:4096
	ds_read_b128 v[200:203], v146 offset:5120
	ds_read_b128 v[204:207], v146 offset:6144
	ds_read_b128 v[208:211], v146 offset:7168
	global_load_lds_dwordx4 v[184:185], off
	v_lshl_add_u64 v[184:185], s[30:31], 0, v[134:135]
	s_mov_b32 m0, s1
	s_nop 0
	global_load_lds_dwordx4 v[184:185], off
	s_waitcnt vmcnt(8)
	s_waitcnt lgkmcnt(0)
	s_setprio 1
	s_barrier
; #define PG8_STAGE(bufoff, gbase, voff) do { _Pragma("unroll") for (int _i = 0; _i < 2; ++_i) \
;         __builtin_amdgcn_global_load_lds((const unsigned*)((const char*)(gbase) + (voff)[_i]), (LAS unsigned*)(lds + (bufoff) + ldsw + _i * 8192), 16, 0, 0); } while (0)
; #define PG8_LDA(dst, b, h) do { _Pragma("unroll") for (int m = 0; m < 4; ++m) _Pragma("unroll") for (int k = 0; k < 2; ++k) dst[m][k] = *(const LAS bf16x8*)(lds + PG8_SA(b, h) + aoff + m * 2048 + k * 1024); } while (0)
; #define PG8_MMA(ai, bj, At, Bt) do { __builtin_amdgcn_s_setprio(1); _Pragma("unroll") for (int m = 0; m < 4; ++m) _Pragma("unroll") for (int n = 0; n < 2; ++n) _Pragma("unroll") for (int k = 0; k < 2; ++k) \
;         acc[ai][bj][m][n] = __builtin_amdgcn_mfma_f32_16x16x32_bf16(Bt[n][k], At[m][k], acc[ai][bj][m][n], 0, 0, 0); __builtin_amdgcn_s_setprio(0); } while (0)
; #define PG8_WAIT_V(n) asm volatile("s_waitcnt vmcnt(" #n ")" ::: "memory")
; #define PG8_WAIT_L(n) asm volatile("s_waitcnt lgkmcnt(" #n ")" ::: "memory")
; #define PG8_BAR __builtin_amdgcn_s_barrier()
; #define PG8_SCHED __builtin_amdgcn_sched_barrier(0)
; template <class Epi>
; __device__ __forceinline__ void gemm_phase(LAS unsigned char* lds, const Gemm g, const StaticOrder& S, const Epi& E) {
;     ...
;             PG8_WAIT_V(8); PG8_WAIT_L(0); PG8_BAR; PG8_MMA(0, 0, At, B0); PG8_MMA(0, 1, At, B1); PG8_BAR; PG8_SCHED;
;             PG8_LDA(At, 0, 1); PG8_STAGE(PG8_SB(0, 0), b2, voffB); PG8_STAGE(PG8_SB(0, 1), b2 + hstepB, voffB); PG8_STAGE(PG8_SA(0, 0), a2, voffA);
;             PG8_WAIT_V(8); PG8_WAIT_L(0); PG8_BAR; PG8_MMA(1, 0, At, B0); PG8_MMA(1, 1, At, B1); PG8_BAR; PG8_SCHED;
	s_waitcnt lgkmcnt(0)
	v_mfma_f32_16x16x32_bf16 v[90:93], v[106:109], v[204:207], v[90:93]
	v_mfma_f32_16x16x32_bf16 v[66:69], v[106:109], v[172:175], v[66:69]
	v_mfma_f32_16x16x32_bf16 v[70:73], v[114:117], v[172:175], v[70:73]
	v_mfma_f32_16x16x32_bf16 v[74:77], v[106:109], v[188:191], v[74:77]
	v_mfma_f32_16x16x32_bf16 v[78:81], v[114:117], v[188:191], v[78:81]
	v_mfma_f32_16x16x32_bf16 v[82:85], v[106:109], v[196:199], v[82:85]
	v_mfma_f32_16x16x32_bf16 v[86:89], v[114:117], v[196:199], v[86:89]
	v_mfma_f32_16x16x32_bf16 v[212:215], v[110:113], v[208:211], v[90:93]
	v_mfma_f32_16x16x32_bf16 v[90:93], v[114:117], v[204:207], v[94:97]
	v_mfma_f32_16x16x32_bf16 v[66:69], v[110:113], v[176:179], v[66:69]
	v_mfma_f32_16x16x32_bf16 v[70:73], v[118:121], v[176:179], v[70:73]
	v_mfma_f32_16x16x32_bf16 v[74:77], v[110:113], v[192:195], v[74:77]
	v_mfma_f32_16x16x32_bf16 v[78:81], v[118:121], v[192:195], v[78:81]
	v_mfma_f32_16x16x32_bf16 v[82:85], v[110:113], v[200:203], v[82:85]
	v_mfma_f32_16x16x32_bf16 v[86:89], v[118:121], v[200:203], v[86:89]
	v_mfma_f32_16x16x32_bf16 v[94:97], v[118:121], v[208:211], v[90:93]
	v_mfma_f32_16x16x32_bf16 v[90:93], v[122:125], v[172:175], v[98:101]
	v_mfma_f32_16x16x32_bf16 v[34:37], v[164:167], v[172:175], v[34:37]
	v_mfma_f32_16x16x32_bf16 v[38:41], v[122:125], v[188:191], v[38:41]
	v_mfma_f32_16x16x32_bf16 v[42:45], v[164:167], v[188:191], v[42:45]
	v_mfma_f32_16x16x32_bf16 v[46:49], v[122:125], v[196:199], v[46:49]
	v_mfma_f32_16x16x32_bf16 v[50:53], v[164:167], v[196:199], v[50:53]
	v_mfma_f32_16x16x32_bf16 v[54:57], v[122:125], v[204:207], v[54:57]
	v_mfma_f32_16x16x32_bf16 v[58:61], v[164:167], v[204:207], v[58:61]
	v_mfma_f32_16x16x32_bf16 v[98:101], v[126:129], v[176:179], v[90:93]
	v_mfma_f32_16x16x32_bf16 v[34:37], v[168:171], v[176:179], v[34:37]
	v_mfma_f32_16x16x32_bf16 v[38:41], v[126:129], v[192:195], v[38:41]
	v_mfma_f32_16x16x32_bf16 v[42:45], v[168:171], v[192:195], v[42:45]
	v_mfma_f32_16x16x32_bf16 v[46:49], v[126:129], v[200:203], v[46:49]
	v_mfma_f32_16x16x32_bf16 v[50:53], v[168:171], v[200:203], v[50:53]
	v_mfma_f32_16x16x32_bf16 v[54:57], v[126:129], v[208:211], v[54:57]
	v_mfma_f32_16x16x32_bf16 v[58:61], v[168:171], v[208:211], v[58:61]
	s_setprio 0
	s_barrier
	s_mov_b32 m0, s33
	v_lshl_add_u64 v[184:185], s[6:7], 0, v[132:133]
	s_add_u32 s30, s6, 0x10000
	ds_read_b128 v[90:93], v146 offset:16384
	ds_read_b128 v[172:175], v146 offset:17408
	ds_read_b128 v[176:179], v146 offset:18432
	ds_read_b128 v[188:191], v146 offset:19456
	ds_read_b128 v[192:195], v146 offset:20480
	ds_read_b128 v[196:199], v146 offset:21504
	ds_read_b128 v[200:203], v146 offset:22528
	ds_read_b128 v[204:207], v146 offset:23552
	global_load_lds_dwordx4 v[184:185], off
	v_lshl_add_u64 v[244:245], s[6:7], 0, v[136:137]
	s_mov_b32 m0, s3
	s_addc_u32 s31, s7, 0
	global_load_lds_dwordx4 v[244:245], off
	v_lshl_add_u64 v[208:209], s[30:31], 0, v[132:133]
	s_mov_b32 m0, s21
	v_lshl_add_u64 v[246:247], s[24:25], 0, v[130:131]
	global_load_lds_dwordx4 v[208:209], off
	v_lshl_add_u64 v[208:209], s[30:31], 0, v[136:137]
	s_mov_b32 m0, s23
	v_lshl_add_u64 v[248:249], s[24:25], 0, v[134:135]
	global_load_lds_dwordx4 v[208:209], off
	s_mov_b32 m0, s14
	s_nop 0
	global_load_lds_dwordx4 v[246:247], off
	s_mov_b32 m0, s15
	s_nop 0
	global_load_lds_dwordx4 v[248:249], off
	s_waitcnt vmcnt(8)
	s_waitcnt lgkmcnt(0)
	s_setprio 1
	s_barrier
	s_waitcnt lgkmcnt(0)
	v_mfma_f32_16x16x32_bf16 v[2:5], v[106:109], v[200:203], v[2:5]
	v_mfma_f32_16x16x32_bf16 v[6:9], v[114:117], v[200:203], v[6:9]
	v_mfma_f32_16x16x32_bf16 v[138:141], v[106:109], v[90:93], v[138:141]
	v_mfma_f32_16x16x32_bf16 v[142:145], v[114:117], v[90:93], v[142:145]
	v_mfma_f32_16x16x32_bf16 v[148:151], v[106:109], v[176:179], v[148:151]
	v_mfma_f32_16x16x32_bf16 v[152:155], v[114:117], v[176:179], v[152:155]
	v_mfma_f32_16x16x32_bf16 v[156:159], v[106:109], v[192:195], v[156:159]
	v_mfma_f32_16x16x32_bf16 v[160:163], v[114:117], v[192:195], v[160:163]
	v_mfma_f32_16x16x32_bf16 v[2:5], v[110:113], v[204:207], v[2:5]
	v_mfma_f32_16x16x32_bf16 v[6:9], v[118:121], v[204:207], v[6:9]
	v_mfma_f32_16x16x32_bf16 v[138:141], v[110:113], v[172:175], v[138:141]
	v_mfma_f32_16x16x32_bf16 v[142:145], v[118:121], v[172:175], v[142:145]
	v_mfma_f32_16x16x32_bf16 v[148:151], v[110:113], v[188:191], v[148:151]
	v_mfma_f32_16x16x32_bf16 v[152:155], v[118:121], v[188:191], v[152:155]
	v_mfma_f32_16x16x32_bf16 v[156:159], v[110:113], v[196:199], v[156:159]
	v_mfma_f32_16x16x32_bf16 v[160:163], v[118:121], v[196:199], v[160:163]
	v_mfma_f32_16x16x32_bf16 v[10:13], v[122:125], v[90:93], v[10:13]
	v_mfma_f32_16x16x32_bf16 v[208:211], v[126:129], v[172:175], v[10:13]
	v_mfma_f32_16x16x32_bf16 v[10:13], v[164:167], v[90:93], v[14:17]
	v_mfma_f32_16x16x32_bf16 v[14:17], v[168:171], v[172:175], v[10:13]
	v_mfma_f32_16x16x32_bf16 v[10:13], v[122:125], v[176:179], v[26:29]
	v_mfma_f32_16x16x32_bf16 v[172:175], v[126:129], v[188:191], v[10:13]
	v_mfma_f32_16x16x32_bf16 v[10:13], v[164:167], v[176:179], v[30:33]
	v_mfma_f32_16x16x32_bf16 v[30:33], v[168:171], v[188:191], v[10:13]
	v_mfma_f32_16x16x32_bf16 v[10:13], v[122:125], v[192:195], v[62:65]
	v_mfma_f32_16x16x32_bf16 v[176:179], v[126:129], v[196:199], v[10:13]
	v_mfma_f32_16x16x32_bf16 v[10:13], v[164:167], v[192:195], v[102:105]
	v_mfma_f32_16x16x32_bf16 v[188:191], v[168:171], v[196:199], v[10:13]
	v_mfma_f32_16x16x32_bf16 v[10:13], v[122:125], v[200:203], v[18:21]
	v_mfma_f32_16x16x32_bf16 v[192:195], v[126:129], v[204:207], v[10:13]
	v_mfma_f32_16x16x32_bf16 v[10:13], v[164:167], v[200:203], v[22:25]
	v_mfma_f32_16x16x32_bf16 v[164:167], v[168:171], v[204:207], v[10:13]
	s_setprio 0
	s_barrier
; #define PG8_STAGE(bufoff, gbase, voff) do { _Pragma("unroll") for (int _i = 0; _i < 2; ++_i) \
;         __builtin_amdgcn_global_load_lds((const unsigned*)((const char*)(gbase) + (voff)[_i]), (LAS unsigned*)(lds + (bufoff) + ldsw + _i * 8192), 16, 0, 0); } while (0)
; #define PG8_LDA(dst, b, h) do { _Pragma("unroll") for (int m = 0; m < 4; ++m) _Pragma("unroll") for (int k = 0; k < 2; ++k) dst[m][k] = *(const LAS bf16x8*)(lds + PG8_SA(b, h) + aoff + m * 2048 + k * 1024); } while (0)
; #define PG8_LDB(dst, b, h) do { _Pragma("unroll") for (int n = 0; n < 2; ++n) _Pragma("unroll") for (int k = 0; k < 2; ++k) dst[n][k] = *(const LAS bf16x8*)(lds + PG8_SB(b, h) + boff + n * 2048 + k * 1024); } while (0)
; #define PG8_MMA(ai, bj, At, Bt) do { __builtin_amdgcn_s_setprio(1); _Pragma("unroll") for (int m = 0; m < 4; ++m) _Pragma("unroll") for (int n = 0; n < 2; ++n) _Pragma("unroll") for (int k = 0; k < 2; ++k) \
;         acc[ai][bj][m][n] = __builtin_amdgcn_mfma_f32_16x16x32_bf16(Bt[n][k], At[m][k], acc[ai][bj][m][n], 0, 0, 0); __builtin_amdgcn_s_setprio(0); } while (0)
; #define PG8_WAIT_V(n) asm volatile("s_waitcnt vmcnt(" #n ")" ::: "memory")
; #define PG8_WAIT_L(n) asm volatile("s_waitcnt lgkmcnt(" #n ")" ::: "memory")
; #define PG8_BAR __builtin_amdgcn_s_barrier()
; #define PG8_SCHED __builtin_amdgcn_sched_barrier(0)
; template <class Epi>
; __device__ __forceinline__ void gemm_phase(LAS unsigned char* lds, const Gemm g, const StaticOrder& S, const Epi& E) {
;     ...
;             PG8_LDB(B0, 1, 0); PG8_LDB(B1, 1, 1); PG8_SCHED; PG8_LDA(At, 1, 0); PG8_STAGE(PG8_SA(0, 1), a2 + hstepA, voffA);
;             PG8_WAIT_V(8); PG8_WAIT_L(0); PG8_BAR; PG8_MMA(0, 0, At, B0); PG8_MMA(0, 1, At, B1); PG8_BAR; PG8_SCHED;
;             PG8_LDA(At, 1, 1); PG8_STAGE(PG8_SB(1, 0), b3, voffB); PG8_STAGE(PG8_SB(1, 1), b3 + hstepB, voffB); PG8_STAGE(PG8_SA(1, 0), a3, voffA);
;             PG8_WAIT_V(8); PG8_WAIT_L(0); PG8_BAR; PG8_MMA(1, 0, At, B0); PG8_MMA(1, 1, At, B1); PG8_BAR; PG8_SCHED;
;         }
;         if (wr == 0) PG8_BAR;
	s_nop 4
	ds_read_b128 v[10:13], v183
	ds_read_b128 v[18:21], v183 offset:1024
	ds_read_b128 v[62:65], v183 offset:2048
	ds_read_b128 v[168:171], v183 offset:3072
	ds_read_b128 v[196:199], v186
	ds_read_b128 v[200:203], v186 offset:1024
	ds_read_b128 v[204:207], v186 offset:2048
	ds_read_b128 v[216:219], v186 offset:3072
	s_add_u32 s30, s24, 0x80000
	s_addc_u32 s31, s25, 0
	s_mov_b32 m0, s29
	v_lshl_add_u64 v[90:91], s[30:31], 0, v[130:131]
	ds_read_b128 v[22:25], v146 offset:32768
	ds_read_b128 v[26:29], v146 offset:33792
	ds_read_b128 v[220:223], v146 offset:34816
	ds_read_b128 v[224:227], v146 offset:35840
	ds_read_b128 v[228:231], v146 offset:36864
	ds_read_b128 v[232:235], v146 offset:37888
	ds_read_b128 v[236:239], v146 offset:38912
	ds_read_b128 v[240:243], v146 offset:39936
	global_load_lds_dwordx4 v[90:91], off
	v_lshl_add_u64 v[90:91], s[30:31], 0, v[134:135]
	s_mov_b32 m0, s42
	s_nop 0
	global_load_lds_dwordx4 v[90:91], off
	s_waitcnt vmcnt(8)
	s_waitcnt lgkmcnt(0)
	s_setprio 1
	s_barrier
	s_waitcnt lgkmcnt(0)
	v_mfma_f32_16x16x32_bf16 v[66:69], v[10:13], v[22:25], v[66:69]
	v_mfma_f32_16x16x32_bf16 v[126:129], v[18:21], v[26:29], v[66:69]
	v_mfma_f32_16x16x32_bf16 v[66:69], v[62:65], v[22:25], v[70:73]
	v_mfma_f32_16x16x32_bf16 v[118:121], v[168:171], v[26:29], v[66:69]
	v_mfma_f32_16x16x32_bf16 v[66:69], v[10:13], v[220:223], v[74:77]
	v_mfma_f32_16x16x32_bf16 v[106:109], v[18:21], v[224:227], v[66:69]
	v_mfma_f32_16x16x32_bf16 v[66:69], v[62:65], v[220:223], v[78:81]
	v_mfma_f32_16x16x32_bf16 v[102:105], v[168:171], v[224:227], v[66:69]
	v_mfma_f32_16x16x32_bf16 v[66:69], v[10:13], v[228:231], v[82:85]
	v_mfma_f32_16x16x32_bf16 v[90:93], v[18:21], v[232:235], v[66:69]
	v_mfma_f32_16x16x32_bf16 v[66:69], v[62:65], v[228:231], v[86:89]
	v_mfma_f32_16x16x32_bf16 v[86:89], v[168:171], v[232:235], v[66:69]
	v_mfma_f32_16x16x32_bf16 v[66:69], v[10:13], v[236:239], v[212:215]
	v_mfma_f32_16x16x32_bf16 v[74:77], v[18:21], v[240:243], v[66:69]
	v_mfma_f32_16x16x32_bf16 v[66:69], v[62:65], v[236:239], v[94:97]
	v_mfma_f32_16x16x32_bf16 v[70:73], v[168:171], v[240:243], v[66:69]
	v_mfma_f32_16x16x32_bf16 v[66:69], v[196:199], v[22:25], v[98:101]
	v_mfma_f32_16x16x32_bf16 v[22:25], v[204:207], v[22:25], v[34:37]
	v_mfma_f32_16x16x32_bf16 v[114:117], v[216:219], v[26:29], v[22:25]
	v_mfma_f32_16x16x32_bf16 v[22:25], v[196:199], v[220:223], v[38:41]
	v_mfma_f32_16x16x32_bf16 v[110:113], v[200:203], v[224:227], v[22:25]
	v_mfma_f32_16x16x32_bf16 v[22:25], v[204:207], v[220:223], v[42:45]
	v_mfma_f32_16x16x32_bf16 v[98:101], v[216:219], v[224:227], v[22:25]
	v_mfma_f32_16x16x32_bf16 v[22:25], v[196:199], v[228:231], v[46:49]
	v_mfma_f32_16x16x32_bf16 v[94:97], v[200:203], v[232:235], v[22:25]
	v_mfma_f32_16x16x32_bf16 v[22:25], v[204:207], v[228:231], v[50:53]
	v_mfma_f32_16x16x32_bf16 v[82:85], v[216:219], v[232:235], v[22:25]
	v_mfma_f32_16x16x32_bf16 v[22:25], v[196:199], v[236:239], v[54:57]
	v_mfma_f32_16x16x32_bf16 v[78:81], v[200:203], v[240:243], v[22:25]
	v_mfma_f32_16x16x32_bf16 v[22:25], v[204:207], v[236:239], v[58:61]
	v_mfma_f32_16x16x32_bf16 v[122:125], v[200:203], v[26:29], v[66:69]
	v_mfma_f32_16x16x32_bf16 v[66:69], v[216:219], v[240:243], v[22:25]
	s_setprio 0
	s_barrier
	s_mov_b32 m0, s52
	s_nop 2
	v_lshl_add_u64 v[22:23], v[184:185], 0, s[84:85]
	s_add_u32 s6, s6, 0x10080
	ds_read_b128 v[34:37], v146 offset:49152
	ds_read_b128 v[46:49], v146 offset:50176
	ds_read_b128 v[212:215], v146 offset:51200
	ds_read_b128 v[220:223], v146 offset:52224
	ds_read_b128 v[224:227], v146 offset:53248
	ds_read_b128 v[228:231], v146 offset:54272
	ds_read_b128 v[232:235], v146 offset:55296
	ds_read_b128 v[236:239], v146 offset:56320
	global_load_lds_dwordx4 v[22:23], off
	v_lshl_add_u64 v[22:23], v[244:245], 0, s[84:85]
	s_mov_b32 m0, s40
	s_addc_u32 s7, s7, 0
	global_load_lds_dwordx4 v[22:23], off
	v_lshl_add_u64 v[22:23], s[6:7], 0, v[132:133]
	s_mov_b32 m0, s34
	s_nop 0
	global_load_lds_dwordx4 v[22:23], off
	v_lshl_add_u64 v[22:23], s[6:7], 0, v[136:137]
	s_mov_b32 m0, s35
	s_nop 0
	global_load_lds_dwordx4 v[22:23], off
	v_lshl_add_u64 v[22:23], v[246:247], 0, s[84:85]
	s_mov_b32 m0, s68
	s_nop 0
	global_load_lds_dwordx4 v[22:23], off
	v_lshl_add_u64 v[22:23], v[248:249], 0, s[84:85]
	s_mov_b32 m0, s69
	s_nop 0
	global_load_lds_dwordx4 v[22:23], off
	s_waitcnt vmcnt(8)
	s_waitcnt lgkmcnt(0)
	s_setprio 1
	s_barrier
	s_waitcnt lgkmcnt(0)
	v_mfma_f32_16x16x32_bf16 v[22:25], v[10:13], v[34:37], v[138:141]
	v_mfma_f32_16x16x32_bf16 v[58:61], v[18:21], v[46:49], v[22:25]
	v_mfma_f32_16x16x32_bf16 v[22:25], v[62:65], v[34:37], v[142:145]
	v_mfma_f32_16x16x32_bf16 v[54:57], v[168:171], v[46:49], v[22:25]
	v_mfma_f32_16x16x32_bf16 v[22:25], v[10:13], v[212:215], v[148:151]
	v_mfma_f32_16x16x32_bf16 v[42:45], v[18:21], v[220:223], v[22:25]
	v_mfma_f32_16x16x32_bf16 v[22:25], v[62:65], v[212:215], v[152:155]
	v_mfma_f32_16x16x32_bf16 v[38:41], v[168:171], v[220:223], v[22:25]
	v_mfma_f32_16x16x32_bf16 v[22:25], v[10:13], v[224:227], v[156:159]
	v_mfma_f32_16x16x32_bf16 v[2:5], v[10:13], v[232:235], v[2:5]
	v_mfma_f32_16x16x32_bf16 v[26:29], v[18:21], v[228:231], v[22:25]
	v_mfma_f32_16x16x32_bf16 v[22:25], v[62:65], v[224:227], v[160:163]
	v_mfma_f32_16x16x32_bf16 v[10:13], v[18:21], v[236:239], v[2:5]
	v_mfma_f32_16x16x32_bf16 v[2:5], v[62:65], v[232:235], v[6:9]
	v_mfma_f32_16x16x32_bf16 v[22:25], v[168:171], v[228:231], v[22:25]
	v_mfma_f32_16x16x32_bf16 v[6:9], v[168:171], v[236:239], v[2:5]
	v_mfma_f32_16x16x32_bf16 v[2:5], v[196:199], v[34:37], v[208:211]
	v_mfma_f32_16x16x32_bf16 v[62:65], v[200:203], v[46:49], v[2:5]
	v_mfma_f32_16x16x32_bf16 v[2:5], v[204:207], v[34:37], v[14:17]
	v_mfma_f32_16x16x32_bf16 v[50:53], v[216:219], v[46:49], v[2:5]
	v_mfma_f32_16x16x32_bf16 v[2:5], v[196:199], v[212:215], v[172:175]
	v_mfma_f32_16x16x32_bf16 v[46:49], v[200:203], v[220:223], v[2:5]
	v_mfma_f32_16x16x32_bf16 v[2:5], v[204:207], v[212:215], v[30:33]
	v_mfma_f32_16x16x32_bf16 v[34:37], v[216:219], v[220:223], v[2:5]
	v_mfma_f32_16x16x32_bf16 v[2:5], v[196:199], v[224:227], v[176:179]
	v_mfma_f32_16x16x32_bf16 v[30:33], v[200:203], v[228:231], v[2:5]
	v_mfma_f32_16x16x32_bf16 v[2:5], v[204:207], v[224:227], v[188:191]
	v_mfma_f32_16x16x32_bf16 v[18:21], v[216:219], v[228:231], v[2:5]
	v_mfma_f32_16x16x32_bf16 v[2:5], v[196:199], v[232:235], v[192:195]
	v_mfma_f32_16x16x32_bf16 v[14:17], v[200:203], v[236:239], v[2:5]
	v_mfma_f32_16x16x32_bf16 v[2:5], v[204:207], v[232:235], v[164:167]
	v_mfma_f32_16x16x32_bf16 v[2:5], v[216:219], v[236:239], v[2:5]
	s_setprio 0
	s_barrier
	s_andn2_b64 vcc, exec, s[16:17]
	s_cbranch_vccnz .LBB0_684
	s_barrier

; #define PG8_STAGE(bufoff, gbase, voff) do { _Pragma("unroll") for (int _i = 0; _i < 2; ++_i) \
;         __builtin_amdgcn_global_load_lds((const unsigned*)((const char*)(gbase) + (voff)[_i]), (LAS unsigned*)(lds + (bufoff) + ldsw + _i * 8192), 16, 0, 0); } while (0)
; #define PG8_LDA(dst, b, h) do { _Pragma("unroll") for (int m = 0; m < 4; ++m) _Pragma("unroll") for (int k = 0; k < 2; ++k) dst[m][k] = *(const LAS bf16x8*)(lds + PG8_SA(b, h) + aoff + m * 2048 + k * 1024); } while (0)
; #define PG8_LDB(dst, b, h) do { _Pragma("unroll") for (int n = 0; n < 2; ++n) _Pragma("unroll") for (int k = 0; k < 2; ++k) dst[n][k] = *(const LAS bf16x8*)(lds + PG8_SB(b, h) + boff + n * 2048 + k * 1024); } while (0)
; #define PG8_MMA(ai, bj, At, Bt) do { __builtin_amdgcn_s_setprio(1); _Pragma("unroll") for (int m = 0; m < 4; ++m) _Pragma("unroll") for (int n = 0; n < 2; ++n) _Pragma("unroll") for (int k = 0; k < 2; ++k) \
;         acc[ai][bj][m][n] = __builtin_amdgcn_mfma_f32_16x16x32_bf16(Bt[n][k], At[m][k], acc[ai][bj][m][n], 0, 0, 0); __builtin_amdgcn_s_setprio(0); } while (0)
; #define PG8_WAIT_V(n) asm volatile("s_waitcnt vmcnt(" #n ")" ::: "memory")
; #define PG8_WAIT_L(n) asm volatile("s_waitcnt lgkmcnt(" #n ")" ::: "memory")
; #define PG8_BAR __builtin_amdgcn_s_barrier()
; #define PG8_SCHED __builtin_amdgcn_sched_barrier(0)
; template <class Epi>
; __device__ __forceinline__ void gemm_phase(LAS unsigned char* lds, const Gemm g, const StaticOrder& S, const Epi& E) {
;     ...
;             const bool last = (t == nt - 2);
;             const char* a1 = cA + (size_t)(t + 1) * kstep;
;             const char* a2 = last ? nA : cA + (size_t)(t + 2) * kstep; const char* b2 = last ? nB : cB + (size_t)(t + 2) * kstep;
;             const char* a3 = a2 + kstep; const char* b3 = b2 + kstep;
;             PG8_LDB(B0, 0, 0); PG8_LDB(B1, 0, 1); PG8_SCHED; PG8_LDA(At, 0, 0); PG8_STAGE(PG8_SA(1, 1), a1 + hstepA, voffA);
;             PG8_WAIT_V(8); PG8_WAIT_L(0); PG8_BAR; PG8_MMA(0, 0, At, B0); PG8_MMA(0, 1, At, B1); PG8_BAR; PG8_SCHED;
;             PG8_LDA(At, 0, 1); PG8_STAGE(PG8_SB(0, 0), b2, voffB); PG8_STAGE(PG8_SB(0, 1), b2 + hstepB, voffB); PG8_STAGE(PG8_SA(0, 0), a2, voffA);
;             PG8_WAIT_V(8); PG8_WAIT_L(0); PG8_BAR; PG8_MMA(1, 0, At, B0); PG8_MMA(1, 1, At, B1); PG8_BAR; PG8_SCHED;
.LBB0_1010:
	s_add_u32 s14, s26, 0xfff80080
	s_addc_u32 s15, s27, -1
	s_add_i32 s41, 0, 0x10000
	s_cmp_eq_u32 s52, 28
	s_cselect_b32 s29, s1, s15
	s_cselect_b32 s28, s3, s14
	s_cselect_b32 s15, s7, s40
	s_cselect_b32 s14, s17, s19
	s_add_i32 s53, 0, 0x14000
	v_add_u32_e32 v142, s41, v1
	v_add_u32_e32 v158, s53, v1
	ds_read_b128 v[130:133], v142
	ds_read_b128 v[134:137], v142 offset:1024
	ds_read_b128 v[138:141], v142 offset:2048
	ds_read_b128 v[142:145], v142 offset:3072
	ds_read_b128 v[146:149], v158
	ds_read_b128 v[150:153], v158 offset:1024
	ds_read_b128 v[154:157], v158 offset:2048
	ds_read_b128 v[158:161], v158 offset:3072
	v_lshl_add_u64 v[178:179], s[26:27], 0, v[196:197]
	s_add_i32 m0, s25, 0xc000
	ds_read_b128 v[162:165], v181
	ds_read_b128 v[166:169], v181 offset:1024
	ds_read_b128 v[170:173], v181 offset:2048
	ds_read_b128 v[174:177], v181 offset:3072
	ds_read_b128 v[200:203], v181 offset:4096
	ds_read_b128 v[204:207], v181 offset:5120
	ds_read_b128 v[208:211], v181 offset:6144
	ds_read_b128 v[212:215], v181 offset:7168
	global_load_lds_dwordx4 v[178:179], off
	v_lshl_add_u64 v[178:179], s[26:27], 0, v[198:199]
	s_add_i32 m0, s25, 0xe000
	s_nop 0
	global_load_lds_dwordx4 v[178:179], off
	s_waitcnt vmcnt(8)
	s_waitcnt lgkmcnt(0)
	s_setprio 1
	s_barrier
	s_waitcnt lgkmcnt(0)
	v_mfma_f32_16x16x32_bf16 v[126:129], v[130:133], v[162:165], v[126:129]
	v_mfma_f32_16x16x32_bf16 v[122:125], v[138:141], v[162:165], v[122:125]
	v_mfma_f32_16x16x32_bf16 v[110:113], v[130:133], v[170:173], v[110:113]
	v_mfma_f32_16x16x32_bf16 v[106:109], v[138:141], v[170:173], v[106:109]
	v_mfma_f32_16x16x32_bf16 v[94:97], v[130:133], v[200:203], v[94:97]
	v_mfma_f32_16x16x32_bf16 v[90:93], v[138:141], v[200:203], v[90:93]
	v_mfma_f32_16x16x32_bf16 v[82:85], v[130:133], v[208:211], v[82:85]
	v_mfma_f32_16x16x32_bf16 v[74:77], v[138:141], v[208:211], v[74:77]
	v_mfma_f32_16x16x32_bf16 v[126:129], v[134:137], v[166:169], v[126:129]
	v_mfma_f32_16x16x32_bf16 v[122:125], v[142:145], v[166:169], v[122:125]
	v_mfma_f32_16x16x32_bf16 v[110:113], v[134:137], v[174:177], v[110:113]
	v_mfma_f32_16x16x32_bf16 v[106:109], v[142:145], v[174:177], v[106:109]
	v_mfma_f32_16x16x32_bf16 v[94:97], v[134:137], v[204:207], v[94:97]
	v_mfma_f32_16x16x32_bf16 v[90:93], v[142:145], v[204:207], v[90:93]
	v_mfma_f32_16x16x32_bf16 v[82:85], v[134:137], v[212:215], v[82:85]
	v_mfma_f32_16x16x32_bf16 v[74:77], v[142:145], v[212:215], v[74:77]
	v_mfma_f32_16x16x32_bf16 v[118:121], v[146:149], v[162:165], v[118:121]
	v_mfma_f32_16x16x32_bf16 v[114:117], v[154:157], v[162:165], v[114:117]
	v_mfma_f32_16x16x32_bf16 v[102:105], v[146:149], v[170:173], v[102:105]
	v_mfma_f32_16x16x32_bf16 v[98:101], v[154:157], v[170:173], v[98:101]
	v_mfma_f32_16x16x32_bf16 v[86:89], v[146:149], v[200:203], v[86:89]
	v_mfma_f32_16x16x32_bf16 v[78:81], v[154:157], v[200:203], v[78:81]
	v_mfma_f32_16x16x32_bf16 v[70:73], v[146:149], v[208:211], v[70:73]
	v_mfma_f32_16x16x32_bf16 v[66:69], v[154:157], v[208:211], v[66:69]
	v_mfma_f32_16x16x32_bf16 v[118:121], v[150:153], v[166:169], v[118:121]
	v_mfma_f32_16x16x32_bf16 v[114:117], v[158:161], v[166:169], v[114:117]
	v_mfma_f32_16x16x32_bf16 v[102:105], v[150:153], v[174:177], v[102:105]
	v_mfma_f32_16x16x32_bf16 v[98:101], v[158:161], v[174:177], v[98:101]
	v_mfma_f32_16x16x32_bf16 v[86:89], v[150:153], v[204:207], v[86:89]
	v_mfma_f32_16x16x32_bf16 v[78:81], v[158:161], v[204:207], v[78:81]
	v_mfma_f32_16x16x32_bf16 v[70:73], v[150:153], v[212:215], v[70:73]
	v_mfma_f32_16x16x32_bf16 v[66:69], v[158:161], v[212:215], v[66:69]
	s_setprio 0
	s_barrier
	s_add_i32 s41, s41, s30
	v_lshl_add_u64 v[178:179], s[14:15], 0, v[190:191]
	s_mov_b32 m0, s41
	ds_read_b128 v[162:165], v181 offset:16384
	ds_read_b128 v[166:169], v181 offset:17408
	ds_read_b128 v[170:173], v181 offset:18432
	ds_read_b128 v[174:177], v181 offset:19456
	ds_read_b128 v[200:203], v181 offset:20480
	ds_read_b128 v[204:207], v181 offset:21504
	ds_read_b128 v[208:211], v181 offset:22528
	ds_read_b128 v[212:215], v181 offset:23552
	global_load_lds_dwordx4 v[178:179], off
	s_add_i32 m0, s41, 0x2000
	s_add_u32 s62, s14, 0x80000
	v_lshl_add_u64 v[184:185], s[14:15], 0, v[194:195]
	s_addc_u32 s63, s15, 0
	s_add_i32 s41, s53, s30
	global_load_lds_dwordx4 v[184:185], off
	v_lshl_add_u64 v[216:217], s[62:63], 0, v[190:191]
	s_mov_b32 m0, s41
	v_lshl_add_u64 v[218:219], s[28:29], 0, v[192:193]
	global_load_lds_dwordx4 v[216:217], off
	v_lshl_add_u64 v[216:217], s[62:63], 0, v[194:195]
	s_add_i32 m0, s41, 0x2000
	s_nop 0
	global_load_lds_dwordx4 v[216:217], off
	v_lshl_add_u64 v[216:217], s[28:29], 0, v[188:189]
	s_mov_b32 m0, s25
	s_nop 0
	global_load_lds_dwordx4 v[216:217], off
	s_mov_b32 m0, s31
	s_nop 0
	global_load_lds_dwordx4 v[218:219], off
	s_waitcnt vmcnt(8)
	s_waitcnt lgkmcnt(0)
	s_setprio 1
	s_barrier
; #define PG8_STAGE(bufoff, gbase, voff) do { _Pragma("unroll") for (int _i = 0; _i < 2; ++_i) \
;         __builtin_amdgcn_global_load_lds((const unsigned*)((const char*)(gbase) + (voff)[_i]), (LAS unsigned*)(lds + (bufoff) + ldsw + _i * 8192), 16, 0, 0); } while (0)
; #define PG8_LDA(dst, b, h) do { _Pragma("unroll") for (int m = 0; m < 4; ++m) _Pragma("unroll") for (int k = 0; k < 2; ++k) dst[m][k] = *(const LAS bf16x8*)(lds + PG8_SA(b, h) + aoff + m * 2048 + k * 1024); } while (0)
; #define PG8_LDB(dst, b, h) do { _Pragma("unroll") for (int n = 0; n < 2; ++n) _Pragma("unroll") for (int k = 0; k < 2; ++k) dst[n][k] = *(const LAS bf16x8*)(lds + PG8_SB(b, h) + boff + n * 2048 + k * 1024); } while (0)
; #define PG8_MMA(ai, bj, At, Bt) do { __builtin_amdgcn_s_setprio(1); _Pragma("unroll") for (int m = 0; m < 4; ++m) _Pragma("unroll") for (int n = 0; n < 2; ++n) _Pragma("unroll") for (int k = 0; k < 2; ++k) \
;         acc[ai][bj][m][n] = __builtin_amdgcn_mfma_f32_16x16x32_bf16(Bt[n][k], At[m][k], acc[ai][bj][m][n], 0, 0, 0); __builtin_amdgcn_s_setprio(0); } while (0)
; #define PG8_WAIT_V(n) asm volatile("s_waitcnt vmcnt(" #n ")" ::: "memory")
; #define PG8_WAIT_L(n) asm volatile("s_waitcnt lgkmcnt(" #n ")" ::: "memory")
; #define PG8_BAR __builtin_amdgcn_s_barrier()
; #define PG8_SCHED __builtin_amdgcn_sched_barrier(0)
; template <class Epi>
; __device__ __forceinline__ void gemm_phase(LAS unsigned char* lds, const Gemm g, const StaticOrder& S, const Epi& E) {
;     ...
;             PG8_WAIT_V(8); PG8_WAIT_L(0); PG8_BAR; PG8_MMA(1, 0, At, B0); PG8_MMA(1, 1, At, B1); PG8_BAR; PG8_SCHED;
;             PG8_LDB(B0, 1, 0); PG8_LDB(B1, 1, 1); PG8_SCHED; PG8_LDA(At, 1, 0); PG8_STAGE(PG8_SA(0, 1), a2 + hstepA, voffA);
;             PG8_WAIT_V(8); PG8_WAIT_L(0); PG8_BAR; PG8_MMA(0, 0, At, B0); PG8_MMA(0, 1, At, B1); PG8_BAR; PG8_SCHED;
	s_waitcnt lgkmcnt(0)
	v_mfma_f32_16x16x32_bf16 v[62:65], v[130:133], v[162:165], v[62:65]
	v_mfma_f32_16x16x32_bf16 v[58:61], v[138:141], v[162:165], v[58:61]
	v_mfma_f32_16x16x32_bf16 v[50:53], v[130:133], v[170:173], v[50:53]
	v_mfma_f32_16x16x32_bf16 v[42:45], v[138:141], v[170:173], v[42:45]
	v_mfma_f32_16x16x32_bf16 v[30:33], v[130:133], v[200:203], v[30:33]
	v_mfma_f32_16x16x32_bf16 v[26:29], v[138:141], v[200:203], v[26:29]
	v_mfma_f32_16x16x32_bf16 v[18:21], v[130:133], v[208:211], v[18:21]
	v_mfma_f32_16x16x32_bf16 v[10:13], v[138:141], v[208:211], v[10:13]
	v_mfma_f32_16x16x32_bf16 v[62:65], v[134:137], v[166:169], v[62:65]
	v_mfma_f32_16x16x32_bf16 v[58:61], v[142:145], v[166:169], v[58:61]
	v_mfma_f32_16x16x32_bf16 v[50:53], v[134:137], v[174:177], v[50:53]
	v_mfma_f32_16x16x32_bf16 v[42:45], v[142:145], v[174:177], v[42:45]
	v_mfma_f32_16x16x32_bf16 v[30:33], v[134:137], v[204:207], v[30:33]
	v_mfma_f32_16x16x32_bf16 v[26:29], v[142:145], v[204:207], v[26:29]
	v_mfma_f32_16x16x32_bf16 v[18:21], v[134:137], v[212:215], v[18:21]
	v_mfma_f32_16x16x32_bf16 v[10:13], v[142:145], v[212:215], v[10:13]
	v_mfma_f32_16x16x32_bf16 v[54:57], v[146:149], v[162:165], v[54:57]
	v_mfma_f32_16x16x32_bf16 v[46:49], v[154:157], v[162:165], v[46:49]
	v_mfma_f32_16x16x32_bf16 v[38:41], v[146:149], v[170:173], v[38:41]
	v_mfma_f32_16x16x32_bf16 v[34:37], v[154:157], v[170:173], v[34:37]
	v_mfma_f32_16x16x32_bf16 v[22:25], v[146:149], v[200:203], v[22:25]
	v_mfma_f32_16x16x32_bf16 v[14:17], v[154:157], v[200:203], v[14:17]
	v_mfma_f32_16x16x32_bf16 v[6:9], v[146:149], v[208:211], v[6:9]
	v_mfma_f32_16x16x32_bf16 v[2:5], v[154:157], v[208:211], v[2:5]
	v_mfma_f32_16x16x32_bf16 v[54:57], v[150:153], v[166:169], v[54:57]
	v_mfma_f32_16x16x32_bf16 v[46:49], v[158:161], v[166:169], v[46:49]
	v_mfma_f32_16x16x32_bf16 v[38:41], v[150:153], v[174:177], v[38:41]
	v_mfma_f32_16x16x32_bf16 v[34:37], v[158:161], v[174:177], v[34:37]
	v_mfma_f32_16x16x32_bf16 v[22:25], v[150:153], v[204:207], v[22:25]
	v_mfma_f32_16x16x32_bf16 v[14:17], v[158:161], v[204:207], v[14:17]
	v_mfma_f32_16x16x32_bf16 v[6:9], v[150:153], v[212:215], v[6:9]
	v_mfma_f32_16x16x32_bf16 v[2:5], v[158:161], v[212:215], v[2:5]
	s_setprio 0
	s_barrier
	s_add_i32 s41, 0, 0x18000
	s_add_i32 s53, 0, 0x1c000
	v_add_u32_e32 v142, s41, v1
	v_add_u32_e32 v158, s53, v1
	ds_read_b128 v[130:133], v142
	ds_read_b128 v[134:137], v142 offset:1024
	ds_read_b128 v[138:141], v142 offset:2048
	ds_read_b128 v[142:145], v142 offset:3072
	ds_read_b128 v[146:149], v158
	ds_read_b128 v[150:153], v158 offset:1024
	ds_read_b128 v[154:157], v158 offset:2048
	ds_read_b128 v[158:161], v158 offset:3072
	s_add_u32 s28, s28, 0x80000
	s_addc_u32 s29, s29, 0
	s_mov_b32 m0, s33
	v_lshl_add_u64 v[220:221], s[28:29], 0, v[188:189]
	ds_read_b128 v[162:165], v181 offset:32768
	ds_read_b128 v[166:169], v181 offset:33792
	ds_read_b128 v[170:173], v181 offset:34816
	ds_read_b128 v[174:177], v181 offset:35840
	ds_read_b128 v[200:203], v181 offset:36864
	ds_read_b128 v[204:207], v181 offset:37888
	ds_read_b128 v[208:211], v181 offset:38912
	ds_read_b128 v[212:215], v181 offset:39936
	global_load_lds_dwordx4 v[220:221], off
	v_lshl_add_u64 v[220:221], s[28:29], 0, v[192:193]
	s_mov_b32 m0, s34
	s_nop 0
	global_load_lds_dwordx4 v[220:221], off
	s_waitcnt vmcnt(8)
	s_waitcnt lgkmcnt(0)
	s_setprio 1
	s_barrier
	s_waitcnt lgkmcnt(0)
	v_mfma_f32_16x16x32_bf16 v[126:129], v[130:133], v[162:165], v[126:129]
	v_mfma_f32_16x16x32_bf16 v[122:125], v[138:141], v[162:165], v[122:125]
	v_mfma_f32_16x16x32_bf16 v[110:113], v[130:133], v[170:173], v[110:113]
	v_mfma_f32_16x16x32_bf16 v[106:109], v[138:141], v[170:173], v[106:109]
	v_mfma_f32_16x16x32_bf16 v[94:97], v[130:133], v[200:203], v[94:97]
	v_mfma_f32_16x16x32_bf16 v[90:93], v[138:141], v[200:203], v[90:93]
	v_mfma_f32_16x16x32_bf16 v[82:85], v[130:133], v[208:211], v[82:85]
	v_mfma_f32_16x16x32_bf16 v[74:77], v[138:141], v[208:211], v[74:77]
	v_mfma_f32_16x16x32_bf16 v[126:129], v[134:137], v[166:169], v[126:129]
	v_mfma_f32_16x16x32_bf16 v[122:125], v[142:145], v[166:169], v[122:125]
	v_mfma_f32_16x16x32_bf16 v[110:113], v[134:137], v[174:177], v[110:113]
	v_mfma_f32_16x16x32_bf16 v[106:109], v[142:145], v[174:177], v[106:109]
	v_mfma_f32_16x16x32_bf16 v[94:97], v[134:137], v[204:207], v[94:97]
	v_mfma_f32_16x16x32_bf16 v[90:93], v[142:145], v[204:207], v[90:93]
	v_mfma_f32_16x16x32_bf16 v[82:85], v[134:137], v[212:215], v[82:85]
	v_mfma_f32_16x16x32_bf16 v[74:77], v[142:145], v[212:215], v[74:77]
	v_mfma_f32_16x16x32_bf16 v[118:121], v[146:149], v[162:165], v[118:121]
	v_mfma_f32_16x16x32_bf16 v[114:117], v[154:157], v[162:165], v[114:117]
	v_mfma_f32_16x16x32_bf16 v[102:105], v[146:149], v[170:173], v[102:105]
	v_mfma_f32_16x16x32_bf16 v[98:101], v[154:157], v[170:173], v[98:101]
	v_mfma_f32_16x16x32_bf16 v[86:89], v[146:149], v[200:203], v[86:89]
	v_mfma_f32_16x16x32_bf16 v[78:81], v[154:157], v[200:203], v[78:81]
	v_mfma_f32_16x16x32_bf16 v[70:73], v[146:149], v[208:211], v[70:73]
	v_mfma_f32_16x16x32_bf16 v[66:69], v[154:157], v[208:211], v[66:69]
	v_mfma_f32_16x16x32_bf16 v[118:121], v[150:153], v[166:169], v[118:121]
	v_mfma_f32_16x16x32_bf16 v[114:117], v[158:161], v[166:169], v[114:117]
	v_mfma_f32_16x16x32_bf16 v[102:105], v[150:153], v[174:177], v[102:105]
	v_mfma_f32_16x16x32_bf16 v[98:101], v[158:161], v[174:177], v[98:101]
	v_mfma_f32_16x16x32_bf16 v[86:89], v[150:153], v[204:207], v[86:89]
	v_mfma_f32_16x16x32_bf16 v[78:81], v[158:161], v[204:207], v[78:81]
	v_mfma_f32_16x16x32_bf16 v[70:73], v[150:153], v[212:215], v[70:73]
	v_mfma_f32_16x16x32_bf16 v[66:69], v[158:161], v[212:215], v[66:69]
	s_setprio 0
	s_barrier
; #define PG8_STAGE(bufoff, gbase, voff) do { _Pragma("unroll") for (int _i = 0; _i < 2; ++_i) \
;         __builtin_amdgcn_global_load_lds((const unsigned*)((const char*)(gbase) + (voff)[_i]), (LAS unsigned*)(lds + (bufoff) + ldsw + _i * 8192), 16, 0, 0); } while (0)
; #define PG8_LDA(dst, b, h) do { _Pragma("unroll") for (int m = 0; m < 4; ++m) _Pragma("unroll") for (int k = 0; k < 2; ++k) dst[m][k] = *(const LAS bf16x8*)(lds + PG8_SA(b, h) + aoff + m * 2048 + k * 1024); } while (0)
; #define PG8_MMA(ai, bj, At, Bt) do { __builtin_amdgcn_s_setprio(1); _Pragma("unroll") for (int m = 0; m < 4; ++m) _Pragma("unroll") for (int n = 0; n < 2; ++n) _Pragma("unroll") for (int k = 0; k < 2; ++k) \
;         acc[ai][bj][m][n] = __builtin_amdgcn_mfma_f32_16x16x32_bf16(Bt[n][k], At[m][k], acc[ai][bj][m][n], 0, 0, 0); __builtin_amdgcn_s_setprio(0); } while (0)
; #define PG8_WAIT_V(n) asm volatile("s_waitcnt vmcnt(" #n ")" ::: "memory")
; #define PG8_WAIT_L(n) asm volatile("s_waitcnt lgkmcnt(" #n ")" ::: "memory")
; #define PG8_BAR __builtin_amdgcn_s_barrier()
; #define PG8_SCHED __builtin_amdgcn_sched_barrier(0)
; template <class Epi>
; __device__ __forceinline__ void gemm_phase(LAS unsigned char* lds, const Gemm g, const StaticOrder& S, const Epi& E) {
;     ...
;             PG8_LDA(At, 1, 1); PG8_STAGE(PG8_SB(1, 0), b3, voffB); PG8_STAGE(PG8_SB(1, 1), b3 + hstepB, voffB); PG8_STAGE(PG8_SA(1, 0), a3, voffA);
;             PG8_WAIT_V(8); PG8_WAIT_L(0); PG8_BAR; PG8_MMA(1, 0, At, B0); PG8_MMA(1, 1, At, B1); PG8_BAR; PG8_SCHED;
;         }
	s_add_i32 s28, s41, s30
	v_lshl_add_u64 v[178:179], v[178:179], 0, s[84:85]
	s_mov_b32 m0, s28
	ds_read_b128 v[162:165], v181 offset:49152
	ds_read_b128 v[166:169], v181 offset:50176
	ds_read_b128 v[170:173], v181 offset:51200
	ds_read_b128 v[174:177], v181 offset:52224
	ds_read_b128 v[200:203], v181 offset:53248
	ds_read_b128 v[204:207], v181 offset:54272
	ds_read_b128 v[208:211], v181 offset:55296
	ds_read_b128 v[212:215], v181 offset:56320
	global_load_lds_dwordx4 v[178:179], off
	s_add_i32 m0, s28, 0x2000
	s_add_u32 s14, s14, 0x80080
	v_lshl_add_u64 v[178:179], v[184:185], 0, s[84:85]
	s_addc_u32 s15, s15, 0
	s_add_i32 s28, s53, s30
	global_load_lds_dwordx4 v[178:179], off
	v_lshl_add_u64 v[178:179], s[14:15], 0, v[190:191]
	s_mov_b32 m0, s28
	s_nop 0
	global_load_lds_dwordx4 v[178:179], off
	v_lshl_add_u64 v[178:179], s[14:15], 0, v[194:195]
	s_add_i32 m0, s28, 0x2000
	s_nop 0
	global_load_lds_dwordx4 v[178:179], off
	v_lshl_add_u64 v[178:179], v[216:217], 0, s[84:85]
	s_mov_b32 m0, s44
	s_nop 0
	global_load_lds_dwordx4 v[178:179], off
	v_lshl_add_u64 v[178:179], v[218:219], 0, s[84:85]
	s_mov_b32 m0, s45
	s_nop 0
	global_load_lds_dwordx4 v[178:179], off
	s_waitcnt vmcnt(8)
	s_waitcnt lgkmcnt(0)
	s_setprio 1
	s_barrier
	s_waitcnt lgkmcnt(0)
	v_mfma_f32_16x16x32_bf16 v[62:65], v[130:133], v[162:165], v[62:65]
	v_mfma_f32_16x16x32_bf16 v[58:61], v[138:141], v[162:165], v[58:61]
	v_mfma_f32_16x16x32_bf16 v[50:53], v[130:133], v[170:173], v[50:53]
	v_mfma_f32_16x16x32_bf16 v[42:45], v[138:141], v[170:173], v[42:45]
	v_mfma_f32_16x16x32_bf16 v[30:33], v[130:133], v[200:203], v[30:33]
	v_mfma_f32_16x16x32_bf16 v[26:29], v[138:141], v[200:203], v[26:29]
	v_mfma_f32_16x16x32_bf16 v[18:21], v[130:133], v[208:211], v[18:21]
	v_mfma_f32_16x16x32_bf16 v[10:13], v[138:141], v[208:211], v[10:13]
	v_mfma_f32_16x16x32_bf16 v[62:65], v[134:137], v[166:169], v[62:65]
	v_mfma_f32_16x16x32_bf16 v[58:61], v[142:145], v[166:169], v[58:61]
	v_mfma_f32_16x16x32_bf16 v[50:53], v[134:137], v[174:177], v[50:53]
	v_mfma_f32_16x16x32_bf16 v[42:45], v[142:145], v[174:177], v[42:45]
	v_mfma_f32_16x16x32_bf16 v[30:33], v[134:137], v[204:207], v[30:33]
	v_mfma_f32_16x16x32_bf16 v[26:29], v[142:145], v[204:207], v[26:29]
	v_mfma_f32_16x16x32_bf16 v[18:21], v[134:137], v[212:215], v[18:21]
	v_mfma_f32_16x16x32_bf16 v[10:13], v[142:145], v[212:215], v[10:13]
	v_mfma_f32_16x16x32_bf16 v[54:57], v[146:149], v[162:165], v[54:57]
	v_mfma_f32_16x16x32_bf16 v[46:49], v[154:157], v[162:165], v[46:49]
	v_mfma_f32_16x16x32_bf16 v[38:41], v[146:149], v[170:173], v[38:41]
	v_mfma_f32_16x16x32_bf16 v[34:37], v[154:157], v[170:173], v[34:37]
	v_mfma_f32_16x16x32_bf16 v[22:25], v[146:149], v[200:203], v[22:25]
	v_mfma_f32_16x16x32_bf16 v[14:17], v[154:157], v[200:203], v[14:17]
	v_mfma_f32_16x16x32_bf16 v[6:9], v[146:149], v[208:211], v[6:9]
	v_mfma_f32_16x16x32_bf16 v[2:5], v[154:157], v[208:211], v[2:5]
	v_mfma_f32_16x16x32_bf16 v[54:57], v[150:153], v[166:169], v[54:57]
	v_mfma_f32_16x16x32_bf16 v[46:49], v[158:161], v[166:169], v[46:49]
	v_mfma_f32_16x16x32_bf16 v[38:41], v[150:153], v[174:177], v[38:41]
	v_mfma_f32_16x16x32_bf16 v[34:37], v[158:161], v[174:177], v[34:37]
	v_mfma_f32_16x16x32_bf16 v[22:25], v[150:153], v[204:207], v[22:25]
	v_mfma_f32_16x16x32_bf16 v[14:17], v[158:161], v[204:207], v[14:17]
	v_mfma_f32_16x16x32_bf16 v[6:9], v[150:153], v[212:215], v[6:9]
	v_mfma_f32_16x16x32_bf16 v[2:5], v[158:161], v[212:215], v[2:5]
	s_setprio 0
	s_barrier
	s_add_i32 s52, s52, 2
	s_add_u32 s26, s26, 0x100
	s_addc_u32 s27, s27, 0
	s_add_u32 s19, s19, 0x100
	s_addc_u32 s40, s40, 0
	s_cmp_gt_u32 s52, 29
	s_cbranch_scc0 .LBB0_1010
	s_cmp_ge_u32 s74, 16
	s_cbranch_scc1 .Lwpf_a
	s_lshl_b32 s100, s74, 9
	v_add_u32_e32 v130, s100, v246
	v_lshrrev_b32_e32 v131, 2, v130
	v_and_b32_e32 v130, 3, v130
	v_lshlrev_b32_e32 v130, 7, v130
	v_lshl_add_u32 v130, v131, 12, v130
	s_add_u32 s100, s88, 0x1800000
	s_addc_u32 s101, s89, 0
	s_mov_b32 m0, 0x21000
	s_nop 0
	global_load_lds_dword v130, s[100:101]

; #define PG8_STAGE(bufoff, gbase, voff) do { _Pragma("unroll") for (int _i = 0; _i < 2; ++_i) \
;         __builtin_amdgcn_global_load_lds((const unsigned*)((const char*)(gbase) + (voff)[_i]), (LAS unsigned*)(lds + (bufoff) + ldsw + _i * 8192), 16, 0, 0); } while (0)
; #define PG8_LDA(dst, b, h) do { _Pragma("unroll") for (int m = 0; m < 4; ++m) _Pragma("unroll") for (int k = 0; k < 2; ++k) dst[m][k] = *(const LAS bf16x8*)(lds + PG8_SA(b, h) + aoff + m * 2048 + k * 1024); } while (0)
; #define PG8_LDB(dst, b, h) do { _Pragma("unroll") for (int n = 0; n < 2; ++n) _Pragma("unroll") for (int k = 0; k < 2; ++k) dst[n][k] = *(const LAS bf16x8*)(lds + PG8_SB(b, h) + boff + n * 2048 + k * 1024); } while (0)
; #define PG8_MMA(ai, bj, At, Bt) do { __builtin_amdgcn_s_setprio(1); _Pragma("unroll") for (int m = 0; m < 4; ++m) _Pragma("unroll") for (int n = 0; n < 2; ++n) _Pragma("unroll") for (int k = 0; k < 2; ++k) \
;         acc[ai][bj][m][n] = __builtin_amdgcn_mfma_f32_16x16x32_bf16(Bt[n][k], At[m][k], acc[ai][bj][m][n], 0, 0, 0); __builtin_amdgcn_s_setprio(0); } while (0)
; #define PG8_WAIT_V(n) asm volatile("s_waitcnt vmcnt(" #n ")" ::: "memory")
; #define PG8_WAIT_L(n) asm volatile("s_waitcnt lgkmcnt(" #n ")" ::: "memory")
; #define PG8_BAR __builtin_amdgcn_s_barrier()
; #define PG8_SCHED __builtin_amdgcn_sched_barrier(0)
; template <class Epi>
; __device__ __forceinline__ void gemm_phase(LAS unsigned char* lds, const Gemm g, const StaticOrder& S, const Epi& E) {
;     ...
;             const bool last = (t == nt - 2);
;             const char* a1 = cA + (size_t)(t + 1) * kstep;
;             const char* a2 = last ? nA : cA + (size_t)(t + 2) * kstep; const char* b2 = last ? nB : cB + (size_t)(t + 2) * kstep;
;             const char* a3 = a2 + kstep; const char* b3 = b2 + kstep;
;             PG8_LDB(B0, 0, 0); PG8_LDB(B1, 0, 1); PG8_SCHED; PG8_LDA(At, 0, 0); PG8_STAGE(PG8_SA(1, 1), a1 + hstepA, voffA);
;             PG8_WAIT_V(8); PG8_WAIT_L(0); PG8_BAR; PG8_MMA(0, 0, At, B0); PG8_MMA(0, 1, At, B1); PG8_BAR; PG8_SCHED;
;             PG8_LDA(At, 0, 1); PG8_STAGE(PG8_SB(0, 0), b2, voffB); PG8_STAGE(PG8_SB(0, 1), b2 + hstepB, voffB); PG8_STAGE(PG8_SA(0, 0), a2, voffA);
;             PG8_WAIT_V(8); PG8_WAIT_L(0); PG8_BAR; PG8_MMA(1, 0, At, B0); PG8_MMA(1, 1, At, B1); PG8_BAR; PG8_SCHED;
.LBB0_1107:
	s_add_u32 s34, vcc_lo, 0xfff80080
	s_addc_u32 s35, vcc_hi, -1
	s_add_i32 s76, 0, 0x10000
	s_cmp_eq_u32 s41, 28
	s_cselect_b32 s69, s3, s35
	s_cselect_b32 s68, s7, s34
	s_cselect_b32 s35, s13, s87
	s_cselect_b32 s34, s40, s65
	s_add_i32 s78, 0, 0x14000
	v_add_u32_e32 v142, s76, v1
	v_add_u32_e32 v163, s78, v1
	ds_read_b128 v[130:133], v142
	ds_read_b128 v[134:137], v142 offset:1024
	ds_read_b128 v[138:141], v142 offset:2048
	ds_read_b128 v[142:145], v142 offset:3072
	ds_read_b128 v[158:161], v163
	ds_read_b128 v[164:167], v163 offset:1024
	ds_read_b128 v[168:171], v163 offset:2048
	ds_read_b128 v[172:175], v163 offset:3072
	v_lshl_add_u64 v[184:185], vcc, 0, v[154:155]
	s_add_i32 m0, s70, 0xc000
	ds_read_b128 v[176:179], v162
	ds_read_b128 v[188:191], v162 offset:1024
	ds_read_b128 v[192:195], v162 offset:2048
	ds_read_b128 v[196:199], v162 offset:3072
	ds_read_b128 v[200:203], v162 offset:4096
	ds_read_b128 v[204:207], v162 offset:5120
	ds_read_b128 v[208:211], v162 offset:6144
	ds_read_b128 v[212:215], v162 offset:7168
	global_load_lds_dwordx4 v[184:185], off
	v_lshl_add_u64 v[184:185], vcc, 0, v[156:157]
	s_add_i32 m0, s70, 0xe000
	s_nop 0
	global_load_lds_dwordx4 v[184:185], off
	s_waitcnt vmcnt(8)
	s_waitcnt lgkmcnt(0)
	s_setprio 1
	s_barrier
	s_waitcnt lgkmcnt(0)
	v_mfma_f32_16x16x32_bf16 v[126:129], v[130:133], v[176:179], v[126:129]
	v_mfma_f32_16x16x32_bf16 v[122:125], v[138:141], v[176:179], v[122:125]
	v_mfma_f32_16x16x32_bf16 v[114:117], v[130:133], v[192:195], v[114:117]
	v_mfma_f32_16x16x32_bf16 v[106:109], v[138:141], v[192:195], v[106:109]
	v_mfma_f32_16x16x32_bf16 v[98:101], v[130:133], v[200:203], v[98:101]
	v_mfma_f32_16x16x32_bf16 v[90:93], v[138:141], v[200:203], v[90:93]
	v_mfma_f32_16x16x32_bf16 v[82:85], v[130:133], v[208:211], v[82:85]
	v_mfma_f32_16x16x32_bf16 v[74:77], v[138:141], v[208:211], v[74:77]
	v_mfma_f32_16x16x32_bf16 v[126:129], v[134:137], v[188:191], v[126:129]
	v_mfma_f32_16x16x32_bf16 v[122:125], v[142:145], v[188:191], v[122:125]
	v_mfma_f32_16x16x32_bf16 v[114:117], v[134:137], v[196:199], v[114:117]
	v_mfma_f32_16x16x32_bf16 v[106:109], v[142:145], v[196:199], v[106:109]
	v_mfma_f32_16x16x32_bf16 v[98:101], v[134:137], v[204:207], v[98:101]
	v_mfma_f32_16x16x32_bf16 v[90:93], v[142:145], v[204:207], v[90:93]
	v_mfma_f32_16x16x32_bf16 v[82:85], v[134:137], v[212:215], v[82:85]
	v_mfma_f32_16x16x32_bf16 v[74:77], v[142:145], v[212:215], v[74:77]
	v_mfma_f32_16x16x32_bf16 v[118:121], v[158:161], v[176:179], v[118:121]
	v_mfma_f32_16x16x32_bf16 v[110:113], v[168:171], v[176:179], v[110:113]
	v_mfma_f32_16x16x32_bf16 v[102:105], v[158:161], v[192:195], v[102:105]
	v_mfma_f32_16x16x32_bf16 v[94:97], v[168:171], v[192:195], v[94:97]
	v_mfma_f32_16x16x32_bf16 v[86:89], v[158:161], v[200:203], v[86:89]
	v_mfma_f32_16x16x32_bf16 v[78:81], v[168:171], v[200:203], v[78:81]
	v_mfma_f32_16x16x32_bf16 v[70:73], v[158:161], v[208:211], v[70:73]
	v_mfma_f32_16x16x32_bf16 v[66:69], v[168:171], v[208:211], v[66:69]
	v_mfma_f32_16x16x32_bf16 v[118:121], v[164:167], v[188:191], v[118:121]
	v_mfma_f32_16x16x32_bf16 v[110:113], v[172:175], v[188:191], v[110:113]
	v_mfma_f32_16x16x32_bf16 v[102:105], v[164:167], v[196:199], v[102:105]
	v_mfma_f32_16x16x32_bf16 v[94:97], v[172:175], v[196:199], v[94:97]
	v_mfma_f32_16x16x32_bf16 v[86:89], v[164:167], v[204:207], v[86:89]
	v_mfma_f32_16x16x32_bf16 v[78:81], v[172:175], v[204:207], v[78:81]
	v_mfma_f32_16x16x32_bf16 v[70:73], v[164:167], v[212:215], v[70:73]
	v_mfma_f32_16x16x32_bf16 v[66:69], v[172:175], v[212:215], v[66:69]
	s_setprio 0
	s_barrier
	s_add_i32 s76, s76, s42
	v_lshl_add_u64 v[184:185], s[34:35], 0, v[148:149]
	s_mov_b32 m0, s76
	ds_read_b128 v[176:179], v162 offset:16384
	ds_read_b128 v[188:191], v162 offset:17408
	ds_read_b128 v[192:195], v162 offset:18432
	ds_read_b128 v[196:199], v162 offset:19456
	ds_read_b128 v[200:203], v162 offset:20480
	ds_read_b128 v[204:207], v162 offset:21504
	ds_read_b128 v[208:211], v162 offset:22528
	ds_read_b128 v[212:215], v162 offset:23552
	global_load_lds_dwordx4 v[184:185], off
	s_add_i32 m0, s76, 0x2000
	s_add_u32 s76, s34, 0x80000
	v_lshl_add_u64 v[216:217], s[34:35], 0, v[152:153]
	s_addc_u32 s77, s35, 0
	s_add_i32 s78, s78, s42
	global_load_lds_dwordx4 v[216:217], off
	v_lshl_add_u64 v[218:219], s[76:77], 0, v[148:149]
	s_mov_b32 m0, s78
	v_lshl_add_u64 v[220:221], s[68:69], 0, v[150:151]
	global_load_lds_dwordx4 v[218:219], off
	v_lshl_add_u64 v[218:219], s[76:77], 0, v[152:153]
	s_add_i32 m0, s78, 0x2000
	s_nop 0
	global_load_lds_dwordx4 v[218:219], off
	v_lshl_add_u64 v[218:219], s[68:69], 0, v[146:147]
	s_mov_b32 m0, s70
	s_nop 0
	global_load_lds_dwordx4 v[218:219], off
	s_mov_b32 m0, s91
	s_nop 0
	global_load_lds_dwordx4 v[220:221], off
	s_waitcnt vmcnt(8)
	s_waitcnt lgkmcnt(0)
	s_setprio 1
	s_barrier
; #define PG8_STAGE(bufoff, gbase, voff) do { _Pragma("unroll") for (int _i = 0; _i < 2; ++_i) \
;         __builtin_amdgcn_global_load_lds((const unsigned*)((const char*)(gbase) + (voff)[_i]), (LAS unsigned*)(lds + (bufoff) + ldsw + _i * 8192), 16, 0, 0); } while (0)
; #define PG8_LDA(dst, b, h) do { _Pragma("unroll") for (int m = 0; m < 4; ++m) _Pragma("unroll") for (int k = 0; k < 2; ++k) dst[m][k] = *(const LAS bf16x8*)(lds + PG8_SA(b, h) + aoff + m * 2048 + k * 1024); } while (0)
; #define PG8_LDB(dst, b, h) do { _Pragma("unroll") for (int n = 0; n < 2; ++n) _Pragma("unroll") for (int k = 0; k < 2; ++k) dst[n][k] = *(const LAS bf16x8*)(lds + PG8_SB(b, h) + boff + n * 2048 + k * 1024); } while (0)
; #define PG8_MMA(ai, bj, At, Bt) do { __builtin_amdgcn_s_setprio(1); _Pragma("unroll") for (int m = 0; m < 4; ++m) _Pragma("unroll") for (int n = 0; n < 2; ++n) _Pragma("unroll") for (int k = 0; k < 2; ++k) \
;         acc[ai][bj][m][n] = __builtin_amdgcn_mfma_f32_16x16x32_bf16(Bt[n][k], At[m][k], acc[ai][bj][m][n], 0, 0, 0); __builtin_amdgcn_s_setprio(0); } while (0)
; #define PG8_WAIT_V(n) asm volatile("s_waitcnt vmcnt(" #n ")" ::: "memory")
; #define PG8_WAIT_L(n) asm volatile("s_waitcnt lgkmcnt(" #n ")" ::: "memory")
; #define PG8_BAR __builtin_amdgcn_s_barrier()
; #define PG8_SCHED __builtin_amdgcn_sched_barrier(0)
; template <class Epi>
; __device__ __forceinline__ void gemm_phase(LAS unsigned char* lds, const Gemm g, const StaticOrder& S, const Epi& E) {
;     ...
;             PG8_WAIT_V(8); PG8_WAIT_L(0); PG8_BAR; PG8_MMA(1, 0, At, B0); PG8_MMA(1, 1, At, B1); PG8_BAR; PG8_SCHED;
;             PG8_LDB(B0, 1, 0); PG8_LDB(B1, 1, 1); PG8_SCHED; PG8_LDA(At, 1, 0); PG8_STAGE(PG8_SA(0, 1), a2 + hstepA, voffA);
;             PG8_WAIT_V(8); PG8_WAIT_L(0); PG8_BAR; PG8_MMA(0, 0, At, B0); PG8_MMA(0, 1, At, B1); PG8_BAR; PG8_SCHED;
	s_waitcnt lgkmcnt(0)
	v_mfma_f32_16x16x32_bf16 v[62:65], v[130:133], v[176:179], v[62:65]
	v_mfma_f32_16x16x32_bf16 v[58:61], v[138:141], v[176:179], v[58:61]
	v_mfma_f32_16x16x32_bf16 v[54:57], v[130:133], v[192:195], v[54:57]
	v_mfma_f32_16x16x32_bf16 v[46:49], v[138:141], v[192:195], v[46:49]
	v_mfma_f32_16x16x32_bf16 v[38:41], v[130:133], v[200:203], v[38:41]
	v_mfma_f32_16x16x32_bf16 v[30:33], v[138:141], v[200:203], v[30:33]
	v_mfma_f32_16x16x32_bf16 v[22:25], v[130:133], v[208:211], v[22:25]
	v_mfma_f32_16x16x32_bf16 v[14:17], v[138:141], v[208:211], v[14:17]
	v_mfma_f32_16x16x32_bf16 v[62:65], v[134:137], v[188:191], v[62:65]
	v_mfma_f32_16x16x32_bf16 v[58:61], v[142:145], v[188:191], v[58:61]
	v_mfma_f32_16x16x32_bf16 v[54:57], v[134:137], v[196:199], v[54:57]
	v_mfma_f32_16x16x32_bf16 v[46:49], v[142:145], v[196:199], v[46:49]
	v_mfma_f32_16x16x32_bf16 v[38:41], v[134:137], v[204:207], v[38:41]
	v_mfma_f32_16x16x32_bf16 v[30:33], v[142:145], v[204:207], v[30:33]
	v_mfma_f32_16x16x32_bf16 v[22:25], v[134:137], v[212:215], v[22:25]
	v_mfma_f32_16x16x32_bf16 v[14:17], v[142:145], v[212:215], v[14:17]
	v_mfma_f32_16x16x32_bf16 v[50:53], v[158:161], v[176:179], v[50:53]
	v_mfma_f32_16x16x32_bf16 v[42:45], v[168:171], v[176:179], v[42:45]
	v_mfma_f32_16x16x32_bf16 v[34:37], v[158:161], v[192:195], v[34:37]
	v_mfma_f32_16x16x32_bf16 v[26:29], v[168:171], v[192:195], v[26:29]
	v_mfma_f32_16x16x32_bf16 v[18:21], v[158:161], v[200:203], v[18:21]
	v_mfma_f32_16x16x32_bf16 v[10:13], v[168:171], v[200:203], v[10:13]
	v_mfma_f32_16x16x32_bf16 v[6:9], v[158:161], v[208:211], v[6:9]
	v_mfma_f32_16x16x32_bf16 v[2:5], v[168:171], v[208:211], v[2:5]
	v_mfma_f32_16x16x32_bf16 v[50:53], v[164:167], v[188:191], v[50:53]
	v_mfma_f32_16x16x32_bf16 v[42:45], v[172:175], v[188:191], v[42:45]
	v_mfma_f32_16x16x32_bf16 v[34:37], v[164:167], v[196:199], v[34:37]
	v_mfma_f32_16x16x32_bf16 v[26:29], v[172:175], v[196:199], v[26:29]
	v_mfma_f32_16x16x32_bf16 v[18:21], v[164:167], v[204:207], v[18:21]
	v_mfma_f32_16x16x32_bf16 v[10:13], v[172:175], v[204:207], v[10:13]
	v_mfma_f32_16x16x32_bf16 v[6:9], v[164:167], v[212:215], v[6:9]
	v_mfma_f32_16x16x32_bf16 v[2:5], v[172:175], v[212:215], v[2:5]
	s_setprio 0
	s_barrier
	s_add_i32 s76, 0, 0x18000
	s_add_i32 s77, 0, 0x1c000
	v_add_u32_e32 v142, s76, v1
	v_add_u32_e32 v163, s77, v1
	ds_read_b128 v[130:133], v142
	ds_read_b128 v[134:137], v142 offset:1024
	ds_read_b128 v[138:141], v142 offset:2048
	ds_read_b128 v[142:145], v142 offset:3072
	ds_read_b128 v[158:161], v163
	ds_read_b128 v[164:167], v163 offset:1024
	ds_read_b128 v[168:171], v163 offset:2048
	ds_read_b128 v[172:175], v163 offset:3072
	s_add_u32 s68, s68, 0x80000
	s_addc_u32 s69, s69, 0
	s_mov_b32 m0, s62
	v_lshl_add_u64 v[222:223], s[68:69], 0, v[146:147]
	ds_read_b128 v[176:179], v162 offset:32768
	ds_read_b128 v[188:191], v162 offset:33792
	ds_read_b128 v[192:195], v162 offset:34816
	ds_read_b128 v[196:199], v162 offset:35840
	ds_read_b128 v[200:203], v162 offset:36864
	ds_read_b128 v[204:207], v162 offset:37888
	ds_read_b128 v[208:211], v162 offset:38912
	ds_read_b128 v[212:215], v162 offset:39936
	global_load_lds_dwordx4 v[222:223], off
	v_lshl_add_u64 v[222:223], s[68:69], 0, v[150:151]
	s_mov_b32 m0, s63
	s_nop 0
	global_load_lds_dwordx4 v[222:223], off
	s_waitcnt vmcnt(8)
	s_waitcnt lgkmcnt(0)
	s_setprio 1
	s_barrier
	s_waitcnt lgkmcnt(0)
	v_mfma_f32_16x16x32_bf16 v[126:129], v[130:133], v[176:179], v[126:129]
	v_mfma_f32_16x16x32_bf16 v[122:125], v[138:141], v[176:179], v[122:125]
	v_mfma_f32_16x16x32_bf16 v[114:117], v[130:133], v[192:195], v[114:117]
	v_mfma_f32_16x16x32_bf16 v[106:109], v[138:141], v[192:195], v[106:109]
	v_mfma_f32_16x16x32_bf16 v[98:101], v[130:133], v[200:203], v[98:101]
	v_mfma_f32_16x16x32_bf16 v[90:93], v[138:141], v[200:203], v[90:93]
	v_mfma_f32_16x16x32_bf16 v[82:85], v[130:133], v[208:211], v[82:85]
	v_mfma_f32_16x16x32_bf16 v[74:77], v[138:141], v[208:211], v[74:77]
	v_mfma_f32_16x16x32_bf16 v[126:129], v[134:137], v[188:191], v[126:129]
	v_mfma_f32_16x16x32_bf16 v[122:125], v[142:145], v[188:191], v[122:125]
	v_mfma_f32_16x16x32_bf16 v[114:117], v[134:137], v[196:199], v[114:117]
	v_mfma_f32_16x16x32_bf16 v[106:109], v[142:145], v[196:199], v[106:109]
	v_mfma_f32_16x16x32_bf16 v[98:101], v[134:137], v[204:207], v[98:101]
	v_mfma_f32_16x16x32_bf16 v[90:93], v[142:145], v[204:207], v[90:93]
	v_mfma_f32_16x16x32_bf16 v[82:85], v[134:137], v[212:215], v[82:85]
	v_mfma_f32_16x16x32_bf16 v[74:77], v[142:145], v[212:215], v[74:77]
	v_mfma_f32_16x16x32_bf16 v[118:121], v[158:161], v[176:179], v[118:121]
	v_mfma_f32_16x16x32_bf16 v[110:113], v[168:171], v[176:179], v[110:113]
	v_mfma_f32_16x16x32_bf16 v[102:105], v[158:161], v[192:195], v[102:105]
	v_mfma_f32_16x16x32_bf16 v[94:97], v[168:171], v[192:195], v[94:97]
	v_mfma_f32_16x16x32_bf16 v[86:89], v[158:161], v[200:203], v[86:89]
	v_mfma_f32_16x16x32_bf16 v[78:81], v[168:171], v[200:203], v[78:81]
	v_mfma_f32_16x16x32_bf16 v[70:73], v[158:161], v[208:211], v[70:73]
	v_mfma_f32_16x16x32_bf16 v[66:69], v[168:171], v[208:211], v[66:69]
	v_mfma_f32_16x16x32_bf16 v[118:121], v[164:167], v[188:191], v[118:121]
	v_mfma_f32_16x16x32_bf16 v[110:113], v[172:175], v[188:191], v[110:113]
	v_mfma_f32_16x16x32_bf16 v[102:105], v[164:167], v[196:199], v[102:105]
	v_mfma_f32_16x16x32_bf16 v[94:97], v[172:175], v[196:199], v[94:97]
	v_mfma_f32_16x16x32_bf16 v[86:89], v[164:167], v[204:207], v[86:89]
	v_mfma_f32_16x16x32_bf16 v[78:81], v[172:175], v[204:207], v[78:81]
	v_mfma_f32_16x16x32_bf16 v[70:73], v[164:167], v[212:215], v[70:73]
	v_mfma_f32_16x16x32_bf16 v[66:69], v[172:175], v[212:215], v[66:69]
	s_setprio 0
	s_barrier
; #define PG8_STAGE(bufoff, gbase, voff) do { _Pragma("unroll") for (int _i = 0; _i < 2; ++_i) \
;         __builtin_amdgcn_global_load_lds((const unsigned*)((const char*)(gbase) + (voff)[_i]), (LAS unsigned*)(lds + (bufoff) + ldsw + _i * 8192), 16, 0, 0); } while (0)
; #define PG8_LDA(dst, b, h) do { _Pragma("unroll") for (int m = 0; m < 4; ++m) _Pragma("unroll") for (int k = 0; k < 2; ++k) dst[m][k] = *(const LAS bf16x8*)(lds + PG8_SA(b, h) + aoff + m * 2048 + k * 1024); } while (0)
; #define PG8_MMA(ai, bj, At, Bt) do { __builtin_amdgcn_s_setprio(1); _Pragma("unroll") for (int m = 0; m < 4; ++m) _Pragma("unroll") for (int n = 0; n < 2; ++n) _Pragma("unroll") for (int k = 0; k < 2; ++k) \
;         acc[ai][bj][m][n] = __builtin_amdgcn_mfma_f32_16x16x32_bf16(Bt[n][k], At[m][k], acc[ai][bj][m][n], 0, 0, 0); __builtin_amdgcn_s_setprio(0); } while (0)
; #define PG8_WAIT_V(n) asm volatile("s_waitcnt vmcnt(" #n ")" ::: "memory")
; #define PG8_WAIT_L(n) asm volatile("s_waitcnt lgkmcnt(" #n ")" ::: "memory")
; #define PG8_BAR __builtin_amdgcn_s_barrier()
; #define PG8_SCHED __builtin_amdgcn_sched_barrier(0)
; template <class Epi>
; __device__ __forceinline__ void gemm_phase(LAS unsigned char* lds, const Gemm g, const StaticOrder& S, const Epi& E) {
;     ...
;             PG8_LDA(At, 1, 1); PG8_STAGE(PG8_SB(1, 0), b3, voffB); PG8_STAGE(PG8_SB(1, 1), b3 + hstepB, voffB); PG8_STAGE(PG8_SA(1, 0), a3, voffA);
;             PG8_WAIT_V(8); PG8_WAIT_L(0); PG8_BAR; PG8_MMA(1, 0, At, B0); PG8_MMA(1, 1, At, B1); PG8_BAR; PG8_SCHED;
;         }
;         if (wr == 0) PG8_BAR;
	s_add_i32 s68, s76, s42
	v_lshl_add_u64 v[184:185], v[184:185], 0, s[84:85]
	s_mov_b32 m0, s68
	ds_read_b128 v[176:179], v162 offset:49152
	ds_read_b128 v[188:191], v162 offset:50176
	ds_read_b128 v[192:195], v162 offset:51200
	ds_read_b128 v[196:199], v162 offset:52224
	ds_read_b128 v[200:203], v162 offset:53248
	ds_read_b128 v[204:207], v162 offset:54272
	ds_read_b128 v[208:211], v162 offset:55296
	ds_read_b128 v[212:215], v162 offset:56320
	global_load_lds_dwordx4 v[184:185], off
	s_add_i32 m0, s68, 0x2000
	s_add_u32 s34, s34, 0x80080
	v_lshl_add_u64 v[184:185], v[216:217], 0, s[84:85]
	s_addc_u32 s35, s35, 0
	s_add_i32 s68, s77, s42
	global_load_lds_dwordx4 v[184:185], off
	v_lshl_add_u64 v[184:185], s[34:35], 0, v[148:149]
	s_mov_b32 m0, s68
	s_nop 0
	global_load_lds_dwordx4 v[184:185], off
	v_lshl_add_u64 v[184:185], s[34:35], 0, v[152:153]
	s_add_i32 m0, s68, 0x2000
	s_nop 0
	global_load_lds_dwordx4 v[184:185], off
	v_lshl_add_u64 v[184:185], v[218:219], 0, s[84:85]
	s_mov_b32 m0, s94
	s_nop 0
	global_load_lds_dwordx4 v[184:185], off
	v_lshl_add_u64 v[184:185], v[220:221], 0, s[84:85]
	s_mov_b32 m0, s95
	s_nop 0
	global_load_lds_dwordx4 v[184:185], off
	s_waitcnt vmcnt(8)
	s_waitcnt lgkmcnt(0)
	s_setprio 1
	s_barrier
	s_waitcnt lgkmcnt(0)
	v_mfma_f32_16x16x32_bf16 v[62:65], v[130:133], v[176:179], v[62:65]
	v_mfma_f32_16x16x32_bf16 v[58:61], v[138:141], v[176:179], v[58:61]
	v_mfma_f32_16x16x32_bf16 v[54:57], v[130:133], v[192:195], v[54:57]
	v_mfma_f32_16x16x32_bf16 v[46:49], v[138:141], v[192:195], v[46:49]
	v_mfma_f32_16x16x32_bf16 v[38:41], v[130:133], v[200:203], v[38:41]
	v_mfma_f32_16x16x32_bf16 v[30:33], v[138:141], v[200:203], v[30:33]
	v_mfma_f32_16x16x32_bf16 v[22:25], v[130:133], v[208:211], v[22:25]
	v_mfma_f32_16x16x32_bf16 v[14:17], v[138:141], v[208:211], v[14:17]
	v_mfma_f32_16x16x32_bf16 v[62:65], v[134:137], v[188:191], v[62:65]
	v_mfma_f32_16x16x32_bf16 v[58:61], v[142:145], v[188:191], v[58:61]
	v_mfma_f32_16x16x32_bf16 v[54:57], v[134:137], v[196:199], v[54:57]
	v_mfma_f32_16x16x32_bf16 v[46:49], v[142:145], v[196:199], v[46:49]
	v_mfma_f32_16x16x32_bf16 v[38:41], v[134:137], v[204:207], v[38:41]
	v_mfma_f32_16x16x32_bf16 v[30:33], v[142:145], v[204:207], v[30:33]
	v_mfma_f32_16x16x32_bf16 v[22:25], v[134:137], v[212:215], v[22:25]
	v_mfma_f32_16x16x32_bf16 v[14:17], v[142:145], v[212:215], v[14:17]
	v_mfma_f32_16x16x32_bf16 v[50:53], v[158:161], v[176:179], v[50:53]
	v_mfma_f32_16x16x32_bf16 v[42:45], v[168:171], v[176:179], v[42:45]
	v_mfma_f32_16x16x32_bf16 v[34:37], v[158:161], v[192:195], v[34:37]
	v_mfma_f32_16x16x32_bf16 v[26:29], v[168:171], v[192:195], v[26:29]
	v_mfma_f32_16x16x32_bf16 v[18:21], v[158:161], v[200:203], v[18:21]
	v_mfma_f32_16x16x32_bf16 v[10:13], v[168:171], v[200:203], v[10:13]
	v_mfma_f32_16x16x32_bf16 v[6:9], v[158:161], v[208:211], v[6:9]
	v_mfma_f32_16x16x32_bf16 v[2:5], v[168:171], v[208:211], v[2:5]
	v_mfma_f32_16x16x32_bf16 v[50:53], v[164:167], v[188:191], v[50:53]
	v_mfma_f32_16x16x32_bf16 v[42:45], v[172:175], v[188:191], v[42:45]
	v_mfma_f32_16x16x32_bf16 v[34:37], v[164:167], v[196:199], v[34:37]
	v_mfma_f32_16x16x32_bf16 v[26:29], v[172:175], v[196:199], v[26:29]
	v_mfma_f32_16x16x32_bf16 v[18:21], v[164:167], v[204:207], v[18:21]
	v_mfma_f32_16x16x32_bf16 v[10:13], v[172:175], v[204:207], v[10:13]
	v_mfma_f32_16x16x32_bf16 v[6:9], v[164:167], v[212:215], v[6:9]
	v_mfma_f32_16x16x32_bf16 v[2:5], v[172:175], v[212:215], v[2:5]
	s_setprio 0
	s_barrier
	s_add_i32 s41, s41, 2
	s_add_u32 vcc_lo, vcc_lo, 0x100
	s_addc_u32 vcc_hi, vcc_hi, 0
	s_add_u32 s65, s65, 0x100
	s_addc_u32 s87, s87, 0
	s_cmp_gt_u32 s41, 29
	s_cbranch_scc0 .LBB0_1107
	s_and_b64 vcc, exec, s[10:11]
	s_cbranch_vccz .LBB0_1110
	s_barrier

; #define PG8_STAGE(bufoff, gbase, voff) do { _Pragma("unroll") for (int _i = 0; _i < 2; ++_i) \
;         __builtin_amdgcn_global_load_lds((const unsigned*)((const char*)(gbase) + (voff)[_i]), (LAS unsigned*)(lds + (bufoff) + ldsw + _i * 8192), 16, 0, 0); } while (0)
; #define PG8_LDA(dst, b, h) do { _Pragma("unroll") for (int m = 0; m < 4; ++m) _Pragma("unroll") for (int k = 0; k < 2; ++k) dst[m][k] = *(const LAS bf16x8*)(lds + PG8_SA(b, h) + aoff + m * 2048 + k * 1024); } while (0)
; #define PG8_LDB(dst, b, h) do { _Pragma("unroll") for (int n = 0; n < 2; ++n) _Pragma("unroll") for (int k = 0; k < 2; ++k) dst[n][k] = *(const LAS bf16x8*)(lds + PG8_SB(b, h) + boff + n * 2048 + k * 1024); } while (0)
; #define PG8_MMA(ai, bj, At, Bt) do { __builtin_amdgcn_s_setprio(1); _Pragma("unroll") for (int m = 0; m < 4; ++m) _Pragma("unroll") for (int n = 0; n < 2; ++n) _Pragma("unroll") for (int k = 0; k < 2; ++k) \
;         acc[ai][bj][m][n] = __builtin_amdgcn_mfma_f32_16x16x32_bf16(Bt[n][k], At[m][k], acc[ai][bj][m][n], 0, 0, 0); __builtin_amdgcn_s_setprio(0); } while (0)
; #define PG8_WAIT_V(n) asm volatile("s_waitcnt vmcnt(" #n ")" ::: "memory")
; #define PG8_WAIT_L(n) asm volatile("s_waitcnt lgkmcnt(" #n ")" ::: "memory")
; #define PG8_BAR __builtin_amdgcn_s_barrier()
; #define PG8_SCHED __builtin_amdgcn_sched_barrier(0)
; template <class Epi>
; __device__ __forceinline__ void gemm_phase(LAS unsigned char* lds, const Gemm g, const StaticOrder& S, const Epi& E) {
;     ...
;             const bool last = (t == nt - 2);
;             const char* a1 = cA + (size_t)(t + 1) * kstep;
;             const char* a2 = last ? nA : cA + (size_t)(t + 2) * kstep; const char* b2 = last ? nB : cB + (size_t)(t + 2) * kstep;
;             const char* a3 = a2 + kstep; const char* b3 = b2 + kstep;
;             PG8_LDB(B0, 0, 0); PG8_LDB(B1, 0, 1); PG8_SCHED; PG8_LDA(At, 0, 0); PG8_STAGE(PG8_SA(1, 1), a1 + hstepA, voffA);
;             PG8_WAIT_V(8); PG8_WAIT_L(0); PG8_BAR; PG8_MMA(0, 0, At, B0); PG8_MMA(0, 1, At, B1); PG8_BAR; PG8_SCHED;
;             PG8_LDA(At, 0, 1); PG8_STAGE(PG8_SB(0, 0), b2, voffB); PG8_STAGE(PG8_SB(0, 1), b2 + hstepB, voffB); PG8_STAGE(PG8_SA(0, 0), a2, voffA);
;             PG8_WAIT_V(8); PG8_WAIT_L(0); PG8_BAR; PG8_MMA(1, 0, At, B0); PG8_MMA(1, 1, At, B1); PG8_BAR; PG8_SCHED;
.LBB0_1324:
	s_add_u32 s14, s24, 0xfff80080
	s_addc_u32 s15, s25, -1
	s_add_i32 s53, 0, 0x10000
	s_cmp_eq_u32 s41, 28
	s_cselect_b32 s27, s3, s15
	s_cselect_b32 s26, s7, s14
	s_cselect_b32 s15, s13, s52
	s_cselect_b32 s14, s17, s40
	s_add_i32 s69, 0, 0x14000
	v_add_u32_e32 v142, s53, v1
	v_add_u32_e32 v158, s69, v1
	ds_read_b128 v[130:133], v142
	ds_read_b128 v[134:137], v142 offset:1024
	ds_read_b128 v[138:141], v142 offset:2048
	ds_read_b128 v[142:145], v142 offset:3072
	ds_read_b128 v[146:149], v158
	ds_read_b128 v[150:153], v158 offset:1024
	ds_read_b128 v[154:157], v158 offset:2048
	ds_read_b128 v[158:161], v158 offset:3072
	v_lshl_add_u64 v[178:179], s[24:25], 0, v[170:171]
	s_add_i32 m0, s23, 0xc000
	ds_read_b128 v[162:165], v181
	ds_read_b128 v[174:177], v181 offset:1024
	ds_read_b128 v[188:191], v181 offset:2048
	ds_read_b128 v[192:195], v181 offset:3072
	ds_read_b128 v[196:199], v181 offset:4096
	ds_read_b128 v[200:203], v181 offset:5120
	ds_read_b128 v[204:207], v181 offset:6144
	ds_read_b128 v[208:211], v181 offset:7168
	global_load_lds_dwordx4 v[178:179], off
	v_lshl_add_u64 v[178:179], s[24:25], 0, v[172:173]
	s_add_i32 m0, s23, 0xe000
	s_nop 0
	global_load_lds_dwordx4 v[178:179], off
	s_waitcnt vmcnt(8)
	s_waitcnt lgkmcnt(0)
	s_setprio 1
	s_barrier
	s_waitcnt lgkmcnt(0)
	v_mfma_f32_16x16x32_bf16 v[122:125], v[130:133], v[162:165], v[122:125]
	v_mfma_f32_16x16x32_bf16 v[118:121], v[138:141], v[162:165], v[118:121]
	v_mfma_f32_16x16x32_bf16 v[110:113], v[130:133], v[188:191], v[110:113]
	v_mfma_f32_16x16x32_bf16 v[102:105], v[138:141], v[188:191], v[102:105]
	v_mfma_f32_16x16x32_bf16 v[94:97], v[130:133], v[196:199], v[94:97]
	v_mfma_f32_16x16x32_bf16 v[86:89], v[138:141], v[196:199], v[86:89]
	v_mfma_f32_16x16x32_bf16 v[78:81], v[130:133], v[204:207], v[78:81]
	v_mfma_f32_16x16x32_bf16 v[70:73], v[138:141], v[204:207], v[70:73]
	v_mfma_f32_16x16x32_bf16 v[122:125], v[134:137], v[174:177], v[122:125]
	v_mfma_f32_16x16x32_bf16 v[118:121], v[142:145], v[174:177], v[118:121]
	v_mfma_f32_16x16x32_bf16 v[110:113], v[134:137], v[192:195], v[110:113]
	v_mfma_f32_16x16x32_bf16 v[102:105], v[142:145], v[192:195], v[102:105]
	v_mfma_f32_16x16x32_bf16 v[94:97], v[134:137], v[200:203], v[94:97]
	v_mfma_f32_16x16x32_bf16 v[86:89], v[142:145], v[200:203], v[86:89]
	v_mfma_f32_16x16x32_bf16 v[78:81], v[134:137], v[208:211], v[78:81]
	v_mfma_f32_16x16x32_bf16 v[70:73], v[142:145], v[208:211], v[70:73]
	v_mfma_f32_16x16x32_bf16 v[126:129], v[146:149], v[162:165], v[126:129]
	v_mfma_f32_16x16x32_bf16 v[114:117], v[154:157], v[162:165], v[114:117]
	v_mfma_f32_16x16x32_bf16 v[106:109], v[146:149], v[188:191], v[106:109]
	v_mfma_f32_16x16x32_bf16 v[98:101], v[154:157], v[188:191], v[98:101]
	v_mfma_f32_16x16x32_bf16 v[90:93], v[146:149], v[196:199], v[90:93]
	v_mfma_f32_16x16x32_bf16 v[82:85], v[154:157], v[196:199], v[82:85]
	v_mfma_f32_16x16x32_bf16 v[74:77], v[146:149], v[204:207], v[74:77]
	v_mfma_f32_16x16x32_bf16 v[66:69], v[154:157], v[204:207], v[66:69]
	v_mfma_f32_16x16x32_bf16 v[126:129], v[150:153], v[174:177], v[126:129]
	v_mfma_f32_16x16x32_bf16 v[114:117], v[158:161], v[174:177], v[114:117]
	v_mfma_f32_16x16x32_bf16 v[106:109], v[150:153], v[192:195], v[106:109]
	v_mfma_f32_16x16x32_bf16 v[98:101], v[158:161], v[192:195], v[98:101]
	v_mfma_f32_16x16x32_bf16 v[90:93], v[150:153], v[200:203], v[90:93]
	v_mfma_f32_16x16x32_bf16 v[82:85], v[158:161], v[200:203], v[82:85]
	v_mfma_f32_16x16x32_bf16 v[74:77], v[150:153], v[208:211], v[74:77]
	v_mfma_f32_16x16x32_bf16 v[66:69], v[158:161], v[208:211], v[66:69]
	s_setprio 0
	s_barrier
	s_add_i32 s53, s53, s28
	v_lshl_add_u64 v[178:179], s[14:15], 0, v[166:167]
	s_mov_b32 m0, s53
	ds_read_b128 v[162:165], v181 offset:16384
	ds_read_b128 v[174:177], v181 offset:17408
	ds_read_b128 v[188:191], v181 offset:18432
	ds_read_b128 v[192:195], v181 offset:19456
	ds_read_b128 v[196:199], v181 offset:20480
	ds_read_b128 v[200:203], v181 offset:21504
	ds_read_b128 v[204:207], v181 offset:22528
	ds_read_b128 v[208:211], v181 offset:23552
	global_load_lds_dwordx4 v[178:179], off
	s_add_i32 m0, s53, 0x2000
	s_add_u32 s64, s14, 0x80000
	v_lshl_add_u64 v[184:185], s[14:15], 0, v[168:169]
	s_addc_u32 s65, s15, 0
	s_add_i32 s53, s69, s28
	global_load_lds_dwordx4 v[184:185], off
	v_lshl_add_u64 v[212:213], s[64:65], 0, v[166:167]
	s_mov_b32 m0, s53
	v_lshl_add_u64 v[214:215], s[26:27], 0, v[168:169]
	global_load_lds_dwordx4 v[212:213], off
	v_lshl_add_u64 v[212:213], s[64:65], 0, v[168:169]
	s_add_i32 m0, s53, 0x2000
	s_nop 0
	global_load_lds_dwordx4 v[212:213], off
	v_lshl_add_u64 v[212:213], s[26:27], 0, v[166:167]
	s_mov_b32 m0, s23
	s_nop 0
	global_load_lds_dwordx4 v[212:213], off
	s_mov_b32 m0, s29
	s_nop 0
	global_load_lds_dwordx4 v[214:215], off
	s_waitcnt vmcnt(8)
	s_waitcnt lgkmcnt(0)
	s_setprio 1
	s_barrier
; #define PG8_STAGE(bufoff, gbase, voff) do { _Pragma("unroll") for (int _i = 0; _i < 2; ++_i) \
;         __builtin_amdgcn_global_load_lds((const unsigned*)((const char*)(gbase) + (voff)[_i]), (LAS unsigned*)(lds + (bufoff) + ldsw + _i * 8192), 16, 0, 0); } while (0)
; #define PG8_LDA(dst, b, h) do { _Pragma("unroll") for (int m = 0; m < 4; ++m) _Pragma("unroll") for (int k = 0; k < 2; ++k) dst[m][k] = *(const LAS bf16x8*)(lds + PG8_SA(b, h) + aoff + m * 2048 + k * 1024); } while (0)
; #define PG8_LDB(dst, b, h) do { _Pragma("unroll") for (int n = 0; n < 2; ++n) _Pragma("unroll") for (int k = 0; k < 2; ++k) dst[n][k] = *(const LAS bf16x8*)(lds + PG8_SB(b, h) + boff + n * 2048 + k * 1024); } while (0)
; #define PG8_MMA(ai, bj, At, Bt) do { __builtin_amdgcn_s_setprio(1); _Pragma("unroll") for (int m = 0; m < 4; ++m) _Pragma("unroll") for (int n = 0; n < 2; ++n) _Pragma("unroll") for (int k = 0; k < 2; ++k) \
;         acc[ai][bj][m][n] = __builtin_amdgcn_mfma_f32_16x16x32_bf16(Bt[n][k], At[m][k], acc[ai][bj][m][n], 0, 0, 0); __builtin_amdgcn_s_setprio(0); } while (0)
; #define PG8_WAIT_V(n) asm volatile("s_waitcnt vmcnt(" #n ")" ::: "memory")
; #define PG8_WAIT_L(n) asm volatile("s_waitcnt lgkmcnt(" #n ")" ::: "memory")
; #define PG8_BAR __builtin_amdgcn_s_barrier()
; #define PG8_SCHED __builtin_amdgcn_sched_barrier(0)
; template <class Epi>
; __device__ __forceinline__ void gemm_phase(LAS unsigned char* lds, const Gemm g, const StaticOrder& S, const Epi& E) {
;     ...
;             PG8_WAIT_V(8); PG8_WAIT_L(0); PG8_BAR; PG8_MMA(1, 0, At, B0); PG8_MMA(1, 1, At, B1); PG8_BAR; PG8_SCHED;
;             PG8_LDB(B0, 1, 0); PG8_LDB(B1, 1, 1); PG8_SCHED; PG8_LDA(At, 1, 0); PG8_STAGE(PG8_SA(0, 1), a2 + hstepA, voffA);
;             PG8_WAIT_V(8); PG8_WAIT_L(0); PG8_BAR; PG8_MMA(0, 0, At, B0); PG8_MMA(0, 1, At, B1); PG8_BAR; PG8_SCHED;
;             PG8_LDA(At, 1, 1); PG8_STAGE(PG8_SB(1, 0), b3, voffB); PG8_STAGE(PG8_SB(1, 1), b3 + hstepB, voffB); PG8_STAGE(PG8_SA(1, 0), a3, voffA);
;             PG8_WAIT_V(8); PG8_WAIT_L(0); PG8_BAR; PG8_MMA(1, 0, At, B0); PG8_MMA(1, 1, At, B1); PG8_BAR; PG8_SCHED;
	s_waitcnt lgkmcnt(0)
	v_mfma_f32_16x16x32_bf16 v[62:65], v[130:133], v[162:165], v[62:65]
	v_mfma_f32_16x16x32_bf16 v[54:57], v[138:141], v[162:165], v[54:57]
	v_mfma_f32_16x16x32_bf16 v[46:49], v[130:133], v[188:191], v[46:49]
	v_mfma_f32_16x16x32_bf16 v[38:41], v[138:141], v[188:191], v[38:41]
	v_mfma_f32_16x16x32_bf16 v[30:33], v[130:133], v[196:199], v[30:33]
	v_mfma_f32_16x16x32_bf16 v[22:25], v[138:141], v[196:199], v[22:25]
	v_mfma_f32_16x16x32_bf16 v[14:17], v[130:133], v[204:207], v[14:17]
	v_mfma_f32_16x16x32_bf16 v[6:9], v[138:141], v[204:207], v[6:9]
	v_mfma_f32_16x16x32_bf16 v[62:65], v[134:137], v[174:177], v[62:65]
	v_mfma_f32_16x16x32_bf16 v[54:57], v[142:145], v[174:177], v[54:57]
	v_mfma_f32_16x16x32_bf16 v[46:49], v[134:137], v[192:195], v[46:49]
	v_mfma_f32_16x16x32_bf16 v[38:41], v[142:145], v[192:195], v[38:41]
	v_mfma_f32_16x16x32_bf16 v[30:33], v[134:137], v[200:203], v[30:33]
	v_mfma_f32_16x16x32_bf16 v[22:25], v[142:145], v[200:203], v[22:25]
	v_mfma_f32_16x16x32_bf16 v[14:17], v[134:137], v[208:211], v[14:17]
	v_mfma_f32_16x16x32_bf16 v[6:9], v[142:145], v[208:211], v[6:9]
	v_mfma_f32_16x16x32_bf16 v[58:61], v[146:149], v[162:165], v[58:61]
	v_mfma_f32_16x16x32_bf16 v[50:53], v[154:157], v[162:165], v[50:53]
	v_mfma_f32_16x16x32_bf16 v[42:45], v[146:149], v[188:191], v[42:45]
	v_mfma_f32_16x16x32_bf16 v[34:37], v[154:157], v[188:191], v[34:37]
	v_mfma_f32_16x16x32_bf16 v[26:29], v[146:149], v[196:199], v[26:29]
	v_mfma_f32_16x16x32_bf16 v[18:21], v[154:157], v[196:199], v[18:21]
	v_mfma_f32_16x16x32_bf16 v[10:13], v[146:149], v[204:207], v[10:13]
	v_mfma_f32_16x16x32_bf16 v[2:5], v[154:157], v[204:207], v[2:5]
	v_mfma_f32_16x16x32_bf16 v[58:61], v[150:153], v[174:177], v[58:61]
	v_mfma_f32_16x16x32_bf16 v[50:53], v[158:161], v[174:177], v[50:53]
	v_mfma_f32_16x16x32_bf16 v[42:45], v[150:153], v[192:195], v[42:45]
	v_mfma_f32_16x16x32_bf16 v[34:37], v[158:161], v[192:195], v[34:37]
	v_mfma_f32_16x16x32_bf16 v[26:29], v[150:153], v[200:203], v[26:29]
	v_mfma_f32_16x16x32_bf16 v[18:21], v[158:161], v[200:203], v[18:21]
	v_mfma_f32_16x16x32_bf16 v[10:13], v[150:153], v[208:211], v[10:13]
	v_mfma_f32_16x16x32_bf16 v[2:5], v[158:161], v[208:211], v[2:5]
	s_setprio 0
	s_barrier
	s_add_i32 s53, 0, 0x18000
	s_add_i32 s64, 0, 0x1c000
	v_add_u32_e32 v142, s53, v1
	v_add_u32_e32 v158, s64, v1
	ds_read_b128 v[130:133], v142
	ds_read_b128 v[134:137], v142 offset:1024
	ds_read_b128 v[138:141], v142 offset:2048
	ds_read_b128 v[142:145], v142 offset:3072
	ds_read_b128 v[146:149], v158
	ds_read_b128 v[150:153], v158 offset:1024
	ds_read_b128 v[154:157], v158 offset:2048
	ds_read_b128 v[158:161], v158 offset:3072
	s_add_u32 s26, s26, 0x80000
	s_addc_u32 s27, s27, 0
	s_mov_b32 m0, s30
	v_lshl_add_u64 v[216:217], s[26:27], 0, v[166:167]
	ds_read_b128 v[162:165], v181 offset:32768
	ds_read_b128 v[174:177], v181 offset:33792
	ds_read_b128 v[188:191], v181 offset:34816
	ds_read_b128 v[192:195], v181 offset:35840
	ds_read_b128 v[196:199], v181 offset:36864
	ds_read_b128 v[200:203], v181 offset:37888
	ds_read_b128 v[204:207], v181 offset:38912
	ds_read_b128 v[208:211], v181 offset:39936
	global_load_lds_dwordx4 v[216:217], off
	v_lshl_add_u64 v[216:217], s[26:27], 0, v[168:169]
	s_mov_b32 m0, s31
	s_nop 0
	global_load_lds_dwordx4 v[216:217], off
	s_waitcnt vmcnt(8)
	s_waitcnt lgkmcnt(0)
	s_setprio 1
	s_barrier
	s_waitcnt lgkmcnt(0)
	v_mfma_f32_16x16x32_bf16 v[122:125], v[130:133], v[162:165], v[122:125]
	v_mfma_f32_16x16x32_bf16 v[118:121], v[138:141], v[162:165], v[118:121]
	v_mfma_f32_16x16x32_bf16 v[110:113], v[130:133], v[188:191], v[110:113]
	v_mfma_f32_16x16x32_bf16 v[102:105], v[138:141], v[188:191], v[102:105]
	v_mfma_f32_16x16x32_bf16 v[94:97], v[130:133], v[196:199], v[94:97]
	v_mfma_f32_16x16x32_bf16 v[86:89], v[138:141], v[196:199], v[86:89]
	v_mfma_f32_16x16x32_bf16 v[78:81], v[130:133], v[204:207], v[78:81]
	v_mfma_f32_16x16x32_bf16 v[70:73], v[138:141], v[204:207], v[70:73]
	v_mfma_f32_16x16x32_bf16 v[122:125], v[134:137], v[174:177], v[122:125]
	v_mfma_f32_16x16x32_bf16 v[118:121], v[142:145], v[174:177], v[118:121]
	v_mfma_f32_16x16x32_bf16 v[110:113], v[134:137], v[192:195], v[110:113]
	v_mfma_f32_16x16x32_bf16 v[102:105], v[142:145], v[192:195], v[102:105]
	v_mfma_f32_16x16x32_bf16 v[94:97], v[134:137], v[200:203], v[94:97]
	v_mfma_f32_16x16x32_bf16 v[86:89], v[142:145], v[200:203], v[86:89]
	v_mfma_f32_16x16x32_bf16 v[78:81], v[134:137], v[208:211], v[78:81]
	v_mfma_f32_16x16x32_bf16 v[70:73], v[142:145], v[208:211], v[70:73]
	v_mfma_f32_16x16x32_bf16 v[126:129], v[146:149], v[162:165], v[126:129]
	v_mfma_f32_16x16x32_bf16 v[114:117], v[154:157], v[162:165], v[114:117]
	v_mfma_f32_16x16x32_bf16 v[106:109], v[146:149], v[188:191], v[106:109]
	v_mfma_f32_16x16x32_bf16 v[98:101], v[154:157], v[188:191], v[98:101]
	v_mfma_f32_16x16x32_bf16 v[90:93], v[146:149], v[196:199], v[90:93]
	v_mfma_f32_16x16x32_bf16 v[82:85], v[154:157], v[196:199], v[82:85]
	v_mfma_f32_16x16x32_bf16 v[74:77], v[146:149], v[204:207], v[74:77]
	v_mfma_f32_16x16x32_bf16 v[66:69], v[154:157], v[204:207], v[66:69]
	v_mfma_f32_16x16x32_bf16 v[126:129], v[150:153], v[174:177], v[126:129]
	v_mfma_f32_16x16x32_bf16 v[114:117], v[158:161], v[174:177], v[114:117]
	v_mfma_f32_16x16x32_bf16 v[106:109], v[150:153], v[192:195], v[106:109]
	v_mfma_f32_16x16x32_bf16 v[98:101], v[158:161], v[192:195], v[98:101]
	v_mfma_f32_16x16x32_bf16 v[90:93], v[150:153], v[200:203], v[90:93]
	v_mfma_f32_16x16x32_bf16 v[82:85], v[158:161], v[200:203], v[82:85]
	v_mfma_f32_16x16x32_bf16 v[74:77], v[150:153], v[208:211], v[74:77]
	v_mfma_f32_16x16x32_bf16 v[66:69], v[158:161], v[208:211], v[66:69]
	s_setprio 0
	s_barrier
; #define PG8_STAGE(bufoff, gbase, voff) do { _Pragma("unroll") for (int _i = 0; _i < 2; ++_i) \
;         __builtin_amdgcn_global_load_lds((const unsigned*)((const char*)(gbase) + (voff)[_i]), (LAS unsigned*)(lds + (bufoff) + ldsw + _i * 8192), 16, 0, 0); } while (0)
; #define PG8_LDA(dst, b, h) do { _Pragma("unroll") for (int m = 0; m < 4; ++m) _Pragma("unroll") for (int k = 0; k < 2; ++k) dst[m][k] = *(const LAS bf16x8*)(lds + PG8_SA(b, h) + aoff + m * 2048 + k * 1024); } while (0)
; #define PG8_MMA(ai, bj, At, Bt) do { __builtin_amdgcn_s_setprio(1); _Pragma("unroll") for (int m = 0; m < 4; ++m) _Pragma("unroll") for (int n = 0; n < 2; ++n) _Pragma("unroll") for (int k = 0; k < 2; ++k) \
;         acc[ai][bj][m][n] = __builtin_amdgcn_mfma_f32_16x16x32_bf16(Bt[n][k], At[m][k], acc[ai][bj][m][n], 0, 0, 0); __builtin_amdgcn_s_setprio(0); } while (0)
; #define PG8_WAIT_V(n) asm volatile("s_waitcnt vmcnt(" #n ")" ::: "memory")
; #define PG8_WAIT_L(n) asm volatile("s_waitcnt lgkmcnt(" #n ")" ::: "memory")
; #define PG8_BAR __builtin_amdgcn_s_barrier()
; #define PG8_SCHED __builtin_amdgcn_sched_barrier(0)
; template <class Epi>
; __device__ __forceinline__ void gemm_phase(LAS unsigned char* lds, const Gemm g, const StaticOrder& S, const Epi& E) {
;     ...
;             PG8_LDA(At, 1, 1); PG8_STAGE(PG8_SB(1, 0), b3, voffB); PG8_STAGE(PG8_SB(1, 1), b3 + hstepB, voffB); PG8_STAGE(PG8_SA(1, 0), a3, voffA);
;             PG8_WAIT_V(8); PG8_WAIT_L(0); PG8_BAR; PG8_MMA(1, 0, At, B0); PG8_MMA(1, 1, At, B1); PG8_BAR; PG8_SCHED;
;         }
	s_add_i32 s26, s53, s28
	v_lshl_add_u64 v[178:179], v[178:179], 0, s[84:85]
	s_mov_b32 m0, s26
	ds_read_b128 v[162:165], v181 offset:49152
	ds_read_b128 v[174:177], v181 offset:50176
	ds_read_b128 v[188:191], v181 offset:51200
	ds_read_b128 v[192:195], v181 offset:52224
	ds_read_b128 v[196:199], v181 offset:53248
	ds_read_b128 v[200:203], v181 offset:54272
	ds_read_b128 v[204:207], v181 offset:55296
	ds_read_b128 v[208:211], v181 offset:56320
	global_load_lds_dwordx4 v[178:179], off
	s_add_i32 m0, s26, 0x2000
	s_add_u32 s14, s14, 0x80080
	v_lshl_add_u64 v[178:179], v[184:185], 0, s[84:85]
	s_addc_u32 s15, s15, 0
	s_add_i32 s26, s64, s28
	global_load_lds_dwordx4 v[178:179], off
	v_lshl_add_u64 v[178:179], s[14:15], 0, v[166:167]
	s_mov_b32 m0, s26
	s_nop 0
	global_load_lds_dwordx4 v[178:179], off
	v_lshl_add_u64 v[178:179], s[14:15], 0, v[168:169]
	s_add_i32 m0, s26, 0x2000
	s_nop 0
	global_load_lds_dwordx4 v[178:179], off
	v_lshl_add_u64 v[178:179], v[212:213], 0, s[84:85]
	s_mov_b32 m0, s35
	s_nop 0
	global_load_lds_dwordx4 v[178:179], off
	v_lshl_add_u64 v[178:179], v[214:215], 0, s[84:85]
	s_mov_b32 m0, s42
	s_nop 0
	global_load_lds_dwordx4 v[178:179], off
	s_waitcnt vmcnt(8)
	s_waitcnt lgkmcnt(0)
	s_setprio 1
	s_barrier
	s_waitcnt lgkmcnt(0)
	v_mfma_f32_16x16x32_bf16 v[62:65], v[130:133], v[162:165], v[62:65]
	v_mfma_f32_16x16x32_bf16 v[54:57], v[138:141], v[162:165], v[54:57]
	v_mfma_f32_16x16x32_bf16 v[46:49], v[130:133], v[188:191], v[46:49]
	v_mfma_f32_16x16x32_bf16 v[38:41], v[138:141], v[188:191], v[38:41]
	v_mfma_f32_16x16x32_bf16 v[30:33], v[130:133], v[196:199], v[30:33]
	v_mfma_f32_16x16x32_bf16 v[22:25], v[138:141], v[196:199], v[22:25]
	v_mfma_f32_16x16x32_bf16 v[14:17], v[130:133], v[204:207], v[14:17]
	v_mfma_f32_16x16x32_bf16 v[6:9], v[138:141], v[204:207], v[6:9]
	v_mfma_f32_16x16x32_bf16 v[62:65], v[134:137], v[174:177], v[62:65]
	v_mfma_f32_16x16x32_bf16 v[54:57], v[142:145], v[174:177], v[54:57]
	v_mfma_f32_16x16x32_bf16 v[46:49], v[134:137], v[192:195], v[46:49]
	v_mfma_f32_16x16x32_bf16 v[38:41], v[142:145], v[192:195], v[38:41]
	v_mfma_f32_16x16x32_bf16 v[30:33], v[134:137], v[200:203], v[30:33]
	v_mfma_f32_16x16x32_bf16 v[22:25], v[142:145], v[200:203], v[22:25]
	v_mfma_f32_16x16x32_bf16 v[14:17], v[134:137], v[208:211], v[14:17]
	v_mfma_f32_16x16x32_bf16 v[6:9], v[142:145], v[208:211], v[6:9]
	v_mfma_f32_16x16x32_bf16 v[58:61], v[146:149], v[162:165], v[58:61]
	v_mfma_f32_16x16x32_bf16 v[50:53], v[154:157], v[162:165], v[50:53]
	v_mfma_f32_16x16x32_bf16 v[42:45], v[146:149], v[188:191], v[42:45]
	v_mfma_f32_16x16x32_bf16 v[34:37], v[154:157], v[188:191], v[34:37]
	v_mfma_f32_16x16x32_bf16 v[26:29], v[146:149], v[196:199], v[26:29]
	v_mfma_f32_16x16x32_bf16 v[18:21], v[154:157], v[196:199], v[18:21]
	v_mfma_f32_16x16x32_bf16 v[10:13], v[146:149], v[204:207], v[10:13]
	v_mfma_f32_16x16x32_bf16 v[2:5], v[154:157], v[204:207], v[2:5]
	v_mfma_f32_16x16x32_bf16 v[58:61], v[150:153], v[174:177], v[58:61]
	v_mfma_f32_16x16x32_bf16 v[50:53], v[158:161], v[174:177], v[50:53]
	v_mfma_f32_16x16x32_bf16 v[42:45], v[150:153], v[192:195], v[42:45]
	v_mfma_f32_16x16x32_bf16 v[34:37], v[158:161], v[192:195], v[34:37]
	v_mfma_f32_16x16x32_bf16 v[26:29], v[150:153], v[200:203], v[26:29]
	v_mfma_f32_16x16x32_bf16 v[18:21], v[158:161], v[200:203], v[18:21]
	v_mfma_f32_16x16x32_bf16 v[10:13], v[150:153], v[208:211], v[10:13]
	v_mfma_f32_16x16x32_bf16 v[2:5], v[158:161], v[208:211], v[2:5]
	s_setprio 0
	s_barrier
	s_add_i32 s41, s41, 2
	s_add_u32 s24, s24, 0x100
	s_addc_u32 s25, s25, 0
	s_add_u32 s40, s40, 0x100
	s_addc_u32 s52, s52, 0
	s_cmp_gt_u32 s41, 29
	s_cbranch_scc0 .LBB0_1324
	s_cmp_ge_u32 s74, 16
	s_cbranch_scc1 .Lwpf_b
	s_lshl_b32 s100, s74, 9
	v_add_u32_e32 v130, s100, v246
	v_lshrrev_b32_e32 v131, 2, v130
	v_and_b32_e32 v130, 3, v130
	v_lshlrev_b32_e32 v130, 7, v130
	v_lshl_add_u32 v130, v131, 12, v130
	s_add_u32 s100, s88, 0x1800000
	s_addc_u32 s101, s89, 0
	s_mov_b32 m0, 0x21000
	s_nop 0
	global_load_lds_dword v130, s[100:101]

; #define PG8_STAGE(bufoff, gbase, voff) do { _Pragma("unroll") for (int _i = 0; _i < 2; ++_i) \
;         __builtin_amdgcn_global_load_lds((const unsigned*)((const char*)(gbase) + (voff)[_i]), (LAS unsigned*)(lds + (bufoff) + ldsw + _i * 8192), 16, 0, 0); } while (0)
; #define PG8_LDA(dst, b, h) do { _Pragma("unroll") for (int m = 0; m < 4; ++m) _Pragma("unroll") for (int k = 0; k < 2; ++k) dst[m][k] = *(const LAS bf16x8*)(lds + PG8_SA(b, h) + aoff + m * 2048 + k * 1024); } while (0)
; #define PG8_LDB(dst, b, h) do { _Pragma("unroll") for (int n = 0; n < 2; ++n) _Pragma("unroll") for (int k = 0; k < 2; ++k) dst[n][k] = *(const LAS bf16x8*)(lds + PG8_SB(b, h) + boff + n * 2048 + k * 1024); } while (0)
; #define PG8_MMA(ai, bj, At, Bt) do { __builtin_amdgcn_s_setprio(1); _Pragma("unroll") for (int m = 0; m < 4; ++m) _Pragma("unroll") for (int n = 0; n < 2; ++n) _Pragma("unroll") for (int k = 0; k < 2; ++k) \
;         acc[ai][bj][m][n] = __builtin_amdgcn_mfma_f32_16x16x32_bf16(Bt[n][k], At[m][k], acc[ai][bj][m][n], 0, 0, 0); __builtin_amdgcn_s_setprio(0); } while (0)
; #define PG8_WAIT_V(n) asm volatile("s_waitcnt vmcnt(" #n ")" ::: "memory")
; #define PG8_WAIT_L(n) asm volatile("s_waitcnt lgkmcnt(" #n ")" ::: "memory")
; #define PG8_BAR __builtin_amdgcn_s_barrier()
; #define PG8_SCHED __builtin_amdgcn_sched_barrier(0)
; template <class Epi>
; __device__ __forceinline__ void gemm_phase(LAS unsigned char* lds, const Gemm g, const StaticOrder& S, const Epi& E) {
;     ...
;             const bool last = (t == nt - 2);
;             const char* a1 = cA + (size_t)(t + 1) * kstep;
;             const char* a2 = last ? nA : cA + (size_t)(t + 2) * kstep; const char* b2 = last ? nB : cB + (size_t)(t + 2) * kstep;
;             const char* a3 = a2 + kstep; const char* b3 = b2 + kstep;
;             PG8_LDB(B0, 0, 0); PG8_LDB(B1, 0, 1); PG8_SCHED; PG8_LDA(At, 0, 0); PG8_STAGE(PG8_SA(1, 1), a1 + hstepA, voffA);
;             PG8_WAIT_V(8); PG8_WAIT_L(0); PG8_BAR; PG8_MMA(0, 0, At, B0); PG8_MMA(0, 1, At, B1); PG8_BAR; PG8_SCHED;
;             PG8_LDA(At, 0, 1); PG8_STAGE(PG8_SB(0, 0), b2, voffB); PG8_STAGE(PG8_SB(0, 1), b2 + hstepB, voffB); PG8_STAGE(PG8_SA(0, 0), a2, voffA);
;             PG8_WAIT_V(8); PG8_WAIT_L(0); PG8_BAR; PG8_MMA(1, 0, At, B0); PG8_MMA(1, 1, At, B1); PG8_BAR; PG8_SCHED;
.LBB0_1412:
	s_add_u32 s14, s22, 0xfff80080
	s_addc_u32 s15, s23, -1
	s_add_i32 s41, 0, 0x10000
	s_cmp_eq_u32 s64, 28
	s_cselect_b32 s25, s3, s15
	s_cselect_b32 s24, s7, s14
	s_cselect_b32 s15, s13, s63
	s_cselect_b32 s14, s17, s40
	s_add_i32 s65, 0, 0x14000
	v_add_u32_e32 v142, s41, v1
	v_add_u32_e32 v163, s65, v1
	ds_read_b128 v[130:133], v142
	ds_read_b128 v[134:137], v142 offset:1024
	ds_read_b128 v[138:141], v142 offset:2048
	ds_read_b128 v[142:145], v142 offset:3072
	ds_read_b128 v[158:161], v163
	ds_read_b128 v[164:167], v163 offset:1024
	ds_read_b128 v[168:171], v163 offset:2048
	ds_read_b128 v[172:175], v163 offset:3072
	v_lshl_add_u64 v[184:185], s[22:23], 0, v[154:155]
	s_add_i32 m0, s30, 0xc000
	ds_read_b128 v[176:179], v162
	ds_read_b128 v[188:191], v162 offset:1024
	ds_read_b128 v[192:195], v162 offset:2048
	ds_read_b128 v[196:199], v162 offset:3072
	ds_read_b128 v[200:203], v162 offset:4096
	ds_read_b128 v[204:207], v162 offset:5120
	ds_read_b128 v[208:211], v162 offset:6144
	ds_read_b128 v[212:215], v162 offset:7168
	global_load_lds_dwordx4 v[184:185], off
	v_lshl_add_u64 v[184:185], s[22:23], 0, v[156:157]
	s_add_i32 m0, s30, 0xe000
	s_nop 0
	global_load_lds_dwordx4 v[184:185], off
	s_waitcnt vmcnt(8)
	s_waitcnt lgkmcnt(0)
	s_setprio 1
	s_barrier
	s_waitcnt lgkmcnt(0)
	v_mfma_f32_16x16x32_bf16 v[126:129], v[130:133], v[176:179], v[126:129]
	v_mfma_f32_16x16x32_bf16 v[122:125], v[138:141], v[176:179], v[122:125]
	v_mfma_f32_16x16x32_bf16 v[118:121], v[130:133], v[192:195], v[118:121]
	v_mfma_f32_16x16x32_bf16 v[110:113], v[138:141], v[192:195], v[110:113]
	v_mfma_f32_16x16x32_bf16 v[102:105], v[130:133], v[200:203], v[102:105]
	v_mfma_f32_16x16x32_bf16 v[94:97], v[138:141], v[200:203], v[94:97]
	v_mfma_f32_16x16x32_bf16 v[86:89], v[130:133], v[208:211], v[86:89]
	v_mfma_f32_16x16x32_bf16 v[78:81], v[138:141], v[208:211], v[78:81]
	v_mfma_f32_16x16x32_bf16 v[126:129], v[134:137], v[188:191], v[126:129]
	v_mfma_f32_16x16x32_bf16 v[122:125], v[142:145], v[188:191], v[122:125]
	v_mfma_f32_16x16x32_bf16 v[118:121], v[134:137], v[196:199], v[118:121]
	v_mfma_f32_16x16x32_bf16 v[110:113], v[142:145], v[196:199], v[110:113]
	v_mfma_f32_16x16x32_bf16 v[102:105], v[134:137], v[204:207], v[102:105]
	v_mfma_f32_16x16x32_bf16 v[94:97], v[142:145], v[204:207], v[94:97]
	v_mfma_f32_16x16x32_bf16 v[86:89], v[134:137], v[212:215], v[86:89]
	v_mfma_f32_16x16x32_bf16 v[78:81], v[142:145], v[212:215], v[78:81]
	v_mfma_f32_16x16x32_bf16 v[114:117], v[158:161], v[176:179], v[114:117]
	v_mfma_f32_16x16x32_bf16 v[106:109], v[168:171], v[176:179], v[106:109]
	v_mfma_f32_16x16x32_bf16 v[98:101], v[158:161], v[192:195], v[98:101]
	v_mfma_f32_16x16x32_bf16 v[90:93], v[168:171], v[192:195], v[90:93]
	v_mfma_f32_16x16x32_bf16 v[82:85], v[158:161], v[200:203], v[82:85]
	v_mfma_f32_16x16x32_bf16 v[74:77], v[168:171], v[200:203], v[74:77]
	v_mfma_f32_16x16x32_bf16 v[70:73], v[158:161], v[208:211], v[70:73]
	v_mfma_f32_16x16x32_bf16 v[66:69], v[168:171], v[208:211], v[66:69]
	v_mfma_f32_16x16x32_bf16 v[114:117], v[164:167], v[188:191], v[114:117]
	v_mfma_f32_16x16x32_bf16 v[106:109], v[172:175], v[188:191], v[106:109]
	v_mfma_f32_16x16x32_bf16 v[98:101], v[164:167], v[196:199], v[98:101]
	v_mfma_f32_16x16x32_bf16 v[90:93], v[172:175], v[196:199], v[90:93]
	v_mfma_f32_16x16x32_bf16 v[82:85], v[164:167], v[204:207], v[82:85]
	v_mfma_f32_16x16x32_bf16 v[74:77], v[172:175], v[204:207], v[74:77]
	v_mfma_f32_16x16x32_bf16 v[70:73], v[164:167], v[212:215], v[70:73]
	v_mfma_f32_16x16x32_bf16 v[66:69], v[172:175], v[212:215], v[66:69]
	s_setprio 0
	s_barrier
	s_add_i32 s41, s41, s28
	v_lshl_add_u64 v[184:185], s[14:15], 0, v[150:151]
	s_mov_b32 m0, s41
	ds_read_b128 v[176:179], v162 offset:16384
	ds_read_b128 v[188:191], v162 offset:17408
	ds_read_b128 v[192:195], v162 offset:18432
	ds_read_b128 v[196:199], v162 offset:19456
	ds_read_b128 v[200:203], v162 offset:20480
	ds_read_b128 v[204:207], v162 offset:21504
	ds_read_b128 v[208:211], v162 offset:22528
	ds_read_b128 v[212:215], v162 offset:23552
	global_load_lds_dwordx4 v[184:185], off
	s_add_i32 m0, s41, 0x2000
	s_add_u32 s68, s14, 0x80000
	v_lshl_add_u64 v[216:217], s[14:15], 0, v[146:147]
	s_addc_u32 s69, s15, 0
	s_add_i32 s41, s65, s28
	global_load_lds_dwordx4 v[216:217], off
	v_lshl_add_u64 v[218:219], s[68:69], 0, v[150:151]
	s_mov_b32 m0, s41
	v_lshl_add_u64 v[220:221], s[24:25], 0, v[148:149]
	global_load_lds_dwordx4 v[218:219], off
	v_lshl_add_u64 v[218:219], s[68:69], 0, v[146:147]
	s_add_i32 m0, s41, 0x2000
	s_nop 0
	global_load_lds_dwordx4 v[218:219], off
	v_lshl_add_u64 v[218:219], s[24:25], 0, v[152:153]
	s_mov_b32 m0, s30
	s_nop 0
	global_load_lds_dwordx4 v[218:219], off
	s_mov_b32 m0, s31
	s_nop 0
	global_load_lds_dwordx4 v[220:221], off
	s_waitcnt vmcnt(8)
	s_waitcnt lgkmcnt(0)
	s_setprio 1
	s_barrier
; #define PG8_STAGE(bufoff, gbase, voff) do { _Pragma("unroll") for (int _i = 0; _i < 2; ++_i) \
;         __builtin_amdgcn_global_load_lds((const unsigned*)((const char*)(gbase) + (voff)[_i]), (LAS unsigned*)(lds + (bufoff) + ldsw + _i * 8192), 16, 0, 0); } while (0)
; #define PG8_LDA(dst, b, h) do { _Pragma("unroll") for (int m = 0; m < 4; ++m) _Pragma("unroll") for (int k = 0; k < 2; ++k) dst[m][k] = *(const LAS bf16x8*)(lds + PG8_SA(b, h) + aoff + m * 2048 + k * 1024); } while (0)
; #define PG8_LDB(dst, b, h) do { _Pragma("unroll") for (int n = 0; n < 2; ++n) _Pragma("unroll") for (int k = 0; k < 2; ++k) dst[n][k] = *(const LAS bf16x8*)(lds + PG8_SB(b, h) + boff + n * 2048 + k * 1024); } while (0)
; #define PG8_MMA(ai, bj, At, Bt) do { __builtin_amdgcn_s_setprio(1); _Pragma("unroll") for (int m = 0; m < 4; ++m) _Pragma("unroll") for (int n = 0; n < 2; ++n) _Pragma("unroll") for (int k = 0; k < 2; ++k) \
;         acc[ai][bj][m][n] = __builtin_amdgcn_mfma_f32_16x16x32_bf16(Bt[n][k], At[m][k], acc[ai][bj][m][n], 0, 0, 0); __builtin_amdgcn_s_setprio(0); } while (0)
; #define PG8_WAIT_V(n) asm volatile("s_waitcnt vmcnt(" #n ")" ::: "memory")
; #define PG8_WAIT_L(n) asm volatile("s_waitcnt lgkmcnt(" #n ")" ::: "memory")
; #define PG8_BAR __builtin_amdgcn_s_barrier()
; #define PG8_SCHED __builtin_amdgcn_sched_barrier(0)
; template <class Epi>
; __device__ __forceinline__ void gemm_phase(LAS unsigned char* lds, const Gemm g, const StaticOrder& S, const Epi& E) {
;     ...
;             PG8_WAIT_V(8); PG8_WAIT_L(0); PG8_BAR; PG8_MMA(1, 0, At, B0); PG8_MMA(1, 1, At, B1); PG8_BAR; PG8_SCHED;
;             PG8_LDB(B0, 1, 0); PG8_LDB(B1, 1, 1); PG8_SCHED; PG8_LDA(At, 1, 0); PG8_STAGE(PG8_SA(0, 1), a2 + hstepA, voffA);
;             PG8_WAIT_V(8); PG8_WAIT_L(0); PG8_BAR; PG8_MMA(0, 0, At, B0); PG8_MMA(0, 1, At, B1); PG8_BAR; PG8_SCHED;
;             PG8_LDA(At, 1, 1); PG8_STAGE(PG8_SB(1, 0), b3, voffB); PG8_STAGE(PG8_SB(1, 1), b3 + hstepB, voffB); PG8_STAGE(PG8_SA(1, 0), a3, voffA);
;             PG8_WAIT_V(8); PG8_WAIT_L(0); PG8_BAR; PG8_MMA(1, 0, At, B0); PG8_MMA(1, 1, At, B1); PG8_BAR; PG8_SCHED;
	s_waitcnt lgkmcnt(0)
	v_mfma_f32_16x16x32_bf16 v[62:65], v[130:133], v[176:179], v[62:65]
	v_mfma_f32_16x16x32_bf16 v[58:61], v[138:141], v[176:179], v[58:61]
	v_mfma_f32_16x16x32_bf16 v[54:57], v[130:133], v[192:195], v[54:57]
	v_mfma_f32_16x16x32_bf16 v[46:49], v[138:141], v[192:195], v[46:49]
	v_mfma_f32_16x16x32_bf16 v[38:41], v[130:133], v[200:203], v[38:41]
	v_mfma_f32_16x16x32_bf16 v[30:33], v[138:141], v[200:203], v[30:33]
	v_mfma_f32_16x16x32_bf16 v[22:25], v[130:133], v[208:211], v[22:25]
	v_mfma_f32_16x16x32_bf16 v[14:17], v[138:141], v[208:211], v[14:17]
	v_mfma_f32_16x16x32_bf16 v[62:65], v[134:137], v[188:191], v[62:65]
	v_mfma_f32_16x16x32_bf16 v[58:61], v[142:145], v[188:191], v[58:61]
	v_mfma_f32_16x16x32_bf16 v[54:57], v[134:137], v[196:199], v[54:57]
	v_mfma_f32_16x16x32_bf16 v[46:49], v[142:145], v[196:199], v[46:49]
	v_mfma_f32_16x16x32_bf16 v[38:41], v[134:137], v[204:207], v[38:41]
	v_mfma_f32_16x16x32_bf16 v[30:33], v[142:145], v[204:207], v[30:33]
	v_mfma_f32_16x16x32_bf16 v[22:25], v[134:137], v[212:215], v[22:25]
	v_mfma_f32_16x16x32_bf16 v[14:17], v[142:145], v[212:215], v[14:17]
	v_mfma_f32_16x16x32_bf16 v[50:53], v[158:161], v[176:179], v[50:53]
	v_mfma_f32_16x16x32_bf16 v[42:45], v[168:171], v[176:179], v[42:45]
	v_mfma_f32_16x16x32_bf16 v[34:37], v[158:161], v[192:195], v[34:37]
	v_mfma_f32_16x16x32_bf16 v[26:29], v[168:171], v[192:195], v[26:29]
	v_mfma_f32_16x16x32_bf16 v[18:21], v[158:161], v[200:203], v[18:21]
	v_mfma_f32_16x16x32_bf16 v[10:13], v[168:171], v[200:203], v[10:13]
	v_mfma_f32_16x16x32_bf16 v[6:9], v[158:161], v[208:211], v[6:9]
	v_mfma_f32_16x16x32_bf16 v[2:5], v[168:171], v[208:211], v[2:5]
	v_mfma_f32_16x16x32_bf16 v[50:53], v[164:167], v[188:191], v[50:53]
	v_mfma_f32_16x16x32_bf16 v[42:45], v[172:175], v[188:191], v[42:45]
	v_mfma_f32_16x16x32_bf16 v[34:37], v[164:167], v[196:199], v[34:37]
	v_mfma_f32_16x16x32_bf16 v[26:29], v[172:175], v[196:199], v[26:29]
	v_mfma_f32_16x16x32_bf16 v[18:21], v[164:167], v[204:207], v[18:21]
	v_mfma_f32_16x16x32_bf16 v[10:13], v[172:175], v[204:207], v[10:13]
	v_mfma_f32_16x16x32_bf16 v[6:9], v[164:167], v[212:215], v[6:9]
	v_mfma_f32_16x16x32_bf16 v[2:5], v[172:175], v[212:215], v[2:5]
	s_setprio 0
	s_barrier
	s_add_i32 s41, 0, 0x18000
	s_add_i32 s65, 0, 0x1c000
	v_add_u32_e32 v142, s41, v1
	v_add_u32_e32 v163, s65, v1
	ds_read_b128 v[130:133], v142
	ds_read_b128 v[134:137], v142 offset:1024
	ds_read_b128 v[138:141], v142 offset:2048
	ds_read_b128 v[142:145], v142 offset:3072
	ds_read_b128 v[158:161], v163
	ds_read_b128 v[164:167], v163 offset:1024
	ds_read_b128 v[168:171], v163 offset:2048
	ds_read_b128 v[172:175], v163 offset:3072
	s_add_u32 s24, s24, 0x80000
	s_addc_u32 s25, s25, 0
	s_mov_b32 m0, s33
	v_lshl_add_u64 v[222:223], s[24:25], 0, v[152:153]
	ds_read_b128 v[176:179], v162 offset:32768
	ds_read_b128 v[188:191], v162 offset:33792
	ds_read_b128 v[192:195], v162 offset:34816
	ds_read_b128 v[196:199], v162 offset:35840
	ds_read_b128 v[200:203], v162 offset:36864
	ds_read_b128 v[204:207], v162 offset:37888
	ds_read_b128 v[208:211], v162 offset:38912
	ds_read_b128 v[212:215], v162 offset:39936
	global_load_lds_dwordx4 v[222:223], off
	v_lshl_add_u64 v[222:223], s[24:25], 0, v[148:149]
	s_mov_b32 m0, s34
	s_nop 0
	global_load_lds_dwordx4 v[222:223], off
	s_waitcnt vmcnt(8)
	s_waitcnt lgkmcnt(0)
	s_setprio 1
	s_barrier
	s_waitcnt lgkmcnt(0)
	v_mfma_f32_16x16x32_bf16 v[126:129], v[130:133], v[176:179], v[126:129]
	v_mfma_f32_16x16x32_bf16 v[122:125], v[138:141], v[176:179], v[122:125]
	v_mfma_f32_16x16x32_bf16 v[118:121], v[130:133], v[192:195], v[118:121]
	v_mfma_f32_16x16x32_bf16 v[110:113], v[138:141], v[192:195], v[110:113]
	v_mfma_f32_16x16x32_bf16 v[102:105], v[130:133], v[200:203], v[102:105]
	v_mfma_f32_16x16x32_bf16 v[94:97], v[138:141], v[200:203], v[94:97]
	v_mfma_f32_16x16x32_bf16 v[86:89], v[130:133], v[208:211], v[86:89]
	v_mfma_f32_16x16x32_bf16 v[78:81], v[138:141], v[208:211], v[78:81]
	v_mfma_f32_16x16x32_bf16 v[126:129], v[134:137], v[188:191], v[126:129]
	v_mfma_f32_16x16x32_bf16 v[122:125], v[142:145], v[188:191], v[122:125]
	v_mfma_f32_16x16x32_bf16 v[118:121], v[134:137], v[196:199], v[118:121]
	v_mfma_f32_16x16x32_bf16 v[110:113], v[142:145], v[196:199], v[110:113]
	v_mfma_f32_16x16x32_bf16 v[102:105], v[134:137], v[204:207], v[102:105]
	v_mfma_f32_16x16x32_bf16 v[94:97], v[142:145], v[204:207], v[94:97]
	v_mfma_f32_16x16x32_bf16 v[86:89], v[134:137], v[212:215], v[86:89]
	v_mfma_f32_16x16x32_bf16 v[78:81], v[142:145], v[212:215], v[78:81]
	v_mfma_f32_16x16x32_bf16 v[114:117], v[158:161], v[176:179], v[114:117]
	v_mfma_f32_16x16x32_bf16 v[106:109], v[168:171], v[176:179], v[106:109]
	v_mfma_f32_16x16x32_bf16 v[98:101], v[158:161], v[192:195], v[98:101]
	v_mfma_f32_16x16x32_bf16 v[90:93], v[168:171], v[192:195], v[90:93]
	v_mfma_f32_16x16x32_bf16 v[82:85], v[158:161], v[200:203], v[82:85]
	v_mfma_f32_16x16x32_bf16 v[74:77], v[168:171], v[200:203], v[74:77]
	v_mfma_f32_16x16x32_bf16 v[70:73], v[158:161], v[208:211], v[70:73]
	v_mfma_f32_16x16x32_bf16 v[66:69], v[168:171], v[208:211], v[66:69]
	v_mfma_f32_16x16x32_bf16 v[114:117], v[164:167], v[188:191], v[114:117]
	v_mfma_f32_16x16x32_bf16 v[106:109], v[172:175], v[188:191], v[106:109]
	v_mfma_f32_16x16x32_bf16 v[98:101], v[164:167], v[196:199], v[98:101]
	v_mfma_f32_16x16x32_bf16 v[90:93], v[172:175], v[196:199], v[90:93]
	v_mfma_f32_16x16x32_bf16 v[82:85], v[164:167], v[204:207], v[82:85]
	v_mfma_f32_16x16x32_bf16 v[74:77], v[172:175], v[204:207], v[74:77]
	v_mfma_f32_16x16x32_bf16 v[70:73], v[164:167], v[212:215], v[70:73]
	v_mfma_f32_16x16x32_bf16 v[66:69], v[172:175], v[212:215], v[66:69]
	s_setprio 0
	s_barrier
; #define PG8_STAGE(bufoff, gbase, voff) do { _Pragma("unroll") for (int _i = 0; _i < 2; ++_i) \
;         __builtin_amdgcn_global_load_lds((const unsigned*)((const char*)(gbase) + (voff)[_i]), (LAS unsigned*)(lds + (bufoff) + ldsw + _i * 8192), 16, 0, 0); } while (0)
; #define PG8_LDA(dst, b, h) do { _Pragma("unroll") for (int m = 0; m < 4; ++m) _Pragma("unroll") for (int k = 0; k < 2; ++k) dst[m][k] = *(const LAS bf16x8*)(lds + PG8_SA(b, h) + aoff + m * 2048 + k * 1024); } while (0)
; #define PG8_MMA(ai, bj, At, Bt) do { __builtin_amdgcn_s_setprio(1); _Pragma("unroll") for (int m = 0; m < 4; ++m) _Pragma("unroll") for (int n = 0; n < 2; ++n) _Pragma("unroll") for (int k = 0; k < 2; ++k) \
;         acc[ai][bj][m][n] = __builtin_amdgcn_mfma_f32_16x16x32_bf16(Bt[n][k], At[m][k], acc[ai][bj][m][n], 0, 0, 0); __builtin_amdgcn_s_setprio(0); } while (0)
; #define PG8_WAIT_V(n) asm volatile("s_waitcnt vmcnt(" #n ")" ::: "memory")
; #define PG8_WAIT_L(n) asm volatile("s_waitcnt lgkmcnt(" #n ")" ::: "memory")
; #define PG8_BAR __builtin_amdgcn_s_barrier()
; #define PG8_SCHED __builtin_amdgcn_sched_barrier(0)
; template <class Epi>
; __device__ __forceinline__ void gemm_phase(LAS unsigned char* lds, const Gemm g, const StaticOrder& S, const Epi& E) {
;     ...
;             PG8_LDA(At, 1, 1); PG8_STAGE(PG8_SB(1, 0), b3, voffB); PG8_STAGE(PG8_SB(1, 1), b3 + hstepB, voffB); PG8_STAGE(PG8_SA(1, 0), a3, voffA);
;             PG8_WAIT_V(8); PG8_WAIT_L(0); PG8_BAR; PG8_MMA(1, 0, At, B0); PG8_MMA(1, 1, At, B1); PG8_BAR; PG8_SCHED;
;         }
;         if (wr == 0) PG8_BAR;
	s_add_i32 s24, s41, s28
	v_lshl_add_u64 v[184:185], v[184:185], 0, s[84:85]
	s_mov_b32 m0, s24
	ds_read_b128 v[176:179], v162 offset:49152
	ds_read_b128 v[188:191], v162 offset:50176
	ds_read_b128 v[192:195], v162 offset:51200
	ds_read_b128 v[196:199], v162 offset:52224
	ds_read_b128 v[200:203], v162 offset:53248
	ds_read_b128 v[204:207], v162 offset:54272
	ds_read_b128 v[208:211], v162 offset:55296
	ds_read_b128 v[212:215], v162 offset:56320
	global_load_lds_dwordx4 v[184:185], off
	s_add_i32 m0, s24, 0x2000
	s_add_u32 s14, s14, 0x80080
	v_lshl_add_u64 v[184:185], v[216:217], 0, s[84:85]
	s_addc_u32 s15, s15, 0
	s_add_i32 s24, s65, s28
	global_load_lds_dwordx4 v[184:185], off
	v_lshl_add_u64 v[184:185], s[14:15], 0, v[150:151]
	s_mov_b32 m0, s24
	s_nop 0
	global_load_lds_dwordx4 v[184:185], off
	v_lshl_add_u64 v[184:185], s[14:15], 0, v[146:147]
	s_add_i32 m0, s24, 0x2000
	s_nop 0
	global_load_lds_dwordx4 v[184:185], off
	v_lshl_add_u64 v[184:185], v[218:219], 0, s[84:85]
	s_mov_b32 m0, s44
	s_nop 0
	global_load_lds_dwordx4 v[184:185], off
	v_lshl_add_u64 v[184:185], v[220:221], 0, s[84:85]
	s_mov_b32 m0, s45
	s_nop 0
	global_load_lds_dwordx4 v[184:185], off
	s_waitcnt vmcnt(8)
	s_waitcnt lgkmcnt(0)
	s_setprio 1
	s_barrier
	s_waitcnt lgkmcnt(0)
	v_mfma_f32_16x16x32_bf16 v[62:65], v[130:133], v[176:179], v[62:65]
	v_mfma_f32_16x16x32_bf16 v[58:61], v[138:141], v[176:179], v[58:61]
	v_mfma_f32_16x16x32_bf16 v[54:57], v[130:133], v[192:195], v[54:57]
	v_mfma_f32_16x16x32_bf16 v[46:49], v[138:141], v[192:195], v[46:49]
	v_mfma_f32_16x16x32_bf16 v[38:41], v[130:133], v[200:203], v[38:41]
	v_mfma_f32_16x16x32_bf16 v[30:33], v[138:141], v[200:203], v[30:33]
	v_mfma_f32_16x16x32_bf16 v[22:25], v[130:133], v[208:211], v[22:25]
	v_mfma_f32_16x16x32_bf16 v[14:17], v[138:141], v[208:211], v[14:17]
	v_mfma_f32_16x16x32_bf16 v[62:65], v[134:137], v[188:191], v[62:65]
	v_mfma_f32_16x16x32_bf16 v[58:61], v[142:145], v[188:191], v[58:61]
	v_mfma_f32_16x16x32_bf16 v[54:57], v[134:137], v[196:199], v[54:57]
	v_mfma_f32_16x16x32_bf16 v[46:49], v[142:145], v[196:199], v[46:49]
	v_mfma_f32_16x16x32_bf16 v[38:41], v[134:137], v[204:207], v[38:41]
	v_mfma_f32_16x16x32_bf16 v[30:33], v[142:145], v[204:207], v[30:33]
	v_mfma_f32_16x16x32_bf16 v[22:25], v[134:137], v[212:215], v[22:25]
	v_mfma_f32_16x16x32_bf16 v[14:17], v[142:145], v[212:215], v[14:17]
	v_mfma_f32_16x16x32_bf16 v[50:53], v[158:161], v[176:179], v[50:53]
	v_mfma_f32_16x16x32_bf16 v[42:45], v[168:171], v[176:179], v[42:45]
	v_mfma_f32_16x16x32_bf16 v[34:37], v[158:161], v[192:195], v[34:37]
	v_mfma_f32_16x16x32_bf16 v[26:29], v[168:171], v[192:195], v[26:29]
	v_mfma_f32_16x16x32_bf16 v[18:21], v[158:161], v[200:203], v[18:21]
	v_mfma_f32_16x16x32_bf16 v[10:13], v[168:171], v[200:203], v[10:13]
	v_mfma_f32_16x16x32_bf16 v[6:9], v[158:161], v[208:211], v[6:9]
	v_mfma_f32_16x16x32_bf16 v[2:5], v[168:171], v[208:211], v[2:5]
	v_mfma_f32_16x16x32_bf16 v[50:53], v[164:167], v[188:191], v[50:53]
	v_mfma_f32_16x16x32_bf16 v[42:45], v[172:175], v[188:191], v[42:45]
	v_mfma_f32_16x16x32_bf16 v[34:37], v[164:167], v[196:199], v[34:37]
	v_mfma_f32_16x16x32_bf16 v[26:29], v[172:175], v[196:199], v[26:29]
	v_mfma_f32_16x16x32_bf16 v[18:21], v[164:167], v[204:207], v[18:21]
	v_mfma_f32_16x16x32_bf16 v[10:13], v[172:175], v[204:207], v[10:13]
	v_mfma_f32_16x16x32_bf16 v[6:9], v[164:167], v[212:215], v[6:9]
	v_mfma_f32_16x16x32_bf16 v[2:5], v[172:175], v[212:215], v[2:5]
	s_setprio 0
	s_barrier
	s_add_i32 s64, s64, 2
	s_add_u32 s22, s22, 0x100
	s_addc_u32 s23, s23, 0
	s_add_u32 s40, s40, 0x100
	s_addc_u32 s63, s63, 0
	s_cmp_gt_u32 s64, 29
	s_cbranch_scc0 .LBB0_1412
	s_and_b64 vcc, exec, s[10:11]
	s_cbranch_vccz .LBB0_1415
	s_barrier

; #define PG8_STAGE(bufoff, gbase, voff) do { _Pragma("unroll") for (int _i = 0; _i < 2; ++_i) \
;         __builtin_amdgcn_global_load_lds((const unsigned*)((const char*)(gbase) + (voff)[_i]), (LAS unsigned*)(lds + (bufoff) + ldsw + _i * 8192), 16, 0, 0); } while (0)
; #define PG8_LDA(dst, b, h) do { _Pragma("unroll") for (int m = 0; m < 4; ++m) _Pragma("unroll") for (int k = 0; k < 2; ++k) dst[m][k] = *(const LAS bf16x8*)(lds + PG8_SA(b, h) + aoff + m * 2048 + k * 1024); } while (0)
; #define PG8_LDB(dst, b, h) do { _Pragma("unroll") for (int n = 0; n < 2; ++n) _Pragma("unroll") for (int k = 0; k < 2; ++k) dst[n][k] = *(const LAS bf16x8*)(lds + PG8_SB(b, h) + boff + n * 2048 + k * 1024); } while (0)
; #define PG8_MMA(ai, bj, At, Bt) do { __builtin_amdgcn_s_setprio(1); _Pragma("unroll") for (int m = 0; m < 4; ++m) _Pragma("unroll") for (int n = 0; n < 2; ++n) _Pragma("unroll") for (int k = 0; k < 2; ++k) \
;         acc[ai][bj][m][n] = __builtin_amdgcn_mfma_f32_16x16x32_bf16(Bt[n][k], At[m][k], acc[ai][bj][m][n], 0, 0, 0); __builtin_amdgcn_s_setprio(0); } while (0)
; #define PG8_WAIT_V(n) asm volatile("s_waitcnt vmcnt(" #n ")" ::: "memory")
; #define PG8_WAIT_L(n) asm volatile("s_waitcnt lgkmcnt(" #n ")" ::: "memory")
; #define PG8_BAR __builtin_amdgcn_s_barrier()
; #define PG8_SCHED __builtin_amdgcn_sched_barrier(0)
; template <class Epi>
; __device__ __forceinline__ void gemm_phase(LAS unsigned char* lds, const Gemm g, const StaticOrder& S, const Epi& E) {
;     ...
;         for (int t = 0; t < nt; t += 2) {
;             const bool last = (t == nt - 2);
;             const char* a1 = cA + (size_t)(t + 1) * kstep;
;             const char* a2 = last ? nA : cA + (size_t)(t + 2) * kstep; const char* b2 = last ? nB : cB + (size_t)(t + 2) * kstep;
;             const char* a3 = a2 + kstep; const char* b3 = b2 + kstep;
;             PG8_LDB(B0, 0, 0); PG8_LDB(B1, 0, 1); PG8_SCHED; PG8_LDA(At, 0, 0); PG8_STAGE(PG8_SA(1, 1), a1 + hstepA, voffA);
;             PG8_WAIT_V(8); PG8_WAIT_L(0); PG8_BAR; PG8_MMA(0, 0, At, B0); PG8_MMA(0, 1, At, B1); PG8_BAR; PG8_SCHED;
;             PG8_LDA(At, 0, 1); PG8_STAGE(PG8_SB(0, 0), b2, voffB); PG8_STAGE(PG8_SB(0, 1), b2 + hstepB, voffB); PG8_STAGE(PG8_SA(0, 0), a2, voffA);
;             PG8_WAIT_V(8); PG8_WAIT_L(0); PG8_BAR; PG8_MMA(1, 0, At, B0); PG8_MMA(1, 1, At, B1); PG8_BAR; PG8_SCHED;
.LBB0_1440:
	s_add_u32 s41, s20, s14
	s_addc_u32 s44, s21, 0
	s_add_u32 s15, s41, 0x100
	s_addc_u32 s34, s44, 0
	s_and_b64 s[30:31], s[28:29], exec
	s_cselect_b32 s31, s19, s34
	s_cselect_b32 s30, s3, s15
	s_add_u32 s14, s12, s14
	s_addc_u32 s15, s13, 0
	s_add_u32 s34, s14, 0x100
	s_addc_u32 s35, s15, 0
	s_add_i32 s81, 0, 0x10000
	s_and_b64 s[14:15], s[28:29], exec
	s_cselect_b32 s35, s17, s35
	s_cselect_b32 s34, s40, s34
	s_add_i32 s29, 0, 0x14000
	s_add_u32 s68, s41, 0x10080
	s_addc_u32 s69, s44, 0
	s_add_i32 s77, s81, s63
	s_add_i32 m0, s11, 0xc000
	s_add_i32 s83, s11, 0xe000
	s_add_i32 s80, s77, 0x2000
	v_add_u32_e32 v139, s81, v1
	s_add_u32 s44, s34, 0x10000
	ds_read_b128 v[140:143], v139
	ds_read_b128 v[144:147], v139 offset:1024
	ds_read_b128 v[148:151], v139 offset:2048
	ds_read_b128 v[152:155], v139 offset:3072
	v_add_u32_e32 v139, s29, v1
	s_addc_u32 s45, s35, 0
	s_add_i32 s79, s29, s63
	ds_read_b128 v[156:159], v139
	ds_read_b128 v[160:163], v139 offset:1024
	ds_read_b128 v[164:167], v139 offset:2048
	ds_read_b128 v[168:171], v139 offset:3072
	s_add_i32 s78, s79, 0x2000
	s_add_i32 vcc_lo, 0, 0x18000
	s_add_i32 vcc_hi, 0, 0x1c000
	s_add_u32 s14, s30, 0x10000
	s_addc_u32 s15, s31, 0
	s_add_i32 s41, vcc_lo, s63
	s_add_i32 s76, s41, 0x2000
	s_add_u32 s28, s34, 0x10080
	s_addc_u32 s29, s35, 0
	s_add_i32 s81, vcc_hi, s63
	s_add_i32 s82, s81, 0x2000
	v_lshl_add_u64 v[184:185], s[68:69], 0, v[130:131]
	ds_read_b128 v[172:175], v138
	ds_read_b128 v[176:179], v138 offset:1024
	ds_read_b128 v[188:191], v138 offset:2048
	ds_read_b128 v[192:195], v138 offset:3072
	ds_read_b128 v[196:199], v138 offset:4096
	ds_read_b128 v[200:203], v138 offset:5120
	ds_read_b128 v[204:207], v138 offset:6144
	ds_read_b128 v[208:211], v138 offset:7168
	global_load_lds_dwordx4 v[184:185], off
	v_lshl_add_u64 v[184:185], s[68:69], 0, v[134:135]
	s_mov_b32 m0, s83
	s_nop 0
	global_load_lds_dwordx4 v[184:185], off
	s_waitcnt vmcnt(8)
	s_waitcnt lgkmcnt(0)
	s_setprio 1
	s_barrier
	s_waitcnt lgkmcnt(0)
	v_mfma_f32_16x16x32_bf16 v[126:129], v[140:143], v[172:175], v[126:129]
	v_mfma_f32_16x16x32_bf16 v[122:125], v[148:151], v[172:175], v[122:125]
	v_mfma_f32_16x16x32_bf16 v[118:121], v[140:143], v[188:191], v[118:121]
	v_mfma_f32_16x16x32_bf16 v[114:117], v[148:151], v[188:191], v[114:117]
	v_mfma_f32_16x16x32_bf16 v[102:105], v[140:143], v[196:199], v[102:105]
	v_mfma_f32_16x16x32_bf16 v[98:101], v[148:151], v[196:199], v[98:101]
	v_mfma_f32_16x16x32_bf16 v[86:89], v[140:143], v[204:207], v[86:89]
	v_mfma_f32_16x16x32_bf16 v[82:85], v[148:151], v[204:207], v[82:85]
	v_mfma_f32_16x16x32_bf16 v[126:129], v[144:147], v[176:179], v[126:129]
	v_mfma_f32_16x16x32_bf16 v[122:125], v[152:155], v[176:179], v[122:125]
	v_mfma_f32_16x16x32_bf16 v[118:121], v[144:147], v[192:195], v[118:121]
	v_mfma_f32_16x16x32_bf16 v[114:117], v[152:155], v[192:195], v[114:117]
	v_mfma_f32_16x16x32_bf16 v[102:105], v[144:147], v[200:203], v[102:105]
	v_mfma_f32_16x16x32_bf16 v[98:101], v[152:155], v[200:203], v[98:101]
	v_mfma_f32_16x16x32_bf16 v[86:89], v[144:147], v[208:211], v[86:89]
	v_mfma_f32_16x16x32_bf16 v[82:85], v[152:155], v[208:211], v[82:85]
	v_mfma_f32_16x16x32_bf16 v[110:113], v[156:159], v[172:175], v[110:113]
	v_mfma_f32_16x16x32_bf16 v[106:109], v[164:167], v[172:175], v[106:109]
	v_mfma_f32_16x16x32_bf16 v[94:97], v[156:159], v[188:191], v[94:97]
	v_mfma_f32_16x16x32_bf16 v[90:93], v[164:167], v[188:191], v[90:93]
	v_mfma_f32_16x16x32_bf16 v[78:81], v[156:159], v[196:199], v[78:81]
	v_mfma_f32_16x16x32_bf16 v[74:77], v[164:167], v[196:199], v[74:77]
	v_mfma_f32_16x16x32_bf16 v[70:73], v[156:159], v[204:207], v[70:73]
	v_mfma_f32_16x16x32_bf16 v[66:69], v[164:167], v[204:207], v[66:69]
	v_mfma_f32_16x16x32_bf16 v[110:113], v[160:163], v[176:179], v[110:113]
	v_mfma_f32_16x16x32_bf16 v[106:109], v[168:171], v[176:179], v[106:109]
	v_mfma_f32_16x16x32_bf16 v[94:97], v[160:163], v[192:195], v[94:97]
	v_mfma_f32_16x16x32_bf16 v[90:93], v[168:171], v[192:195], v[90:93]
	v_mfma_f32_16x16x32_bf16 v[78:81], v[160:163], v[200:203], v[78:81]
	v_mfma_f32_16x16x32_bf16 v[74:77], v[168:171], v[200:203], v[74:77]
	v_mfma_f32_16x16x32_bf16 v[70:73], v[160:163], v[208:211], v[70:73]
	v_mfma_f32_16x16x32_bf16 v[66:69], v[168:171], v[208:211], v[66:69]
	s_setprio 0
	s_barrier
	s_mov_b32 m0, s77
	v_lshl_add_u64 v[184:185], s[34:35], 0, v[132:133]
	ds_read_b128 v[172:175], v138 offset:16384
	ds_read_b128 v[176:179], v138 offset:17408
	ds_read_b128 v[188:191], v138 offset:18432
	ds_read_b128 v[192:195], v138 offset:19456
	ds_read_b128 v[196:199], v138 offset:20480
	ds_read_b128 v[200:203], v138 offset:21504
	ds_read_b128 v[204:207], v138 offset:22528
	ds_read_b128 v[208:211], v138 offset:23552
	global_load_lds_dwordx4 v[184:185], off
	v_lshl_add_u64 v[212:213], s[34:35], 0, v[136:137]
	s_mov_b32 m0, s80
	v_lshl_add_u64 v[214:215], s[44:45], 0, v[132:133]
	global_load_lds_dwordx4 v[212:213], off
	s_mov_b32 m0, s79
	v_lshl_add_u64 v[216:217], s[30:31], 0, v[134:135]
	global_load_lds_dwordx4 v[214:215], off
	v_lshl_add_u64 v[214:215], s[44:45], 0, v[136:137]
	s_mov_b32 m0, s78
	s_nop 0
	global_load_lds_dwordx4 v[214:215], off
	v_lshl_add_u64 v[214:215], s[30:31], 0, v[130:131]
	s_mov_b32 m0, s11
	s_nop 0
	global_load_lds_dwordx4 v[214:215], off
	s_mov_b32 m0, s64
	s_nop 0
	global_load_lds_dwordx4 v[216:217], off
	s_waitcnt vmcnt(8)
	s_waitcnt lgkmcnt(0)
	s_setprio 1
	s_barrier
; #define PG8_STAGE(bufoff, gbase, voff) do { _Pragma("unroll") for (int _i = 0; _i < 2; ++_i) \
;         __builtin_amdgcn_global_load_lds((const unsigned*)((const char*)(gbase) + (voff)[_i]), (LAS unsigned*)(lds + (bufoff) + ldsw + _i * 8192), 16, 0, 0); } while (0)
; #define PG8_LDA(dst, b, h) do { _Pragma("unroll") for (int m = 0; m < 4; ++m) _Pragma("unroll") for (int k = 0; k < 2; ++k) dst[m][k] = *(const LAS bf16x8*)(lds + PG8_SA(b, h) + aoff + m * 2048 + k * 1024); } while (0)
; #define PG8_LDB(dst, b, h) do { _Pragma("unroll") for (int n = 0; n < 2; ++n) _Pragma("unroll") for (int k = 0; k < 2; ++k) dst[n][k] = *(const LAS bf16x8*)(lds + PG8_SB(b, h) + boff + n * 2048 + k * 1024); } while (0)
; #define PG8_MMA(ai, bj, At, Bt) do { __builtin_amdgcn_s_setprio(1); _Pragma("unroll") for (int m = 0; m < 4; ++m) _Pragma("unroll") for (int n = 0; n < 2; ++n) _Pragma("unroll") for (int k = 0; k < 2; ++k) \
;         acc[ai][bj][m][n] = __builtin_amdgcn_mfma_f32_16x16x32_bf16(Bt[n][k], At[m][k], acc[ai][bj][m][n], 0, 0, 0); __builtin_amdgcn_s_setprio(0); } while (0)
; #define PG8_WAIT_V(n) asm volatile("s_waitcnt vmcnt(" #n ")" ::: "memory")
; #define PG8_WAIT_L(n) asm volatile("s_waitcnt lgkmcnt(" #n ")" ::: "memory")
; #define PG8_BAR __builtin_amdgcn_s_barrier()
; #define PG8_SCHED __builtin_amdgcn_sched_barrier(0)
; template <class Epi>
; __device__ __forceinline__ void gemm_phase(LAS unsigned char* lds, const Gemm g, const StaticOrder& S, const Epi& E) {
;     ...
;             PG8_WAIT_V(8); PG8_WAIT_L(0); PG8_BAR; PG8_MMA(1, 0, At, B0); PG8_MMA(1, 1, At, B1); PG8_BAR; PG8_SCHED;
;             PG8_LDB(B0, 1, 0); PG8_LDB(B1, 1, 1); PG8_SCHED; PG8_LDA(At, 1, 0); PG8_STAGE(PG8_SA(0, 1), a2 + hstepA, voffA);
;             PG8_WAIT_V(8); PG8_WAIT_L(0); PG8_BAR; PG8_MMA(0, 0, At, B0); PG8_MMA(0, 1, At, B1); PG8_BAR; PG8_SCHED;
;             PG8_LDA(At, 1, 1); PG8_STAGE(PG8_SB(1, 0), b3, voffB); PG8_STAGE(PG8_SB(1, 1), b3 + hstepB, voffB); PG8_STAGE(PG8_SA(1, 0), a3, voffA);
;             PG8_WAIT_V(8); PG8_WAIT_L(0); PG8_BAR; PG8_MMA(1, 0, At, B0); PG8_MMA(1, 1, At, B1); PG8_BAR; PG8_SCHED;
	s_waitcnt lgkmcnt(0)
	v_mfma_f32_16x16x32_bf16 v[62:65], v[140:143], v[172:175], v[62:65]
	v_mfma_f32_16x16x32_bf16 v[58:61], v[148:151], v[172:175], v[58:61]
	v_mfma_f32_16x16x32_bf16 v[54:57], v[140:143], v[188:191], v[54:57]
	v_mfma_f32_16x16x32_bf16 v[50:53], v[148:151], v[188:191], v[50:53]
	v_mfma_f32_16x16x32_bf16 v[38:41], v[140:143], v[196:199], v[38:41]
	v_mfma_f32_16x16x32_bf16 v[34:37], v[148:151], v[196:199], v[34:37]
	v_mfma_f32_16x16x32_bf16 v[22:25], v[140:143], v[204:207], v[22:25]
	v_mfma_f32_16x16x32_bf16 v[18:21], v[148:151], v[204:207], v[18:21]
	v_mfma_f32_16x16x32_bf16 v[62:65], v[144:147], v[176:179], v[62:65]
	v_mfma_f32_16x16x32_bf16 v[58:61], v[152:155], v[176:179], v[58:61]
	v_mfma_f32_16x16x32_bf16 v[54:57], v[144:147], v[192:195], v[54:57]
	v_mfma_f32_16x16x32_bf16 v[50:53], v[152:155], v[192:195], v[50:53]
	v_mfma_f32_16x16x32_bf16 v[38:41], v[144:147], v[200:203], v[38:41]
	v_mfma_f32_16x16x32_bf16 v[34:37], v[152:155], v[200:203], v[34:37]
	v_mfma_f32_16x16x32_bf16 v[22:25], v[144:147], v[208:211], v[22:25]
	v_mfma_f32_16x16x32_bf16 v[18:21], v[152:155], v[208:211], v[18:21]
	v_mfma_f32_16x16x32_bf16 v[46:49], v[156:159], v[172:175], v[46:49]
	v_mfma_f32_16x16x32_bf16 v[42:45], v[164:167], v[172:175], v[42:45]
	v_mfma_f32_16x16x32_bf16 v[30:33], v[156:159], v[188:191], v[30:33]
	v_mfma_f32_16x16x32_bf16 v[26:29], v[164:167], v[188:191], v[26:29]
	v_mfma_f32_16x16x32_bf16 v[14:17], v[156:159], v[196:199], v[14:17]
	v_mfma_f32_16x16x32_bf16 v[10:13], v[164:167], v[196:199], v[10:13]
	v_mfma_f32_16x16x32_bf16 v[6:9], v[156:159], v[204:207], v[6:9]
	v_mfma_f32_16x16x32_bf16 v[2:5], v[164:167], v[204:207], v[2:5]
	v_mfma_f32_16x16x32_bf16 v[46:49], v[160:163], v[176:179], v[46:49]
	v_mfma_f32_16x16x32_bf16 v[42:45], v[168:171], v[176:179], v[42:45]
	v_mfma_f32_16x16x32_bf16 v[30:33], v[160:163], v[192:195], v[30:33]
	v_mfma_f32_16x16x32_bf16 v[26:29], v[168:171], v[192:195], v[26:29]
	v_mfma_f32_16x16x32_bf16 v[14:17], v[160:163], v[200:203], v[14:17]
	v_mfma_f32_16x16x32_bf16 v[10:13], v[168:171], v[200:203], v[10:13]
	v_mfma_f32_16x16x32_bf16 v[6:9], v[160:163], v[208:211], v[6:9]
	v_mfma_f32_16x16x32_bf16 v[2:5], v[168:171], v[208:211], v[2:5]
	s_setprio 0
	s_barrier
	v_add_u32_e32 v139, vcc_lo, v1
	ds_read_b128 v[140:143], v139
	ds_read_b128 v[144:147], v139 offset:1024
	ds_read_b128 v[148:151], v139 offset:2048
	ds_read_b128 v[152:155], v139 offset:3072
	v_add_u32_e32 v139, vcc_hi, v1
	ds_read_b128 v[156:159], v139
	ds_read_b128 v[160:163], v139 offset:1024
	ds_read_b128 v[164:167], v139 offset:2048
	ds_read_b128 v[168:171], v139 offset:3072
	s_mov_b32 m0, s65
	v_lshl_add_u64 v[218:219], s[14:15], 0, v[130:131]
	ds_read_b128 v[172:175], v138 offset:32768
	ds_read_b128 v[176:179], v138 offset:33792
	ds_read_b128 v[188:191], v138 offset:34816
	ds_read_b128 v[192:195], v138 offset:35840
	ds_read_b128 v[196:199], v138 offset:36864
	ds_read_b128 v[200:203], v138 offset:37888
	ds_read_b128 v[204:207], v138 offset:38912
	ds_read_b128 v[208:211], v138 offset:39936
	global_load_lds_dwordx4 v[218:219], off
	v_lshl_add_u64 v[218:219], s[14:15], 0, v[134:135]
	s_mov_b32 m0, s70
	s_nop 0
	global_load_lds_dwordx4 v[218:219], off
	s_waitcnt vmcnt(8)
	s_waitcnt lgkmcnt(0)
	s_setprio 1
	s_barrier
	s_waitcnt lgkmcnt(0)
	v_mfma_f32_16x16x32_bf16 v[126:129], v[140:143], v[172:175], v[126:129]
	v_mfma_f32_16x16x32_bf16 v[122:125], v[148:151], v[172:175], v[122:125]
	v_mfma_f32_16x16x32_bf16 v[118:121], v[140:143], v[188:191], v[118:121]
	v_mfma_f32_16x16x32_bf16 v[114:117], v[148:151], v[188:191], v[114:117]
	v_mfma_f32_16x16x32_bf16 v[102:105], v[140:143], v[196:199], v[102:105]
	v_mfma_f32_16x16x32_bf16 v[98:101], v[148:151], v[196:199], v[98:101]
	v_mfma_f32_16x16x32_bf16 v[86:89], v[140:143], v[204:207], v[86:89]
	v_mfma_f32_16x16x32_bf16 v[82:85], v[148:151], v[204:207], v[82:85]
	v_mfma_f32_16x16x32_bf16 v[126:129], v[144:147], v[176:179], v[126:129]
	v_mfma_f32_16x16x32_bf16 v[122:125], v[152:155], v[176:179], v[122:125]
	v_mfma_f32_16x16x32_bf16 v[118:121], v[144:147], v[192:195], v[118:121]
	v_mfma_f32_16x16x32_bf16 v[114:117], v[152:155], v[192:195], v[114:117]
	v_mfma_f32_16x16x32_bf16 v[102:105], v[144:147], v[200:203], v[102:105]
	v_mfma_f32_16x16x32_bf16 v[98:101], v[152:155], v[200:203], v[98:101]
	v_mfma_f32_16x16x32_bf16 v[86:89], v[144:147], v[208:211], v[86:89]
	v_mfma_f32_16x16x32_bf16 v[82:85], v[152:155], v[208:211], v[82:85]
	v_mfma_f32_16x16x32_bf16 v[110:113], v[156:159], v[172:175], v[110:113]
	v_mfma_f32_16x16x32_bf16 v[106:109], v[164:167], v[172:175], v[106:109]
	v_mfma_f32_16x16x32_bf16 v[94:97], v[156:159], v[188:191], v[94:97]
	v_mfma_f32_16x16x32_bf16 v[90:93], v[164:167], v[188:191], v[90:93]
	v_mfma_f32_16x16x32_bf16 v[78:81], v[156:159], v[196:199], v[78:81]
	v_mfma_f32_16x16x32_bf16 v[74:77], v[164:167], v[196:199], v[74:77]
	v_mfma_f32_16x16x32_bf16 v[70:73], v[156:159], v[204:207], v[70:73]
	v_mfma_f32_16x16x32_bf16 v[66:69], v[164:167], v[204:207], v[66:69]
	v_mfma_f32_16x16x32_bf16 v[110:113], v[160:163], v[176:179], v[110:113]
	v_mfma_f32_16x16x32_bf16 v[106:109], v[168:171], v[176:179], v[106:109]
	v_mfma_f32_16x16x32_bf16 v[94:97], v[160:163], v[192:195], v[94:97]
	v_mfma_f32_16x16x32_bf16 v[90:93], v[168:171], v[192:195], v[90:93]
	v_mfma_f32_16x16x32_bf16 v[78:81], v[160:163], v[200:203], v[78:81]
	v_mfma_f32_16x16x32_bf16 v[74:77], v[168:171], v[200:203], v[74:77]
	v_mfma_f32_16x16x32_bf16 v[70:73], v[160:163], v[208:211], v[70:73]
	v_mfma_f32_16x16x32_bf16 v[66:69], v[168:171], v[208:211], v[66:69]
	s_setprio 0
	s_barrier
; #define PG8_STAGE(bufoff, gbase, voff) do { _Pragma("unroll") for (int _i = 0; _i < 2; ++_i) \
;         __builtin_amdgcn_global_load_lds((const unsigned*)((const char*)(gbase) + (voff)[_i]), (LAS unsigned*)(lds + (bufoff) + ldsw + _i * 8192), 16, 0, 0); } while (0)
; #define PG8_LDA(dst, b, h) do { _Pragma("unroll") for (int m = 0; m < 4; ++m) _Pragma("unroll") for (int k = 0; k < 2; ++k) dst[m][k] = *(const LAS bf16x8*)(lds + PG8_SA(b, h) + aoff + m * 2048 + k * 1024); } while (0)
; #define PG8_MMA(ai, bj, At, Bt) do { __builtin_amdgcn_s_setprio(1); _Pragma("unroll") for (int m = 0; m < 4; ++m) _Pragma("unroll") for (int n = 0; n < 2; ++n) _Pragma("unroll") for (int k = 0; k < 2; ++k) \
;         acc[ai][bj][m][n] = __builtin_amdgcn_mfma_f32_16x16x32_bf16(Bt[n][k], At[m][k], acc[ai][bj][m][n], 0, 0, 0); __builtin_amdgcn_s_setprio(0); } while (0)
; #define PG8_WAIT_V(n) asm volatile("s_waitcnt vmcnt(" #n ")" ::: "memory")
; #define PG8_WAIT_L(n) asm volatile("s_waitcnt lgkmcnt(" #n ")" ::: "memory")
; #define PG8_BAR __builtin_amdgcn_s_barrier()
; #define PG8_SCHED __builtin_amdgcn_sched_barrier(0)
; template <class Epi>
; __device__ __forceinline__ void gemm_phase(LAS unsigned char* lds, const Gemm g, const StaticOrder& S, const Epi& E) {
;     ...
;             PG8_LDA(At, 1, 1); PG8_STAGE(PG8_SB(1, 0), b3, voffB); PG8_STAGE(PG8_SB(1, 1), b3 + hstepB, voffB); PG8_STAGE(PG8_SA(1, 0), a3, voffA);
;             PG8_WAIT_V(8); PG8_WAIT_L(0); PG8_BAR; PG8_MMA(1, 0, At, B0); PG8_MMA(1, 1, At, B1); PG8_BAR; PG8_SCHED;
;         }
;         if (wr == 0) PG8_BAR;
	s_mov_b32 m0, s41
	v_lshl_add_u64 v[184:185], v[184:185], 0, s[84:85]
	ds_read_b128 v[172:175], v138 offset:49152
	ds_read_b128 v[176:179], v138 offset:50176
	ds_read_b128 v[188:191], v138 offset:51200
	ds_read_b128 v[192:195], v138 offset:52224
	ds_read_b128 v[196:199], v138 offset:53248
	ds_read_b128 v[200:203], v138 offset:54272
	ds_read_b128 v[204:207], v138 offset:55296
	ds_read_b128 v[208:211], v138 offset:56320
	global_load_lds_dwordx4 v[184:185], off
	v_lshl_add_u64 v[184:185], v[212:213], 0, s[84:85]
	s_mov_b32 m0, s76
	s_nop 0
	global_load_lds_dwordx4 v[184:185], off
	v_lshl_add_u64 v[184:185], s[28:29], 0, v[132:133]
	s_mov_b32 m0, s81
	s_nop 0
	global_load_lds_dwordx4 v[184:185], off
	v_lshl_add_u64 v[184:185], s[28:29], 0, v[136:137]
	s_mov_b32 m0, s82
	s_nop 0
	global_load_lds_dwordx4 v[184:185], off
	v_lshl_add_u64 v[184:185], v[214:215], 0, s[84:85]
	s_mov_b32 m0, s86
	s_nop 0
	global_load_lds_dwordx4 v[184:185], off
	v_lshl_add_u64 v[184:185], v[216:217], 0, s[84:85]
	s_mov_b32 m0, s87
	s_nop 0
	global_load_lds_dwordx4 v[184:185], off
	s_waitcnt vmcnt(8)
	s_waitcnt lgkmcnt(0)
	s_setprio 1
	s_barrier
	s_waitcnt lgkmcnt(0)
	v_mfma_f32_16x16x32_bf16 v[62:65], v[140:143], v[172:175], v[62:65]
	v_mfma_f32_16x16x32_bf16 v[58:61], v[148:151], v[172:175], v[58:61]
	v_mfma_f32_16x16x32_bf16 v[54:57], v[140:143], v[188:191], v[54:57]
	v_mfma_f32_16x16x32_bf16 v[50:53], v[148:151], v[188:191], v[50:53]
	v_mfma_f32_16x16x32_bf16 v[38:41], v[140:143], v[196:199], v[38:41]
	v_mfma_f32_16x16x32_bf16 v[34:37], v[148:151], v[196:199], v[34:37]
	v_mfma_f32_16x16x32_bf16 v[22:25], v[140:143], v[204:207], v[22:25]
	v_mfma_f32_16x16x32_bf16 v[18:21], v[148:151], v[204:207], v[18:21]
	v_mfma_f32_16x16x32_bf16 v[62:65], v[144:147], v[176:179], v[62:65]
	v_mfma_f32_16x16x32_bf16 v[58:61], v[152:155], v[176:179], v[58:61]
	v_mfma_f32_16x16x32_bf16 v[54:57], v[144:147], v[192:195], v[54:57]
	v_mfma_f32_16x16x32_bf16 v[50:53], v[152:155], v[192:195], v[50:53]
	v_mfma_f32_16x16x32_bf16 v[38:41], v[144:147], v[200:203], v[38:41]
	v_mfma_f32_16x16x32_bf16 v[34:37], v[152:155], v[200:203], v[34:37]
	v_mfma_f32_16x16x32_bf16 v[22:25], v[144:147], v[208:211], v[22:25]
	v_mfma_f32_16x16x32_bf16 v[18:21], v[152:155], v[208:211], v[18:21]
	v_mfma_f32_16x16x32_bf16 v[46:49], v[156:159], v[172:175], v[46:49]
	v_mfma_f32_16x16x32_bf16 v[42:45], v[164:167], v[172:175], v[42:45]
	v_mfma_f32_16x16x32_bf16 v[30:33], v[156:159], v[188:191], v[30:33]
	v_mfma_f32_16x16x32_bf16 v[26:29], v[164:167], v[188:191], v[26:29]
	v_mfma_f32_16x16x32_bf16 v[14:17], v[156:159], v[196:199], v[14:17]
	v_mfma_f32_16x16x32_bf16 v[10:13], v[164:167], v[196:199], v[10:13]
	v_mfma_f32_16x16x32_bf16 v[6:9], v[156:159], v[204:207], v[6:9]
	v_mfma_f32_16x16x32_bf16 v[2:5], v[164:167], v[204:207], v[2:5]
	v_mfma_f32_16x16x32_bf16 v[46:49], v[160:163], v[176:179], v[46:49]
	v_mfma_f32_16x16x32_bf16 v[42:45], v[168:171], v[176:179], v[42:45]
	v_mfma_f32_16x16x32_bf16 v[30:33], v[160:163], v[192:195], v[30:33]
	v_mfma_f32_16x16x32_bf16 v[26:29], v[168:171], v[192:195], v[26:29]
	v_mfma_f32_16x16x32_bf16 v[14:17], v[160:163], v[200:203], v[14:17]
	v_mfma_f32_16x16x32_bf16 v[10:13], v[168:171], v[200:203], v[10:13]
	v_mfma_f32_16x16x32_bf16 v[6:9], v[160:163], v[208:211], v[6:9]
	v_mfma_f32_16x16x32_bf16 v[2:5], v[168:171], v[208:211], v[2:5]
	s_setprio 0
	s_barrier
	s_movk_i32 s14, 0x100
	s_andn2_b64 vcc, exec, s[26:27]
	s_mov_b64 s[28:29], -1
	s_mov_b64 s[26:27], 0
	s_cbranch_vccz .LBB0_1440
	v_readlane_b32 s28, v255, 28
	s_and_b64 vcc, exec, s[8:9]
	v_readlane_b32 s29, v255, 29
	s_cbranch_vccz .LBB0_1443
	s_barrier

; #define PG8_STAGE(bufoff, gbase, voff) do { _Pragma("unroll") for (int _i = 0; _i < 2; ++_i) \
;         __builtin_amdgcn_global_load_lds((const unsigned*)((const char*)(gbase) + (voff)[_i]), (LAS unsigned*)(lds + (bufoff) + ldsw + _i * 8192), 16, 0, 0); } while (0)
; #define PG8_LDA(dst, b, h) do { _Pragma("unroll") for (int m = 0; m < 4; ++m) _Pragma("unroll") for (int k = 0; k < 2; ++k) dst[m][k] = *(const LAS bf16x8*)(lds + PG8_SA(b, h) + aoff + m * 2048 + k * 1024); } while (0)
; #define PG8_LDB(dst, b, h) do { _Pragma("unroll") for (int n = 0; n < 2; ++n) _Pragma("unroll") for (int k = 0; k < 2; ++k) dst[n][k] = *(const LAS bf16x8*)(lds + PG8_SB(b, h) + boff + n * 2048 + k * 1024); } while (0)
; #define PG8_MMA(ai, bj, At, Bt) do { __builtin_amdgcn_s_setprio(1); _Pragma("unroll") for (int m = 0; m < 4; ++m) _Pragma("unroll") for (int n = 0; n < 2; ++n) _Pragma("unroll") for (int k = 0; k < 2; ++k) \
;         acc[ai][bj][m][n] = __builtin_amdgcn_mfma_f32_16x16x32_bf16(Bt[n][k], At[m][k], acc[ai][bj][m][n], 0, 0, 0); __builtin_amdgcn_s_setprio(0); } while (0)
; #define PG8_WAIT_V(n) asm volatile("s_waitcnt vmcnt(" #n ")" ::: "memory")
; #define PG8_WAIT_L(n) asm volatile("s_waitcnt lgkmcnt(" #n ")" ::: "memory")
; #define PG8_BAR __builtin_amdgcn_s_barrier()
; #define PG8_SCHED __builtin_amdgcn_sched_barrier(0)
; template <class Epi>
; __device__ __forceinline__ void gemm_phase(LAS unsigned char* lds, const Gemm g, const StaticOrder& S, const Epi& E) {
;     ...
;             const bool last = (t == nt - 2);
;             const char* a1 = cA + (size_t)(t + 1) * kstep;
;             const char* a2 = last ? nA : cA + (size_t)(t + 2) * kstep; const char* b2 = last ? nB : cB + (size_t)(t + 2) * kstep;
;             const char* a3 = a2 + kstep; const char* b3 = b2 + kstep;
;             PG8_LDB(B0, 0, 0); PG8_LDB(B1, 0, 1); PG8_SCHED; PG8_LDA(At, 0, 0); PG8_STAGE(PG8_SA(1, 1), a1 + hstepA, voffA);
;             PG8_WAIT_V(8); PG8_WAIT_L(0); PG8_BAR; PG8_MMA(0, 0, At, B0); PG8_MMA(0, 1, At, B1); PG8_BAR; PG8_SCHED;
;             PG8_LDA(At, 0, 1); PG8_STAGE(PG8_SB(0, 0), b2, voffB); PG8_STAGE(PG8_SB(0, 1), b2 + hstepB, voffB); PG8_STAGE(PG8_SA(0, 0), a2, voffA);
;             PG8_WAIT_V(8); PG8_WAIT_L(0); PG8_BAR; PG8_MMA(1, 0, At, B0); PG8_MMA(1, 1, At, B1); PG8_BAR; PG8_SCHED;
.LBB0_2035:
	s_add_u32 s14, s24, 0xfff80080
	s_addc_u32 s15, s25, -1
	s_add_i32 s41, 0, 0x10000
	s_cmp_eq_u32 s52, 28
	s_cselect_b32 s27, s1, s15
	s_cselect_b32 s26, s3, s14
	s_cselect_b32 s15, s7, s40
	s_cselect_b32 s14, s13, s17
	s_add_i32 s53, 0, 0x14000
	v_add_u32_e32 v142, s41, v1
	v_add_u32_e32 v158, s53, v1
	ds_read_b128 v[130:133], v142
	ds_read_b128 v[134:137], v142 offset:1024
	ds_read_b128 v[138:141], v142 offset:2048
	ds_read_b128 v[142:145], v142 offset:3072
	ds_read_b128 v[146:149], v158
	ds_read_b128 v[150:153], v158 offset:1024
	ds_read_b128 v[154:157], v158 offset:2048
	ds_read_b128 v[158:161], v158 offset:3072
	v_lshl_add_u64 v[178:179], s[24:25], 0, v[196:197]
	s_add_i32 m0, s23, 0xc000
	ds_read_b128 v[162:165], v181
	ds_read_b128 v[166:169], v181 offset:1024
	ds_read_b128 v[170:173], v181 offset:2048
	ds_read_b128 v[174:177], v181 offset:3072
	ds_read_b128 v[200:203], v181 offset:4096
	ds_read_b128 v[204:207], v181 offset:5120
	ds_read_b128 v[208:211], v181 offset:6144
	ds_read_b128 v[212:215], v181 offset:7168
	global_load_lds_dwordx4 v[178:179], off
	v_lshl_add_u64 v[178:179], s[24:25], 0, v[198:199]
	s_add_i32 m0, s23, 0xe000
	s_nop 0
	global_load_lds_dwordx4 v[178:179], off
	s_waitcnt vmcnt(8)
	s_waitcnt lgkmcnt(0)
	s_setprio 1
	s_barrier
	s_waitcnt lgkmcnt(0)
	v_mfma_f32_16x16x32_bf16 v[126:129], v[130:133], v[162:165], v[126:129]
	v_mfma_f32_16x16x32_bf16 v[122:125], v[138:141], v[162:165], v[122:125]
	v_mfma_f32_16x16x32_bf16 v[110:113], v[130:133], v[170:173], v[110:113]
	v_mfma_f32_16x16x32_bf16 v[106:109], v[138:141], v[170:173], v[106:109]
	v_mfma_f32_16x16x32_bf16 v[94:97], v[130:133], v[200:203], v[94:97]
	v_mfma_f32_16x16x32_bf16 v[90:93], v[138:141], v[200:203], v[90:93]
	v_mfma_f32_16x16x32_bf16 v[82:85], v[130:133], v[208:211], v[82:85]
	v_mfma_f32_16x16x32_bf16 v[74:77], v[138:141], v[208:211], v[74:77]
	v_mfma_f32_16x16x32_bf16 v[126:129], v[134:137], v[166:169], v[126:129]
	v_mfma_f32_16x16x32_bf16 v[122:125], v[142:145], v[166:169], v[122:125]
	v_mfma_f32_16x16x32_bf16 v[110:113], v[134:137], v[174:177], v[110:113]
	v_mfma_f32_16x16x32_bf16 v[106:109], v[142:145], v[174:177], v[106:109]
	v_mfma_f32_16x16x32_bf16 v[94:97], v[134:137], v[204:207], v[94:97]
	v_mfma_f32_16x16x32_bf16 v[90:93], v[142:145], v[204:207], v[90:93]
	v_mfma_f32_16x16x32_bf16 v[82:85], v[134:137], v[212:215], v[82:85]
	v_mfma_f32_16x16x32_bf16 v[74:77], v[142:145], v[212:215], v[74:77]
	v_mfma_f32_16x16x32_bf16 v[118:121], v[146:149], v[162:165], v[118:121]
	v_mfma_f32_16x16x32_bf16 v[114:117], v[154:157], v[162:165], v[114:117]
	v_mfma_f32_16x16x32_bf16 v[102:105], v[146:149], v[170:173], v[102:105]
	v_mfma_f32_16x16x32_bf16 v[98:101], v[154:157], v[170:173], v[98:101]
	v_mfma_f32_16x16x32_bf16 v[86:89], v[146:149], v[200:203], v[86:89]
	v_mfma_f32_16x16x32_bf16 v[78:81], v[154:157], v[200:203], v[78:81]
	v_mfma_f32_16x16x32_bf16 v[70:73], v[146:149], v[208:211], v[70:73]
	v_mfma_f32_16x16x32_bf16 v[66:69], v[154:157], v[208:211], v[66:69]
	v_mfma_f32_16x16x32_bf16 v[118:121], v[150:153], v[166:169], v[118:121]
	v_mfma_f32_16x16x32_bf16 v[114:117], v[158:161], v[166:169], v[114:117]
	v_mfma_f32_16x16x32_bf16 v[102:105], v[150:153], v[174:177], v[102:105]
	v_mfma_f32_16x16x32_bf16 v[98:101], v[158:161], v[174:177], v[98:101]
	v_mfma_f32_16x16x32_bf16 v[86:89], v[150:153], v[204:207], v[86:89]
	v_mfma_f32_16x16x32_bf16 v[78:81], v[158:161], v[204:207], v[78:81]
	v_mfma_f32_16x16x32_bf16 v[70:73], v[150:153], v[212:215], v[70:73]
	v_mfma_f32_16x16x32_bf16 v[66:69], v[158:161], v[212:215], v[66:69]
	s_setprio 0
	s_barrier
	s_add_i32 s41, s41, s30
	v_lshl_add_u64 v[178:179], s[14:15], 0, v[190:191]
	s_mov_b32 m0, s41
	ds_read_b128 v[162:165], v181 offset:16384
	ds_read_b128 v[166:169], v181 offset:17408
	ds_read_b128 v[170:173], v181 offset:18432
	ds_read_b128 v[174:177], v181 offset:19456
	ds_read_b128 v[200:203], v181 offset:20480
	ds_read_b128 v[204:207], v181 offset:21504
	ds_read_b128 v[208:211], v181 offset:22528
	ds_read_b128 v[212:215], v181 offset:23552
	global_load_lds_dwordx4 v[178:179], off
	s_add_i32 m0, s41, 0x2000
	s_add_u32 s62, s14, 0x80000
	v_lshl_add_u64 v[184:185], s[14:15], 0, v[194:195]
	s_addc_u32 s63, s15, 0
	s_add_i32 s41, s53, s30
	global_load_lds_dwordx4 v[184:185], off
	v_lshl_add_u64 v[216:217], s[62:63], 0, v[190:191]
	s_mov_b32 m0, s41
	v_lshl_add_u64 v[218:219], s[26:27], 0, v[192:193]
	global_load_lds_dwordx4 v[216:217], off
	v_lshl_add_u64 v[216:217], s[62:63], 0, v[194:195]
	s_add_i32 m0, s41, 0x2000
	s_nop 0
	global_load_lds_dwordx4 v[216:217], off
	v_lshl_add_u64 v[216:217], s[26:27], 0, v[188:189]
	s_mov_b32 m0, s23
	s_nop 0
	global_load_lds_dwordx4 v[216:217], off
	s_mov_b32 m0, s34
	s_nop 0
	global_load_lds_dwordx4 v[218:219], off
	s_waitcnt vmcnt(8)
	s_waitcnt lgkmcnt(0)
	s_setprio 1
	s_barrier
; #define PG8_STAGE(bufoff, gbase, voff) do { _Pragma("unroll") for (int _i = 0; _i < 2; ++_i) \
;         __builtin_amdgcn_global_load_lds((const unsigned*)((const char*)(gbase) + (voff)[_i]), (LAS unsigned*)(lds + (bufoff) + ldsw + _i * 8192), 16, 0, 0); } while (0)
; #define PG8_LDA(dst, b, h) do { _Pragma("unroll") for (int m = 0; m < 4; ++m) _Pragma("unroll") for (int k = 0; k < 2; ++k) dst[m][k] = *(const LAS bf16x8*)(lds + PG8_SA(b, h) + aoff + m * 2048 + k * 1024); } while (0)
; #define PG8_LDB(dst, b, h) do { _Pragma("unroll") for (int n = 0; n < 2; ++n) _Pragma("unroll") for (int k = 0; k < 2; ++k) dst[n][k] = *(const LAS bf16x8*)(lds + PG8_SB(b, h) + boff + n * 2048 + k * 1024); } while (0)
; #define PG8_MMA(ai, bj, At, Bt) do { __builtin_amdgcn_s_setprio(1); _Pragma("unroll") for (int m = 0; m < 4; ++m) _Pragma("unroll") for (int n = 0; n < 2; ++n) _Pragma("unroll") for (int k = 0; k < 2; ++k) \
;         acc[ai][bj][m][n] = __builtin_amdgcn_mfma_f32_16x16x32_bf16(Bt[n][k], At[m][k], acc[ai][bj][m][n], 0, 0, 0); __builtin_amdgcn_s_setprio(0); } while (0)
; #define PG8_WAIT_V(n) asm volatile("s_waitcnt vmcnt(" #n ")" ::: "memory")
; #define PG8_WAIT_L(n) asm volatile("s_waitcnt lgkmcnt(" #n ")" ::: "memory")
; #define PG8_BAR __builtin_amdgcn_s_barrier()
; #define PG8_SCHED __builtin_amdgcn_sched_barrier(0)
; template <class Epi>
; __device__ __forceinline__ void gemm_phase(LAS unsigned char* lds, const Gemm g, const StaticOrder& S, const Epi& E) {
;     ...
;             PG8_WAIT_V(8); PG8_WAIT_L(0); PG8_BAR; PG8_MMA(1, 0, At, B0); PG8_MMA(1, 1, At, B1); PG8_BAR; PG8_SCHED;
;             PG8_LDB(B0, 1, 0); PG8_LDB(B1, 1, 1); PG8_SCHED; PG8_LDA(At, 1, 0); PG8_STAGE(PG8_SA(0, 1), a2 + hstepA, voffA);
;             PG8_WAIT_V(8); PG8_WAIT_L(0); PG8_BAR; PG8_MMA(0, 0, At, B0); PG8_MMA(0, 1, At, B1); PG8_BAR; PG8_SCHED;
;             PG8_LDA(At, 1, 1); PG8_STAGE(PG8_SB(1, 0), b3, voffB); PG8_STAGE(PG8_SB(1, 1), b3 + hstepB, voffB); PG8_STAGE(PG8_SA(1, 0), a3, voffA);
;             PG8_WAIT_V(8); PG8_WAIT_L(0); PG8_BAR; PG8_MMA(1, 0, At, B0); PG8_MMA(1, 1, At, B1); PG8_BAR; PG8_SCHED;
	s_waitcnt lgkmcnt(0)
	v_mfma_f32_16x16x32_bf16 v[62:65], v[130:133], v[162:165], v[62:65]
	v_mfma_f32_16x16x32_bf16 v[58:61], v[138:141], v[162:165], v[58:61]
	v_mfma_f32_16x16x32_bf16 v[50:53], v[130:133], v[170:173], v[50:53]
	v_mfma_f32_16x16x32_bf16 v[42:45], v[138:141], v[170:173], v[42:45]
	v_mfma_f32_16x16x32_bf16 v[30:33], v[130:133], v[200:203], v[30:33]
	v_mfma_f32_16x16x32_bf16 v[26:29], v[138:141], v[200:203], v[26:29]
	v_mfma_f32_16x16x32_bf16 v[18:21], v[130:133], v[208:211], v[18:21]
	v_mfma_f32_16x16x32_bf16 v[10:13], v[138:141], v[208:211], v[10:13]
	v_mfma_f32_16x16x32_bf16 v[62:65], v[134:137], v[166:169], v[62:65]
	v_mfma_f32_16x16x32_bf16 v[58:61], v[142:145], v[166:169], v[58:61]
	v_mfma_f32_16x16x32_bf16 v[50:53], v[134:137], v[174:177], v[50:53]
	v_mfma_f32_16x16x32_bf16 v[42:45], v[142:145], v[174:177], v[42:45]
	v_mfma_f32_16x16x32_bf16 v[30:33], v[134:137], v[204:207], v[30:33]
	v_mfma_f32_16x16x32_bf16 v[26:29], v[142:145], v[204:207], v[26:29]
	v_mfma_f32_16x16x32_bf16 v[18:21], v[134:137], v[212:215], v[18:21]
	v_mfma_f32_16x16x32_bf16 v[10:13], v[142:145], v[212:215], v[10:13]
	v_mfma_f32_16x16x32_bf16 v[54:57], v[146:149], v[162:165], v[54:57]
	v_mfma_f32_16x16x32_bf16 v[46:49], v[154:157], v[162:165], v[46:49]
	v_mfma_f32_16x16x32_bf16 v[38:41], v[146:149], v[170:173], v[38:41]
	v_mfma_f32_16x16x32_bf16 v[34:37], v[154:157], v[170:173], v[34:37]
	v_mfma_f32_16x16x32_bf16 v[22:25], v[146:149], v[200:203], v[22:25]
	v_mfma_f32_16x16x32_bf16 v[14:17], v[154:157], v[200:203], v[14:17]
	v_mfma_f32_16x16x32_bf16 v[6:9], v[146:149], v[208:211], v[6:9]
	v_mfma_f32_16x16x32_bf16 v[2:5], v[154:157], v[208:211], v[2:5]
	v_mfma_f32_16x16x32_bf16 v[54:57], v[150:153], v[166:169], v[54:57]
	v_mfma_f32_16x16x32_bf16 v[46:49], v[158:161], v[166:169], v[46:49]
	v_mfma_f32_16x16x32_bf16 v[38:41], v[150:153], v[174:177], v[38:41]
	v_mfma_f32_16x16x32_bf16 v[34:37], v[158:161], v[174:177], v[34:37]
	v_mfma_f32_16x16x32_bf16 v[22:25], v[150:153], v[204:207], v[22:25]
	v_mfma_f32_16x16x32_bf16 v[14:17], v[158:161], v[204:207], v[14:17]
	v_mfma_f32_16x16x32_bf16 v[6:9], v[150:153], v[212:215], v[6:9]
	v_mfma_f32_16x16x32_bf16 v[2:5], v[158:161], v[212:215], v[2:5]
	s_setprio 0
	s_barrier
	s_add_i32 s41, 0, 0x18000
	s_add_i32 s53, 0, 0x1c000
	v_add_u32_e32 v142, s41, v1
	v_add_u32_e32 v158, s53, v1
	ds_read_b128 v[130:133], v142
	ds_read_b128 v[134:137], v142 offset:1024
	ds_read_b128 v[138:141], v142 offset:2048
	ds_read_b128 v[142:145], v142 offset:3072
	ds_read_b128 v[146:149], v158
	ds_read_b128 v[150:153], v158 offset:1024
	ds_read_b128 v[154:157], v158 offset:2048
	ds_read_b128 v[158:161], v158 offset:3072
	s_add_u32 s26, s26, 0x80000
	s_addc_u32 s27, s27, 0
	s_mov_b32 m0, s35
	v_lshl_add_u64 v[220:221], s[26:27], 0, v[188:189]
	ds_read_b128 v[162:165], v181 offset:32768
	ds_read_b128 v[166:169], v181 offset:33792
	ds_read_b128 v[170:173], v181 offset:34816
	ds_read_b128 v[174:177], v181 offset:35840
	ds_read_b128 v[200:203], v181 offset:36864
	ds_read_b128 v[204:207], v181 offset:37888
	ds_read_b128 v[208:211], v181 offset:38912
	ds_read_b128 v[212:215], v181 offset:39936
	global_load_lds_dwordx4 v[220:221], off
	v_lshl_add_u64 v[220:221], s[26:27], 0, v[192:193]
	s_mov_b32 m0, s42
	s_nop 0
	global_load_lds_dwordx4 v[220:221], off
	s_waitcnt vmcnt(8)
	s_waitcnt lgkmcnt(0)
	s_setprio 1
	s_barrier
	s_waitcnt lgkmcnt(0)
	v_mfma_f32_16x16x32_bf16 v[126:129], v[130:133], v[162:165], v[126:129]
	v_mfma_f32_16x16x32_bf16 v[122:125], v[138:141], v[162:165], v[122:125]
	v_mfma_f32_16x16x32_bf16 v[110:113], v[130:133], v[170:173], v[110:113]
	v_mfma_f32_16x16x32_bf16 v[106:109], v[138:141], v[170:173], v[106:109]
	v_mfma_f32_16x16x32_bf16 v[94:97], v[130:133], v[200:203], v[94:97]
	v_mfma_f32_16x16x32_bf16 v[90:93], v[138:141], v[200:203], v[90:93]
	v_mfma_f32_16x16x32_bf16 v[82:85], v[130:133], v[208:211], v[82:85]
	v_mfma_f32_16x16x32_bf16 v[74:77], v[138:141], v[208:211], v[74:77]
	v_mfma_f32_16x16x32_bf16 v[126:129], v[134:137], v[166:169], v[126:129]
	v_mfma_f32_16x16x32_bf16 v[122:125], v[142:145], v[166:169], v[122:125]
	v_mfma_f32_16x16x32_bf16 v[110:113], v[134:137], v[174:177], v[110:113]
	v_mfma_f32_16x16x32_bf16 v[106:109], v[142:145], v[174:177], v[106:109]
	v_mfma_f32_16x16x32_bf16 v[94:97], v[134:137], v[204:207], v[94:97]
	v_mfma_f32_16x16x32_bf16 v[90:93], v[142:145], v[204:207], v[90:93]
	v_mfma_f32_16x16x32_bf16 v[82:85], v[134:137], v[212:215], v[82:85]
	v_mfma_f32_16x16x32_bf16 v[74:77], v[142:145], v[212:215], v[74:77]
	v_mfma_f32_16x16x32_bf16 v[118:121], v[146:149], v[162:165], v[118:121]
	v_mfma_f32_16x16x32_bf16 v[114:117], v[154:157], v[162:165], v[114:117]
	v_mfma_f32_16x16x32_bf16 v[102:105], v[146:149], v[170:173], v[102:105]
	v_mfma_f32_16x16x32_bf16 v[98:101], v[154:157], v[170:173], v[98:101]
	v_mfma_f32_16x16x32_bf16 v[86:89], v[146:149], v[200:203], v[86:89]
	v_mfma_f32_16x16x32_bf16 v[78:81], v[154:157], v[200:203], v[78:81]
	v_mfma_f32_16x16x32_bf16 v[70:73], v[146:149], v[208:211], v[70:73]
	v_mfma_f32_16x16x32_bf16 v[66:69], v[154:157], v[208:211], v[66:69]
	v_mfma_f32_16x16x32_bf16 v[118:121], v[150:153], v[166:169], v[118:121]
	v_mfma_f32_16x16x32_bf16 v[114:117], v[158:161], v[166:169], v[114:117]
	v_mfma_f32_16x16x32_bf16 v[102:105], v[150:153], v[174:177], v[102:105]
	v_mfma_f32_16x16x32_bf16 v[98:101], v[158:161], v[174:177], v[98:101]
	v_mfma_f32_16x16x32_bf16 v[86:89], v[150:153], v[204:207], v[86:89]
	v_mfma_f32_16x16x32_bf16 v[78:81], v[158:161], v[204:207], v[78:81]
	v_mfma_f32_16x16x32_bf16 v[70:73], v[150:153], v[212:215], v[70:73]
	v_mfma_f32_16x16x32_bf16 v[66:69], v[158:161], v[212:215], v[66:69]
	s_setprio 0
	s_barrier
; #define PG8_STAGE(bufoff, gbase, voff) do { _Pragma("unroll") for (int _i = 0; _i < 2; ++_i) \
;         __builtin_amdgcn_global_load_lds((const unsigned*)((const char*)(gbase) + (voff)[_i]), (LAS unsigned*)(lds + (bufoff) + ldsw + _i * 8192), 16, 0, 0); } while (0)
; #define PG8_LDA(dst, b, h) do { _Pragma("unroll") for (int m = 0; m < 4; ++m) _Pragma("unroll") for (int k = 0; k < 2; ++k) dst[m][k] = *(const LAS bf16x8*)(lds + PG8_SA(b, h) + aoff + m * 2048 + k * 1024); } while (0)
; #define PG8_MMA(ai, bj, At, Bt) do { __builtin_amdgcn_s_setprio(1); _Pragma("unroll") for (int m = 0; m < 4; ++m) _Pragma("unroll") for (int n = 0; n < 2; ++n) _Pragma("unroll") for (int k = 0; k < 2; ++k) \
;         acc[ai][bj][m][n] = __builtin_amdgcn_mfma_f32_16x16x32_bf16(Bt[n][k], At[m][k], acc[ai][bj][m][n], 0, 0, 0); __builtin_amdgcn_s_setprio(0); } while (0)
; #define PG8_WAIT_V(n) asm volatile("s_waitcnt vmcnt(" #n ")" ::: "memory")
; #define PG8_WAIT_L(n) asm volatile("s_waitcnt lgkmcnt(" #n ")" ::: "memory")
; #define PG8_BAR __builtin_amdgcn_s_barrier()
; #define PG8_SCHED __builtin_amdgcn_sched_barrier(0)
; template <class Epi>
; __device__ __forceinline__ void gemm_phase(LAS unsigned char* lds, const Gemm g, const StaticOrder& S, const Epi& E) {
;     ...
;             PG8_LDA(At, 1, 1); PG8_STAGE(PG8_SB(1, 0), b3, voffB); PG8_STAGE(PG8_SB(1, 1), b3 + hstepB, voffB); PG8_STAGE(PG8_SA(1, 0), a3, voffA);
;             PG8_WAIT_V(8); PG8_WAIT_L(0); PG8_BAR; PG8_MMA(1, 0, At, B0); PG8_MMA(1, 1, At, B1); PG8_BAR; PG8_SCHED;
;         }
	s_add_i32 s26, s41, s30
	v_lshl_add_u64 v[178:179], v[178:179], 0, s[84:85]
	s_mov_b32 m0, s26
	ds_read_b128 v[162:165], v181 offset:49152
	ds_read_b128 v[166:169], v181 offset:50176
	ds_read_b128 v[170:173], v181 offset:51200
	ds_read_b128 v[174:177], v181 offset:52224
	ds_read_b128 v[200:203], v181 offset:53248
	ds_read_b128 v[204:207], v181 offset:54272
	ds_read_b128 v[208:211], v181 offset:55296
	ds_read_b128 v[212:215], v181 offset:56320
	global_load_lds_dwordx4 v[178:179], off
	s_add_i32 m0, s26, 0x2000
	s_add_u32 s14, s14, 0x80080
	v_lshl_add_u64 v[178:179], v[184:185], 0, s[84:85]
	s_addc_u32 s15, s15, 0
	s_add_i32 s26, s53, s30
	global_load_lds_dwordx4 v[178:179], off
	v_lshl_add_u64 v[178:179], s[14:15], 0, v[190:191]
	s_mov_b32 m0, s26
	s_nop 0
	global_load_lds_dwordx4 v[178:179], off
	v_lshl_add_u64 v[178:179], s[14:15], 0, v[194:195]
	s_add_i32 m0, s26, 0x2000
	s_nop 0
	global_load_lds_dwordx4 v[178:179], off
	v_lshl_add_u64 v[178:179], v[216:217], 0, s[84:85]
	s_mov_b32 m0, s68
	s_nop 0
	global_load_lds_dwordx4 v[178:179], off
	v_lshl_add_u64 v[178:179], v[218:219], 0, s[84:85]
	s_mov_b32 m0, s69
	s_nop 0
	global_load_lds_dwordx4 v[178:179], off
	s_waitcnt vmcnt(8)
	s_waitcnt lgkmcnt(0)
	s_setprio 1
	s_barrier
	s_waitcnt lgkmcnt(0)
	v_mfma_f32_16x16x32_bf16 v[62:65], v[130:133], v[162:165], v[62:65]
	v_mfma_f32_16x16x32_bf16 v[58:61], v[138:141], v[162:165], v[58:61]
	v_mfma_f32_16x16x32_bf16 v[50:53], v[130:133], v[170:173], v[50:53]
	v_mfma_f32_16x16x32_bf16 v[42:45], v[138:141], v[170:173], v[42:45]
	v_mfma_f32_16x16x32_bf16 v[30:33], v[130:133], v[200:203], v[30:33]
	v_mfma_f32_16x16x32_bf16 v[26:29], v[138:141], v[200:203], v[26:29]
	v_mfma_f32_16x16x32_bf16 v[18:21], v[130:133], v[208:211], v[18:21]
	v_mfma_f32_16x16x32_bf16 v[10:13], v[138:141], v[208:211], v[10:13]
	v_mfma_f32_16x16x32_bf16 v[62:65], v[134:137], v[166:169], v[62:65]
	v_mfma_f32_16x16x32_bf16 v[58:61], v[142:145], v[166:169], v[58:61]
	v_mfma_f32_16x16x32_bf16 v[50:53], v[134:137], v[174:177], v[50:53]
	v_mfma_f32_16x16x32_bf16 v[42:45], v[142:145], v[174:177], v[42:45]
	v_mfma_f32_16x16x32_bf16 v[30:33], v[134:137], v[204:207], v[30:33]
	v_mfma_f32_16x16x32_bf16 v[26:29], v[142:145], v[204:207], v[26:29]
	v_mfma_f32_16x16x32_bf16 v[18:21], v[134:137], v[212:215], v[18:21]
	v_mfma_f32_16x16x32_bf16 v[10:13], v[142:145], v[212:215], v[10:13]
	v_mfma_f32_16x16x32_bf16 v[54:57], v[146:149], v[162:165], v[54:57]
	v_mfma_f32_16x16x32_bf16 v[46:49], v[154:157], v[162:165], v[46:49]
	v_mfma_f32_16x16x32_bf16 v[38:41], v[146:149], v[170:173], v[38:41]
	v_mfma_f32_16x16x32_bf16 v[34:37], v[154:157], v[170:173], v[34:37]
	v_mfma_f32_16x16x32_bf16 v[22:25], v[146:149], v[200:203], v[22:25]
	v_mfma_f32_16x16x32_bf16 v[14:17], v[154:157], v[200:203], v[14:17]
	v_mfma_f32_16x16x32_bf16 v[6:9], v[146:149], v[208:211], v[6:9]
	v_mfma_f32_16x16x32_bf16 v[2:5], v[154:157], v[208:211], v[2:5]
	v_mfma_f32_16x16x32_bf16 v[54:57], v[150:153], v[166:169], v[54:57]
	v_mfma_f32_16x16x32_bf16 v[46:49], v[158:161], v[166:169], v[46:49]
	v_mfma_f32_16x16x32_bf16 v[38:41], v[150:153], v[174:177], v[38:41]
	v_mfma_f32_16x16x32_bf16 v[34:37], v[158:161], v[174:177], v[34:37]
	v_mfma_f32_16x16x32_bf16 v[22:25], v[150:153], v[204:207], v[22:25]
	v_mfma_f32_16x16x32_bf16 v[14:17], v[158:161], v[204:207], v[14:17]
	v_mfma_f32_16x16x32_bf16 v[6:9], v[150:153], v[212:215], v[6:9]
	v_mfma_f32_16x16x32_bf16 v[2:5], v[158:161], v[212:215], v[2:5]
	s_setprio 0
	s_barrier
	s_add_i32 s52, s52, 2
	s_add_u32 s24, s24, 0x100
	s_addc_u32 s25, s25, 0
	s_add_u32 s17, s17, 0x100
	s_addc_u32 s40, s40, 0
	s_cmp_gt_u32 s52, 29
	s_cbranch_scc0 .LBB0_2035
	s_cmp_ge_u32 s74, 16
	s_cbranch_scc1 .Lwpf_c
	s_lshl_b32 s100, s74, 9
	v_add_u32_e32 v130, s100, v246
	v_lshrrev_b32_e32 v131, 2, v130
	v_and_b32_e32 v130, 3, v130
	v_lshlrev_b32_e32 v130, 7, v130
	v_lshl_add_u32 v130, v131, 12, v130
	s_add_u32 s100, s88, 0x1800000
	s_addc_u32 s101, s89, 0
	s_mov_b32 m0, 0x21000
	s_nop 0
	global_load_lds_dword v130, s[100:101]

; #define PG8_STAGE(bufoff, gbase, voff) do { _Pragma("unroll") for (int _i = 0; _i < 2; ++_i) \
;         __builtin_amdgcn_global_load_lds((const unsigned*)((const char*)(gbase) + (voff)[_i]), (LAS unsigned*)(lds + (bufoff) + ldsw + _i * 8192), 16, 0, 0); } while (0)
; #define PG8_LDA(dst, b, h) do { _Pragma("unroll") for (int m = 0; m < 4; ++m) _Pragma("unroll") for (int k = 0; k < 2; ++k) dst[m][k] = *(const LAS bf16x8*)(lds + PG8_SA(b, h) + aoff + m * 2048 + k * 1024); } while (0)
; #define PG8_LDB(dst, b, h) do { _Pragma("unroll") for (int n = 0; n < 2; ++n) _Pragma("unroll") for (int k = 0; k < 2; ++k) dst[n][k] = *(const LAS bf16x8*)(lds + PG8_SB(b, h) + boff + n * 2048 + k * 1024); } while (0)
; #define PG8_MMA(ai, bj, At, Bt) do { __builtin_amdgcn_s_setprio(1); _Pragma("unroll") for (int m = 0; m < 4; ++m) _Pragma("unroll") for (int n = 0; n < 2; ++n) _Pragma("unroll") for (int k = 0; k < 2; ++k) \
;         acc[ai][bj][m][n] = __builtin_amdgcn_mfma_f32_16x16x32_bf16(Bt[n][k], At[m][k], acc[ai][bj][m][n], 0, 0, 0); __builtin_amdgcn_s_setprio(0); } while (0)
; #define PG8_WAIT_V(n) asm volatile("s_waitcnt vmcnt(" #n ")" ::: "memory")
; #define PG8_WAIT_L(n) asm volatile("s_waitcnt lgkmcnt(" #n ")" ::: "memory")
; #define PG8_BAR __builtin_amdgcn_s_barrier()
; #define PG8_SCHED __builtin_amdgcn_sched_barrier(0)
; template <class Epi>
; __device__ __forceinline__ void gemm_phase(LAS unsigned char* lds, const Gemm g, const StaticOrder& S, const Epi& E) {
;     ...
;             const bool last = (t == nt - 2);
;             const char* a1 = cA + (size_t)(t + 1) * kstep;
;             const char* a2 = last ? nA : cA + (size_t)(t + 2) * kstep; const char* b2 = last ? nB : cB + (size_t)(t + 2) * kstep;
;             const char* a3 = a2 + kstep; const char* b3 = b2 + kstep;
;             PG8_LDB(B0, 0, 0); PG8_LDB(B1, 0, 1); PG8_SCHED; PG8_LDA(At, 0, 0); PG8_STAGE(PG8_SA(1, 1), a1 + hstepA, voffA);
;             PG8_WAIT_V(8); PG8_WAIT_L(0); PG8_BAR; PG8_MMA(0, 0, At, B0); PG8_MMA(0, 1, At, B1); PG8_BAR; PG8_SCHED;
;             PG8_LDA(At, 0, 1); PG8_STAGE(PG8_SB(0, 0), b2, voffB); PG8_STAGE(PG8_SB(0, 1), b2 + hstepB, voffB); PG8_STAGE(PG8_SA(0, 0), a2, voffA);
;             PG8_WAIT_V(8); PG8_WAIT_L(0); PG8_BAR; PG8_MMA(1, 0, At, B0); PG8_MMA(1, 1, At, B1); PG8_BAR; PG8_SCHED;
.LBB0_2130:
	s_add_u32 s14, s20, 0xfff80080
	s_addc_u32 s15, s21, -1
	s_add_i32 s62, 0, 0x10000
	s_cmp_eq_u32 s41, 28
	s_cselect_b32 s23, s3, s15
	s_cselect_b32 s22, s11, s14
	v_add_u32_e32 v142, s62, v1
	s_cselect_b32 s15, s9, s53
	s_cselect_b32 s14, s40, s52
	s_add_i32 s64, 0, 0x14000
	ds_read_b128 v[146:149], v142
	ds_read_b128 v[150:153], v142 offset:1024
	ds_read_b128 v[154:157], v142 offset:2048
	ds_read_b128 v[158:161], v142 offset:3072
	v_add_u32_e32 v142, s64, v1
	ds_read_b128 v[162:165], v142
	ds_read_b128 v[166:169], v142 offset:1024
	ds_read_b128 v[170:173], v142 offset:2048
	ds_read_b128 v[174:177], v142 offset:3072
	v_lshl_add_u64 v[142:143], s[20:21], 0, v[138:139]
	s_add_i32 m0, s19, 0xc000
	ds_read_b128 v[188:191], v144
	ds_read_b128 v[192:195], v144 offset:1024
	ds_read_b128 v[196:199], v144 offset:2048
	ds_read_b128 v[200:203], v144 offset:3072
	ds_read_b128 v[204:207], v144 offset:4096
	ds_read_b128 v[208:211], v144 offset:5120
	ds_read_b128 v[212:215], v144 offset:6144
	ds_read_b128 v[216:219], v144 offset:7168
	global_load_lds_dwordx4 v[142:143], off
	v_lshl_add_u64 v[142:143], s[20:21], 0, v[140:141]
	s_add_i32 m0, s19, 0xe000
	s_nop 0
	global_load_lds_dwordx4 v[142:143], off
	s_waitcnt vmcnt(8)
	s_waitcnt lgkmcnt(0)
	s_setprio 1
	s_barrier
	s_waitcnt lgkmcnt(0)
	v_mfma_f32_16x16x32_bf16 v[126:129], v[146:149], v[188:191], v[126:129]
	v_mfma_f32_16x16x32_bf16 v[122:125], v[154:157], v[188:191], v[122:125]
	v_mfma_f32_16x16x32_bf16 v[110:113], v[146:149], v[196:199], v[110:113]
	v_mfma_f32_16x16x32_bf16 v[106:109], v[154:157], v[196:199], v[106:109]
	v_mfma_f32_16x16x32_bf16 v[94:97], v[146:149], v[204:207], v[94:97]
	v_mfma_f32_16x16x32_bf16 v[90:93], v[154:157], v[204:207], v[90:93]
	v_mfma_f32_16x16x32_bf16 v[78:81], v[146:149], v[212:215], v[78:81]
	v_mfma_f32_16x16x32_bf16 v[74:77], v[154:157], v[212:215], v[74:77]
	v_mfma_f32_16x16x32_bf16 v[126:129], v[150:153], v[192:195], v[126:129]
	v_mfma_f32_16x16x32_bf16 v[122:125], v[158:161], v[192:195], v[122:125]
	v_mfma_f32_16x16x32_bf16 v[110:113], v[150:153], v[200:203], v[110:113]
	v_mfma_f32_16x16x32_bf16 v[106:109], v[158:161], v[200:203], v[106:109]
	v_mfma_f32_16x16x32_bf16 v[94:97], v[150:153], v[208:211], v[94:97]
	v_mfma_f32_16x16x32_bf16 v[90:93], v[158:161], v[208:211], v[90:93]
	v_mfma_f32_16x16x32_bf16 v[78:81], v[150:153], v[216:219], v[78:81]
	v_mfma_f32_16x16x32_bf16 v[74:77], v[158:161], v[216:219], v[74:77]
	v_mfma_f32_16x16x32_bf16 v[118:121], v[162:165], v[188:191], v[118:121]
	v_mfma_f32_16x16x32_bf16 v[114:117], v[170:173], v[188:191], v[114:117]
	v_mfma_f32_16x16x32_bf16 v[102:105], v[162:165], v[196:199], v[102:105]
	v_mfma_f32_16x16x32_bf16 v[98:101], v[170:173], v[196:199], v[98:101]
	v_mfma_f32_16x16x32_bf16 v[86:89], v[162:165], v[204:207], v[86:89]
	v_mfma_f32_16x16x32_bf16 v[82:85], v[170:173], v[204:207], v[82:85]
	v_mfma_f32_16x16x32_bf16 v[70:73], v[162:165], v[212:215], v[70:73]
	v_mfma_f32_16x16x32_bf16 v[66:69], v[170:173], v[212:215], v[66:69]
	v_mfma_f32_16x16x32_bf16 v[118:121], v[166:169], v[192:195], v[118:121]
	v_mfma_f32_16x16x32_bf16 v[114:117], v[174:177], v[192:195], v[114:117]
	v_mfma_f32_16x16x32_bf16 v[102:105], v[166:169], v[200:203], v[102:105]
	v_mfma_f32_16x16x32_bf16 v[98:101], v[174:177], v[200:203], v[98:101]
	v_mfma_f32_16x16x32_bf16 v[86:89], v[166:169], v[208:211], v[86:89]
	v_mfma_f32_16x16x32_bf16 v[82:85], v[174:177], v[208:211], v[82:85]
	v_mfma_f32_16x16x32_bf16 v[70:73], v[166:169], v[216:219], v[70:73]
	v_mfma_f32_16x16x32_bf16 v[66:69], v[174:177], v[216:219], v[66:69]
	s_setprio 0
	s_barrier
	s_add_i32 s62, s62, s27
	v_lshl_add_u64 v[142:143], s[14:15], 0, v[132:133]
	s_mov_b32 m0, s62
	ds_read_b128 v[188:191], v144 offset:16384
	ds_read_b128 v[192:195], v144 offset:17408
	ds_read_b128 v[196:199], v144 offset:18432
	ds_read_b128 v[200:203], v144 offset:19456
	ds_read_b128 v[204:207], v144 offset:20480
	ds_read_b128 v[208:211], v144 offset:21504
	ds_read_b128 v[212:215], v144 offset:22528
	ds_read_b128 v[216:219], v144 offset:23552
	global_load_lds_dwordx4 v[142:143], off
	s_add_i32 m0, s62, 0x2000
	s_add_u32 s62, s14, 0x80000
	v_lshl_add_u64 v[178:179], s[14:15], 0, v[136:137]
	s_addc_u32 s63, s15, 0
	s_add_i32 s64, s64, s27
	global_load_lds_dwordx4 v[178:179], off
	v_lshl_add_u64 v[184:185], s[62:63], 0, v[132:133]
	s_mov_b32 m0, s64
	v_lshl_add_u64 v[220:221], s[22:23], 0, v[134:135]
	global_load_lds_dwordx4 v[184:185], off
	v_lshl_add_u64 v[184:185], s[62:63], 0, v[136:137]
	s_add_i32 m0, s64, 0x2000
	s_nop 0
	global_load_lds_dwordx4 v[184:185], off
	v_lshl_add_u64 v[184:185], s[22:23], 0, v[130:131]
	s_mov_b32 m0, s19
	s_nop 0
	global_load_lds_dwordx4 v[184:185], off
	s_mov_b32 m0, s28
	s_nop 0
	global_load_lds_dwordx4 v[220:221], off
	s_waitcnt vmcnt(8)
	s_waitcnt lgkmcnt(0)
	s_setprio 1
	s_barrier
; #define PG8_STAGE(bufoff, gbase, voff) do { _Pragma("unroll") for (int _i = 0; _i < 2; ++_i) \
;         __builtin_amdgcn_global_load_lds((const unsigned*)((const char*)(gbase) + (voff)[_i]), (LAS unsigned*)(lds + (bufoff) + ldsw + _i * 8192), 16, 0, 0); } while (0)
; #define PG8_LDA(dst, b, h) do { _Pragma("unroll") for (int m = 0; m < 4; ++m) _Pragma("unroll") for (int k = 0; k < 2; ++k) dst[m][k] = *(const LAS bf16x8*)(lds + PG8_SA(b, h) + aoff + m * 2048 + k * 1024); } while (0)
; #define PG8_LDB(dst, b, h) do { _Pragma("unroll") for (int n = 0; n < 2; ++n) _Pragma("unroll") for (int k = 0; k < 2; ++k) dst[n][k] = *(const LAS bf16x8*)(lds + PG8_SB(b, h) + boff + n * 2048 + k * 1024); } while (0)
; #define PG8_MMA(ai, bj, At, Bt) do { __builtin_amdgcn_s_setprio(1); _Pragma("unroll") for (int m = 0; m < 4; ++m) _Pragma("unroll") for (int n = 0; n < 2; ++n) _Pragma("unroll") for (int k = 0; k < 2; ++k) \
;         acc[ai][bj][m][n] = __builtin_amdgcn_mfma_f32_16x16x32_bf16(Bt[n][k], At[m][k], acc[ai][bj][m][n], 0, 0, 0); __builtin_amdgcn_s_setprio(0); } while (0)
; #define PG8_WAIT_V(n) asm volatile("s_waitcnt vmcnt(" #n ")" ::: "memory")
; #define PG8_WAIT_L(n) asm volatile("s_waitcnt lgkmcnt(" #n ")" ::: "memory")
; #define PG8_BAR __builtin_amdgcn_s_barrier()
; #define PG8_SCHED __builtin_amdgcn_sched_barrier(0)
; template <class Epi>
; __device__ __forceinline__ void gemm_phase(LAS unsigned char* lds, const Gemm g, const StaticOrder& S, const Epi& E) {
;     ...
;             PG8_WAIT_V(8); PG8_WAIT_L(0); PG8_BAR; PG8_MMA(1, 0, At, B0); PG8_MMA(1, 1, At, B1); PG8_BAR; PG8_SCHED;
;             PG8_LDB(B0, 1, 0); PG8_LDB(B1, 1, 1); PG8_SCHED; PG8_LDA(At, 1, 0); PG8_STAGE(PG8_SA(0, 1), a2 + hstepA, voffA);
;             PG8_WAIT_V(8); PG8_WAIT_L(0); PG8_BAR; PG8_MMA(0, 0, At, B0); PG8_MMA(0, 1, At, B1); PG8_BAR; PG8_SCHED;
;             PG8_LDA(At, 1, 1); PG8_STAGE(PG8_SB(1, 0), b3, voffB); PG8_STAGE(PG8_SB(1, 1), b3 + hstepB, voffB); PG8_STAGE(PG8_SA(1, 0), a3, voffA);
;             PG8_WAIT_V(8); PG8_WAIT_L(0); PG8_BAR; PG8_MMA(1, 0, At, B0); PG8_MMA(1, 1, At, B1); PG8_BAR; PG8_SCHED;
	s_waitcnt lgkmcnt(0)
	v_mfma_f32_16x16x32_bf16 v[62:65], v[146:149], v[188:191], v[62:65]
	v_mfma_f32_16x16x32_bf16 v[58:61], v[154:157], v[188:191], v[58:61]
	v_mfma_f32_16x16x32_bf16 v[46:49], v[146:149], v[196:199], v[46:49]
	v_mfma_f32_16x16x32_bf16 v[42:45], v[154:157], v[196:199], v[42:45]
	v_mfma_f32_16x16x32_bf16 v[30:33], v[146:149], v[204:207], v[30:33]
	v_mfma_f32_16x16x32_bf16 v[26:29], v[154:157], v[204:207], v[26:29]
	v_mfma_f32_16x16x32_bf16 v[14:17], v[146:149], v[212:215], v[14:17]
	v_mfma_f32_16x16x32_bf16 v[10:13], v[154:157], v[212:215], v[10:13]
	v_mfma_f32_16x16x32_bf16 v[62:65], v[150:153], v[192:195], v[62:65]
	v_mfma_f32_16x16x32_bf16 v[58:61], v[158:161], v[192:195], v[58:61]
	v_mfma_f32_16x16x32_bf16 v[46:49], v[150:153], v[200:203], v[46:49]
	v_mfma_f32_16x16x32_bf16 v[42:45], v[158:161], v[200:203], v[42:45]
	v_mfma_f32_16x16x32_bf16 v[30:33], v[150:153], v[208:211], v[30:33]
	v_mfma_f32_16x16x32_bf16 v[26:29], v[158:161], v[208:211], v[26:29]
	v_mfma_f32_16x16x32_bf16 v[14:17], v[150:153], v[216:219], v[14:17]
	v_mfma_f32_16x16x32_bf16 v[10:13], v[158:161], v[216:219], v[10:13]
	v_mfma_f32_16x16x32_bf16 v[54:57], v[162:165], v[188:191], v[54:57]
	v_mfma_f32_16x16x32_bf16 v[50:53], v[170:173], v[188:191], v[50:53]
	v_mfma_f32_16x16x32_bf16 v[38:41], v[162:165], v[196:199], v[38:41]
	v_mfma_f32_16x16x32_bf16 v[34:37], v[170:173], v[196:199], v[34:37]
	v_mfma_f32_16x16x32_bf16 v[22:25], v[162:165], v[204:207], v[22:25]
	v_mfma_f32_16x16x32_bf16 v[18:21], v[170:173], v[204:207], v[18:21]
	v_mfma_f32_16x16x32_bf16 v[6:9], v[162:165], v[212:215], v[6:9]
	v_mfma_f32_16x16x32_bf16 v[2:5], v[170:173], v[212:215], v[2:5]
	v_mfma_f32_16x16x32_bf16 v[54:57], v[166:169], v[192:195], v[54:57]
	v_mfma_f32_16x16x32_bf16 v[50:53], v[174:177], v[192:195], v[50:53]
	v_mfma_f32_16x16x32_bf16 v[38:41], v[166:169], v[200:203], v[38:41]
	v_mfma_f32_16x16x32_bf16 v[34:37], v[174:177], v[200:203], v[34:37]
	v_mfma_f32_16x16x32_bf16 v[22:25], v[166:169], v[208:211], v[22:25]
	v_mfma_f32_16x16x32_bf16 v[18:21], v[174:177], v[208:211], v[18:21]
	v_mfma_f32_16x16x32_bf16 v[6:9], v[166:169], v[216:219], v[6:9]
	v_mfma_f32_16x16x32_bf16 v[2:5], v[174:177], v[216:219], v[2:5]
	s_setprio 0
	s_barrier
	s_add_i32 s62, 0, 0x18000
	v_add_u32_e32 v145, s62, v1
	s_add_i32 s63, 0, 0x1c000
	ds_read_b128 v[146:149], v145
	ds_read_b128 v[150:153], v145 offset:1024
	ds_read_b128 v[154:157], v145 offset:2048
	ds_read_b128 v[158:161], v145 offset:3072
	v_add_u32_e32 v145, s63, v1
	ds_read_b128 v[162:165], v145
	ds_read_b128 v[166:169], v145 offset:1024
	ds_read_b128 v[170:173], v145 offset:2048
	ds_read_b128 v[174:177], v145 offset:3072
	s_add_u32 s22, s22, 0x80000
	s_addc_u32 s23, s23, 0
	s_mov_b32 m0, s29
	v_lshl_add_u64 v[222:223], s[22:23], 0, v[130:131]
	ds_read_b128 v[188:191], v144 offset:32768
	ds_read_b128 v[192:195], v144 offset:33792
	ds_read_b128 v[196:199], v144 offset:34816
	ds_read_b128 v[200:203], v144 offset:35840
	ds_read_b128 v[204:207], v144 offset:36864
	ds_read_b128 v[208:211], v144 offset:37888
	ds_read_b128 v[212:215], v144 offset:38912
	ds_read_b128 v[216:219], v144 offset:39936
	global_load_lds_dwordx4 v[222:223], off
	v_lshl_add_u64 v[222:223], s[22:23], 0, v[134:135]
	s_mov_b32 m0, s30
	s_nop 0
	global_load_lds_dwordx4 v[222:223], off
	s_waitcnt vmcnt(8)
	s_waitcnt lgkmcnt(0)
	s_setprio 1
	s_barrier
	s_waitcnt lgkmcnt(0)
	v_mfma_f32_16x16x32_bf16 v[126:129], v[146:149], v[188:191], v[126:129]
	v_mfma_f32_16x16x32_bf16 v[122:125], v[154:157], v[188:191], v[122:125]
	v_mfma_f32_16x16x32_bf16 v[110:113], v[146:149], v[196:199], v[110:113]
	v_mfma_f32_16x16x32_bf16 v[106:109], v[154:157], v[196:199], v[106:109]
	v_mfma_f32_16x16x32_bf16 v[94:97], v[146:149], v[204:207], v[94:97]
	v_mfma_f32_16x16x32_bf16 v[90:93], v[154:157], v[204:207], v[90:93]
	v_mfma_f32_16x16x32_bf16 v[78:81], v[146:149], v[212:215], v[78:81]
	v_mfma_f32_16x16x32_bf16 v[74:77], v[154:157], v[212:215], v[74:77]
	v_mfma_f32_16x16x32_bf16 v[126:129], v[150:153], v[192:195], v[126:129]
	v_mfma_f32_16x16x32_bf16 v[122:125], v[158:161], v[192:195], v[122:125]
	v_mfma_f32_16x16x32_bf16 v[110:113], v[150:153], v[200:203], v[110:113]
	v_mfma_f32_16x16x32_bf16 v[106:109], v[158:161], v[200:203], v[106:109]
	v_mfma_f32_16x16x32_bf16 v[94:97], v[150:153], v[208:211], v[94:97]
	v_mfma_f32_16x16x32_bf16 v[90:93], v[158:161], v[208:211], v[90:93]
	v_mfma_f32_16x16x32_bf16 v[78:81], v[150:153], v[216:219], v[78:81]
	v_mfma_f32_16x16x32_bf16 v[74:77], v[158:161], v[216:219], v[74:77]
	v_mfma_f32_16x16x32_bf16 v[118:121], v[162:165], v[188:191], v[118:121]
	v_mfma_f32_16x16x32_bf16 v[114:117], v[170:173], v[188:191], v[114:117]
	v_mfma_f32_16x16x32_bf16 v[102:105], v[162:165], v[196:199], v[102:105]
	v_mfma_f32_16x16x32_bf16 v[98:101], v[170:173], v[196:199], v[98:101]
	v_mfma_f32_16x16x32_bf16 v[86:89], v[162:165], v[204:207], v[86:89]
	v_mfma_f32_16x16x32_bf16 v[82:85], v[170:173], v[204:207], v[82:85]
	v_mfma_f32_16x16x32_bf16 v[70:73], v[162:165], v[212:215], v[70:73]
	v_mfma_f32_16x16x32_bf16 v[66:69], v[170:173], v[212:215], v[66:69]
	v_mfma_f32_16x16x32_bf16 v[118:121], v[166:169], v[192:195], v[118:121]
	v_mfma_f32_16x16x32_bf16 v[114:117], v[174:177], v[192:195], v[114:117]
	v_mfma_f32_16x16x32_bf16 v[102:105], v[166:169], v[200:203], v[102:105]
	v_mfma_f32_16x16x32_bf16 v[98:101], v[174:177], v[200:203], v[98:101]
	v_mfma_f32_16x16x32_bf16 v[86:89], v[166:169], v[208:211], v[86:89]
	v_mfma_f32_16x16x32_bf16 v[82:85], v[174:177], v[208:211], v[82:85]
	v_mfma_f32_16x16x32_bf16 v[70:73], v[166:169], v[216:219], v[70:73]
	v_mfma_f32_16x16x32_bf16 v[66:69], v[174:177], v[216:219], v[66:69]
	s_setprio 0
	s_barrier
; #define PG8_STAGE(bufoff, gbase, voff) do { _Pragma("unroll") for (int _i = 0; _i < 2; ++_i) \
;         __builtin_amdgcn_global_load_lds((const unsigned*)((const char*)(gbase) + (voff)[_i]), (LAS unsigned*)(lds + (bufoff) + ldsw + _i * 8192), 16, 0, 0); } while (0)
; #define PG8_LDA(dst, b, h) do { _Pragma("unroll") for (int m = 0; m < 4; ++m) _Pragma("unroll") for (int k = 0; k < 2; ++k) dst[m][k] = *(const LAS bf16x8*)(lds + PG8_SA(b, h) + aoff + m * 2048 + k * 1024); } while (0)
; #define PG8_MMA(ai, bj, At, Bt) do { __builtin_amdgcn_s_setprio(1); _Pragma("unroll") for (int m = 0; m < 4; ++m) _Pragma("unroll") for (int n = 0; n < 2; ++n) _Pragma("unroll") for (int k = 0; k < 2; ++k) \
;         acc[ai][bj][m][n] = __builtin_amdgcn_mfma_f32_16x16x32_bf16(Bt[n][k], At[m][k], acc[ai][bj][m][n], 0, 0, 0); __builtin_amdgcn_s_setprio(0); } while (0)
; #define PG8_WAIT_V(n) asm volatile("s_waitcnt vmcnt(" #n ")" ::: "memory")
; #define PG8_WAIT_L(n) asm volatile("s_waitcnt lgkmcnt(" #n ")" ::: "memory")
; #define PG8_BAR __builtin_amdgcn_s_barrier()
; #define PG8_SCHED __builtin_amdgcn_sched_barrier(0)
; template <class Epi>
; __device__ __forceinline__ void gemm_phase(LAS unsigned char* lds, const Gemm g, const StaticOrder& S, const Epi& E) {
;     ...
;             PG8_LDA(At, 1, 1); PG8_STAGE(PG8_SB(1, 0), b3, voffB); PG8_STAGE(PG8_SB(1, 1), b3 + hstepB, voffB); PG8_STAGE(PG8_SA(1, 0), a3, voffA);
;             PG8_WAIT_V(8); PG8_WAIT_L(0); PG8_BAR; PG8_MMA(1, 0, At, B0); PG8_MMA(1, 1, At, B1); PG8_BAR; PG8_SCHED;
;         }
	s_add_i32 s22, s62, s27
	v_lshl_add_u64 v[142:143], v[142:143], 0, s[84:85]
	s_mov_b32 m0, s22
	ds_read_b128 v[188:191], v144 offset:49152
	ds_read_b128 v[192:195], v144 offset:50176
	ds_read_b128 v[196:199], v144 offset:51200
	ds_read_b128 v[200:203], v144 offset:52224
	ds_read_b128 v[204:207], v144 offset:53248
	ds_read_b128 v[208:211], v144 offset:54272
	ds_read_b128 v[212:215], v144 offset:55296
	ds_read_b128 v[216:219], v144 offset:56320
	global_load_lds_dwordx4 v[142:143], off
	s_add_i32 m0, s22, 0x2000
	s_add_u32 s14, s14, 0x80080
	v_lshl_add_u64 v[142:143], v[178:179], 0, s[84:85]
	s_addc_u32 s15, s15, 0
	s_add_i32 s22, s63, s27
	global_load_lds_dwordx4 v[142:143], off
	v_lshl_add_u64 v[142:143], s[14:15], 0, v[132:133]
	s_mov_b32 m0, s22
	s_nop 0
	global_load_lds_dwordx4 v[142:143], off
	v_lshl_add_u64 v[142:143], s[14:15], 0, v[136:137]
	s_add_i32 m0, s22, 0x2000
	s_nop 0
	global_load_lds_dwordx4 v[142:143], off
	v_lshl_add_u64 v[142:143], v[184:185], 0, s[84:85]
	s_mov_b32 m0, s34
	s_nop 0
	global_load_lds_dwordx4 v[142:143], off
	v_lshl_add_u64 v[142:143], v[220:221], 0, s[84:85]
	s_mov_b32 m0, s35
	s_nop 0
	global_load_lds_dwordx4 v[142:143], off
	s_waitcnt vmcnt(8)
	s_waitcnt lgkmcnt(0)
	s_setprio 1
	s_barrier
	s_waitcnt lgkmcnt(0)
	v_mfma_f32_16x16x32_bf16 v[62:65], v[146:149], v[188:191], v[62:65]
	v_mfma_f32_16x16x32_bf16 v[58:61], v[154:157], v[188:191], v[58:61]
	v_mfma_f32_16x16x32_bf16 v[46:49], v[146:149], v[196:199], v[46:49]
	v_mfma_f32_16x16x32_bf16 v[42:45], v[154:157], v[196:199], v[42:45]
	v_mfma_f32_16x16x32_bf16 v[30:33], v[146:149], v[204:207], v[30:33]
	v_mfma_f32_16x16x32_bf16 v[26:29], v[154:157], v[204:207], v[26:29]
	v_mfma_f32_16x16x32_bf16 v[14:17], v[146:149], v[212:215], v[14:17]
	v_mfma_f32_16x16x32_bf16 v[10:13], v[154:157], v[212:215], v[10:13]
	v_mfma_f32_16x16x32_bf16 v[62:65], v[150:153], v[192:195], v[62:65]
	v_mfma_f32_16x16x32_bf16 v[58:61], v[158:161], v[192:195], v[58:61]
	v_mfma_f32_16x16x32_bf16 v[46:49], v[150:153], v[200:203], v[46:49]
	v_mfma_f32_16x16x32_bf16 v[42:45], v[158:161], v[200:203], v[42:45]
	v_mfma_f32_16x16x32_bf16 v[30:33], v[150:153], v[208:211], v[30:33]
	v_mfma_f32_16x16x32_bf16 v[26:29], v[158:161], v[208:211], v[26:29]
	v_mfma_f32_16x16x32_bf16 v[14:17], v[150:153], v[216:219], v[14:17]
	v_mfma_f32_16x16x32_bf16 v[10:13], v[158:161], v[216:219], v[10:13]
	v_mfma_f32_16x16x32_bf16 v[54:57], v[162:165], v[188:191], v[54:57]
	v_mfma_f32_16x16x32_bf16 v[50:53], v[170:173], v[188:191], v[50:53]
	v_mfma_f32_16x16x32_bf16 v[38:41], v[162:165], v[196:199], v[38:41]
	v_mfma_f32_16x16x32_bf16 v[34:37], v[170:173], v[196:199], v[34:37]
	v_mfma_f32_16x16x32_bf16 v[22:25], v[162:165], v[204:207], v[22:25]
	v_mfma_f32_16x16x32_bf16 v[18:21], v[170:173], v[204:207], v[18:21]
	v_mfma_f32_16x16x32_bf16 v[6:9], v[162:165], v[212:215], v[6:9]
	v_mfma_f32_16x16x32_bf16 v[2:5], v[170:173], v[212:215], v[2:5]
	v_mfma_f32_16x16x32_bf16 v[54:57], v[166:169], v[192:195], v[54:57]
	v_mfma_f32_16x16x32_bf16 v[50:53], v[174:177], v[192:195], v[50:53]
	v_mfma_f32_16x16x32_bf16 v[38:41], v[166:169], v[200:203], v[38:41]
	v_mfma_f32_16x16x32_bf16 v[34:37], v[174:177], v[200:203], v[34:37]
	v_mfma_f32_16x16x32_bf16 v[22:25], v[166:169], v[208:211], v[22:25]
	v_mfma_f32_16x16x32_bf16 v[18:21], v[174:177], v[208:211], v[18:21]
	v_mfma_f32_16x16x32_bf16 v[6:9], v[166:169], v[216:219], v[6:9]
	v_mfma_f32_16x16x32_bf16 v[2:5], v[174:177], v[216:219], v[2:5]
	s_setprio 0
	s_barrier
	s_add_i32 s41, s41, 2
	s_add_u32 s20, s20, 0x100
	s_addc_u32 s21, s21, 0
	s_add_u32 s52, s52, 0x100
	s_addc_u32 s53, s53, 0
	s_cmp_gt_u32 s41, 29
	s_cbranch_scc0 .LBB0_2130
	s_cmp_ge_u32 s74, 16
	s_cbranch_scc1 .Lwpf_d
	s_lshl_b32 s100, s74, 9
	v_add_u32_e32 v146, s100, v246
	v_lshrrev_b32_e32 v147, 2, v146
	v_and_b32_e32 v146, 3, v146
	v_lshlrev_b32_e32 v146, 7, v146
	v_lshl_add_u32 v146, v147, 14, v146
	s_add_u32 s100, s88, 0x2000000
	s_addc_u32 s101, s89, 0
	s_mov_b32 m0, 0x21000
	s_nop 0
	global_load_lds_dword v146, s[100:101]

; #define PG8_STAGE(bufoff, gbase, voff) do { _Pragma("unroll") for (int _i = 0; _i < 2; ++_i) \
;         __builtin_amdgcn_global_load_lds((const unsigned*)((const char*)(gbase) + (voff)[_i]), (LAS unsigned*)(lds + (bufoff) + ldsw + _i * 8192), 16, 0, 0); } while (0)
; #define PG8_LDA(dst, b, h) do { _Pragma("unroll") for (int m = 0; m < 4; ++m) _Pragma("unroll") for (int k = 0; k < 2; ++k) dst[m][k] = *(const LAS bf16x8*)(lds + PG8_SA(b, h) + aoff + m * 2048 + k * 1024); } while (0)
; #define PG8_LDB(dst, b, h) do { _Pragma("unroll") for (int n = 0; n < 2; ++n) _Pragma("unroll") for (int k = 0; k < 2; ++k) dst[n][k] = *(const LAS bf16x8*)(lds + PG8_SB(b, h) + boff + n * 2048 + k * 1024); } while (0)
; #define PG8_MMA(ai, bj, At, Bt) do { __builtin_amdgcn_s_setprio(1); _Pragma("unroll") for (int m = 0; m < 4; ++m) _Pragma("unroll") for (int n = 0; n < 2; ++n) _Pragma("unroll") for (int k = 0; k < 2; ++k) \
;         acc[ai][bj][m][n] = __builtin_amdgcn_mfma_f32_16x16x32_bf16(Bt[n][k], At[m][k], acc[ai][bj][m][n], 0, 0, 0); __builtin_amdgcn_s_setprio(0); } while (0)
; #define PG8_WAIT_V(n) asm volatile("s_waitcnt vmcnt(" #n ")" ::: "memory")
; #define PG8_WAIT_L(n) asm volatile("s_waitcnt lgkmcnt(" #n ")" ::: "memory")
; #define PG8_BAR __builtin_amdgcn_s_barrier()
; #define PG8_SCHED __builtin_amdgcn_sched_barrier(0)
; template <class Epi>
; __device__ __forceinline__ void gemm_phase(LAS unsigned char* lds, const Gemm g, const StaticOrder& S, const Epi& E) {
;     ...
;         for (int t = 0; t < nt; t += 2) {
;             const bool last = (t == nt - 2);
;             const char* a1 = cA + (size_t)(t + 1) * kstep;
;             const char* a2 = last ? nA : cA + (size_t)(t + 2) * kstep; const char* b2 = last ? nB : cB + (size_t)(t + 2) * kstep;
;             const char* a3 = a2 + kstep; const char* b3 = b2 + kstep;
;             PG8_LDB(B0, 0, 0); PG8_LDB(B1, 0, 1); PG8_SCHED; PG8_LDA(At, 0, 0); PG8_STAGE(PG8_SA(1, 1), a1 + hstepA, voffA);
;             PG8_WAIT_V(8); PG8_WAIT_L(0); PG8_BAR; PG8_MMA(0, 0, At, B0); PG8_MMA(0, 1, At, B1); PG8_BAR; PG8_SCHED;
;             PG8_LDA(At, 0, 1); PG8_STAGE(PG8_SB(0, 0), b2, voffB); PG8_STAGE(PG8_SB(0, 1), b2 + hstepB, voffB); PG8_STAGE(PG8_SA(0, 0), a2, voffA);
;             PG8_WAIT_V(8); PG8_WAIT_L(0); PG8_BAR; PG8_MMA(1, 0, At, B0); PG8_MMA(1, 1, At, B1); PG8_BAR; PG8_SCHED;
.LBB0_2155:
	s_add_u32 s41, s20, s14
	s_addc_u32 s44, s21, 0
	s_add_u32 s15, s41, 0x100
	s_addc_u32 s34, s44, 0
	s_and_b64 s[30:31], s[28:29], exec
	s_cselect_b32 s31, s19, s34
	s_cselect_b32 s30, s3, s15
	s_add_u32 s14, s12, s14
	s_addc_u32 s15, s13, 0
	s_add_u32 s34, s14, 0x100
	s_addc_u32 s35, s15, 0
	s_add_i32 s81, 0, 0x10000
	s_and_b64 s[14:15], s[28:29], exec
	s_cselect_b32 s35, s17, s35
	s_cselect_b32 s34, s40, s34
	s_add_i32 s29, 0, 0x14000
	s_add_u32 s68, s41, 0x10080
	s_addc_u32 s69, s44, 0
	s_add_i32 s80, s81, s63
	s_add_i32 m0, s11, 0xc000
	s_add_i32 s83, s11, 0xe000
	s_add_i32 s77, s80, 0x2000
	v_add_u32_e32 v139, s81, v1
	s_add_u32 s44, s34, 0x10000
	ds_read_b128 v[140:143], v139
	ds_read_b128 v[144:147], v139 offset:1024
	ds_read_b128 v[148:151], v139 offset:2048
	ds_read_b128 v[152:155], v139 offset:3072
	v_add_u32_e32 v139, s29, v1
	s_addc_u32 s45, s35, 0
	s_add_i32 s79, s29, s63
	ds_read_b128 v[156:159], v139
	ds_read_b128 v[160:163], v139 offset:1024
	ds_read_b128 v[164:167], v139 offset:2048
	ds_read_b128 v[168:171], v139 offset:3072
	s_add_i32 s78, s79, 0x2000
	s_add_i32 s76, 0, 0x18000
	s_add_i32 vcc_hi, 0, 0x1c000
	s_add_u32 s14, s30, 0x10000
	s_addc_u32 s15, s31, 0
	s_add_i32 vcc_lo, s76, s63
	s_add_i32 s41, vcc_lo, 0x2000
	s_add_u32 s28, s34, 0x10080
	s_addc_u32 s29, s35, 0
	s_add_i32 s82, vcc_hi, s63
	s_add_i32 s81, s82, 0x2000
	v_lshl_add_u64 v[184:185], s[68:69], 0, v[130:131]
	ds_read_b128 v[172:175], v138
	ds_read_b128 v[176:179], v138 offset:1024
	ds_read_b128 v[188:191], v138 offset:2048
	ds_read_b128 v[192:195], v138 offset:3072
	ds_read_b128 v[196:199], v138 offset:4096
	ds_read_b128 v[200:203], v138 offset:5120
	ds_read_b128 v[204:207], v138 offset:6144
	ds_read_b128 v[208:211], v138 offset:7168
	global_load_lds_dwordx4 v[184:185], off
	v_lshl_add_u64 v[184:185], s[68:69], 0, v[134:135]
	s_mov_b32 m0, s83
	s_nop 0
	global_load_lds_dwordx4 v[184:185], off
	s_waitcnt vmcnt(8)
	s_waitcnt lgkmcnt(0)
	s_setprio 1
	s_barrier
	s_waitcnt lgkmcnt(0)
	v_mfma_f32_16x16x32_bf16 v[126:129], v[140:143], v[172:175], v[126:129]
	v_mfma_f32_16x16x32_bf16 v[122:125], v[148:151], v[172:175], v[122:125]
	v_mfma_f32_16x16x32_bf16 v[118:121], v[140:143], v[188:191], v[118:121]
	v_mfma_f32_16x16x32_bf16 v[114:117], v[148:151], v[188:191], v[114:117]
	v_mfma_f32_16x16x32_bf16 v[102:105], v[140:143], v[196:199], v[102:105]
	v_mfma_f32_16x16x32_bf16 v[98:101], v[148:151], v[196:199], v[98:101]
	v_mfma_f32_16x16x32_bf16 v[86:89], v[140:143], v[204:207], v[86:89]
	v_mfma_f32_16x16x32_bf16 v[82:85], v[148:151], v[204:207], v[82:85]
	v_mfma_f32_16x16x32_bf16 v[126:129], v[144:147], v[176:179], v[126:129]
	v_mfma_f32_16x16x32_bf16 v[122:125], v[152:155], v[176:179], v[122:125]
	v_mfma_f32_16x16x32_bf16 v[118:121], v[144:147], v[192:195], v[118:121]
	v_mfma_f32_16x16x32_bf16 v[114:117], v[152:155], v[192:195], v[114:117]
	v_mfma_f32_16x16x32_bf16 v[102:105], v[144:147], v[200:203], v[102:105]
	v_mfma_f32_16x16x32_bf16 v[98:101], v[152:155], v[200:203], v[98:101]
	v_mfma_f32_16x16x32_bf16 v[86:89], v[144:147], v[208:211], v[86:89]
	v_mfma_f32_16x16x32_bf16 v[82:85], v[152:155], v[208:211], v[82:85]
	v_mfma_f32_16x16x32_bf16 v[110:113], v[156:159], v[172:175], v[110:113]
	v_mfma_f32_16x16x32_bf16 v[106:109], v[164:167], v[172:175], v[106:109]
	v_mfma_f32_16x16x32_bf16 v[94:97], v[156:159], v[188:191], v[94:97]
	v_mfma_f32_16x16x32_bf16 v[90:93], v[164:167], v[188:191], v[90:93]
	v_mfma_f32_16x16x32_bf16 v[78:81], v[156:159], v[196:199], v[78:81]
	v_mfma_f32_16x16x32_bf16 v[74:77], v[164:167], v[196:199], v[74:77]
	v_mfma_f32_16x16x32_bf16 v[70:73], v[156:159], v[204:207], v[70:73]
	v_mfma_f32_16x16x32_bf16 v[66:69], v[164:167], v[204:207], v[66:69]
	v_mfma_f32_16x16x32_bf16 v[110:113], v[160:163], v[176:179], v[110:113]
	v_mfma_f32_16x16x32_bf16 v[106:109], v[168:171], v[176:179], v[106:109]
	v_mfma_f32_16x16x32_bf16 v[94:97], v[160:163], v[192:195], v[94:97]
	v_mfma_f32_16x16x32_bf16 v[90:93], v[168:171], v[192:195], v[90:93]
	v_mfma_f32_16x16x32_bf16 v[78:81], v[160:163], v[200:203], v[78:81]
	v_mfma_f32_16x16x32_bf16 v[74:77], v[168:171], v[200:203], v[74:77]
	v_mfma_f32_16x16x32_bf16 v[70:73], v[160:163], v[208:211], v[70:73]
	v_mfma_f32_16x16x32_bf16 v[66:69], v[168:171], v[208:211], v[66:69]
	s_setprio 0
	s_barrier
	s_mov_b32 m0, s80
	v_lshl_add_u64 v[184:185], s[34:35], 0, v[132:133]
	ds_read_b128 v[172:175], v138 offset:16384
	ds_read_b128 v[176:179], v138 offset:17408
	ds_read_b128 v[188:191], v138 offset:18432
	ds_read_b128 v[192:195], v138 offset:19456
	ds_read_b128 v[196:199], v138 offset:20480
	ds_read_b128 v[200:203], v138 offset:21504
	ds_read_b128 v[204:207], v138 offset:22528
	ds_read_b128 v[208:211], v138 offset:23552
	global_load_lds_dwordx4 v[184:185], off
	v_lshl_add_u64 v[212:213], s[34:35], 0, v[136:137]
	s_mov_b32 m0, s77
	v_lshl_add_u64 v[214:215], s[44:45], 0, v[132:133]
	global_load_lds_dwordx4 v[212:213], off
	s_mov_b32 m0, s79
	v_lshl_add_u64 v[216:217], s[30:31], 0, v[134:135]
	global_load_lds_dwordx4 v[214:215], off
	v_lshl_add_u64 v[214:215], s[44:45], 0, v[136:137]
	s_mov_b32 m0, s78
	s_nop 0
	global_load_lds_dwordx4 v[214:215], off
	v_lshl_add_u64 v[214:215], s[30:31], 0, v[130:131]
	s_mov_b32 m0, s11
	s_nop 0
	global_load_lds_dwordx4 v[214:215], off
	s_mov_b32 m0, s64
	s_nop 0
	global_load_lds_dwordx4 v[216:217], off
	s_waitcnt vmcnt(8)
	s_waitcnt lgkmcnt(0)
	s_setprio 1
	s_barrier
; #define PG8_STAGE(bufoff, gbase, voff) do { _Pragma("unroll") for (int _i = 0; _i < 2; ++_i) \
;         __builtin_amdgcn_global_load_lds((const unsigned*)((const char*)(gbase) + (voff)[_i]), (LAS unsigned*)(lds + (bufoff) + ldsw + _i * 8192), 16, 0, 0); } while (0)
; #define PG8_LDA(dst, b, h) do { _Pragma("unroll") for (int m = 0; m < 4; ++m) _Pragma("unroll") for (int k = 0; k < 2; ++k) dst[m][k] = *(const LAS bf16x8*)(lds + PG8_SA(b, h) + aoff + m * 2048 + k * 1024); } while (0)
; #define PG8_LDB(dst, b, h) do { _Pragma("unroll") for (int n = 0; n < 2; ++n) _Pragma("unroll") for (int k = 0; k < 2; ++k) dst[n][k] = *(const LAS bf16x8*)(lds + PG8_SB(b, h) + boff + n * 2048 + k * 1024); } while (0)
; #define PG8_MMA(ai, bj, At, Bt) do { __builtin_amdgcn_s_setprio(1); _Pragma("unroll") for (int m = 0; m < 4; ++m) _Pragma("unroll") for (int n = 0; n < 2; ++n) _Pragma("unroll") for (int k = 0; k < 2; ++k) \
;         acc[ai][bj][m][n] = __builtin_amdgcn_mfma_f32_16x16x32_bf16(Bt[n][k], At[m][k], acc[ai][bj][m][n], 0, 0, 0); __builtin_amdgcn_s_setprio(0); } while (0)
; #define PG8_WAIT_V(n) asm volatile("s_waitcnt vmcnt(" #n ")" ::: "memory")
; #define PG8_WAIT_L(n) asm volatile("s_waitcnt lgkmcnt(" #n ")" ::: "memory")
; #define PG8_BAR __builtin_amdgcn_s_barrier()
; #define PG8_SCHED __builtin_amdgcn_sched_barrier(0)
; template <class Epi>
; __device__ __forceinline__ void gemm_phase(LAS unsigned char* lds, const Gemm g, const StaticOrder& S, const Epi& E) {
;     ...
;             PG8_WAIT_V(8); PG8_WAIT_L(0); PG8_BAR; PG8_MMA(1, 0, At, B0); PG8_MMA(1, 1, At, B1); PG8_BAR; PG8_SCHED;
;             PG8_LDB(B0, 1, 0); PG8_LDB(B1, 1, 1); PG8_SCHED; PG8_LDA(At, 1, 0); PG8_STAGE(PG8_SA(0, 1), a2 + hstepA, voffA);
;             PG8_WAIT_V(8); PG8_WAIT_L(0); PG8_BAR; PG8_MMA(0, 0, At, B0); PG8_MMA(0, 1, At, B1); PG8_BAR; PG8_SCHED;
;             PG8_LDA(At, 1, 1); PG8_STAGE(PG8_SB(1, 0), b3, voffB); PG8_STAGE(PG8_SB(1, 1), b3 + hstepB, voffB); PG8_STAGE(PG8_SA(1, 0), a3, voffA);
;             PG8_WAIT_V(8); PG8_WAIT_L(0); PG8_BAR; PG8_MMA(1, 0, At, B0); PG8_MMA(1, 1, At, B1); PG8_BAR; PG8_SCHED;
	s_waitcnt lgkmcnt(0)
	v_mfma_f32_16x16x32_bf16 v[62:65], v[140:143], v[172:175], v[62:65]
	v_mfma_f32_16x16x32_bf16 v[58:61], v[148:151], v[172:175], v[58:61]
	v_mfma_f32_16x16x32_bf16 v[54:57], v[140:143], v[188:191], v[54:57]
	v_mfma_f32_16x16x32_bf16 v[50:53], v[148:151], v[188:191], v[50:53]
	v_mfma_f32_16x16x32_bf16 v[38:41], v[140:143], v[196:199], v[38:41]
	v_mfma_f32_16x16x32_bf16 v[34:37], v[148:151], v[196:199], v[34:37]
	v_mfma_f32_16x16x32_bf16 v[22:25], v[140:143], v[204:207], v[22:25]
	v_mfma_f32_16x16x32_bf16 v[18:21], v[148:151], v[204:207], v[18:21]
	v_mfma_f32_16x16x32_bf16 v[62:65], v[144:147], v[176:179], v[62:65]
	v_mfma_f32_16x16x32_bf16 v[58:61], v[152:155], v[176:179], v[58:61]
	v_mfma_f32_16x16x32_bf16 v[54:57], v[144:147], v[192:195], v[54:57]
	v_mfma_f32_16x16x32_bf16 v[50:53], v[152:155], v[192:195], v[50:53]
	v_mfma_f32_16x16x32_bf16 v[38:41], v[144:147], v[200:203], v[38:41]
	v_mfma_f32_16x16x32_bf16 v[34:37], v[152:155], v[200:203], v[34:37]
	v_mfma_f32_16x16x32_bf16 v[22:25], v[144:147], v[208:211], v[22:25]
	v_mfma_f32_16x16x32_bf16 v[18:21], v[152:155], v[208:211], v[18:21]
	v_mfma_f32_16x16x32_bf16 v[46:49], v[156:159], v[172:175], v[46:49]
	v_mfma_f32_16x16x32_bf16 v[42:45], v[164:167], v[172:175], v[42:45]
	v_mfma_f32_16x16x32_bf16 v[30:33], v[156:159], v[188:191], v[30:33]
	v_mfma_f32_16x16x32_bf16 v[26:29], v[164:167], v[188:191], v[26:29]
	v_mfma_f32_16x16x32_bf16 v[14:17], v[156:159], v[196:199], v[14:17]
	v_mfma_f32_16x16x32_bf16 v[10:13], v[164:167], v[196:199], v[10:13]
	v_mfma_f32_16x16x32_bf16 v[6:9], v[156:159], v[204:207], v[6:9]
	v_mfma_f32_16x16x32_bf16 v[2:5], v[164:167], v[204:207], v[2:5]
	v_mfma_f32_16x16x32_bf16 v[46:49], v[160:163], v[176:179], v[46:49]
	v_mfma_f32_16x16x32_bf16 v[42:45], v[168:171], v[176:179], v[42:45]
	v_mfma_f32_16x16x32_bf16 v[30:33], v[160:163], v[192:195], v[30:33]
	v_mfma_f32_16x16x32_bf16 v[26:29], v[168:171], v[192:195], v[26:29]
	v_mfma_f32_16x16x32_bf16 v[14:17], v[160:163], v[200:203], v[14:17]
	v_mfma_f32_16x16x32_bf16 v[10:13], v[168:171], v[200:203], v[10:13]
	v_mfma_f32_16x16x32_bf16 v[6:9], v[160:163], v[208:211], v[6:9]
	v_mfma_f32_16x16x32_bf16 v[2:5], v[168:171], v[208:211], v[2:5]
	s_setprio 0
	s_barrier
	v_add_u32_e32 v139, s76, v1
	ds_read_b128 v[140:143], v139
	ds_read_b128 v[144:147], v139 offset:1024
	ds_read_b128 v[148:151], v139 offset:2048
	ds_read_b128 v[152:155], v139 offset:3072
	v_add_u32_e32 v139, vcc_hi, v1
	ds_read_b128 v[156:159], v139
	ds_read_b128 v[160:163], v139 offset:1024
	ds_read_b128 v[164:167], v139 offset:2048
	ds_read_b128 v[168:171], v139 offset:3072
	s_mov_b32 m0, s65
	v_lshl_add_u64 v[218:219], s[14:15], 0, v[130:131]
	ds_read_b128 v[172:175], v138 offset:32768
	ds_read_b128 v[176:179], v138 offset:33792
	ds_read_b128 v[188:191], v138 offset:34816
	ds_read_b128 v[192:195], v138 offset:35840
	ds_read_b128 v[196:199], v138 offset:36864
	ds_read_b128 v[200:203], v138 offset:37888
	ds_read_b128 v[204:207], v138 offset:38912
	ds_read_b128 v[208:211], v138 offset:39936
	global_load_lds_dwordx4 v[218:219], off
	v_lshl_add_u64 v[218:219], s[14:15], 0, v[134:135]
	s_mov_b32 m0, s70
	s_nop 0
	global_load_lds_dwordx4 v[218:219], off
	s_waitcnt vmcnt(8)
	s_waitcnt lgkmcnt(0)
	s_setprio 1
	s_barrier
	s_waitcnt lgkmcnt(0)
	v_mfma_f32_16x16x32_bf16 v[126:129], v[140:143], v[172:175], v[126:129]
	v_mfma_f32_16x16x32_bf16 v[122:125], v[148:151], v[172:175], v[122:125]
	v_mfma_f32_16x16x32_bf16 v[118:121], v[140:143], v[188:191], v[118:121]
	v_mfma_f32_16x16x32_bf16 v[114:117], v[148:151], v[188:191], v[114:117]
	v_mfma_f32_16x16x32_bf16 v[102:105], v[140:143], v[196:199], v[102:105]
	v_mfma_f32_16x16x32_bf16 v[98:101], v[148:151], v[196:199], v[98:101]
	v_mfma_f32_16x16x32_bf16 v[86:89], v[140:143], v[204:207], v[86:89]
	v_mfma_f32_16x16x32_bf16 v[82:85], v[148:151], v[204:207], v[82:85]
	v_mfma_f32_16x16x32_bf16 v[126:129], v[144:147], v[176:179], v[126:129]
	v_mfma_f32_16x16x32_bf16 v[122:125], v[152:155], v[176:179], v[122:125]
	v_mfma_f32_16x16x32_bf16 v[118:121], v[144:147], v[192:195], v[118:121]
	v_mfma_f32_16x16x32_bf16 v[114:117], v[152:155], v[192:195], v[114:117]
	v_mfma_f32_16x16x32_bf16 v[102:105], v[144:147], v[200:203], v[102:105]
	v_mfma_f32_16x16x32_bf16 v[98:101], v[152:155], v[200:203], v[98:101]
	v_mfma_f32_16x16x32_bf16 v[86:89], v[144:147], v[208:211], v[86:89]
	v_mfma_f32_16x16x32_bf16 v[82:85], v[152:155], v[208:211], v[82:85]
	v_mfma_f32_16x16x32_bf16 v[110:113], v[156:159], v[172:175], v[110:113]
	v_mfma_f32_16x16x32_bf16 v[106:109], v[164:167], v[172:175], v[106:109]
	v_mfma_f32_16x16x32_bf16 v[94:97], v[156:159], v[188:191], v[94:97]
	v_mfma_f32_16x16x32_bf16 v[90:93], v[164:167], v[188:191], v[90:93]
	v_mfma_f32_16x16x32_bf16 v[78:81], v[156:159], v[196:199], v[78:81]
	v_mfma_f32_16x16x32_bf16 v[74:77], v[164:167], v[196:199], v[74:77]
	v_mfma_f32_16x16x32_bf16 v[70:73], v[156:159], v[204:207], v[70:73]
	v_mfma_f32_16x16x32_bf16 v[66:69], v[164:167], v[204:207], v[66:69]
	v_mfma_f32_16x16x32_bf16 v[110:113], v[160:163], v[176:179], v[110:113]
	v_mfma_f32_16x16x32_bf16 v[106:109], v[168:171], v[176:179], v[106:109]
	v_mfma_f32_16x16x32_bf16 v[94:97], v[160:163], v[192:195], v[94:97]
	v_mfma_f32_16x16x32_bf16 v[90:93], v[168:171], v[192:195], v[90:93]
	v_mfma_f32_16x16x32_bf16 v[78:81], v[160:163], v[200:203], v[78:81]
	v_mfma_f32_16x16x32_bf16 v[74:77], v[168:171], v[200:203], v[74:77]
	v_mfma_f32_16x16x32_bf16 v[70:73], v[160:163], v[208:211], v[70:73]
	v_mfma_f32_16x16x32_bf16 v[66:69], v[168:171], v[208:211], v[66:69]
	s_setprio 0
	s_barrier
; #define PG8_STAGE(bufoff, gbase, voff) do { _Pragma("unroll") for (int _i = 0; _i < 2; ++_i) \
;         __builtin_amdgcn_global_load_lds((const unsigned*)((const char*)(gbase) + (voff)[_i]), (LAS unsigned*)(lds + (bufoff) + ldsw + _i * 8192), 16, 0, 0); } while (0)
; #define PG8_LDA(dst, b, h) do { _Pragma("unroll") for (int m = 0; m < 4; ++m) _Pragma("unroll") for (int k = 0; k < 2; ++k) dst[m][k] = *(const LAS bf16x8*)(lds + PG8_SA(b, h) + aoff + m * 2048 + k * 1024); } while (0)
; #define PG8_MMA(ai, bj, At, Bt) do { __builtin_amdgcn_s_setprio(1); _Pragma("unroll") for (int m = 0; m < 4; ++m) _Pragma("unroll") for (int n = 0; n < 2; ++n) _Pragma("unroll") for (int k = 0; k < 2; ++k) \
;         acc[ai][bj][m][n] = __builtin_amdgcn_mfma_f32_16x16x32_bf16(Bt[n][k], At[m][k], acc[ai][bj][m][n], 0, 0, 0); __builtin_amdgcn_s_setprio(0); } while (0)
; #define PG8_WAIT_V(n) asm volatile("s_waitcnt vmcnt(" #n ")" ::: "memory")
; #define PG8_WAIT_L(n) asm volatile("s_waitcnt lgkmcnt(" #n ")" ::: "memory")
; #define PG8_BAR __builtin_amdgcn_s_barrier()
; #define PG8_SCHED __builtin_amdgcn_sched_barrier(0)
; template <class Epi>
; __device__ __forceinline__ void gemm_phase(LAS unsigned char* lds, const Gemm g, const StaticOrder& S, const Epi& E) {
;     ...
;             PG8_LDA(At, 1, 1); PG8_STAGE(PG8_SB(1, 0), b3, voffB); PG8_STAGE(PG8_SB(1, 1), b3 + hstepB, voffB); PG8_STAGE(PG8_SA(1, 0), a3, voffA);
;             PG8_WAIT_V(8); PG8_WAIT_L(0); PG8_BAR; PG8_MMA(1, 0, At, B0); PG8_MMA(1, 1, At, B1); PG8_BAR; PG8_SCHED;
;         }
;         if (wr == 0) PG8_BAR;
	s_mov_b32 m0, vcc_lo
	v_lshl_add_u64 v[184:185], v[184:185], 0, s[84:85]
	ds_read_b128 v[172:175], v138 offset:49152
	ds_read_b128 v[176:179], v138 offset:50176
	ds_read_b128 v[188:191], v138 offset:51200
	ds_read_b128 v[192:195], v138 offset:52224
	ds_read_b128 v[196:199], v138 offset:53248
	ds_read_b128 v[200:203], v138 offset:54272
	ds_read_b128 v[204:207], v138 offset:55296
	ds_read_b128 v[208:211], v138 offset:56320
	global_load_lds_dwordx4 v[184:185], off
	v_lshl_add_u64 v[184:185], v[212:213], 0, s[84:85]
	s_mov_b32 m0, s41
	s_nop 0
	global_load_lds_dwordx4 v[184:185], off
	v_lshl_add_u64 v[184:185], s[28:29], 0, v[132:133]
	s_mov_b32 m0, s82
	s_nop 0
	global_load_lds_dwordx4 v[184:185], off
	v_lshl_add_u64 v[184:185], s[28:29], 0, v[136:137]
	s_mov_b32 m0, s81
	s_nop 0
	global_load_lds_dwordx4 v[184:185], off
	v_lshl_add_u64 v[184:185], v[214:215], 0, s[84:85]
	s_mov_b32 m0, s86
	s_nop 0
	global_load_lds_dwordx4 v[184:185], off
	v_lshl_add_u64 v[184:185], v[216:217], 0, s[84:85]
	s_mov_b32 m0, s87
	s_nop 0
	global_load_lds_dwordx4 v[184:185], off
	s_waitcnt vmcnt(8)
	s_waitcnt lgkmcnt(0)
	s_setprio 1
	s_barrier
	s_waitcnt lgkmcnt(0)
	v_mfma_f32_16x16x32_bf16 v[62:65], v[140:143], v[172:175], v[62:65]
	v_mfma_f32_16x16x32_bf16 v[58:61], v[148:151], v[172:175], v[58:61]
	v_mfma_f32_16x16x32_bf16 v[54:57], v[140:143], v[188:191], v[54:57]
	v_mfma_f32_16x16x32_bf16 v[50:53], v[148:151], v[188:191], v[50:53]
	v_mfma_f32_16x16x32_bf16 v[38:41], v[140:143], v[196:199], v[38:41]
	v_mfma_f32_16x16x32_bf16 v[34:37], v[148:151], v[196:199], v[34:37]
	v_mfma_f32_16x16x32_bf16 v[22:25], v[140:143], v[204:207], v[22:25]
	v_mfma_f32_16x16x32_bf16 v[18:21], v[148:151], v[204:207], v[18:21]
	v_mfma_f32_16x16x32_bf16 v[62:65], v[144:147], v[176:179], v[62:65]
	v_mfma_f32_16x16x32_bf16 v[58:61], v[152:155], v[176:179], v[58:61]
	v_mfma_f32_16x16x32_bf16 v[54:57], v[144:147], v[192:195], v[54:57]
	v_mfma_f32_16x16x32_bf16 v[50:53], v[152:155], v[192:195], v[50:53]
	v_mfma_f32_16x16x32_bf16 v[38:41], v[144:147], v[200:203], v[38:41]
	v_mfma_f32_16x16x32_bf16 v[34:37], v[152:155], v[200:203], v[34:37]
	v_mfma_f32_16x16x32_bf16 v[22:25], v[144:147], v[208:211], v[22:25]
	v_mfma_f32_16x16x32_bf16 v[18:21], v[152:155], v[208:211], v[18:21]
	v_mfma_f32_16x16x32_bf16 v[46:49], v[156:159], v[172:175], v[46:49]
	v_mfma_f32_16x16x32_bf16 v[42:45], v[164:167], v[172:175], v[42:45]
	v_mfma_f32_16x16x32_bf16 v[30:33], v[156:159], v[188:191], v[30:33]
	v_mfma_f32_16x16x32_bf16 v[26:29], v[164:167], v[188:191], v[26:29]
	v_mfma_f32_16x16x32_bf16 v[14:17], v[156:159], v[196:199], v[14:17]
	v_mfma_f32_16x16x32_bf16 v[10:13], v[164:167], v[196:199], v[10:13]
	v_mfma_f32_16x16x32_bf16 v[6:9], v[156:159], v[204:207], v[6:9]
	v_mfma_f32_16x16x32_bf16 v[2:5], v[164:167], v[204:207], v[2:5]
	v_mfma_f32_16x16x32_bf16 v[46:49], v[160:163], v[176:179], v[46:49]
	v_mfma_f32_16x16x32_bf16 v[42:45], v[168:171], v[176:179], v[42:45]
	v_mfma_f32_16x16x32_bf16 v[30:33], v[160:163], v[192:195], v[30:33]
	v_mfma_f32_16x16x32_bf16 v[26:29], v[168:171], v[192:195], v[26:29]
	v_mfma_f32_16x16x32_bf16 v[14:17], v[160:163], v[200:203], v[14:17]
	v_mfma_f32_16x16x32_bf16 v[10:13], v[168:171], v[200:203], v[10:13]
	v_mfma_f32_16x16x32_bf16 v[6:9], v[160:163], v[208:211], v[6:9]
	v_mfma_f32_16x16x32_bf16 v[2:5], v[168:171], v[208:211], v[2:5]
	s_setprio 0
	s_barrier
	s_movk_i32 s14, 0x100
	s_andn2_b64 vcc, exec, s[26:27]
	s_mov_b64 s[28:29], -1
	s_mov_b64 s[26:27], 0
	s_cbranch_vccz .LBB0_2155
	v_readlane_b32 s28, v255, 28
	s_and_b64 vcc, exec, s[8:9]
	v_readlane_b32 s29, v255, 29
	s_cbranch_vccz .LBB0_2158
	s_barrier

; #define PG8_STAGE(bufoff, gbase, voff) do { _Pragma("unroll") for (int _i = 0; _i < 2; ++_i) \
;         __builtin_amdgcn_global_load_lds((const unsigned*)((const char*)(gbase) + (voff)[_i]), (LAS unsigned*)(lds + (bufoff) + ldsw + _i * 8192), 16, 0, 0); } while (0)
; #define PG8_LDA(dst, b, h) do { _Pragma("unroll") for (int m = 0; m < 4; ++m) _Pragma("unroll") for (int k = 0; k < 2; ++k) dst[m][k] = *(const LAS bf16x8*)(lds + PG8_SA(b, h) + aoff + m * 2048 + k * 1024); } while (0)
; #define PG8_LDB(dst, b, h) do { _Pragma("unroll") for (int n = 0; n < 2; ++n) _Pragma("unroll") for (int k = 0; k < 2; ++k) dst[n][k] = *(const LAS bf16x8*)(lds + PG8_SB(b, h) + boff + n * 2048 + k * 1024); } while (0)
; #define PG8_MMA(ai, bj, At, Bt) do { __builtin_amdgcn_s_setprio(1); _Pragma("unroll") for (int m = 0; m < 4; ++m) _Pragma("unroll") for (int n = 0; n < 2; ++n) _Pragma("unroll") for (int k = 0; k < 2; ++k) \
;         acc[ai][bj][m][n] = __builtin_amdgcn_mfma_f32_16x16x32_bf16(Bt[n][k], At[m][k], acc[ai][bj][m][n], 0, 0, 0); __builtin_amdgcn_s_setprio(0); } while (0)
; #define PG8_WAIT_V(n) asm volatile("s_waitcnt vmcnt(" #n ")" ::: "memory")
; #define PG8_WAIT_L(n) asm volatile("s_waitcnt lgkmcnt(" #n ")" ::: "memory")
; #define PG8_BAR __builtin_amdgcn_s_barrier()
; #define PG8_SCHED __builtin_amdgcn_sched_barrier(0)
; template <class Epi>
; __device__ __forceinline__ void gemm_phase(LAS unsigned char* lds, const Gemm g, const StaticOrder& S, const Epi& E) {
;     ...
;             const bool last = (t == nt - 2);
;             const char* a1 = cA + (size_t)(t + 1) * kstep;
;             const char* a2 = last ? nA : cA + (size_t)(t + 2) * kstep; const char* b2 = last ? nB : cB + (size_t)(t + 2) * kstep;
;             const char* a3 = a2 + kstep; const char* b3 = b2 + kstep;
;             PG8_LDB(B0, 0, 0); PG8_LDB(B1, 0, 1); PG8_SCHED; PG8_LDA(At, 0, 0); PG8_STAGE(PG8_SA(1, 1), a1 + hstepA, voffA);
;             PG8_WAIT_V(8); PG8_WAIT_L(0); PG8_BAR; PG8_MMA(0, 0, At, B0); PG8_MMA(0, 1, At, B1); PG8_BAR; PG8_SCHED;
;             PG8_LDA(At, 0, 1); PG8_STAGE(PG8_SB(0, 0), b2, voffB); PG8_STAGE(PG8_SB(0, 1), b2 + hstepB, voffB); PG8_STAGE(PG8_SA(0, 0), a2, voffA);
;             PG8_WAIT_V(8); PG8_WAIT_L(0); PG8_BAR; PG8_MMA(1, 0, At, B0); PG8_MMA(1, 1, At, B1); PG8_BAR; PG8_SCHED;
.LBB0_2233:
	s_add_u32 s14, s24, 0xffe00080
	s_addc_u32 s15, s25, -1
	s_add_i32 s52, 0, 0x10000
	s_cmpk_eq_i32 s41, 0x7c
	s_cselect_b32 s27, s1, s15
	s_cselect_b32 s26, s3, s14
	s_cselect_b32 s15, s9, s40
	s_cselect_b32 s14, s17, s19
	s_add_i32 s62, 0, 0x14000
	v_add_u32_e32 v142, s52, v1
	v_add_u32_e32 v167, s62, v1
	ds_read_b128 v[130:133], v142
	ds_read_b128 v[134:137], v142 offset:1024
	ds_read_b128 v[138:141], v142 offset:2048
	ds_read_b128 v[142:145], v142 offset:3072
	ds_read_b128 v[146:149], v167
	ds_read_b128 v[162:165], v167 offset:1024
	ds_read_b128 v[168:171], v167 offset:2048
	ds_read_b128 v[172:175], v167 offset:3072
	v_lshl_add_u64 v[184:185], s[24:25], 0, v[158:159]
	s_add_i32 m0, s31, 0xc000
	ds_read_b128 v[176:179], v166
	ds_read_b128 v[188:191], v166 offset:1024
	ds_read_b128 v[192:195], v166 offset:2048
	ds_read_b128 v[196:199], v166 offset:3072
	ds_read_b128 v[200:203], v166 offset:4096
	ds_read_b128 v[204:207], v166 offset:5120
	ds_read_b128 v[208:211], v166 offset:6144
	ds_read_b128 v[212:215], v166 offset:7168
	global_load_lds_dwordx4 v[184:185], off
	v_lshl_add_u64 v[184:185], s[24:25], 0, v[160:161]
	s_add_i32 m0, s31, 0xe000
	s_nop 0
	global_load_lds_dwordx4 v[184:185], off
	s_waitcnt vmcnt(8)
	s_waitcnt lgkmcnt(0)
	s_setprio 1
	s_barrier
	s_waitcnt lgkmcnt(0)
	v_mfma_f32_16x16x32_bf16 v[126:129], v[130:133], v[176:179], v[126:129]
	v_mfma_f32_16x16x32_bf16 v[122:125], v[138:141], v[176:179], v[122:125]
	v_mfma_f32_16x16x32_bf16 v[118:121], v[130:133], v[192:195], v[118:121]
	v_mfma_f32_16x16x32_bf16 v[114:117], v[138:141], v[192:195], v[114:117]
	v_mfma_f32_16x16x32_bf16 v[94:97], v[130:133], v[200:203], v[94:97]
	v_mfma_f32_16x16x32_bf16 v[90:93], v[138:141], v[200:203], v[90:93]
	v_mfma_f32_16x16x32_bf16 v[82:85], v[130:133], v[208:211], v[82:85]
	v_mfma_f32_16x16x32_bf16 v[74:77], v[138:141], v[208:211], v[74:77]
	v_mfma_f32_16x16x32_bf16 v[126:129], v[134:137], v[188:191], v[126:129]
	v_mfma_f32_16x16x32_bf16 v[122:125], v[142:145], v[188:191], v[122:125]
	v_mfma_f32_16x16x32_bf16 v[118:121], v[134:137], v[196:199], v[118:121]
	v_mfma_f32_16x16x32_bf16 v[114:117], v[142:145], v[196:199], v[114:117]
	v_mfma_f32_16x16x32_bf16 v[94:97], v[134:137], v[204:207], v[94:97]
	v_mfma_f32_16x16x32_bf16 v[90:93], v[142:145], v[204:207], v[90:93]
	v_mfma_f32_16x16x32_bf16 v[82:85], v[134:137], v[212:215], v[82:85]
	v_mfma_f32_16x16x32_bf16 v[74:77], v[142:145], v[212:215], v[74:77]
	v_mfma_f32_16x16x32_bf16 v[110:113], v[146:149], v[176:179], v[110:113]
	v_mfma_f32_16x16x32_bf16 v[106:109], v[168:171], v[176:179], v[106:109]
	v_mfma_f32_16x16x32_bf16 v[102:105], v[146:149], v[192:195], v[102:105]
	v_mfma_f32_16x16x32_bf16 v[98:101], v[168:171], v[192:195], v[98:101]
	v_mfma_f32_16x16x32_bf16 v[86:89], v[146:149], v[200:203], v[86:89]
	v_mfma_f32_16x16x32_bf16 v[78:81], v[168:171], v[200:203], v[78:81]
	v_mfma_f32_16x16x32_bf16 v[70:73], v[146:149], v[208:211], v[70:73]
	v_mfma_f32_16x16x32_bf16 v[66:69], v[168:171], v[208:211], v[66:69]
	v_mfma_f32_16x16x32_bf16 v[110:113], v[162:165], v[188:191], v[110:113]
	v_mfma_f32_16x16x32_bf16 v[106:109], v[172:175], v[188:191], v[106:109]
	v_mfma_f32_16x16x32_bf16 v[102:105], v[162:165], v[196:199], v[102:105]
	v_mfma_f32_16x16x32_bf16 v[98:101], v[172:175], v[196:199], v[98:101]
	v_mfma_f32_16x16x32_bf16 v[86:89], v[162:165], v[204:207], v[86:89]
	v_mfma_f32_16x16x32_bf16 v[78:81], v[172:175], v[204:207], v[78:81]
	v_mfma_f32_16x16x32_bf16 v[70:73], v[162:165], v[212:215], v[70:73]
	v_mfma_f32_16x16x32_bf16 v[66:69], v[172:175], v[212:215], v[66:69]
	s_setprio 0
	s_barrier
	s_add_i32 s52, s52, s30
	v_lshl_add_u64 v[184:185], s[14:15], 0, v[152:153]
	s_mov_b32 m0, s52
	ds_read_b128 v[176:179], v166 offset:16384
	ds_read_b128 v[188:191], v166 offset:17408
	ds_read_b128 v[192:195], v166 offset:18432
	ds_read_b128 v[196:199], v166 offset:19456
	ds_read_b128 v[200:203], v166 offset:20480
	ds_read_b128 v[204:207], v166 offset:21504
	ds_read_b128 v[208:211], v166 offset:22528
	ds_read_b128 v[212:215], v166 offset:23552
	global_load_lds_dwordx4 v[184:185], off
	s_add_i32 m0, s52, 0x2000
	s_add_u32 s52, s14, 0x200000
	v_lshl_add_u64 v[216:217], s[14:15], 0, v[156:157]
	s_addc_u32 s53, s15, 0
	s_add_i32 s62, s62, s30
	global_load_lds_dwordx4 v[216:217], off
	v_lshl_add_u64 v[218:219], s[52:53], 0, v[152:153]
	s_mov_b32 m0, s62
	v_lshl_add_u64 v[220:221], s[26:27], 0, v[154:155]
	global_load_lds_dwordx4 v[218:219], off
	v_lshl_add_u64 v[218:219], s[52:53], 0, v[156:157]
	s_add_i32 m0, s62, 0x2000
	s_nop 0
	global_load_lds_dwordx4 v[218:219], off
	v_lshl_add_u64 v[218:219], s[26:27], 0, v[150:151]
	s_mov_b32 m0, s31
	s_nop 0
	global_load_lds_dwordx4 v[218:219], off
	s_mov_b32 m0, s34
	s_nop 0
	global_load_lds_dwordx4 v[220:221], off
	s_waitcnt vmcnt(8)
	s_waitcnt lgkmcnt(0)
	s_setprio 1
	s_barrier
; #define PG8_STAGE(bufoff, gbase, voff) do { _Pragma("unroll") for (int _i = 0; _i < 2; ++_i) \
;         __builtin_amdgcn_global_load_lds((const unsigned*)((const char*)(gbase) + (voff)[_i]), (LAS unsigned*)(lds + (bufoff) + ldsw + _i * 8192), 16, 0, 0); } while (0)
; #define PG8_LDA(dst, b, h) do { _Pragma("unroll") for (int m = 0; m < 4; ++m) _Pragma("unroll") for (int k = 0; k < 2; ++k) dst[m][k] = *(const LAS bf16x8*)(lds + PG8_SA(b, h) + aoff + m * 2048 + k * 1024); } while (0)
; #define PG8_LDB(dst, b, h) do { _Pragma("unroll") for (int n = 0; n < 2; ++n) _Pragma("unroll") for (int k = 0; k < 2; ++k) dst[n][k] = *(const LAS bf16x8*)(lds + PG8_SB(b, h) + boff + n * 2048 + k * 1024); } while (0)
; #define PG8_MMA(ai, bj, At, Bt) do { __builtin_amdgcn_s_setprio(1); _Pragma("unroll") for (int m = 0; m < 4; ++m) _Pragma("unroll") for (int n = 0; n < 2; ++n) _Pragma("unroll") for (int k = 0; k < 2; ++k) \
;         acc[ai][bj][m][n] = __builtin_amdgcn_mfma_f32_16x16x32_bf16(Bt[n][k], At[m][k], acc[ai][bj][m][n], 0, 0, 0); __builtin_amdgcn_s_setprio(0); } while (0)
; #define PG8_WAIT_V(n) asm volatile("s_waitcnt vmcnt(" #n ")" ::: "memory")
; #define PG8_WAIT_L(n) asm volatile("s_waitcnt lgkmcnt(" #n ")" ::: "memory")
; #define PG8_BAR __builtin_amdgcn_s_barrier()
; #define PG8_SCHED __builtin_amdgcn_sched_barrier(0)
; template <class Epi>
; __device__ __forceinline__ void gemm_phase(LAS unsigned char* lds, const Gemm g, const StaticOrder& S, const Epi& E) {
;     ...
;             PG8_WAIT_V(8); PG8_WAIT_L(0); PG8_BAR; PG8_MMA(1, 0, At, B0); PG8_MMA(1, 1, At, B1); PG8_BAR; PG8_SCHED;
;             PG8_LDB(B0, 1, 0); PG8_LDB(B1, 1, 1); PG8_SCHED; PG8_LDA(At, 1, 0); PG8_STAGE(PG8_SA(0, 1), a2 + hstepA, voffA);
;             PG8_WAIT_V(8); PG8_WAIT_L(0); PG8_BAR; PG8_MMA(0, 0, At, B0); PG8_MMA(0, 1, At, B1); PG8_BAR; PG8_SCHED;
;             PG8_LDA(At, 1, 1); PG8_STAGE(PG8_SB(1, 0), b3, voffB); PG8_STAGE(PG8_SB(1, 1), b3 + hstepB, voffB); PG8_STAGE(PG8_SA(1, 0), a3, voffA);
;             PG8_WAIT_V(8); PG8_WAIT_L(0); PG8_BAR; PG8_MMA(1, 0, At, B0); PG8_MMA(1, 1, At, B1); PG8_BAR; PG8_SCHED;
	s_waitcnt lgkmcnt(0)
	v_mfma_f32_16x16x32_bf16 v[62:65], v[130:133], v[176:179], v[62:65]
	v_mfma_f32_16x16x32_bf16 v[58:61], v[138:141], v[176:179], v[58:61]
	v_mfma_f32_16x16x32_bf16 v[50:53], v[130:133], v[192:195], v[50:53]
	v_mfma_f32_16x16x32_bf16 v[42:45], v[138:141], v[192:195], v[42:45]
	v_mfma_f32_16x16x32_bf16 v[30:33], v[130:133], v[200:203], v[30:33]
	v_mfma_f32_16x16x32_bf16 v[26:29], v[138:141], v[200:203], v[26:29]
	v_mfma_f32_16x16x32_bf16 v[18:21], v[130:133], v[208:211], v[18:21]
	v_mfma_f32_16x16x32_bf16 v[10:13], v[138:141], v[208:211], v[10:13]
	v_mfma_f32_16x16x32_bf16 v[62:65], v[134:137], v[188:191], v[62:65]
	v_mfma_f32_16x16x32_bf16 v[58:61], v[142:145], v[188:191], v[58:61]
	v_mfma_f32_16x16x32_bf16 v[50:53], v[134:137], v[196:199], v[50:53]
	v_mfma_f32_16x16x32_bf16 v[42:45], v[142:145], v[196:199], v[42:45]
	v_mfma_f32_16x16x32_bf16 v[30:33], v[134:137], v[204:207], v[30:33]
	v_mfma_f32_16x16x32_bf16 v[26:29], v[142:145], v[204:207], v[26:29]
	v_mfma_f32_16x16x32_bf16 v[18:21], v[134:137], v[212:215], v[18:21]
	v_mfma_f32_16x16x32_bf16 v[10:13], v[142:145], v[212:215], v[10:13]
	v_mfma_f32_16x16x32_bf16 v[54:57], v[146:149], v[176:179], v[54:57]
	v_mfma_f32_16x16x32_bf16 v[46:49], v[168:171], v[176:179], v[46:49]
	v_mfma_f32_16x16x32_bf16 v[38:41], v[146:149], v[192:195], v[38:41]
	v_mfma_f32_16x16x32_bf16 v[34:37], v[168:171], v[192:195], v[34:37]
	v_mfma_f32_16x16x32_bf16 v[22:25], v[146:149], v[200:203], v[22:25]
	v_mfma_f32_16x16x32_bf16 v[14:17], v[168:171], v[200:203], v[14:17]
	v_mfma_f32_16x16x32_bf16 v[6:9], v[146:149], v[208:211], v[6:9]
	v_mfma_f32_16x16x32_bf16 v[2:5], v[168:171], v[208:211], v[2:5]
	v_mfma_f32_16x16x32_bf16 v[54:57], v[162:165], v[188:191], v[54:57]
	v_mfma_f32_16x16x32_bf16 v[46:49], v[172:175], v[188:191], v[46:49]
	v_mfma_f32_16x16x32_bf16 v[38:41], v[162:165], v[196:199], v[38:41]
	v_mfma_f32_16x16x32_bf16 v[34:37], v[172:175], v[196:199], v[34:37]
	v_mfma_f32_16x16x32_bf16 v[22:25], v[162:165], v[204:207], v[22:25]
	v_mfma_f32_16x16x32_bf16 v[14:17], v[172:175], v[204:207], v[14:17]
	v_mfma_f32_16x16x32_bf16 v[6:9], v[162:165], v[212:215], v[6:9]
	v_mfma_f32_16x16x32_bf16 v[2:5], v[172:175], v[212:215], v[2:5]
	s_setprio 0
	s_barrier
	s_add_i32 s52, 0, 0x18000
	s_add_i32 s53, 0, 0x1c000
	v_add_u32_e32 v142, s52, v1
	v_add_u32_e32 v167, s53, v1
	ds_read_b128 v[130:133], v142
	ds_read_b128 v[134:137], v142 offset:1024
	ds_read_b128 v[138:141], v142 offset:2048
	ds_read_b128 v[142:145], v142 offset:3072
	ds_read_b128 v[146:149], v167
	ds_read_b128 v[162:165], v167 offset:1024
	ds_read_b128 v[168:171], v167 offset:2048
	ds_read_b128 v[172:175], v167 offset:3072
	s_add_u32 s26, s26, 0x200000
	s_addc_u32 s27, s27, 0
	s_mov_b32 m0, s35
	v_lshl_add_u64 v[222:223], s[26:27], 0, v[150:151]
	ds_read_b128 v[176:179], v166 offset:32768
	ds_read_b128 v[188:191], v166 offset:33792
	ds_read_b128 v[192:195], v166 offset:34816
	ds_read_b128 v[196:199], v166 offset:35840
	ds_read_b128 v[200:203], v166 offset:36864
	ds_read_b128 v[204:207], v166 offset:37888
	ds_read_b128 v[208:211], v166 offset:38912
	ds_read_b128 v[212:215], v166 offset:39936
	global_load_lds_dwordx4 v[222:223], off
	v_lshl_add_u64 v[222:223], s[26:27], 0, v[154:155]
	s_mov_b32 m0, s42
	s_nop 0
	global_load_lds_dwordx4 v[222:223], off
	s_waitcnt vmcnt(8)
	s_waitcnt lgkmcnt(0)
	s_setprio 1
	s_barrier
	s_waitcnt lgkmcnt(0)
	v_mfma_f32_16x16x32_bf16 v[126:129], v[130:133], v[176:179], v[126:129]
	v_mfma_f32_16x16x32_bf16 v[122:125], v[138:141], v[176:179], v[122:125]
	v_mfma_f32_16x16x32_bf16 v[118:121], v[130:133], v[192:195], v[118:121]
	v_mfma_f32_16x16x32_bf16 v[114:117], v[138:141], v[192:195], v[114:117]
	v_mfma_f32_16x16x32_bf16 v[94:97], v[130:133], v[200:203], v[94:97]
	v_mfma_f32_16x16x32_bf16 v[90:93], v[138:141], v[200:203], v[90:93]
	v_mfma_f32_16x16x32_bf16 v[82:85], v[130:133], v[208:211], v[82:85]
	v_mfma_f32_16x16x32_bf16 v[74:77], v[138:141], v[208:211], v[74:77]
	v_mfma_f32_16x16x32_bf16 v[126:129], v[134:137], v[188:191], v[126:129]
	v_mfma_f32_16x16x32_bf16 v[122:125], v[142:145], v[188:191], v[122:125]
	v_mfma_f32_16x16x32_bf16 v[118:121], v[134:137], v[196:199], v[118:121]
	v_mfma_f32_16x16x32_bf16 v[114:117], v[142:145], v[196:199], v[114:117]
	v_mfma_f32_16x16x32_bf16 v[94:97], v[134:137], v[204:207], v[94:97]
	v_mfma_f32_16x16x32_bf16 v[90:93], v[142:145], v[204:207], v[90:93]
	v_mfma_f32_16x16x32_bf16 v[82:85], v[134:137], v[212:215], v[82:85]
	v_mfma_f32_16x16x32_bf16 v[74:77], v[142:145], v[212:215], v[74:77]
	v_mfma_f32_16x16x32_bf16 v[110:113], v[146:149], v[176:179], v[110:113]
	v_mfma_f32_16x16x32_bf16 v[106:109], v[168:171], v[176:179], v[106:109]
	v_mfma_f32_16x16x32_bf16 v[102:105], v[146:149], v[192:195], v[102:105]
	v_mfma_f32_16x16x32_bf16 v[98:101], v[168:171], v[192:195], v[98:101]
	v_mfma_f32_16x16x32_bf16 v[86:89], v[146:149], v[200:203], v[86:89]
	v_mfma_f32_16x16x32_bf16 v[78:81], v[168:171], v[200:203], v[78:81]
	v_mfma_f32_16x16x32_bf16 v[70:73], v[146:149], v[208:211], v[70:73]
	v_mfma_f32_16x16x32_bf16 v[66:69], v[168:171], v[208:211], v[66:69]
	v_mfma_f32_16x16x32_bf16 v[110:113], v[162:165], v[188:191], v[110:113]
	v_mfma_f32_16x16x32_bf16 v[106:109], v[172:175], v[188:191], v[106:109]
	v_mfma_f32_16x16x32_bf16 v[102:105], v[162:165], v[196:199], v[102:105]
	v_mfma_f32_16x16x32_bf16 v[98:101], v[172:175], v[196:199], v[98:101]
	v_mfma_f32_16x16x32_bf16 v[86:89], v[162:165], v[204:207], v[86:89]
	v_mfma_f32_16x16x32_bf16 v[78:81], v[172:175], v[204:207], v[78:81]
	v_mfma_f32_16x16x32_bf16 v[70:73], v[162:165], v[212:215], v[70:73]
	v_mfma_f32_16x16x32_bf16 v[66:69], v[172:175], v[212:215], v[66:69]
	s_setprio 0
	s_barrier
; #define PG8_STAGE(bufoff, gbase, voff) do { _Pragma("unroll") for (int _i = 0; _i < 2; ++_i) \
;         __builtin_amdgcn_global_load_lds((const unsigned*)((const char*)(gbase) + (voff)[_i]), (LAS unsigned*)(lds + (bufoff) + ldsw + _i * 8192), 16, 0, 0); } while (0)
; #define PG8_LDA(dst, b, h) do { _Pragma("unroll") for (int m = 0; m < 4; ++m) _Pragma("unroll") for (int k = 0; k < 2; ++k) dst[m][k] = *(const LAS bf16x8*)(lds + PG8_SA(b, h) + aoff + m * 2048 + k * 1024); } while (0)
; #define PG8_MMA(ai, bj, At, Bt) do { __builtin_amdgcn_s_setprio(1); _Pragma("unroll") for (int m = 0; m < 4; ++m) _Pragma("unroll") for (int n = 0; n < 2; ++n) _Pragma("unroll") for (int k = 0; k < 2; ++k) \
;         acc[ai][bj][m][n] = __builtin_amdgcn_mfma_f32_16x16x32_bf16(Bt[n][k], At[m][k], acc[ai][bj][m][n], 0, 0, 0); __builtin_amdgcn_s_setprio(0); } while (0)
; #define PG8_WAIT_V(n) asm volatile("s_waitcnt vmcnt(" #n ")" ::: "memory")
; #define PG8_WAIT_L(n) asm volatile("s_waitcnt lgkmcnt(" #n ")" ::: "memory")
; #define PG8_BAR __builtin_amdgcn_s_barrier()
; #define PG8_SCHED __builtin_amdgcn_sched_barrier(0)
; template <class Epi>
; __device__ __forceinline__ void gemm_phase(LAS unsigned char* lds, const Gemm g, const StaticOrder& S, const Epi& E) {
;     ...
;             PG8_LDA(At, 1, 1); PG8_STAGE(PG8_SB(1, 0), b3, voffB); PG8_STAGE(PG8_SB(1, 1), b3 + hstepB, voffB); PG8_STAGE(PG8_SA(1, 0), a3, voffA);
;             PG8_WAIT_V(8); PG8_WAIT_L(0); PG8_BAR; PG8_MMA(1, 0, At, B0); PG8_MMA(1, 1, At, B1); PG8_BAR; PG8_SCHED;
;         }
	s_add_i32 s26, s52, s30
	v_lshl_add_u64 v[184:185], v[184:185], 0, s[84:85]
	s_mov_b32 m0, s26
	ds_read_b128 v[176:179], v166 offset:49152
	ds_read_b128 v[188:191], v166 offset:50176
	ds_read_b128 v[192:195], v166 offset:51200
	ds_read_b128 v[196:199], v166 offset:52224
	ds_read_b128 v[200:203], v166 offset:53248
	ds_read_b128 v[204:207], v166 offset:54272
	ds_read_b128 v[208:211], v166 offset:55296
	ds_read_b128 v[212:215], v166 offset:56320
	global_load_lds_dwordx4 v[184:185], off
	s_add_i32 m0, s26, 0x2000
	s_add_u32 s14, s14, 0x200080
	v_lshl_add_u64 v[184:185], v[216:217], 0, s[84:85]
	s_addc_u32 s15, s15, 0
	s_add_i32 s26, s53, s30
	global_load_lds_dwordx4 v[184:185], off
	v_lshl_add_u64 v[184:185], s[14:15], 0, v[152:153]
	s_mov_b32 m0, s26
	s_nop 0
	global_load_lds_dwordx4 v[184:185], off
	v_lshl_add_u64 v[184:185], s[14:15], 0, v[156:157]
	s_add_i32 m0, s26, 0x2000
	s_nop 0
	global_load_lds_dwordx4 v[184:185], off
	v_lshl_add_u64 v[184:185], v[218:219], 0, s[84:85]
	s_mov_b32 m0, s68
	s_nop 0
	global_load_lds_dwordx4 v[184:185], off
	v_lshl_add_u64 v[184:185], v[220:221], 0, s[84:85]
	s_mov_b32 m0, s69
	s_nop 0
	global_load_lds_dwordx4 v[184:185], off
	s_waitcnt vmcnt(8)
	s_waitcnt lgkmcnt(0)
	s_setprio 1
	s_barrier
	s_waitcnt lgkmcnt(0)
	v_mfma_f32_16x16x32_bf16 v[62:65], v[130:133], v[176:179], v[62:65]
	v_mfma_f32_16x16x32_bf16 v[58:61], v[138:141], v[176:179], v[58:61]
	v_mfma_f32_16x16x32_bf16 v[50:53], v[130:133], v[192:195], v[50:53]
	v_mfma_f32_16x16x32_bf16 v[42:45], v[138:141], v[192:195], v[42:45]
	v_mfma_f32_16x16x32_bf16 v[30:33], v[130:133], v[200:203], v[30:33]
	v_mfma_f32_16x16x32_bf16 v[26:29], v[138:141], v[200:203], v[26:29]
	v_mfma_f32_16x16x32_bf16 v[18:21], v[130:133], v[208:211], v[18:21]
	v_mfma_f32_16x16x32_bf16 v[10:13], v[138:141], v[208:211], v[10:13]
	v_mfma_f32_16x16x32_bf16 v[62:65], v[134:137], v[188:191], v[62:65]
	v_mfma_f32_16x16x32_bf16 v[58:61], v[142:145], v[188:191], v[58:61]
	v_mfma_f32_16x16x32_bf16 v[50:53], v[134:137], v[196:199], v[50:53]
	v_mfma_f32_16x16x32_bf16 v[42:45], v[142:145], v[196:199], v[42:45]
	v_mfma_f32_16x16x32_bf16 v[30:33], v[134:137], v[204:207], v[30:33]
	v_mfma_f32_16x16x32_bf16 v[26:29], v[142:145], v[204:207], v[26:29]
	v_mfma_f32_16x16x32_bf16 v[18:21], v[134:137], v[212:215], v[18:21]
	v_mfma_f32_16x16x32_bf16 v[10:13], v[142:145], v[212:215], v[10:13]
	v_mfma_f32_16x16x32_bf16 v[54:57], v[146:149], v[176:179], v[54:57]
	v_mfma_f32_16x16x32_bf16 v[46:49], v[168:171], v[176:179], v[46:49]
	v_mfma_f32_16x16x32_bf16 v[38:41], v[146:149], v[192:195], v[38:41]
	v_mfma_f32_16x16x32_bf16 v[34:37], v[168:171], v[192:195], v[34:37]
	v_mfma_f32_16x16x32_bf16 v[22:25], v[146:149], v[200:203], v[22:25]
	v_mfma_f32_16x16x32_bf16 v[14:17], v[168:171], v[200:203], v[14:17]
	v_mfma_f32_16x16x32_bf16 v[6:9], v[146:149], v[208:211], v[6:9]
	v_mfma_f32_16x16x32_bf16 v[2:5], v[168:171], v[208:211], v[2:5]
	v_mfma_f32_16x16x32_bf16 v[54:57], v[162:165], v[188:191], v[54:57]
	v_mfma_f32_16x16x32_bf16 v[46:49], v[172:175], v[188:191], v[46:49]
	v_mfma_f32_16x16x32_bf16 v[38:41], v[162:165], v[196:199], v[38:41]
	v_mfma_f32_16x16x32_bf16 v[34:37], v[172:175], v[196:199], v[34:37]
	v_mfma_f32_16x16x32_bf16 v[22:25], v[162:165], v[204:207], v[22:25]
	v_mfma_f32_16x16x32_bf16 v[14:17], v[172:175], v[204:207], v[14:17]
	v_mfma_f32_16x16x32_bf16 v[6:9], v[162:165], v[212:215], v[6:9]
	v_mfma_f32_16x16x32_bf16 v[2:5], v[172:175], v[212:215], v[2:5]
	s_setprio 0
	s_barrier
	s_add_i32 s41, s41, 2
	s_add_u32 s24, s24, 0x100
	s_addc_u32 s25, s25, 0
	s_add_u32 s19, s19, 0x100
	s_addc_u32 s40, s40, 0
	s_cmpk_gt_u32 s41, 0x7d
	s_cbranch_scc0 .LBB0_2233
	s_cmp_ge_u32 s74, 16
	s_cbranch_scc1 .Lwpf_e
	s_lshl_b32 s100, s74, 9
	v_add_u32_e32 v130, s100, v246
	v_lshrrev_b32_e32 v131, 2, v130
	v_and_b32_e32 v130, 3, v130
	v_lshlrev_b32_e32 v130, 7, v130
	v_lshl_add_u32 v130, v131, 12, v130
	s_add_u32 s100, s88, 0x4000000
	s_addc_u32 s101, s89, 0
	s_mov_b32 m0, 0x21000
	s_nop 0
	global_load_lds_dword v130, s[100:101]

; #define PG8_STAGE(bufoff, gbase, voff) do { _Pragma("unroll") for (int _i = 0; _i < 2; ++_i) \
;         __builtin_amdgcn_global_load_lds((const unsigned*)((const char*)(gbase) + (voff)[_i]), (LAS unsigned*)(lds + (bufoff) + ldsw + _i * 8192), 16, 0, 0); } while (0)
; #define PG8_LDA(dst, b, h) do { _Pragma("unroll") for (int m = 0; m < 4; ++m) _Pragma("unroll") for (int k = 0; k < 2; ++k) dst[m][k] = *(const LAS bf16x8*)(lds + PG8_SA(b, h) + aoff + m * 2048 + k * 1024); } while (0)
; #define PG8_LDB(dst, b, h) do { _Pragma("unroll") for (int n = 0; n < 2; ++n) _Pragma("unroll") for (int k = 0; k < 2; ++k) dst[n][k] = *(const LAS bf16x8*)(lds + PG8_SB(b, h) + boff + n * 2048 + k * 1024); } while (0)
; #define PG8_MMA(ai, bj, At, Bt) do { __builtin_amdgcn_s_setprio(1); _Pragma("unroll") for (int m = 0; m < 4; ++m) _Pragma("unroll") for (int n = 0; n < 2; ++n) _Pragma("unroll") for (int k = 0; k < 2; ++k) \
;         acc[ai][bj][m][n] = __builtin_amdgcn_mfma_f32_16x16x32_bf16(Bt[n][k], At[m][k], acc[ai][bj][m][n], 0, 0, 0); __builtin_amdgcn_s_setprio(0); } while (0)
; #define PG8_WAIT_V(n) asm volatile("s_waitcnt vmcnt(" #n ")" ::: "memory")
; #define PG8_WAIT_L(n) asm volatile("s_waitcnt lgkmcnt(" #n ")" ::: "memory")
; #define PG8_BAR __builtin_amdgcn_s_barrier()
; #define PG8_SCHED __builtin_amdgcn_sched_barrier(0)
; template <class Epi>
; __device__ __forceinline__ void gemm_phase(LAS unsigned char* lds, const Gemm g, const StaticOrder& S, const Epi& E) {
;     ...
;             const bool last = (t == nt - 2);
;             const char* a1 = cA + (size_t)(t + 1) * kstep;
;             const char* a2 = last ? nA : cA + (size_t)(t + 2) * kstep; const char* b2 = last ? nB : cB + (size_t)(t + 2) * kstep;
;             const char* a3 = a2 + kstep; const char* b3 = b2 + kstep;
;             PG8_LDB(B0, 0, 0); PG8_LDB(B1, 0, 1); PG8_SCHED; PG8_LDA(At, 0, 0); PG8_STAGE(PG8_SA(1, 1), a1 + hstepA, voffA);
;             PG8_WAIT_V(8); PG8_WAIT_L(0); PG8_BAR; PG8_MMA(0, 0, At, B0); PG8_MMA(0, 1, At, B1); PG8_BAR; PG8_SCHED;
;             PG8_LDA(At, 0, 1); PG8_STAGE(PG8_SB(0, 0), b2, voffB); PG8_STAGE(PG8_SB(0, 1), b2 + hstepB, voffB); PG8_STAGE(PG8_SA(0, 0), a2, voffA);
;             PG8_WAIT_V(8); PG8_WAIT_L(0); PG8_BAR; PG8_MMA(1, 0, At, B0); PG8_MMA(1, 1, At, B1); PG8_BAR; PG8_SCHED;
.LBB0_2332:
	s_add_u32 s14, s24, 0xfff80080
	s_addc_u32 s15, s25, -1
	s_add_i32 s41, 0, 0x10000
	s_cmp_eq_u32 s40, 28
	s_cselect_b32 s27, s1, s15
	s_cselect_b32 s26, s3, s14
	s_cselect_b32 s15, s9, s33
	s_cselect_b32 s14, s17, s19
	s_add_i32 s62, 0, 0x14000
	v_add_u32_e32 v142, s41, v1
	v_add_u32_e32 v170, s62, v1
	ds_read_b128 v[130:133], v142
	ds_read_b128 v[134:137], v142 offset:1024
	ds_read_b128 v[138:141], v142 offset:2048
	ds_read_b128 v[142:145], v142 offset:3072
	ds_read_b128 v[146:149], v170
	ds_read_b128 v[150:153], v170 offset:1024
	ds_read_b128 v[166:169], v170 offset:2048
	ds_read_b128 v[170:173], v170 offset:3072
	v_lshl_add_u64 v[178:179], s[24:25], 0, v[162:163]
	s_add_i32 m0, s35, 0xc000
	ds_read_b128 v[174:177], v181
	ds_read_b128 v[188:191], v181 offset:1024
	ds_read_b128 v[192:195], v181 offset:2048
	ds_read_b128 v[196:199], v181 offset:3072
	ds_read_b128 v[200:203], v181 offset:4096
	ds_read_b128 v[204:207], v181 offset:5120
	ds_read_b128 v[208:211], v181 offset:6144
	ds_read_b128 v[212:215], v181 offset:7168
	global_load_lds_dwordx4 v[178:179], off
	v_lshl_add_u64 v[178:179], s[24:25], 0, v[164:165]
	s_add_i32 m0, s35, 0xe000
	s_nop 0
	global_load_lds_dwordx4 v[178:179], off
	s_waitcnt vmcnt(8)
	s_waitcnt lgkmcnt(0)
	s_setprio 1
	s_barrier
	s_waitcnt lgkmcnt(0)
	v_mfma_f32_16x16x32_bf16 v[126:129], v[130:133], v[174:177], v[126:129]
	v_mfma_f32_16x16x32_bf16 v[122:125], v[138:141], v[174:177], v[122:125]
	v_mfma_f32_16x16x32_bf16 v[118:121], v[130:133], v[192:195], v[118:121]
	v_mfma_f32_16x16x32_bf16 v[114:117], v[138:141], v[192:195], v[114:117]
	v_mfma_f32_16x16x32_bf16 v[102:105], v[130:133], v[200:203], v[102:105]
	v_mfma_f32_16x16x32_bf16 v[98:101], v[138:141], v[200:203], v[98:101]
	v_mfma_f32_16x16x32_bf16 v[86:89], v[130:133], v[208:211], v[86:89]
	v_mfma_f32_16x16x32_bf16 v[82:85], v[138:141], v[208:211], v[82:85]
	v_mfma_f32_16x16x32_bf16 v[126:129], v[134:137], v[188:191], v[126:129]
	v_mfma_f32_16x16x32_bf16 v[122:125], v[142:145], v[188:191], v[122:125]
	v_mfma_f32_16x16x32_bf16 v[118:121], v[134:137], v[196:199], v[118:121]
	v_mfma_f32_16x16x32_bf16 v[114:117], v[142:145], v[196:199], v[114:117]
	v_mfma_f32_16x16x32_bf16 v[102:105], v[134:137], v[204:207], v[102:105]
	v_mfma_f32_16x16x32_bf16 v[98:101], v[142:145], v[204:207], v[98:101]
	v_mfma_f32_16x16x32_bf16 v[86:89], v[134:137], v[212:215], v[86:89]
	v_mfma_f32_16x16x32_bf16 v[82:85], v[142:145], v[212:215], v[82:85]
	v_mfma_f32_16x16x32_bf16 v[110:113], v[146:149], v[174:177], v[110:113]
	v_mfma_f32_16x16x32_bf16 v[106:109], v[166:169], v[174:177], v[106:109]
	v_mfma_f32_16x16x32_bf16 v[94:97], v[146:149], v[192:195], v[94:97]
	v_mfma_f32_16x16x32_bf16 v[90:93], v[166:169], v[192:195], v[90:93]
	v_mfma_f32_16x16x32_bf16 v[78:81], v[146:149], v[200:203], v[78:81]
	v_mfma_f32_16x16x32_bf16 v[74:77], v[166:169], v[200:203], v[74:77]
	v_mfma_f32_16x16x32_bf16 v[70:73], v[146:149], v[208:211], v[70:73]
	v_mfma_f32_16x16x32_bf16 v[66:69], v[166:169], v[208:211], v[66:69]
	v_mfma_f32_16x16x32_bf16 v[110:113], v[150:153], v[188:191], v[110:113]
	v_mfma_f32_16x16x32_bf16 v[106:109], v[170:173], v[188:191], v[106:109]
	v_mfma_f32_16x16x32_bf16 v[94:97], v[150:153], v[196:199], v[94:97]
	v_mfma_f32_16x16x32_bf16 v[90:93], v[170:173], v[196:199], v[90:93]
	v_mfma_f32_16x16x32_bf16 v[78:81], v[150:153], v[204:207], v[78:81]
	v_mfma_f32_16x16x32_bf16 v[74:77], v[170:173], v[204:207], v[74:77]
	v_mfma_f32_16x16x32_bf16 v[70:73], v[150:153], v[212:215], v[70:73]
	v_mfma_f32_16x16x32_bf16 v[66:69], v[170:173], v[212:215], v[66:69]
	s_setprio 0
	s_barrier
	s_add_i32 s41, s41, s34
	v_lshl_add_u64 v[178:179], s[14:15], 0, v[156:157]
	s_mov_b32 m0, s41
	ds_read_b128 v[174:177], v181 offset:16384
	ds_read_b128 v[188:191], v181 offset:17408
	ds_read_b128 v[192:195], v181 offset:18432
	ds_read_b128 v[196:199], v181 offset:19456
	ds_read_b128 v[200:203], v181 offset:20480
	ds_read_b128 v[204:207], v181 offset:21504
	ds_read_b128 v[208:211], v181 offset:22528
	ds_read_b128 v[212:215], v181 offset:23552
	global_load_lds_dwordx4 v[178:179], off
	s_add_i32 m0, s41, 0x2000
	s_add_u32 s52, s14, 0x80000
	v_lshl_add_u64 v[184:185], s[14:15], 0, v[160:161]
	s_addc_u32 s53, s15, 0
	s_add_i32 s41, s62, s34
	global_load_lds_dwordx4 v[184:185], off
	v_lshl_add_u64 v[216:217], s[52:53], 0, v[156:157]
	s_mov_b32 m0, s41
	v_lshl_add_u64 v[218:219], s[26:27], 0, v[158:159]
	global_load_lds_dwordx4 v[216:217], off
	v_lshl_add_u64 v[216:217], s[52:53], 0, v[160:161]
	s_add_i32 m0, s41, 0x2000
	s_nop 0
	global_load_lds_dwordx4 v[216:217], off
	v_lshl_add_u64 v[216:217], s[26:27], 0, v[154:155]
	s_mov_b32 m0, s35
	s_nop 0
	global_load_lds_dwordx4 v[216:217], off
	s_mov_b32 m0, s42
	s_nop 0
	global_load_lds_dwordx4 v[218:219], off
	s_waitcnt vmcnt(8)
	s_waitcnt lgkmcnt(0)
	s_setprio 1
	s_barrier
; #define PG8_STAGE(bufoff, gbase, voff) do { _Pragma("unroll") for (int _i = 0; _i < 2; ++_i) \
;         __builtin_amdgcn_global_load_lds((const unsigned*)((const char*)(gbase) + (voff)[_i]), (LAS unsigned*)(lds + (bufoff) + ldsw + _i * 8192), 16, 0, 0); } while (0)
; #define PG8_LDA(dst, b, h) do { _Pragma("unroll") for (int m = 0; m < 4; ++m) _Pragma("unroll") for (int k = 0; k < 2; ++k) dst[m][k] = *(const LAS bf16x8*)(lds + PG8_SA(b, h) + aoff + m * 2048 + k * 1024); } while (0)
; #define PG8_LDB(dst, b, h) do { _Pragma("unroll") for (int n = 0; n < 2; ++n) _Pragma("unroll") for (int k = 0; k < 2; ++k) dst[n][k] = *(const LAS bf16x8*)(lds + PG8_SB(b, h) + boff + n * 2048 + k * 1024); } while (0)
; #define PG8_MMA(ai, bj, At, Bt) do { __builtin_amdgcn_s_setprio(1); _Pragma("unroll") for (int m = 0; m < 4; ++m) _Pragma("unroll") for (int n = 0; n < 2; ++n) _Pragma("unroll") for (int k = 0; k < 2; ++k) \
;         acc[ai][bj][m][n] = __builtin_amdgcn_mfma_f32_16x16x32_bf16(Bt[n][k], At[m][k], acc[ai][bj][m][n], 0, 0, 0); __builtin_amdgcn_s_setprio(0); } while (0)
; #define PG8_WAIT_V(n) asm volatile("s_waitcnt vmcnt(" #n ")" ::: "memory")
; #define PG8_WAIT_L(n) asm volatile("s_waitcnt lgkmcnt(" #n ")" ::: "memory")
; #define PG8_BAR __builtin_amdgcn_s_barrier()
; #define PG8_SCHED __builtin_amdgcn_sched_barrier(0)
; template <class Epi>
; __device__ __forceinline__ void gemm_phase(LAS unsigned char* lds, const Gemm g, const StaticOrder& S, const Epi& E) {
;     ...
;             PG8_WAIT_V(8); PG8_WAIT_L(0); PG8_BAR; PG8_MMA(1, 0, At, B0); PG8_MMA(1, 1, At, B1); PG8_BAR; PG8_SCHED;
;             PG8_LDB(B0, 1, 0); PG8_LDB(B1, 1, 1); PG8_SCHED; PG8_LDA(At, 1, 0); PG8_STAGE(PG8_SA(0, 1), a2 + hstepA, voffA);
;             PG8_WAIT_V(8); PG8_WAIT_L(0); PG8_BAR; PG8_MMA(0, 0, At, B0); PG8_MMA(0, 1, At, B1); PG8_BAR; PG8_SCHED;
;             PG8_LDA(At, 1, 1); PG8_STAGE(PG8_SB(1, 0), b3, voffB); PG8_STAGE(PG8_SB(1, 1), b3 + hstepB, voffB); PG8_STAGE(PG8_SA(1, 0), a3, voffA);
;             PG8_WAIT_V(8); PG8_WAIT_L(0); PG8_BAR; PG8_MMA(1, 0, At, B0); PG8_MMA(1, 1, At, B1); PG8_BAR; PG8_SCHED;
	s_waitcnt lgkmcnt(0)
	v_mfma_f32_16x16x32_bf16 v[62:65], v[130:133], v[174:177], v[62:65]
	v_mfma_f32_16x16x32_bf16 v[58:61], v[138:141], v[174:177], v[58:61]
	v_mfma_f32_16x16x32_bf16 v[54:57], v[130:133], v[192:195], v[54:57]
	v_mfma_f32_16x16x32_bf16 v[50:53], v[138:141], v[192:195], v[50:53]
	v_mfma_f32_16x16x32_bf16 v[46:49], v[130:133], v[200:203], v[46:49]
	v_mfma_f32_16x16x32_bf16 v[38:41], v[138:141], v[200:203], v[38:41]
	v_mfma_f32_16x16x32_bf16 v[30:33], v[130:133], v[208:211], v[30:33]
	v_mfma_f32_16x16x32_bf16 v[22:25], v[138:141], v[208:211], v[22:25]
	v_mfma_f32_16x16x32_bf16 v[62:65], v[134:137], v[188:191], v[62:65]
	v_mfma_f32_16x16x32_bf16 v[58:61], v[142:145], v[188:191], v[58:61]
	v_mfma_f32_16x16x32_bf16 v[54:57], v[134:137], v[196:199], v[54:57]
	v_mfma_f32_16x16x32_bf16 v[50:53], v[142:145], v[196:199], v[50:53]
	v_mfma_f32_16x16x32_bf16 v[46:49], v[134:137], v[204:207], v[46:49]
	v_mfma_f32_16x16x32_bf16 v[38:41], v[142:145], v[204:207], v[38:41]
	v_mfma_f32_16x16x32_bf16 v[30:33], v[134:137], v[212:215], v[30:33]
	v_mfma_f32_16x16x32_bf16 v[22:25], v[142:145], v[212:215], v[22:25]
	v_mfma_f32_16x16x32_bf16 v[42:45], v[146:149], v[174:177], v[42:45]
	v_mfma_f32_16x16x32_bf16 v[34:37], v[166:169], v[174:177], v[34:37]
	v_mfma_f32_16x16x32_bf16 v[26:29], v[146:149], v[192:195], v[26:29]
	v_mfma_f32_16x16x32_bf16 v[18:21], v[166:169], v[192:195], v[18:21]
	v_mfma_f32_16x16x32_bf16 v[14:17], v[146:149], v[200:203], v[14:17]
	v_mfma_f32_16x16x32_bf16 v[10:13], v[166:169], v[200:203], v[10:13]
	v_mfma_f32_16x16x32_bf16 v[6:9], v[146:149], v[208:211], v[6:9]
	v_mfma_f32_16x16x32_bf16 v[2:5], v[166:169], v[208:211], v[2:5]
	v_mfma_f32_16x16x32_bf16 v[42:45], v[150:153], v[188:191], v[42:45]
	v_mfma_f32_16x16x32_bf16 v[34:37], v[170:173], v[188:191], v[34:37]
	v_mfma_f32_16x16x32_bf16 v[26:29], v[150:153], v[196:199], v[26:29]
	v_mfma_f32_16x16x32_bf16 v[18:21], v[170:173], v[196:199], v[18:21]
	v_mfma_f32_16x16x32_bf16 v[14:17], v[150:153], v[204:207], v[14:17]
	v_mfma_f32_16x16x32_bf16 v[10:13], v[170:173], v[204:207], v[10:13]
	v_mfma_f32_16x16x32_bf16 v[6:9], v[150:153], v[212:215], v[6:9]
	v_mfma_f32_16x16x32_bf16 v[2:5], v[170:173], v[212:215], v[2:5]
	s_setprio 0
	s_barrier
	s_add_i32 s41, 0, 0x18000
	s_add_i32 s52, 0, 0x1c000
	v_add_u32_e32 v142, s41, v1
	v_add_u32_e32 v170, s52, v1
	ds_read_b128 v[130:133], v142
	ds_read_b128 v[134:137], v142 offset:1024
	ds_read_b128 v[138:141], v142 offset:2048
	ds_read_b128 v[142:145], v142 offset:3072
	ds_read_b128 v[146:149], v170
	ds_read_b128 v[150:153], v170 offset:1024
	ds_read_b128 v[166:169], v170 offset:2048
	ds_read_b128 v[170:173], v170 offset:3072
	s_add_u32 s26, s26, 0x80000
	s_addc_u32 s27, s27, 0
	s_mov_b32 m0, s44
	v_lshl_add_u64 v[220:221], s[26:27], 0, v[154:155]
	ds_read_b128 v[174:177], v181 offset:32768
	ds_read_b128 v[188:191], v181 offset:33792
	ds_read_b128 v[192:195], v181 offset:34816
	ds_read_b128 v[196:199], v181 offset:35840
	ds_read_b128 v[200:203], v181 offset:36864
	ds_read_b128 v[204:207], v181 offset:37888
	ds_read_b128 v[208:211], v181 offset:38912
	ds_read_b128 v[212:215], v181 offset:39936
	global_load_lds_dwordx4 v[220:221], off
	v_lshl_add_u64 v[220:221], s[26:27], 0, v[158:159]
	s_mov_b32 m0, s45
	s_nop 0
	global_load_lds_dwordx4 v[220:221], off
	s_waitcnt vmcnt(8)
	s_waitcnt lgkmcnt(0)
	s_setprio 1
	s_barrier
	s_waitcnt lgkmcnt(0)
	v_mfma_f32_16x16x32_bf16 v[126:129], v[130:133], v[174:177], v[126:129]
	v_mfma_f32_16x16x32_bf16 v[122:125], v[138:141], v[174:177], v[122:125]
	v_mfma_f32_16x16x32_bf16 v[118:121], v[130:133], v[192:195], v[118:121]
	v_mfma_f32_16x16x32_bf16 v[114:117], v[138:141], v[192:195], v[114:117]
	v_mfma_f32_16x16x32_bf16 v[102:105], v[130:133], v[200:203], v[102:105]
	v_mfma_f32_16x16x32_bf16 v[98:101], v[138:141], v[200:203], v[98:101]
	v_mfma_f32_16x16x32_bf16 v[86:89], v[130:133], v[208:211], v[86:89]
	v_mfma_f32_16x16x32_bf16 v[82:85], v[138:141], v[208:211], v[82:85]
	v_mfma_f32_16x16x32_bf16 v[126:129], v[134:137], v[188:191], v[126:129]
	v_mfma_f32_16x16x32_bf16 v[122:125], v[142:145], v[188:191], v[122:125]
	v_mfma_f32_16x16x32_bf16 v[118:121], v[134:137], v[196:199], v[118:121]
	v_mfma_f32_16x16x32_bf16 v[114:117], v[142:145], v[196:199], v[114:117]
	v_mfma_f32_16x16x32_bf16 v[102:105], v[134:137], v[204:207], v[102:105]
	v_mfma_f32_16x16x32_bf16 v[98:101], v[142:145], v[204:207], v[98:101]
	v_mfma_f32_16x16x32_bf16 v[86:89], v[134:137], v[212:215], v[86:89]
	v_mfma_f32_16x16x32_bf16 v[82:85], v[142:145], v[212:215], v[82:85]
	v_mfma_f32_16x16x32_bf16 v[110:113], v[146:149], v[174:177], v[110:113]
	v_mfma_f32_16x16x32_bf16 v[106:109], v[166:169], v[174:177], v[106:109]
	v_mfma_f32_16x16x32_bf16 v[94:97], v[146:149], v[192:195], v[94:97]
	v_mfma_f32_16x16x32_bf16 v[90:93], v[166:169], v[192:195], v[90:93]
	v_mfma_f32_16x16x32_bf16 v[78:81], v[146:149], v[200:203], v[78:81]
	v_mfma_f32_16x16x32_bf16 v[74:77], v[166:169], v[200:203], v[74:77]
	v_mfma_f32_16x16x32_bf16 v[70:73], v[146:149], v[208:211], v[70:73]
	v_mfma_f32_16x16x32_bf16 v[66:69], v[166:169], v[208:211], v[66:69]
	v_mfma_f32_16x16x32_bf16 v[110:113], v[150:153], v[188:191], v[110:113]
	v_mfma_f32_16x16x32_bf16 v[106:109], v[170:173], v[188:191], v[106:109]
	v_mfma_f32_16x16x32_bf16 v[94:97], v[150:153], v[196:199], v[94:97]
	v_mfma_f32_16x16x32_bf16 v[90:93], v[170:173], v[196:199], v[90:93]
	v_mfma_f32_16x16x32_bf16 v[78:81], v[150:153], v[204:207], v[78:81]
	v_mfma_f32_16x16x32_bf16 v[74:77], v[170:173], v[204:207], v[74:77]
	v_mfma_f32_16x16x32_bf16 v[70:73], v[150:153], v[212:215], v[70:73]
	v_mfma_f32_16x16x32_bf16 v[66:69], v[170:173], v[212:215], v[66:69]
	s_setprio 0
	s_barrier
; #define PG8_STAGE(bufoff, gbase, voff) do { _Pragma("unroll") for (int _i = 0; _i < 2; ++_i) \
;         __builtin_amdgcn_global_load_lds((const unsigned*)((const char*)(gbase) + (voff)[_i]), (LAS unsigned*)(lds + (bufoff) + ldsw + _i * 8192), 16, 0, 0); } while (0)
; #define PG8_LDA(dst, b, h) do { _Pragma("unroll") for (int m = 0; m < 4; ++m) _Pragma("unroll") for (int k = 0; k < 2; ++k) dst[m][k] = *(const LAS bf16x8*)(lds + PG8_SA(b, h) + aoff + m * 2048 + k * 1024); } while (0)
; #define PG8_MMA(ai, bj, At, Bt) do { __builtin_amdgcn_s_setprio(1); _Pragma("unroll") for (int m = 0; m < 4; ++m) _Pragma("unroll") for (int n = 0; n < 2; ++n) _Pragma("unroll") for (int k = 0; k < 2; ++k) \
;         acc[ai][bj][m][n] = __builtin_amdgcn_mfma_f32_16x16x32_bf16(Bt[n][k], At[m][k], acc[ai][bj][m][n], 0, 0, 0); __builtin_amdgcn_s_setprio(0); } while (0)
; #define PG8_WAIT_V(n) asm volatile("s_waitcnt vmcnt(" #n ")" ::: "memory")
; #define PG8_WAIT_L(n) asm volatile("s_waitcnt lgkmcnt(" #n ")" ::: "memory")
; #define PG8_BAR __builtin_amdgcn_s_barrier()
; #define PG8_SCHED __builtin_amdgcn_sched_barrier(0)
; template <class Epi>
; __device__ __forceinline__ void gemm_phase(LAS unsigned char* lds, const Gemm g, const StaticOrder& S, const Epi& E) {
;     ...
;             PG8_LDA(At, 1, 1); PG8_STAGE(PG8_SB(1, 0), b3, voffB); PG8_STAGE(PG8_SB(1, 1), b3 + hstepB, voffB); PG8_STAGE(PG8_SA(1, 0), a3, voffA);
;             PG8_WAIT_V(8); PG8_WAIT_L(0); PG8_BAR; PG8_MMA(1, 0, At, B0); PG8_MMA(1, 1, At, B1); PG8_BAR; PG8_SCHED;
;         }
	s_add_i32 s26, s41, s34
	v_lshl_add_u64 v[178:179], v[178:179], 0, s[84:85]
	s_mov_b32 m0, s26
	ds_read_b128 v[174:177], v181 offset:49152
	ds_read_b128 v[188:191], v181 offset:50176
	ds_read_b128 v[192:195], v181 offset:51200
	ds_read_b128 v[196:199], v181 offset:52224
	ds_read_b128 v[200:203], v181 offset:53248
	ds_read_b128 v[204:207], v181 offset:54272
	ds_read_b128 v[208:211], v181 offset:55296
	ds_read_b128 v[212:215], v181 offset:56320
	global_load_lds_dwordx4 v[178:179], off
	s_add_i32 m0, s26, 0x2000
	s_add_u32 s14, s14, 0x80080
	v_lshl_add_u64 v[178:179], v[184:185], 0, s[84:85]
	s_addc_u32 s15, s15, 0
	s_add_i32 s26, s52, s34
	global_load_lds_dwordx4 v[178:179], off
	v_lshl_add_u64 v[178:179], s[14:15], 0, v[156:157]
	s_mov_b32 m0, s26
	s_nop 0
	global_load_lds_dwordx4 v[178:179], off
	v_lshl_add_u64 v[178:179], s[14:15], 0, v[160:161]
	s_add_i32 m0, s26, 0x2000
	s_nop 0
	global_load_lds_dwordx4 v[178:179], off
	v_lshl_add_u64 v[178:179], v[216:217], 0, s[84:85]
	s_mov_b32 m0, s86
	s_nop 0
	global_load_lds_dwordx4 v[178:179], off
	v_lshl_add_u64 v[178:179], v[218:219], 0, s[84:85]
	s_mov_b32 m0, s87
	s_nop 0
	global_load_lds_dwordx4 v[178:179], off
	s_waitcnt vmcnt(8)
	s_waitcnt lgkmcnt(0)
	s_setprio 1
	s_barrier
	s_waitcnt lgkmcnt(0)
	v_mfma_f32_16x16x32_bf16 v[62:65], v[130:133], v[174:177], v[62:65]
	v_mfma_f32_16x16x32_bf16 v[58:61], v[138:141], v[174:177], v[58:61]
	v_mfma_f32_16x16x32_bf16 v[54:57], v[130:133], v[192:195], v[54:57]
	v_mfma_f32_16x16x32_bf16 v[50:53], v[138:141], v[192:195], v[50:53]
	v_mfma_f32_16x16x32_bf16 v[46:49], v[130:133], v[200:203], v[46:49]
	v_mfma_f32_16x16x32_bf16 v[38:41], v[138:141], v[200:203], v[38:41]
	v_mfma_f32_16x16x32_bf16 v[30:33], v[130:133], v[208:211], v[30:33]
	v_mfma_f32_16x16x32_bf16 v[22:25], v[138:141], v[208:211], v[22:25]
	v_mfma_f32_16x16x32_bf16 v[62:65], v[134:137], v[188:191], v[62:65]
	v_mfma_f32_16x16x32_bf16 v[58:61], v[142:145], v[188:191], v[58:61]
	v_mfma_f32_16x16x32_bf16 v[54:57], v[134:137], v[196:199], v[54:57]
	v_mfma_f32_16x16x32_bf16 v[50:53], v[142:145], v[196:199], v[50:53]
	v_mfma_f32_16x16x32_bf16 v[46:49], v[134:137], v[204:207], v[46:49]
	v_mfma_f32_16x16x32_bf16 v[38:41], v[142:145], v[204:207], v[38:41]
	v_mfma_f32_16x16x32_bf16 v[30:33], v[134:137], v[212:215], v[30:33]
	v_mfma_f32_16x16x32_bf16 v[22:25], v[142:145], v[212:215], v[22:25]
	v_mfma_f32_16x16x32_bf16 v[42:45], v[146:149], v[174:177], v[42:45]
	v_mfma_f32_16x16x32_bf16 v[34:37], v[166:169], v[174:177], v[34:37]
	v_mfma_f32_16x16x32_bf16 v[26:29], v[146:149], v[192:195], v[26:29]
	v_mfma_f32_16x16x32_bf16 v[18:21], v[166:169], v[192:195], v[18:21]
	v_mfma_f32_16x16x32_bf16 v[14:17], v[146:149], v[200:203], v[14:17]
	v_mfma_f32_16x16x32_bf16 v[10:13], v[166:169], v[200:203], v[10:13]
	v_mfma_f32_16x16x32_bf16 v[6:9], v[146:149], v[208:211], v[6:9]
	v_mfma_f32_16x16x32_bf16 v[2:5], v[166:169], v[208:211], v[2:5]
	v_mfma_f32_16x16x32_bf16 v[42:45], v[150:153], v[188:191], v[42:45]
	v_mfma_f32_16x16x32_bf16 v[34:37], v[170:173], v[188:191], v[34:37]
	v_mfma_f32_16x16x32_bf16 v[26:29], v[150:153], v[196:199], v[26:29]
	v_mfma_f32_16x16x32_bf16 v[18:21], v[170:173], v[196:199], v[18:21]
	v_mfma_f32_16x16x32_bf16 v[14:17], v[150:153], v[204:207], v[14:17]
	v_mfma_f32_16x16x32_bf16 v[10:13], v[170:173], v[204:207], v[10:13]
	v_mfma_f32_16x16x32_bf16 v[6:9], v[150:153], v[212:215], v[6:9]
	v_mfma_f32_16x16x32_bf16 v[2:5], v[170:173], v[212:215], v[2:5]
	s_setprio 0
	s_barrier
	s_add_i32 s40, s40, 2
	s_add_u32 s24, s24, 0x100
	s_addc_u32 s25, s25, 0
	s_add_u32 s19, s19, 0x100
	s_addc_u32 s33, s33, 0
	s_cmp_gt_u32 s40, 29
	s_cbranch_scc0 .LBB0_2332
	s_cmp_ge_u32 s74, 16
	s_cbranch_scc1 .Lwpf_f
	s_lshl_b32 s100, s74, 9
	v_add_u32_e32 v130, s100, v246
	v_lshrrev_b32_e32 v131, 2, v130
	v_and_b32_e32 v130, 3, v130
	v_lshlrev_b32_e32 v130, 7, v130
	v_lshl_add_u32 v130, v131, 12, v130
	v_readlane_b32 s100, v255, 42
	s_nop 3
	s_mov_b32 s101, 0x16900000
	s_cmp_eq_u32 s100, 1
	s_cselect_b32 s101, 0x15100000, s101
	s_cmp_eq_u32 s100, 0
	s_cselect_b32 s101, 0x13700000, s101
	s_add_u32 s100, s38, s101
	s_addc_u32 s101, s39, 0
	s_mov_b32 m0, 0x21000
	s_nop 0
	global_load_lds_dword v130, s[100:101]

; #define PG8_STAGE(bufoff, gbase, voff) do { _Pragma("unroll") for (int _i = 0; _i < 2; ++_i) \
;         __builtin_amdgcn_global_load_lds((const unsigned*)((const char*)(gbase) + (voff)[_i]), (LAS unsigned*)(lds + (bufoff) + ldsw + _i * 8192), 16, 0, 0); } while (0)
; #define PG8_LDA(dst, b, h) do { _Pragma("unroll") for (int m = 0; m < 4; ++m) _Pragma("unroll") for (int k = 0; k < 2; ++k) dst[m][k] = *(const LAS bf16x8*)(lds + PG8_SA(b, h) + aoff + m * 2048 + k * 1024); } while (0)
; #define PG8_LDB(dst, b, h) do { _Pragma("unroll") for (int n = 0; n < 2; ++n) _Pragma("unroll") for (int k = 0; k < 2; ++k) dst[n][k] = *(const LAS bf16x8*)(lds + PG8_SB(b, h) + boff + n * 2048 + k * 1024); } while (0)
; #define PG8_MMA(ai, bj, At, Bt) do { __builtin_amdgcn_s_setprio(1); _Pragma("unroll") for (int m = 0; m < 4; ++m) _Pragma("unroll") for (int n = 0; n < 2; ++n) _Pragma("unroll") for (int k = 0; k < 2; ++k) \
;         acc[ai][bj][m][n] = __builtin_amdgcn_mfma_f32_16x16x32_bf16(Bt[n][k], At[m][k], acc[ai][bj][m][n], 0, 0, 0); __builtin_amdgcn_s_setprio(0); } while (0)
; #define PG8_WAIT_V(n) asm volatile("s_waitcnt vmcnt(" #n ")" ::: "memory")
; #define PG8_WAIT_L(n) asm volatile("s_waitcnt lgkmcnt(" #n ")" ::: "memory")
; #define PG8_BAR __builtin_amdgcn_s_barrier()
; #define PG8_SCHED __builtin_amdgcn_sched_barrier(0)
; template <class Epi>
; __device__ __forceinline__ void gemm_phase(LAS unsigned char* lds, const Gemm g, const StaticOrder& S, const Epi& E) {
;     ...
;             const bool last = (t == nt - 2);
;             const char* a1 = cA + (size_t)(t + 1) * kstep;
;             const char* a2 = last ? nA : cA + (size_t)(t + 2) * kstep; const char* b2 = last ? nB : cB + (size_t)(t + 2) * kstep;
;             const char* a3 = a2 + kstep; const char* b3 = b2 + kstep;
;             PG8_LDB(B0, 0, 0); PG8_LDB(B1, 0, 1); PG8_SCHED; PG8_LDA(At, 0, 0); PG8_STAGE(PG8_SA(1, 1), a1 + hstepA, voffA);
;             PG8_WAIT_V(8); PG8_WAIT_L(0); PG8_BAR; PG8_MMA(0, 0, At, B0); PG8_MMA(0, 1, At, B1); PG8_BAR; PG8_SCHED;
;             PG8_LDA(At, 0, 1); PG8_STAGE(PG8_SB(0, 0), b2, voffB); PG8_STAGE(PG8_SB(0, 1), b2 + hstepB, voffB); PG8_STAGE(PG8_SA(0, 0), a2, voffA);
;             PG8_WAIT_V(8); PG8_WAIT_L(0); PG8_BAR; PG8_MMA(1, 0, At, B0); PG8_MMA(1, 1, At, B1); PG8_BAR; PG8_SCHED;
.LBB0_2376:
	s_add_u32 s14, s22, 0xfff80080
	s_addc_u32 s15, s23, -1
	s_add_i32 s53, 0, 0x10000
	s_cmp_eq_u32 s41, 28
	s_cselect_b32 s25, s3, s15
	s_cselect_b32 s24, s9, s14
	s_cselect_b32 s15, s13, s52
	s_cselect_b32 s14, s17, s40
	s_add_i32 s64, 0, 0x14000
	v_add_u32_e32 v142, s53, v1
	v_add_u32_e32 v170, s64, v1
	ds_read_b128 v[130:133], v142
	ds_read_b128 v[134:137], v142 offset:1024
	ds_read_b128 v[138:141], v142 offset:2048
	ds_read_b128 v[142:145], v142 offset:3072
	ds_read_b128 v[146:149], v170
	ds_read_b128 v[150:153], v170 offset:1024
	ds_read_b128 v[166:169], v170 offset:2048
	ds_read_b128 v[170:173], v170 offset:3072
	v_lshl_add_u64 v[178:179], s[22:23], 0, v[162:163]
	s_add_i32 m0, s30, 0xc000
	ds_read_b128 v[174:177], v181
	ds_read_b128 v[188:191], v181 offset:1024
	ds_read_b128 v[192:195], v181 offset:2048
	ds_read_b128 v[196:199], v181 offset:3072
	ds_read_b128 v[200:203], v181 offset:4096
	ds_read_b128 v[204:207], v181 offset:5120
	ds_read_b128 v[208:211], v181 offset:6144
	ds_read_b128 v[212:215], v181 offset:7168
	global_load_lds_dwordx4 v[178:179], off
	v_lshl_add_u64 v[178:179], s[22:23], 0, v[164:165]
	s_add_i32 m0, s30, 0xe000
	s_nop 0
	global_load_lds_dwordx4 v[178:179], off
	s_waitcnt vmcnt(8)
	s_waitcnt lgkmcnt(0)
	s_setprio 1
	s_barrier
	s_waitcnt lgkmcnt(0)
	v_mfma_f32_16x16x32_bf16 v[126:129], v[130:133], v[174:177], v[126:129]
	v_mfma_f32_16x16x32_bf16 v[122:125], v[138:141], v[174:177], v[122:125]
	v_mfma_f32_16x16x32_bf16 v[118:121], v[130:133], v[192:195], v[118:121]
	v_mfma_f32_16x16x32_bf16 v[114:117], v[138:141], v[192:195], v[114:117]
	v_mfma_f32_16x16x32_bf16 v[102:105], v[130:133], v[200:203], v[102:105]
	v_mfma_f32_16x16x32_bf16 v[98:101], v[138:141], v[200:203], v[98:101]
	v_mfma_f32_16x16x32_bf16 v[86:89], v[130:133], v[208:211], v[86:89]
	v_mfma_f32_16x16x32_bf16 v[82:85], v[138:141], v[208:211], v[82:85]
	v_mfma_f32_16x16x32_bf16 v[126:129], v[134:137], v[188:191], v[126:129]
	v_mfma_f32_16x16x32_bf16 v[122:125], v[142:145], v[188:191], v[122:125]
	v_mfma_f32_16x16x32_bf16 v[118:121], v[134:137], v[196:199], v[118:121]
	v_mfma_f32_16x16x32_bf16 v[114:117], v[142:145], v[196:199], v[114:117]
	v_mfma_f32_16x16x32_bf16 v[102:105], v[134:137], v[204:207], v[102:105]
	v_mfma_f32_16x16x32_bf16 v[98:101], v[142:145], v[204:207], v[98:101]
	v_mfma_f32_16x16x32_bf16 v[86:89], v[134:137], v[212:215], v[86:89]
	v_mfma_f32_16x16x32_bf16 v[82:85], v[142:145], v[212:215], v[82:85]
	v_mfma_f32_16x16x32_bf16 v[110:113], v[146:149], v[174:177], v[110:113]
	v_mfma_f32_16x16x32_bf16 v[106:109], v[166:169], v[174:177], v[106:109]
	v_mfma_f32_16x16x32_bf16 v[94:97], v[146:149], v[192:195], v[94:97]
	v_mfma_f32_16x16x32_bf16 v[90:93], v[166:169], v[192:195], v[90:93]
	v_mfma_f32_16x16x32_bf16 v[78:81], v[146:149], v[200:203], v[78:81]
	v_mfma_f32_16x16x32_bf16 v[74:77], v[166:169], v[200:203], v[74:77]
	v_mfma_f32_16x16x32_bf16 v[70:73], v[146:149], v[208:211], v[70:73]
	v_mfma_f32_16x16x32_bf16 v[66:69], v[166:169], v[208:211], v[66:69]
	v_mfma_f32_16x16x32_bf16 v[110:113], v[150:153], v[188:191], v[110:113]
	v_mfma_f32_16x16x32_bf16 v[106:109], v[170:173], v[188:191], v[106:109]
	v_mfma_f32_16x16x32_bf16 v[94:97], v[150:153], v[196:199], v[94:97]
	v_mfma_f32_16x16x32_bf16 v[90:93], v[170:173], v[196:199], v[90:93]
	v_mfma_f32_16x16x32_bf16 v[78:81], v[150:153], v[204:207], v[78:81]
	v_mfma_f32_16x16x32_bf16 v[74:77], v[170:173], v[204:207], v[74:77]
	v_mfma_f32_16x16x32_bf16 v[70:73], v[150:153], v[212:215], v[70:73]
	v_mfma_f32_16x16x32_bf16 v[66:69], v[170:173], v[212:215], v[66:69]
	s_setprio 0
	s_barrier
	s_add_i32 s53, s53, s27
	v_lshl_add_u64 v[178:179], s[14:15], 0, v[156:157]
	s_mov_b32 m0, s53
	ds_read_b128 v[174:177], v181 offset:16384
	ds_read_b128 v[188:191], v181 offset:17408
	ds_read_b128 v[192:195], v181 offset:18432
	ds_read_b128 v[196:199], v181 offset:19456
	ds_read_b128 v[200:203], v181 offset:20480
	ds_read_b128 v[204:207], v181 offset:21504
	ds_read_b128 v[208:211], v181 offset:22528
	ds_read_b128 v[212:215], v181 offset:23552
	global_load_lds_dwordx4 v[178:179], off
	s_add_i32 m0, s53, 0x2000
	s_add_u32 s62, s14, 0x80000
	v_lshl_add_u64 v[184:185], s[14:15], 0, v[160:161]
	s_addc_u32 s63, s15, 0
	s_add_i32 s53, s64, s27
	global_load_lds_dwordx4 v[184:185], off
	v_lshl_add_u64 v[186:187], s[62:63], 0, v[156:157]
	s_mov_b32 m0, s53
	v_lshl_add_u64 v[216:217], s[24:25], 0, v[158:159]
	global_load_lds_dwordx4 v[186:187], off
	v_lshl_add_u64 v[186:187], s[62:63], 0, v[160:161]
	s_add_i32 m0, s53, 0x2000
	s_nop 0
	global_load_lds_dwordx4 v[186:187], off
	v_lshl_add_u64 v[186:187], s[24:25], 0, v[154:155]
	s_mov_b32 m0, s30
	s_nop 0
	global_load_lds_dwordx4 v[186:187], off
	s_mov_b32 m0, s31
	s_nop 0
	global_load_lds_dwordx4 v[216:217], off
	s_waitcnt vmcnt(8)
	s_waitcnt lgkmcnt(0)
	s_setprio 1
	s_barrier
; #define PG8_STAGE(bufoff, gbase, voff) do { _Pragma("unroll") for (int _i = 0; _i < 2; ++_i) \
;         __builtin_amdgcn_global_load_lds((const unsigned*)((const char*)(gbase) + (voff)[_i]), (LAS unsigned*)(lds + (bufoff) + ldsw + _i * 8192), 16, 0, 0); } while (0)
; #define PG8_LDA(dst, b, h) do { _Pragma("unroll") for (int m = 0; m < 4; ++m) _Pragma("unroll") for (int k = 0; k < 2; ++k) dst[m][k] = *(const LAS bf16x8*)(lds + PG8_SA(b, h) + aoff + m * 2048 + k * 1024); } while (0)
; #define PG8_LDB(dst, b, h) do { _Pragma("unroll") for (int n = 0; n < 2; ++n) _Pragma("unroll") for (int k = 0; k < 2; ++k) dst[n][k] = *(const LAS bf16x8*)(lds + PG8_SB(b, h) + boff + n * 2048 + k * 1024); } while (0)
; #define PG8_MMA(ai, bj, At, Bt) do { __builtin_amdgcn_s_setprio(1); _Pragma("unroll") for (int m = 0; m < 4; ++m) _Pragma("unroll") for (int n = 0; n < 2; ++n) _Pragma("unroll") for (int k = 0; k < 2; ++k) \
;         acc[ai][bj][m][n] = __builtin_amdgcn_mfma_f32_16x16x32_bf16(Bt[n][k], At[m][k], acc[ai][bj][m][n], 0, 0, 0); __builtin_amdgcn_s_setprio(0); } while (0)
; #define PG8_WAIT_V(n) asm volatile("s_waitcnt vmcnt(" #n ")" ::: "memory")
; #define PG8_WAIT_L(n) asm volatile("s_waitcnt lgkmcnt(" #n ")" ::: "memory")
; #define PG8_BAR __builtin_amdgcn_s_barrier()
; #define PG8_SCHED __builtin_amdgcn_sched_barrier(0)
; template <class Epi>
; __device__ __forceinline__ void gemm_phase(LAS unsigned char* lds, const Gemm g, const StaticOrder& S, const Epi& E) {
;     ...
;             PG8_WAIT_V(8); PG8_WAIT_L(0); PG8_BAR; PG8_MMA(0, 0, At, B0); PG8_MMA(0, 1, At, B1); PG8_BAR; PG8_SCHED;
;             PG8_LDA(At, 0, 1); PG8_STAGE(PG8_SB(0, 0), b2, voffB); PG8_STAGE(PG8_SB(0, 1), b2 + hstepB, voffB); PG8_STAGE(PG8_SA(0, 0), a2, voffA);
;             PG8_WAIT_V(8); PG8_WAIT_L(0); PG8_BAR; PG8_MMA(1, 0, At, B0); PG8_MMA(1, 1, At, B1); PG8_BAR; PG8_SCHED;
;             PG8_LDB(B0, 1, 0); PG8_LDB(B1, 1, 1); PG8_SCHED; PG8_LDA(At, 1, 0); PG8_STAGE(PG8_SA(0, 1), a2 + hstepA, voffA);
;             PG8_WAIT_V(8); PG8_WAIT_L(0); PG8_BAR; PG8_MMA(0, 0, At, B0); PG8_MMA(0, 1, At, B1); PG8_BAR; PG8_SCHED;
	s_waitcnt lgkmcnt(0)
	v_mfma_f32_16x16x32_bf16 v[62:65], v[130:133], v[174:177], v[62:65]
	v_mfma_f32_16x16x32_bf16 v[58:61], v[138:141], v[174:177], v[58:61]
	v_mfma_f32_16x16x32_bf16 v[54:57], v[130:133], v[192:195], v[54:57]
	v_mfma_f32_16x16x32_bf16 v[50:53], v[138:141], v[192:195], v[50:53]
	v_mfma_f32_16x16x32_bf16 v[46:49], v[130:133], v[200:203], v[46:49]
	v_mfma_f32_16x16x32_bf16 v[38:41], v[138:141], v[200:203], v[38:41]
	v_mfma_f32_16x16x32_bf16 v[30:33], v[130:133], v[208:211], v[30:33]
	v_mfma_f32_16x16x32_bf16 v[22:25], v[138:141], v[208:211], v[22:25]
	v_mfma_f32_16x16x32_bf16 v[62:65], v[134:137], v[188:191], v[62:65]
	v_mfma_f32_16x16x32_bf16 v[58:61], v[142:145], v[188:191], v[58:61]
	v_mfma_f32_16x16x32_bf16 v[54:57], v[134:137], v[196:199], v[54:57]
	v_mfma_f32_16x16x32_bf16 v[50:53], v[142:145], v[196:199], v[50:53]
	v_mfma_f32_16x16x32_bf16 v[46:49], v[134:137], v[204:207], v[46:49]
	v_mfma_f32_16x16x32_bf16 v[38:41], v[142:145], v[204:207], v[38:41]
	v_mfma_f32_16x16x32_bf16 v[30:33], v[134:137], v[212:215], v[30:33]
	v_mfma_f32_16x16x32_bf16 v[22:25], v[142:145], v[212:215], v[22:25]
	v_mfma_f32_16x16x32_bf16 v[42:45], v[146:149], v[174:177], v[42:45]
	v_mfma_f32_16x16x32_bf16 v[34:37], v[166:169], v[174:177], v[34:37]
	v_mfma_f32_16x16x32_bf16 v[26:29], v[146:149], v[192:195], v[26:29]
	v_mfma_f32_16x16x32_bf16 v[18:21], v[166:169], v[192:195], v[18:21]
	v_mfma_f32_16x16x32_bf16 v[14:17], v[146:149], v[200:203], v[14:17]
	v_mfma_f32_16x16x32_bf16 v[10:13], v[166:169], v[200:203], v[10:13]
	v_mfma_f32_16x16x32_bf16 v[6:9], v[146:149], v[208:211], v[6:9]
	v_mfma_f32_16x16x32_bf16 v[2:5], v[166:169], v[208:211], v[2:5]
	v_mfma_f32_16x16x32_bf16 v[42:45], v[150:153], v[188:191], v[42:45]
	v_mfma_f32_16x16x32_bf16 v[34:37], v[170:173], v[188:191], v[34:37]
	v_mfma_f32_16x16x32_bf16 v[26:29], v[150:153], v[196:199], v[26:29]
	v_mfma_f32_16x16x32_bf16 v[18:21], v[170:173], v[196:199], v[18:21]
	v_mfma_f32_16x16x32_bf16 v[14:17], v[150:153], v[204:207], v[14:17]
	v_mfma_f32_16x16x32_bf16 v[10:13], v[170:173], v[204:207], v[10:13]
	v_mfma_f32_16x16x32_bf16 v[6:9], v[150:153], v[212:215], v[6:9]
	v_mfma_f32_16x16x32_bf16 v[2:5], v[170:173], v[212:215], v[2:5]
	s_setprio 0
	s_barrier
	s_add_i32 s53, 0, 0x18000
	s_add_i32 s62, 0, 0x1c000
	v_add_u32_e32 v142, s53, v1
	v_add_u32_e32 v170, s62, v1
	ds_read_b128 v[130:133], v142
	ds_read_b128 v[134:137], v142 offset:1024
	ds_read_b128 v[138:141], v142 offset:2048
	ds_read_b128 v[142:145], v142 offset:3072
	ds_read_b128 v[146:149], v170
	ds_read_b128 v[150:153], v170 offset:1024
	ds_read_b128 v[166:169], v170 offset:2048
	ds_read_b128 v[170:173], v170 offset:3072
	s_add_u32 s24, s24, 0x80000
	s_addc_u32 s25, s25, 0
	s_mov_b32 m0, s34
	v_lshl_add_u64 v[218:219], s[24:25], 0, v[154:155]
	ds_read_b128 v[174:177], v181 offset:32768
	ds_read_b128 v[188:191], v181 offset:33792
	ds_read_b128 v[192:195], v181 offset:34816
	ds_read_b128 v[196:199], v181 offset:35840
	ds_read_b128 v[200:203], v181 offset:36864
	ds_read_b128 v[204:207], v181 offset:37888
	ds_read_b128 v[208:211], v181 offset:38912
	ds_read_b128 v[212:215], v181 offset:39936
	global_load_lds_dwordx4 v[218:219], off
	v_lshl_add_u64 v[218:219], s[24:25], 0, v[158:159]
	s_mov_b32 m0, s35
	s_nop 0
	global_load_lds_dwordx4 v[218:219], off
	s_waitcnt vmcnt(8)
	s_waitcnt lgkmcnt(0)
	s_setprio 1
	s_barrier
	s_waitcnt lgkmcnt(0)
	v_mfma_f32_16x16x32_bf16 v[126:129], v[130:133], v[174:177], v[126:129]
	v_mfma_f32_16x16x32_bf16 v[122:125], v[138:141], v[174:177], v[122:125]
	v_mfma_f32_16x16x32_bf16 v[118:121], v[130:133], v[192:195], v[118:121]
	v_mfma_f32_16x16x32_bf16 v[114:117], v[138:141], v[192:195], v[114:117]
	v_mfma_f32_16x16x32_bf16 v[102:105], v[130:133], v[200:203], v[102:105]
	v_mfma_f32_16x16x32_bf16 v[98:101], v[138:141], v[200:203], v[98:101]
	v_mfma_f32_16x16x32_bf16 v[86:89], v[130:133], v[208:211], v[86:89]
	v_mfma_f32_16x16x32_bf16 v[82:85], v[138:141], v[208:211], v[82:85]
	v_mfma_f32_16x16x32_bf16 v[126:129], v[134:137], v[188:191], v[126:129]
	v_mfma_f32_16x16x32_bf16 v[122:125], v[142:145], v[188:191], v[122:125]
	v_mfma_f32_16x16x32_bf16 v[118:121], v[134:137], v[196:199], v[118:121]
	v_mfma_f32_16x16x32_bf16 v[114:117], v[142:145], v[196:199], v[114:117]
	v_mfma_f32_16x16x32_bf16 v[102:105], v[134:137], v[204:207], v[102:105]
	v_mfma_f32_16x16x32_bf16 v[98:101], v[142:145], v[204:207], v[98:101]
	v_mfma_f32_16x16x32_bf16 v[86:89], v[134:137], v[212:215], v[86:89]
	v_mfma_f32_16x16x32_bf16 v[82:85], v[142:145], v[212:215], v[82:85]
	v_mfma_f32_16x16x32_bf16 v[110:113], v[146:149], v[174:177], v[110:113]
	v_mfma_f32_16x16x32_bf16 v[106:109], v[166:169], v[174:177], v[106:109]
	v_mfma_f32_16x16x32_bf16 v[94:97], v[146:149], v[192:195], v[94:97]
	v_mfma_f32_16x16x32_bf16 v[90:93], v[166:169], v[192:195], v[90:93]
	v_mfma_f32_16x16x32_bf16 v[78:81], v[146:149], v[200:203], v[78:81]
	v_mfma_f32_16x16x32_bf16 v[74:77], v[166:169], v[200:203], v[74:77]
	v_mfma_f32_16x16x32_bf16 v[70:73], v[146:149], v[208:211], v[70:73]
	v_mfma_f32_16x16x32_bf16 v[66:69], v[166:169], v[208:211], v[66:69]
	v_mfma_f32_16x16x32_bf16 v[110:113], v[150:153], v[188:191], v[110:113]
	v_mfma_f32_16x16x32_bf16 v[106:109], v[170:173], v[188:191], v[106:109]
	v_mfma_f32_16x16x32_bf16 v[94:97], v[150:153], v[196:199], v[94:97]
	v_mfma_f32_16x16x32_bf16 v[90:93], v[170:173], v[196:199], v[90:93]
	v_mfma_f32_16x16x32_bf16 v[78:81], v[150:153], v[204:207], v[78:81]
	v_mfma_f32_16x16x32_bf16 v[74:77], v[170:173], v[204:207], v[74:77]
	v_mfma_f32_16x16x32_bf16 v[70:73], v[150:153], v[212:215], v[70:73]
	v_mfma_f32_16x16x32_bf16 v[66:69], v[170:173], v[212:215], v[66:69]
	s_setprio 0
	s_barrier
; #define PG8_STAGE(bufoff, gbase, voff) do { _Pragma("unroll") for (int _i = 0; _i < 2; ++_i) \
;         __builtin_amdgcn_global_load_lds((const unsigned*)((const char*)(gbase) + (voff)[_i]), (LAS unsigned*)(lds + (bufoff) + ldsw + _i * 8192), 16, 0, 0); } while (0)
; #define PG8_LDA(dst, b, h) do { _Pragma("unroll") for (int m = 0; m < 4; ++m) _Pragma("unroll") for (int k = 0; k < 2; ++k) dst[m][k] = *(const LAS bf16x8*)(lds + PG8_SA(b, h) + aoff + m * 2048 + k * 1024); } while (0)
; #define PG8_MMA(ai, bj, At, Bt) do { __builtin_amdgcn_s_setprio(1); _Pragma("unroll") for (int m = 0; m < 4; ++m) _Pragma("unroll") for (int n = 0; n < 2; ++n) _Pragma("unroll") for (int k = 0; k < 2; ++k) \
;         acc[ai][bj][m][n] = __builtin_amdgcn_mfma_f32_16x16x32_bf16(Bt[n][k], At[m][k], acc[ai][bj][m][n], 0, 0, 0); __builtin_amdgcn_s_setprio(0); } while (0)
; #define PG8_WAIT_V(n) asm volatile("s_waitcnt vmcnt(" #n ")" ::: "memory")
; #define PG8_WAIT_L(n) asm volatile("s_waitcnt lgkmcnt(" #n ")" ::: "memory")
; #define PG8_BAR __builtin_amdgcn_s_barrier()
; #define PG8_SCHED __builtin_amdgcn_sched_barrier(0)
; template <class Epi>
; __device__ __forceinline__ void gemm_phase(LAS unsigned char* lds, const Gemm g, const StaticOrder& S, const Epi& E) {
;     ...
;             PG8_LDA(At, 1, 1); PG8_STAGE(PG8_SB(1, 0), b3, voffB); PG8_STAGE(PG8_SB(1, 1), b3 + hstepB, voffB); PG8_STAGE(PG8_SA(1, 0), a3, voffA);
;             PG8_WAIT_V(8); PG8_WAIT_L(0); PG8_BAR; PG8_MMA(1, 0, At, B0); PG8_MMA(1, 1, At, B1); PG8_BAR; PG8_SCHED;
;         }
;         if (wr == 0) PG8_BAR;
	s_add_i32 s24, s53, s27
	v_lshl_add_u64 v[178:179], v[178:179], 0, s[84:85]
	s_mov_b32 m0, s24
	ds_read_b128 v[174:177], v181 offset:49152
	ds_read_b128 v[188:191], v181 offset:50176
	ds_read_b128 v[192:195], v181 offset:51200
	ds_read_b128 v[196:199], v181 offset:52224
	ds_read_b128 v[200:203], v181 offset:53248
	ds_read_b128 v[204:207], v181 offset:54272
	ds_read_b128 v[208:211], v181 offset:55296
	ds_read_b128 v[212:215], v181 offset:56320
	global_load_lds_dwordx4 v[178:179], off
	s_add_i32 m0, s24, 0x2000
	s_add_u32 s14, s14, 0x80080
	v_lshl_add_u64 v[178:179], v[184:185], 0, s[84:85]
	s_addc_u32 s15, s15, 0
	s_add_i32 s24, s62, s27
	global_load_lds_dwordx4 v[178:179], off
	v_lshl_add_u64 v[178:179], s[14:15], 0, v[156:157]
	s_mov_b32 m0, s24
	s_nop 0
	global_load_lds_dwordx4 v[178:179], off
	v_lshl_add_u64 v[178:179], s[14:15], 0, v[160:161]
	s_add_i32 m0, s24, 0x2000
	s_nop 0
	global_load_lds_dwordx4 v[178:179], off
	v_lshl_add_u64 v[178:179], v[186:187], 0, s[84:85]
	s_mov_b32 m0, s45
	s_nop 0
	global_load_lds_dwordx4 v[178:179], off
	v_lshl_add_u64 v[178:179], v[216:217], 0, s[84:85]
	s_mov_b32 m0, s68
	s_nop 0
	global_load_lds_dwordx4 v[178:179], off
	s_waitcnt vmcnt(8)
	s_waitcnt lgkmcnt(0)
	s_setprio 1
	s_barrier
	s_waitcnt lgkmcnt(0)
	v_mfma_f32_16x16x32_bf16 v[62:65], v[130:133], v[174:177], v[62:65]
	v_mfma_f32_16x16x32_bf16 v[58:61], v[138:141], v[174:177], v[58:61]
	v_mfma_f32_16x16x32_bf16 v[54:57], v[130:133], v[192:195], v[54:57]
	v_mfma_f32_16x16x32_bf16 v[50:53], v[138:141], v[192:195], v[50:53]
	v_mfma_f32_16x16x32_bf16 v[46:49], v[130:133], v[200:203], v[46:49]
	v_mfma_f32_16x16x32_bf16 v[38:41], v[138:141], v[200:203], v[38:41]
	v_mfma_f32_16x16x32_bf16 v[30:33], v[130:133], v[208:211], v[30:33]
	v_mfma_f32_16x16x32_bf16 v[22:25], v[138:141], v[208:211], v[22:25]
	v_mfma_f32_16x16x32_bf16 v[62:65], v[134:137], v[188:191], v[62:65]
	v_mfma_f32_16x16x32_bf16 v[58:61], v[142:145], v[188:191], v[58:61]
	v_mfma_f32_16x16x32_bf16 v[54:57], v[134:137], v[196:199], v[54:57]
	v_mfma_f32_16x16x32_bf16 v[50:53], v[142:145], v[196:199], v[50:53]
	v_mfma_f32_16x16x32_bf16 v[46:49], v[134:137], v[204:207], v[46:49]
	v_mfma_f32_16x16x32_bf16 v[38:41], v[142:145], v[204:207], v[38:41]
	v_mfma_f32_16x16x32_bf16 v[30:33], v[134:137], v[212:215], v[30:33]
	v_mfma_f32_16x16x32_bf16 v[22:25], v[142:145], v[212:215], v[22:25]
	v_mfma_f32_16x16x32_bf16 v[42:45], v[146:149], v[174:177], v[42:45]
	v_mfma_f32_16x16x32_bf16 v[34:37], v[166:169], v[174:177], v[34:37]
	v_mfma_f32_16x16x32_bf16 v[26:29], v[146:149], v[192:195], v[26:29]
	v_mfma_f32_16x16x32_bf16 v[18:21], v[166:169], v[192:195], v[18:21]
	v_mfma_f32_16x16x32_bf16 v[14:17], v[146:149], v[200:203], v[14:17]
	v_mfma_f32_16x16x32_bf16 v[10:13], v[166:169], v[200:203], v[10:13]
	v_mfma_f32_16x16x32_bf16 v[6:9], v[146:149], v[208:211], v[6:9]
	v_mfma_f32_16x16x32_bf16 v[2:5], v[166:169], v[208:211], v[2:5]
	v_mfma_f32_16x16x32_bf16 v[42:45], v[150:153], v[188:191], v[42:45]
	v_mfma_f32_16x16x32_bf16 v[34:37], v[170:173], v[188:191], v[34:37]
	v_mfma_f32_16x16x32_bf16 v[26:29], v[150:153], v[196:199], v[26:29]
	v_mfma_f32_16x16x32_bf16 v[18:21], v[170:173], v[196:199], v[18:21]
	v_mfma_f32_16x16x32_bf16 v[14:17], v[150:153], v[204:207], v[14:17]
	v_mfma_f32_16x16x32_bf16 v[10:13], v[170:173], v[204:207], v[10:13]
	v_mfma_f32_16x16x32_bf16 v[6:9], v[150:153], v[212:215], v[6:9]
	v_mfma_f32_16x16x32_bf16 v[2:5], v[170:173], v[212:215], v[2:5]
	s_setprio 0
	s_barrier
	s_add_i32 s41, s41, 2
	s_add_u32 s22, s22, 0x100
	s_addc_u32 s23, s23, 0
	s_add_u32 s40, s40, 0x100
	s_addc_u32 s52, s52, 0
	s_cmp_gt_u32 s41, 29
	s_cbranch_scc0 .LBB0_2376
	v_mov_b64_e32 v[250:251], 0xff
	v_mov_b64_e32 v[252:253], 0x100
	v_mov_b32_e32 v183, 0x7f800000
	s_and_b64 vcc, exec, s[10:11]
	s_cbranch_vccz .LBB0_2379
	s_barrier
